# speedup vs baseline: 1.0131x; 1.0095x over previous
; #define WAIT_V(n) asm volatile("s_waitcnt vmcnt(" #n ")" ::: "memory")
; #define BAR __builtin_amdgcn_s_barrier()
;     ...
;     const int tid = opaque_tid(wave);
;     const int wid = tid >> 6, lane = tid & 63, wr = wid >> 2, wc = wid & 3, fr = lane & 15, fq = lane >> 4;
;     int offA[2], offB[2];
;     _Pragma("unroll") for (int i = 0; i < 2; ++i) {
;       int r, c; stage_rc(tid * 16 + i * 8192, r, c);
;       offA[i] = (r * lda + c) * 2; offB[i] = (r * ldb + c) * 2;
;     }
;     const int brow = pm * BM;
;     f32x4 acc[2][2][4][2];
;     _Pragma("unroll") for (int a = 0; a < 2; ++a) _Pragma("unroll") for (int b = 0; b < 2; ++b) _Pragma("unroll") for (int m = 0; m < 4; ++m) _Pragma("unroll") for (int n = 0; n < 2; ++n)
;       acc[a][b][m][n] = f32x4{0.f, 0.f, 0.f, 0.f};
;     bf16x8 At[4][2], B0[2][2], B1[2][2];
;     if (wr == 1) BAR;
;     if (first_tile) { WAIT_V(0); }
;     else if constexpr (mode == MODE_RESID_LN) { WAIT_V(0); }
;     else if constexpr (mode == MODE_SWIGLU) { WAIT_V(6); }
;     else if constexpr (mode == MODE_V) { WAIT_V(24); }
;     else { WAIT_V(12); }
;     first_tile = false;
;     BAR;
;     BAR;
.LBB0_94:
	v_bfe_i32 v4, v130, 27, 1
	v_lshlrev_b32_e32 v2, 4, v130
	v_lshrrev_b32_e32 v4, 22, v4
	v_add_u32_e32 v4, v2, v4
	v_and_b32_e32 v4, 0xfffffc00, v4
	v_sub_u32_e32 v4, v2, v4
	v_lshrrev_b32_e32 v5, 4, v4
	v_bitop3_b32 v4, v5, v4, 32 bitop3:0x6c
	v_ashrrev_i32_e32 v3, 31, v130
	v_ashrrev_i32_e32 v6, 31, v4
	v_lshrrev_b32_e32 v3, 26, v3
	v_lshrrev_b32_e32 v6, 26, v6
	v_add_u32_e32 v3, v130, v3
	v_add_u32_e32 v6, v4, v6
	v_ashrrev_i32_e32 v3, 6, v3
	v_lshrrev_b32_e32 v7, 6, v6
	v_and_b32_e32 v6, 0xc0, v6
	v_lshlrev_b32_e32 v5, 3, v3
	v_lshlrev_b32_e32 v3, 5, v3
	v_sub_u32_e32 v4, v4, v6
	v_and_b32_e32 v5, 0xffff0, v5
	v_and_b32_e32 v3, 32, v3
	v_ashrrev_i16_sdwa v4, v128, sext(v4) dst_sel:DWORD dst_unused:UNUSED_PAD src0_sel:DWORD src1_sel:BYTE_0
	v_add_u32_sdwa v3, v3, sext(v4) dst_sel:DWORD dst_unused:UNUSED_PAD src0_sel:DWORD src1_sel:WORD_0
	v_add_lshl_u32 v4, v7, v5, 12
	v_add_u32_e32 v2, 0x2000, v2
	v_lshl_add_u32 v143, v3, 1, v4
	v_ashrrev_i32_e32 v3, 31, v2
	v_lshrrev_b32_e32 v3, 22, v3
	v_add_u32_e32 v3, v2, v3
	v_ashrrev_i32_e32 v3, 10, v3
	v_mul_i32_i24_e32 v4, 0x400, v3
	v_sub_u32_e32 v2, v2, v4
	v_lshrrev_b32_e32 v4, 4, v2
	v_bitop3_b32 v2, v4, v2, 32 bitop3:0x6c
	v_ashrrev_i32_e32 v5, 31, v2
	v_lshrrev_b32_e32 v5, 26, v5
	v_add_u32_e32 v5, v2, v5
	v_lshrrev_b32_e32 v6, 6, v5
	v_and_b32_e32 v5, 0xc0, v5
	v_lshlrev_b32_e32 v4, 3, v3
	v_lshlrev_b32_e32 v3, 5, v3
	v_sub_u32_e32 v2, v2, v5
	v_and_b32_e32 v4, 0xffff0, v4
	v_and_b32_e32 v3, 32, v3
	v_ashrrev_i16_sdwa v2, v128, sext(v2) dst_sel:DWORD dst_unused:UNUSED_PAD src0_sel:DWORD src1_sel:BYTE_0
	v_add_u32_sdwa v2, v3, sext(v2) dst_sel:DWORD dst_unused:UNUSED_PAD src0_sel:DWORD src1_sel:WORD_0
	v_add_lshl_u32 v3, v6, v4, 12
	v_lshl_add_u32 v144, v2, 1, v3
	v_and_b32_e32 v3, 15, v0
	v_lshlrev_b32_e32 v5, 2, v0
	v_and_b32_e32 v2, 48, v0
	v_lshlrev_b32_e32 v3, 6, v3
	v_and_b32_e32 v5, 32, v5
	v_lshlrev_b32_e32 v0, 6, v0
	v_or_b32_e32 v4, v3, v2
	v_bitop3_b32 v3, v3, v5, v2 bitop3:0x36
	v_lshlrev_b32_e32 v6, 6, v130
	v_lshlrev_b32_e32 v1, 13, v1
	v_and_or_b32 v0, v0, s34, v2
	v_and_or_b32 v3, v6, s33, v3
	v_bitop3_b32 v0, v1, v0, v5 bitop3:0xf6
	v_or_b32_e32 v6, 0x400, v3
	v_or_b32_e32 v7, 0x800, v3
	v_or_b32_e32 v8, 0xc00, v3
	v_or_b32_e32 v134, 0x800, v0
	v_or_b32_e32 v133, 0x1000, v0
	v_or_b32_e32 v132, 0x1800, v0
	v_mov_b32_e32 v0, 0
	v_bitop3_b32 v131, v4, v1, v5 bitop3:0xde
	s_mov_b32 s14, -2
	s_mov_b32 s15, 0
	v_or_b32_e32 v149, 0x10000, v3
	v_or_b32_e32 v150, 0x10000, v6
	v_or_b32_e32 v151, 0x10000, v7
	v_or_b32_e32 v152, 0x10000, v8
	v_or_b32_e32 v145, 0x14000, v3
	v_or_b32_e32 v146, 0x14000, v6
	v_or_b32_e32 v147, 0x14000, v7
	v_or_b32_e32 v148, 0x14000, v8
	v_or_b32_e32 v139, 0x18000, v3
	v_or_b32_e32 v140, 0x18000, v6
	v_or_b32_e32 v141, 0x18000, v7
	v_or_b32_e32 v142, 0x18000, v8
	v_or_b32_e32 v135, 0x1c000, v3
	v_or_b32_e32 v136, 0x1c000, v6
	v_or_b32_e32 v137, 0x1c000, v7
	v_or_b32_e32 v138, 0x1c000, v8
	v_mov_b32_e32 v1, v0
	v_mov_b32_e32 v2, v0
	v_mov_b32_e32 v3, v0
	v_mov_b32_e32 v4, v0
	v_mov_b32_e32 v5, v0
	v_mov_b32_e32 v6, v0
	v_mov_b32_e32 v7, v0
	v_mov_b32_e32 v8, v0
	v_mov_b32_e32 v9, v0
	v_mov_b32_e32 v10, v0
	v_mov_b32_e32 v11, v0
	v_mov_b32_e32 v12, v0
	v_mov_b32_e32 v13, v0
	v_mov_b32_e32 v14, v0
	v_mov_b32_e32 v15, v0
	v_mov_b32_e32 v16, v0
	v_mov_b32_e32 v17, v0
	v_mov_b32_e32 v18, v0
	v_mov_b32_e32 v19, v0
	v_mov_b32_e32 v20, v0
	v_mov_b32_e32 v21, v0
	v_mov_b32_e32 v22, v0
	v_mov_b32_e32 v23, v0
	v_mov_b32_e32 v24, v0
	v_mov_b32_e32 v25, v0
	v_mov_b32_e32 v26, v0
	v_mov_b32_e32 v27, v0
	v_mov_b32_e32 v28, v0
	v_mov_b32_e32 v29, v0
	v_mov_b32_e32 v30, v0
	v_mov_b32_e32 v31, v0
	v_mov_b32_e32 v32, v0
	v_mov_b32_e32 v33, v0
	v_mov_b32_e32 v34, v0
	v_mov_b32_e32 v35, v0
	v_mov_b32_e32 v36, v0
	v_mov_b32_e32 v37, v0
	v_mov_b32_e32 v38, v0
	v_mov_b32_e32 v39, v0
	v_mov_b32_e32 v40, v0
	v_mov_b32_e32 v41, v0
	v_mov_b32_e32 v42, v0
	v_mov_b32_e32 v43, v0
	v_mov_b32_e32 v44, v0
	v_mov_b32_e32 v45, v0
	v_mov_b32_e32 v46, v0
	v_mov_b32_e32 v47, v0
	v_mov_b32_e32 v48, v0
	v_mov_b32_e32 v49, v0
	v_mov_b32_e32 v50, v0
	v_mov_b32_e32 v51, v0
	v_mov_b32_e32 v52, v0
	v_mov_b32_e32 v53, v0
	v_mov_b32_e32 v54, v0
	v_mov_b32_e32 v55, v0
	v_mov_b32_e32 v56, v0
	v_mov_b32_e32 v57, v0
	v_mov_b32_e32 v58, v0
	v_mov_b32_e32 v59, v0
	v_mov_b32_e32 v60, v0
	v_mov_b32_e32 v61, v0
	v_mov_b32_e32 v62, v0
	v_mov_b32_e32 v63, v0
	v_mov_b32_e32 v64, v0
	v_mov_b32_e32 v65, v0
	v_mov_b32_e32 v66, v0
	v_mov_b32_e32 v67, v0
	v_mov_b32_e32 v68, v0
	v_mov_b32_e32 v69, v0
	v_mov_b32_e32 v70, v0
	v_mov_b32_e32 v71, v0
	v_mov_b32_e32 v72, v0
	v_mov_b32_e32 v73, v0
	v_mov_b32_e32 v74, v0
	v_mov_b32_e32 v75, v0
	v_mov_b32_e32 v76, v0
	v_mov_b32_e32 v77, v0
	v_mov_b32_e32 v78, v0
	v_mov_b32_e32 v79, v0
	v_mov_b32_e32 v80, v0
	v_mov_b32_e32 v81, v0
	v_mov_b32_e32 v82, v0
	v_mov_b32_e32 v83, v0
	v_mov_b32_e32 v84, v0
	v_mov_b32_e32 v85, v0
	v_mov_b32_e32 v86, v0
	v_mov_b32_e32 v87, v0
	v_mov_b32_e32 v88, v0
	v_mov_b32_e32 v89, v0
	v_mov_b32_e32 v90, v0
	v_mov_b32_e32 v91, v0
	v_mov_b32_e32 v92, v0
	v_mov_b32_e32 v93, v0
	v_mov_b32_e32 v94, v0
	v_mov_b32_e32 v95, v0
	v_mov_b32_e32 v96, v0
	v_mov_b32_e32 v97, v0
	v_mov_b32_e32 v98, v0
	v_mov_b32_e32 v99, v0
	v_mov_b32_e32 v100, v0
	v_mov_b32_e32 v101, v0
	v_mov_b32_e32 v102, v0
	v_mov_b32_e32 v103, v0
	v_mov_b32_e32 v104, v0
	v_mov_b32_e32 v105, v0
	v_mov_b32_e32 v106, v0
	v_mov_b32_e32 v107, v0
	v_mov_b32_e32 v108, v0
	v_mov_b32_e32 v109, v0
	v_mov_b32_e32 v110, v0
	v_mov_b32_e32 v111, v0
	v_mov_b32_e32 v112, v0
	v_mov_b32_e32 v113, v0
	v_mov_b32_e32 v114, v0
	v_mov_b32_e32 v115, v0
	v_mov_b32_e32 v116, v0
	v_mov_b32_e32 v117, v0
	v_mov_b32_e32 v118, v0
	v_mov_b32_e32 v119, v0
	v_mov_b32_e32 v120, v0
	v_mov_b32_e32 v121, v0
	v_mov_b32_e32 v122, v0
	v_mov_b32_e32 v123, v0
	v_mov_b32_e32 v124, v0
	v_mov_b32_e32 v125, v0
	v_mov_b32_e32 v126, v0
	v_mov_b32_e32 v127, v0
	s_barrier
	s_barrier
	s_branch .Lmy_rot_95
; #define STAGE(P, RS, SOFF, OFF, kt) do { const int _so = (SOFF) + (kt) * (BK * 2); \
;     _Pragma("unroll") for (int _i = 0; _i < 2; ++_i) { \
;       __builtin_amdgcn_raw_ptr_buffer_load_lds(RS, (__attribute__((address_space(3))) void*)((P) + wave * 1024 + _i * 8192), 16, OFF[_i], _so, 0, 0); } } while (0)
; #define LDA(dst, b, h) _Pragma("unroll") for (int m = 0; m < 4; ++m) _Pragma("unroll") for (int k = 0; k < 2; ++k) \
;     dst[m][k] = *reinterpret_cast<const bf16x8*>(SA(b, h) + lds_byte(wr * 64 + m * 16 + fr, k * 32 + fq * 8))
; #define LDB(dst, b, h) _Pragma("unroll") for (int n = 0; n < 2; ++n) _Pragma("unroll") for (int k = 0; k < 2; ++k) \
;     dst[n][k] = *reinterpret_cast<const bf16x8*>(SB(b, h) + lds_byte(wc * 32 + n * 16 + fr, k * 32 + fq * 8))
; #define WAIT_V(n) asm volatile("s_waitcnt vmcnt(" #n ")" ::: "memory")
; #define WAIT_L(n) asm volatile("s_waitcnt lgkmcnt(" #n ")" ::: "memory")
; #define BAR __builtin_amdgcn_s_barrier()
; #define SCHED __builtin_amdgcn_sched_barrier(0)
;     ...
;       LDB(B0, 0, 0); SCHED; LDA(At, 0, 0); STAGE(SA(1, 1), rsA, sA1, offA, t + 1);
;       WAIT_L(8); BAR; WAIT_L(0); MMA(0, 0, At, B0); BAR; SCHED;
;       LDB(B1, 0, 1); STAGE(SB(0, 0), rsB, sB0, offB, t + 2);
;       BAR; WAIT_L(0); MMA(0, 1, At, B1); BAR;
;       LDA(At, 0, 1); STAGE(SA(0, 0), rsA, sA0, offA, t + 2);
;       BAR; WAIT_L(0); MMA(1, 0, At, B0); BAR; SCHED;
;     ...
;       WAIT_V(6); BAR; MMA(1, 1, At, B1); BAR;
.LBB0_95:
	s_waitcnt vmcnt(6)
	s_barrier
	v_mfma_f32_16x16x32_bf16 v[28:31], v[202:205], v[170:173], v[28:31]
	v_mfma_f32_16x16x32_bf16 v[28:31], v[206:209], v[174:177], v[28:31]
	v_mfma_f32_16x16x32_bf16 v[24:27], v[210:213], v[170:173], v[24:27]
	v_mfma_f32_16x16x32_bf16 v[24:27], v[214:217], v[174:177], v[24:27]
	v_mfma_f32_16x16x32_bf16 v[20:23], v[202:205], v[178:181], v[20:23]
	v_mfma_f32_16x16x32_bf16 v[20:23], v[206:209], v[182:185], v[20:23]
	v_mfma_f32_16x16x32_bf16 v[16:19], v[210:213], v[178:181], v[16:19]
	v_mfma_f32_16x16x32_bf16 v[16:19], v[214:217], v[182:185], v[16:19]
	v_mfma_f32_16x16x32_bf16 v[12:15], v[202:205], v[186:189], v[12:15]
	v_mfma_f32_16x16x32_bf16 v[12:15], v[206:209], v[190:193], v[12:15]
	v_mfma_f32_16x16x32_bf16 v[8:11], v[210:213], v[186:189], v[8:11]
	v_mfma_f32_16x16x32_bf16 v[8:11], v[214:217], v[190:193], v[8:11]
	v_mfma_f32_16x16x32_bf16 v[4:7], v[202:205], v[194:197], v[4:7]
	v_mfma_f32_16x16x32_bf16 v[4:7], v[206:209], v[198:201], v[4:7]
	v_mfma_f32_16x16x32_bf16 v[0:3], v[210:213], v[194:197], v[0:3]
	v_mfma_f32_16x16x32_bf16 v[0:3], v[214:217], v[198:201], v[0:3]
	s_barrier
.Lmy_rot_95:
	ds_read_b128 v[154:157], v149
	ds_read_b128 v[158:161], v150
	ds_read_b128 v[162:165], v151
	ds_read_b128 v[166:169], v152
	s_add_i32 s43, s37, s15
	s_add_i32 s10, s43, 0x80
	s_mov_b32 m0, s30
	ds_read_b128 v[170:173], v131
	ds_read_b128 v[174:177], v131 offset:1024
	ds_read_b128 v[178:181], v134
	ds_read_b128 v[182:185], v134 offset:1024
	ds_read_b128 v[186:189], v133
	ds_read_b128 v[190:193], v133 offset:1024
	ds_read_b128 v[194:197], v132
	ds_read_b128 v[198:201], v132 offset:1024
	buffer_load_dwordx4 v143, s[4:7], s10 offen lds
	s_mov_b32 m0, s31
	s_nop 0
	buffer_load_dwordx4 v144, s[4:7], s10 offen lds
	s_waitcnt lgkmcnt(8)
	s_barrier
	s_waitcnt lgkmcnt(0)
	v_mfma_f32_16x16x32_bf16 v[124:127], v[154:157], v[170:173], v[124:127]
	v_mfma_f32_16x16x32_bf16 v[124:127], v[158:161], v[174:177], v[124:127]
	v_mfma_f32_16x16x32_bf16 v[120:123], v[162:165], v[170:173], v[120:123]
	v_mfma_f32_16x16x32_bf16 v[120:123], v[166:169], v[174:177], v[120:123]
	v_mfma_f32_16x16x32_bf16 v[116:119], v[154:157], v[178:181], v[116:119]
	v_mfma_f32_16x16x32_bf16 v[116:119], v[158:161], v[182:185], v[116:119]
	v_mfma_f32_16x16x32_bf16 v[112:115], v[162:165], v[178:181], v[112:115]
	v_mfma_f32_16x16x32_bf16 v[112:115], v[166:169], v[182:185], v[112:115]
	v_mfma_f32_16x16x32_bf16 v[108:111], v[154:157], v[186:189], v[108:111]
	v_mfma_f32_16x16x32_bf16 v[108:111], v[158:161], v[190:193], v[108:111]
	v_mfma_f32_16x16x32_bf16 v[104:107], v[162:165], v[186:189], v[104:107]
	v_mfma_f32_16x16x32_bf16 v[104:107], v[166:169], v[190:193], v[104:107]
	v_mfma_f32_16x16x32_bf16 v[100:103], v[154:157], v[194:197], v[100:103]
	v_mfma_f32_16x16x32_bf16 v[100:103], v[158:161], v[198:201], v[100:103]
	v_mfma_f32_16x16x32_bf16 v[96:99], v[162:165], v[194:197], v[96:99]
	v_mfma_f32_16x16x32_bf16 v[96:99], v[166:169], v[198:201], v[96:99]
	s_barrier
	s_add_i32 s44, s39, s15
	s_add_i32 s45, s44, 0x100
	s_mov_b32 s10, s6
	s_mov_b32 s11, s7
	s_mov_b32 m0, s1
	ds_read_b128 v[202:205], v145
	ds_read_b128 v[206:209], v146
	ds_read_b128 v[210:213], v147
	ds_read_b128 v[214:217], v148
	buffer_load_dwordx4 v143, s[8:11], s45 offen lds
	s_mov_b32 m0, s3
	s_nop 0
	buffer_load_dwordx4 v144, s[8:11], s45 offen lds
	s_barrier
	s_waitcnt lgkmcnt(0)
	v_mfma_f32_16x16x32_bf16 v[92:95], v[202:205], v[170:173], v[92:95]
	v_mfma_f32_16x16x32_bf16 v[92:95], v[206:209], v[174:177], v[92:95]
	v_mfma_f32_16x16x32_bf16 v[88:91], v[210:213], v[170:173], v[88:91]
	v_mfma_f32_16x16x32_bf16 v[88:91], v[214:217], v[174:177], v[88:91]
	v_mfma_f32_16x16x32_bf16 v[84:87], v[202:205], v[178:181], v[84:87]
	v_mfma_f32_16x16x32_bf16 v[84:87], v[206:209], v[182:185], v[84:87]
	v_mfma_f32_16x16x32_bf16 v[80:83], v[210:213], v[178:181], v[80:83]
	v_mfma_f32_16x16x32_bf16 v[80:83], v[214:217], v[182:185], v[80:83]
	v_mfma_f32_16x16x32_bf16 v[76:79], v[202:205], v[186:189], v[76:79]
	v_mfma_f32_16x16x32_bf16 v[76:79], v[206:209], v[190:193], v[76:79]
	v_mfma_f32_16x16x32_bf16 v[72:75], v[210:213], v[186:189], v[72:75]
	v_mfma_f32_16x16x32_bf16 v[72:75], v[214:217], v[190:193], v[72:75]
	v_mfma_f32_16x16x32_bf16 v[68:71], v[202:205], v[194:197], v[68:71]
	v_mfma_f32_16x16x32_bf16 v[68:71], v[206:209], v[198:201], v[68:71]
	v_mfma_f32_16x16x32_bf16 v[64:67], v[210:213], v[194:197], v[64:67]
	v_mfma_f32_16x16x32_bf16 v[64:67], v[214:217], v[198:201], v[64:67]
	s_barrier
	s_add_i32 s45, s38, s15
	s_add_i32 s46, s45, 0x100
	s_mov_b32 m0, s0
	ds_read_b128 v[170:173], v131 offset:16384
	ds_read_b128 v[174:177], v131 offset:17408
	ds_read_b128 v[178:181], v134 offset:16384
	ds_read_b128 v[182:185], v134 offset:17408
	ds_read_b128 v[186:189], v133 offset:16384
	ds_read_b128 v[190:193], v133 offset:17408
	ds_read_b128 v[194:197], v132 offset:16384
	ds_read_b128 v[198:201], v132 offset:17408
	buffer_load_dwordx4 v143, s[4:7], s46 offen lds
	s_mov_b32 m0, s18
	s_nop 0
	buffer_load_dwordx4 v144, s[4:7], s46 offen lds
	s_barrier
	s_waitcnt lgkmcnt(0)
	v_mfma_f32_16x16x32_bf16 v[60:63], v[154:157], v[170:173], v[60:63]
	v_mfma_f32_16x16x32_bf16 v[60:63], v[158:161], v[174:177], v[60:63]
	v_mfma_f32_16x16x32_bf16 v[56:59], v[162:165], v[170:173], v[56:59]
	v_mfma_f32_16x16x32_bf16 v[56:59], v[166:169], v[174:177], v[56:59]
	v_mfma_f32_16x16x32_bf16 v[52:55], v[154:157], v[178:181], v[52:55]
	v_mfma_f32_16x16x32_bf16 v[52:55], v[158:161], v[182:185], v[52:55]
	v_mfma_f32_16x16x32_bf16 v[48:51], v[162:165], v[178:181], v[48:51]
	v_mfma_f32_16x16x32_bf16 v[48:51], v[166:169], v[182:185], v[48:51]
	v_mfma_f32_16x16x32_bf16 v[44:47], v[154:157], v[186:189], v[44:47]
	v_mfma_f32_16x16x32_bf16 v[44:47], v[158:161], v[190:193], v[44:47]
	v_mfma_f32_16x16x32_bf16 v[40:43], v[162:165], v[186:189], v[40:43]
	v_mfma_f32_16x16x32_bf16 v[40:43], v[166:169], v[190:193], v[40:43]
	v_mfma_f32_16x16x32_bf16 v[36:39], v[154:157], v[194:197], v[36:39]
	v_mfma_f32_16x16x32_bf16 v[36:39], v[158:161], v[198:201], v[36:39]
	v_mfma_f32_16x16x32_bf16 v[32:35], v[162:165], v[194:197], v[32:35]
	v_mfma_f32_16x16x32_bf16 v[32:35], v[166:169], v[198:201], v[32:35]
	s_barrier
; #define STAGE(P, RS, SOFF, OFF, kt) do { const int _so = (SOFF) + (kt) * (BK * 2); \
;     _Pragma("unroll") for (int _i = 0; _i < 2; ++_i) { \
;       __builtin_amdgcn_raw_ptr_buffer_load_lds(RS, (__attribute__((address_space(3))) void*)((P) + wave * 1024 + _i * 8192), 16, OFF[_i], _so, 0, 0); } } while (0)
; #define LDA(dst, b, h) _Pragma("unroll") for (int m = 0; m < 4; ++m) _Pragma("unroll") for (int k = 0; k < 2; ++k) \
;     dst[m][k] = *reinterpret_cast<const bf16x8*>(SA(b, h) + lds_byte(wr * 64 + m * 16 + fr, k * 32 + fq * 8))
; #define LDB(dst, b, h) _Pragma("unroll") for (int n = 0; n < 2; ++n) _Pragma("unroll") for (int k = 0; k < 2; ++k) \
;     dst[n][k] = *reinterpret_cast<const bf16x8*>(SB(b, h) + lds_byte(wc * 32 + n * 16 + fr, k * 32 + fq * 8))
; #define WAIT_V(n) asm volatile("s_waitcnt vmcnt(" #n ")" ::: "memory")
; #define WAIT_L(n) asm volatile("s_waitcnt lgkmcnt(" #n ")" ::: "memory")
; #define BAR __builtin_amdgcn_s_barrier()
; #define SCHED __builtin_amdgcn_sched_barrier(0)
;     ...
;       STAGE(SB(0, 1), rsB, sB1, offB, t + 2);
;       WAIT_V(6); BAR; MMA(1, 1, At, B1); BAR;
;       LDB(B0, 1, 0); SCHED; LDA(At, 1, 0); STAGE(SA(0, 1), rsA, sA1, offA, t + 2);
;       WAIT_L(8); BAR; WAIT_L(0); MMA(0, 0, At, B0); BAR; SCHED;
;       LDB(B1, 1, 1); STAGE(SB(1, 0), rsB, sB0, offB, t + 3);
;       BAR; WAIT_L(0); MMA(0, 1, At, B1); BAR;
;       LDA(At, 1, 1); STAGE(SA(1, 0), rsA, sA0, offA, t + 3);
	s_add_i32 s46, s40, s15
	s_add_i32 s47, s46, 0x100
	s_mov_b32 m0, s19
	s_nop 0
	buffer_load_dwordx4 v143, s[8:11], s47 offen lds
	s_mov_b32 m0, s20
	s_nop 0
	buffer_load_dwordx4 v144, s[8:11], s47 offen lds
	s_waitcnt vmcnt(6)
	s_barrier
	v_mfma_f32_16x16x32_bf16 v[28:31], v[202:205], v[170:173], v[28:31]
	v_mfma_f32_16x16x32_bf16 v[28:31], v[206:209], v[174:177], v[28:31]
	v_mfma_f32_16x16x32_bf16 v[24:27], v[210:213], v[170:173], v[24:27]
	v_mfma_f32_16x16x32_bf16 v[24:27], v[214:217], v[174:177], v[24:27]
	v_mfma_f32_16x16x32_bf16 v[20:23], v[202:205], v[178:181], v[20:23]
	v_mfma_f32_16x16x32_bf16 v[20:23], v[206:209], v[182:185], v[20:23]
	v_mfma_f32_16x16x32_bf16 v[16:19], v[210:213], v[178:181], v[16:19]
	v_mfma_f32_16x16x32_bf16 v[16:19], v[214:217], v[182:185], v[16:19]
	v_mfma_f32_16x16x32_bf16 v[12:15], v[202:205], v[186:189], v[12:15]
	v_mfma_f32_16x16x32_bf16 v[12:15], v[206:209], v[190:193], v[12:15]
	v_mfma_f32_16x16x32_bf16 v[8:11], v[210:213], v[186:189], v[8:11]
	v_mfma_f32_16x16x32_bf16 v[8:11], v[214:217], v[190:193], v[8:11]
	v_mfma_f32_16x16x32_bf16 v[4:7], v[202:205], v[194:197], v[4:7]
	v_mfma_f32_16x16x32_bf16 v[4:7], v[206:209], v[198:201], v[4:7]
	v_mfma_f32_16x16x32_bf16 v[0:3], v[210:213], v[194:197], v[0:3]
	v_mfma_f32_16x16x32_bf16 v[0:3], v[214:217], v[198:201], v[0:3]
	s_barrier
	ds_read_b128 v[154:157], v139
	ds_read_b128 v[158:161], v140
	ds_read_b128 v[162:165], v141
	ds_read_b128 v[166:169], v142
	s_addk_i32 s43, 0x100
	s_mov_b32 m0, s21
	ds_read_b128 v[170:173], v131 offset:32768
	ds_read_b128 v[174:177], v131 offset:33792
	ds_read_b128 v[178:181], v134 offset:32768
	ds_read_b128 v[182:185], v134 offset:33792
	ds_read_b128 v[186:189], v133 offset:32768
	ds_read_b128 v[190:193], v133 offset:33792
	ds_read_b128 v[194:197], v132 offset:32768
	ds_read_b128 v[198:201], v132 offset:33792
	buffer_load_dwordx4 v143, s[4:7], s43 offen lds
	s_mov_b32 m0, s22
	s_nop 0
	buffer_load_dwordx4 v144, s[4:7], s43 offen lds
	s_waitcnt lgkmcnt(8)
	s_barrier
	s_waitcnt lgkmcnt(0)
	v_mfma_f32_16x16x32_bf16 v[124:127], v[154:157], v[170:173], v[124:127]
	v_mfma_f32_16x16x32_bf16 v[124:127], v[158:161], v[174:177], v[124:127]
	v_mfma_f32_16x16x32_bf16 v[120:123], v[162:165], v[170:173], v[120:123]
	v_mfma_f32_16x16x32_bf16 v[120:123], v[166:169], v[174:177], v[120:123]
	v_mfma_f32_16x16x32_bf16 v[116:119], v[154:157], v[178:181], v[116:119]
	v_mfma_f32_16x16x32_bf16 v[116:119], v[158:161], v[182:185], v[116:119]
	v_mfma_f32_16x16x32_bf16 v[112:115], v[162:165], v[178:181], v[112:115]
	v_mfma_f32_16x16x32_bf16 v[112:115], v[166:169], v[182:185], v[112:115]
	v_mfma_f32_16x16x32_bf16 v[108:111], v[154:157], v[186:189], v[108:111]
	v_mfma_f32_16x16x32_bf16 v[108:111], v[158:161], v[190:193], v[108:111]
	v_mfma_f32_16x16x32_bf16 v[104:107], v[162:165], v[186:189], v[104:107]
	v_mfma_f32_16x16x32_bf16 v[104:107], v[166:169], v[190:193], v[104:107]
	v_mfma_f32_16x16x32_bf16 v[100:103], v[154:157], v[194:197], v[100:103]
	v_mfma_f32_16x16x32_bf16 v[100:103], v[158:161], v[198:201], v[100:103]
	v_mfma_f32_16x16x32_bf16 v[96:99], v[162:165], v[194:197], v[96:99]
	v_mfma_f32_16x16x32_bf16 v[96:99], v[166:169], v[198:201], v[96:99]
	s_barrier
	s_addk_i32 s44, 0x180
	s_mov_b32 m0, s23
	ds_read_b128 v[202:205], v135
	ds_read_b128 v[206:209], v136
	ds_read_b128 v[210:213], v137
	ds_read_b128 v[214:217], v138
	buffer_load_dwordx4 v143, s[8:11], s44 offen lds
	s_mov_b32 m0, s24
	s_nop 0
	buffer_load_dwordx4 v144, s[8:11], s44 offen lds
	s_barrier
	s_waitcnt lgkmcnt(0)
	v_mfma_f32_16x16x32_bf16 v[92:95], v[202:205], v[170:173], v[92:95]
	v_mfma_f32_16x16x32_bf16 v[92:95], v[206:209], v[174:177], v[92:95]
	v_mfma_f32_16x16x32_bf16 v[88:91], v[210:213], v[170:173], v[88:91]
	v_mfma_f32_16x16x32_bf16 v[88:91], v[214:217], v[174:177], v[88:91]
	v_mfma_f32_16x16x32_bf16 v[84:87], v[202:205], v[178:181], v[84:87]
	v_mfma_f32_16x16x32_bf16 v[84:87], v[206:209], v[182:185], v[84:87]
	v_mfma_f32_16x16x32_bf16 v[80:83], v[210:213], v[178:181], v[80:83]
	v_mfma_f32_16x16x32_bf16 v[80:83], v[214:217], v[182:185], v[80:83]
	v_mfma_f32_16x16x32_bf16 v[76:79], v[202:205], v[186:189], v[76:79]
	v_mfma_f32_16x16x32_bf16 v[76:79], v[206:209], v[190:193], v[76:79]
	v_mfma_f32_16x16x32_bf16 v[72:75], v[210:213], v[186:189], v[72:75]
	v_mfma_f32_16x16x32_bf16 v[72:75], v[214:217], v[190:193], v[72:75]
	v_mfma_f32_16x16x32_bf16 v[68:71], v[202:205], v[194:197], v[68:71]
	v_mfma_f32_16x16x32_bf16 v[68:71], v[206:209], v[198:201], v[68:71]
	v_mfma_f32_16x16x32_bf16 v[64:67], v[210:213], v[194:197], v[64:67]
	v_mfma_f32_16x16x32_bf16 v[64:67], v[214:217], v[198:201], v[64:67]
	s_barrier
	s_addk_i32 s45, 0x180
	s_mov_b32 m0, s25
	ds_read_b128 v[170:173], v131 offset:49152
	ds_read_b128 v[174:177], v131 offset:50176
	ds_read_b128 v[178:181], v134 offset:49152
	ds_read_b128 v[182:185], v134 offset:50176
	ds_read_b128 v[186:189], v133 offset:49152
	ds_read_b128 v[190:193], v133 offset:50176
	ds_read_b128 v[194:197], v132 offset:49152
	ds_read_b128 v[198:201], v132 offset:50176
	buffer_load_dwordx4 v143, s[4:7], s45 offen lds
	s_mov_b32 m0, s26
	s_nop 0
	buffer_load_dwordx4 v144, s[4:7], s45 offen lds
	s_barrier
; #define STAGE(P, RS, SOFF, OFF, kt) do { const int _so = (SOFF) + (kt) * (BK * 2); \
;     _Pragma("unroll") for (int _i = 0; _i < 2; ++_i) { \
;       __builtin_amdgcn_raw_ptr_buffer_load_lds(RS, (__attribute__((address_space(3))) void*)((P) + wave * 1024 + _i * 8192), 16, OFF[_i], _so, 0, 0); } } while (0)
; #define LDA(dst, b, h) _Pragma("unroll") for (int m = 0; m < 4; ++m) _Pragma("unroll") for (int k = 0; k < 2; ++k) \
;     dst[m][k] = *reinterpret_cast<const bf16x8*>(SA(b, h) + lds_byte(wr * 64 + m * 16 + fr, k * 32 + fq * 8))
; #define LDB(dst, b, h) _Pragma("unroll") for (int n = 0; n < 2; ++n) _Pragma("unroll") for (int k = 0; k < 2; ++k) \
;     dst[n][k] = *reinterpret_cast<const bf16x8*>(SB(b, h) + lds_byte(wc * 32 + n * 16 + fr, k * 32 + fq * 8))
; #define WAIT_V(n) asm volatile("s_waitcnt vmcnt(" #n ")" ::: "memory")
; #define WAIT_L(n) asm volatile("s_waitcnt lgkmcnt(" #n ")" ::: "memory")
; #define BAR __builtin_amdgcn_s_barrier()
; #define SCHED __builtin_amdgcn_sched_barrier(0)
;     ...
;       BAR; WAIT_L(0); MMA(1, 0, At, B0); BAR; SCHED;
;       STAGE(SB(1, 1), rsB, sB1, offB, t + 3);
;       WAIT_V(6); BAR; MMA(1, 1, At, B1); BAR;
;     }
;     { LDB(B0, 0, 0); LDA(At, 0, 0); STAGE(SA(1, 1), rsA, sA1, offA, nt - 1);
;       BAR; WAIT_L(0); MMA(0, 0, At, B0); BAR;
;       LDB(B1, 0, 1); BAR; WAIT_L(0); MMA(0, 1, At, B1); BAR;
;       LDA(At, 0, 1); WAIT_V(4); BAR; WAIT_L(0); MMA(1, 0, At, B0); MMA(1, 1, At, B1); BAR; }
	s_waitcnt lgkmcnt(0)
	v_mfma_f32_16x16x32_bf16 v[60:63], v[154:157], v[170:173], v[60:63]
	v_mfma_f32_16x16x32_bf16 v[60:63], v[158:161], v[174:177], v[60:63]
	v_mfma_f32_16x16x32_bf16 v[56:59], v[162:165], v[170:173], v[56:59]
	v_mfma_f32_16x16x32_bf16 v[56:59], v[166:169], v[174:177], v[56:59]
	v_mfma_f32_16x16x32_bf16 v[52:55], v[154:157], v[178:181], v[52:55]
	v_mfma_f32_16x16x32_bf16 v[52:55], v[158:161], v[182:185], v[52:55]
	v_mfma_f32_16x16x32_bf16 v[48:51], v[162:165], v[178:181], v[48:51]
	v_mfma_f32_16x16x32_bf16 v[48:51], v[166:169], v[182:185], v[48:51]
	v_mfma_f32_16x16x32_bf16 v[44:47], v[154:157], v[186:189], v[44:47]
	v_mfma_f32_16x16x32_bf16 v[44:47], v[158:161], v[190:193], v[44:47]
	v_mfma_f32_16x16x32_bf16 v[40:43], v[162:165], v[186:189], v[40:43]
	v_mfma_f32_16x16x32_bf16 v[40:43], v[166:169], v[190:193], v[40:43]
	v_mfma_f32_16x16x32_bf16 v[36:39], v[154:157], v[194:197], v[36:39]
	v_mfma_f32_16x16x32_bf16 v[36:39], v[158:161], v[198:201], v[36:39]
	v_mfma_f32_16x16x32_bf16 v[32:35], v[162:165], v[194:197], v[32:35]
	v_mfma_f32_16x16x32_bf16 v[32:35], v[166:169], v[198:201], v[32:35]
	s_barrier
	s_addk_i32 s46, 0x180
	s_mov_b32 m0, s27
	s_nop 0
	buffer_load_dwordx4 v143, s[8:11], s46 offen lds
	s_mov_b32 m0, s28
	s_nop 0
	buffer_load_dwordx4 v144, s[8:11], s46 offen lds
	s_add_i32 s14, s14, 2
	s_addk_i32 s15, 0x100
	s_cmp_gt_u32 s14, 27
	s_cbranch_scc0 .LBB0_95
	s_waitcnt vmcnt(6)
	s_barrier
	v_mfma_f32_16x16x32_bf16 v[28:31], v[202:205], v[170:173], v[28:31]
	v_mfma_f32_16x16x32_bf16 v[28:31], v[206:209], v[174:177], v[28:31]
	v_mfma_f32_16x16x32_bf16 v[24:27], v[210:213], v[170:173], v[24:27]
	v_mfma_f32_16x16x32_bf16 v[24:27], v[214:217], v[174:177], v[24:27]
	v_mfma_f32_16x16x32_bf16 v[20:23], v[202:205], v[178:181], v[20:23]
	v_mfma_f32_16x16x32_bf16 v[20:23], v[206:209], v[182:185], v[20:23]
	v_mfma_f32_16x16x32_bf16 v[16:19], v[210:213], v[178:181], v[16:19]
	v_mfma_f32_16x16x32_bf16 v[16:19], v[214:217], v[182:185], v[16:19]
	v_mfma_f32_16x16x32_bf16 v[12:15], v[202:205], v[186:189], v[12:15]
	v_mfma_f32_16x16x32_bf16 v[12:15], v[206:209], v[190:193], v[12:15]
	v_mfma_f32_16x16x32_bf16 v[8:11], v[210:213], v[186:189], v[8:11]
	v_mfma_f32_16x16x32_bf16 v[8:11], v[214:217], v[190:193], v[8:11]
	v_mfma_f32_16x16x32_bf16 v[4:7], v[202:205], v[194:197], v[4:7]
	v_mfma_f32_16x16x32_bf16 v[4:7], v[206:209], v[198:201], v[4:7]
	v_mfma_f32_16x16x32_bf16 v[0:3], v[210:213], v[194:197], v[0:3]
	v_mfma_f32_16x16x32_bf16 v[0:3], v[214:217], v[198:201], v[0:3]
	s_barrier
	s_add_i32 s10, s37, 0xf80
	s_mov_b32 m0, s30
	ds_read_b128 v[154:157], v149
	ds_read_b128 v[158:161], v150
	ds_read_b128 v[162:165], v151
	ds_read_b128 v[150:153], v152
	ds_read_b128 v[166:169], v131
	ds_read_b128 v[170:173], v131 offset:1024
	ds_read_b128 v[174:177], v134
	ds_read_b128 v[178:181], v134 offset:1024
	ds_read_b128 v[182:185], v133
	ds_read_b128 v[186:189], v133 offset:1024
	ds_read_b128 v[190:193], v132
	ds_read_b128 v[194:197], v132 offset:1024
	buffer_load_dwordx4 v143, s[4:7], s10 offen lds
	s_mov_b32 m0, s31
	s_nop 0
	buffer_load_dwordx4 v144, s[4:7], s10 offen lds
	s_barrier
	s_waitcnt lgkmcnt(0)
	v_mfma_f32_16x16x32_bf16 v[124:127], v[154:157], v[166:169], v[124:127]
	v_mfma_f32_16x16x32_bf16 v[124:127], v[158:161], v[170:173], v[124:127]
	v_mfma_f32_16x16x32_bf16 v[120:123], v[162:165], v[166:169], v[120:123]
	v_mfma_f32_16x16x32_bf16 v[120:123], v[150:153], v[170:173], v[120:123]
	v_mfma_f32_16x16x32_bf16 v[116:119], v[154:157], v[174:177], v[116:119]
	v_mfma_f32_16x16x32_bf16 v[116:119], v[158:161], v[178:181], v[116:119]
	v_mfma_f32_16x16x32_bf16 v[112:115], v[162:165], v[174:177], v[112:115]
	v_mfma_f32_16x16x32_bf16 v[112:115], v[150:153], v[178:181], v[112:115]
	v_mfma_f32_16x16x32_bf16 v[108:111], v[154:157], v[182:185], v[108:111]
	v_mfma_f32_16x16x32_bf16 v[108:111], v[158:161], v[186:189], v[108:111]
	v_mfma_f32_16x16x32_bf16 v[104:107], v[162:165], v[182:185], v[104:107]
	v_mfma_f32_16x16x32_bf16 v[104:107], v[150:153], v[186:189], v[104:107]
	v_mfma_f32_16x16x32_bf16 v[100:103], v[154:157], v[190:193], v[100:103]
	v_mfma_f32_16x16x32_bf16 v[100:103], v[158:161], v[194:197], v[100:103]
	v_mfma_f32_16x16x32_bf16 v[96:99], v[162:165], v[190:193], v[96:99]
	v_mfma_f32_16x16x32_bf16 v[96:99], v[150:153], v[194:197], v[96:99]
	s_barrier
	ds_read_b128 v[198:201], v145
	ds_read_b128 v[202:205], v146
	ds_read_b128 v[144:147], v147
	ds_read_b128 v[206:209], v148
	s_barrier
	s_waitcnt lgkmcnt(0)
	v_mfma_f32_16x16x32_bf16 v[92:95], v[198:201], v[166:169], v[92:95]
	v_mfma_f32_16x16x32_bf16 v[84:87], v[198:201], v[174:177], v[84:87]
	v_mfma_f32_16x16x32_bf16 v[76:79], v[198:201], v[182:185], v[76:79]
	v_mfma_f32_16x16x32_bf16 v[68:71], v[198:201], v[190:193], v[68:71]
	v_mfma_f32_16x16x32_bf16 v[88:91], v[144:147], v[166:169], v[88:91]
	v_mfma_f32_16x16x32_bf16 v[80:83], v[144:147], v[174:177], v[80:83]
	v_mfma_f32_16x16x32_bf16 v[72:75], v[144:147], v[182:185], v[72:75]
	v_mfma_f32_16x16x32_bf16 v[64:67], v[144:147], v[190:193], v[64:67]
	v_mfma_f32_16x16x32_bf16 v[92:95], v[202:205], v[170:173], v[92:95]
	v_mfma_f32_16x16x32_bf16 v[84:87], v[202:205], v[178:181], v[84:87]
	v_mfma_f32_16x16x32_bf16 v[76:79], v[202:205], v[186:189], v[76:79]
	v_mfma_f32_16x16x32_bf16 v[68:71], v[202:205], v[194:197], v[68:71]
	v_mfma_f32_16x16x32_bf16 v[166:169], v[206:209], v[170:173], v[88:91]
	v_mfma_f32_16x16x32_bf16 v[170:173], v[206:209], v[178:181], v[80:83]
	v_mfma_f32_16x16x32_bf16 v[174:177], v[206:209], v[186:189], v[72:75]
	v_mfma_f32_16x16x32_bf16 v[178:181], v[206:209], v[194:197], v[64:67]
	s_barrier
; #define LDA(dst, b, h) _Pragma("unroll") for (int m = 0; m < 4; ++m) _Pragma("unroll") for (int k = 0; k < 2; ++k) \
;     dst[m][k] = *reinterpret_cast<const bf16x8*>(SA(b, h) + lds_byte(wr * 64 + m * 16 + fr, k * 32 + fq * 8))
; #define LDB(dst, b, h) _Pragma("unroll") for (int n = 0; n < 2; ++n) _Pragma("unroll") for (int k = 0; k < 2; ++k) \
;     dst[n][k] = *reinterpret_cast<const bf16x8*>(SB(b, h) + lds_byte(wc * 32 + n * 16 + fr, k * 32 + fq * 8))
; #define WAIT_V(n) asm volatile("s_waitcnt vmcnt(" #n ")" ::: "memory")
; #define WAIT_L(n) asm volatile("s_waitcnt lgkmcnt(" #n ")" ::: "memory")
; #define BAR __builtin_amdgcn_s_barrier()
;     ...
;       LDA(At, 0, 1); WAIT_V(4); BAR; WAIT_L(0); MMA(1, 0, At, B0); MMA(1, 1, At, B1); BAR; }
;     { LDB(B0, 1, 0); LDA(At, 1, 0); WAIT_V(2); BAR; WAIT_L(0); MMA(0, 0, At, B0); BAR;
;       LDB(B1, 1, 1); WAIT_V(0); BAR; WAIT_L(0); MMA(0, 1, At, B1); BAR;
	s_nop 0
	ds_read_b128 v[64:67], v131 offset:16384
	ds_read_b128 v[72:75], v131 offset:17408
	ds_read_b128 v[80:83], v134 offset:16384
	ds_read_b128 v[88:91], v134 offset:17408
	ds_read_b128 v[182:185], v133 offset:16384
	ds_read_b128 v[186:189], v133 offset:17408
	ds_read_b128 v[190:193], v132 offset:16384
	ds_read_b128 v[194:197], v132 offset:17408
	s_waitcnt vmcnt(4)
	s_barrier
	s_waitcnt lgkmcnt(0)
	v_mfma_f32_16x16x32_bf16 v[60:63], v[154:157], v[64:67], v[60:63]
	v_mfma_f32_16x16x32_bf16 v[56:59], v[162:165], v[64:67], v[56:59]
	v_mfma_f32_16x16x32_bf16 v[52:55], v[154:157], v[80:83], v[52:55]
	v_mfma_f32_16x16x32_bf16 v[48:51], v[162:165], v[80:83], v[48:51]
	v_mfma_f32_16x16x32_bf16 v[44:47], v[154:157], v[182:185], v[44:47]
	v_mfma_f32_16x16x32_bf16 v[40:43], v[162:165], v[182:185], v[40:43]
	v_mfma_f32_16x16x32_bf16 v[36:39], v[154:157], v[190:193], v[36:39]
	v_mfma_f32_16x16x32_bf16 v[32:35], v[162:165], v[190:193], v[32:35]
	v_mfma_f32_16x16x32_bf16 v[60:63], v[158:161], v[72:75], v[60:63]
	v_mfma_f32_16x16x32_bf16 v[56:59], v[150:153], v[72:75], v[56:59]
	v_mfma_f32_16x16x32_bf16 v[52:55], v[158:161], v[88:91], v[52:55]
	v_mfma_f32_16x16x32_bf16 v[48:51], v[150:153], v[88:91], v[48:51]
	v_mfma_f32_16x16x32_bf16 v[44:47], v[158:161], v[186:189], v[44:47]
	v_mfma_f32_16x16x32_bf16 v[40:43], v[150:153], v[186:189], v[40:43]
	v_mfma_f32_16x16x32_bf16 v[36:39], v[158:161], v[194:197], v[36:39]
	v_mfma_f32_16x16x32_bf16 v[32:35], v[150:153], v[194:197], v[32:35]
	v_mfma_f32_16x16x32_bf16 v[28:31], v[198:201], v[64:67], v[28:31]
	v_mfma_f32_16x16x32_bf16 v[20:23], v[198:201], v[80:83], v[20:23]
	v_mfma_f32_16x16x32_bf16 v[12:15], v[198:201], v[182:185], v[12:15]
	v_mfma_f32_16x16x32_bf16 v[4:7], v[198:201], v[190:193], v[4:7]
	v_mfma_f32_16x16x32_bf16 v[24:27], v[144:147], v[64:67], v[24:27]
	v_mfma_f32_16x16x32_bf16 v[16:19], v[144:147], v[80:83], v[16:19]
	v_mfma_f32_16x16x32_bf16 v[8:11], v[144:147], v[182:185], v[8:11]
	v_mfma_f32_16x16x32_bf16 v[0:3], v[144:147], v[190:193], v[0:3]
	v_mfma_f32_16x16x32_bf16 v[28:31], v[202:205], v[72:75], v[28:31]
	v_mfma_f32_16x16x32_bf16 v[20:23], v[202:205], v[88:91], v[20:23]
	v_mfma_f32_16x16x32_bf16 v[12:15], v[202:205], v[186:189], v[12:15]
	v_mfma_f32_16x16x32_bf16 v[4:7], v[202:205], v[194:197], v[4:7]
	v_mfma_f32_16x16x32_bf16 v[144:147], v[206:209], v[72:75], v[24:27]
	v_mfma_f32_16x16x32_bf16 v[148:151], v[206:209], v[88:91], v[16:19]
	v_mfma_f32_16x16x32_bf16 v[152:155], v[206:209], v[186:189], v[8:11]
	v_mfma_f32_16x16x32_bf16 v[156:159], v[206:209], v[194:197], v[0:3]
	s_barrier
	s_nop 0
	ds_read_b128 v[0:3], v139
	ds_read_b128 v[8:11], v140
	ds_read_b128 v[16:19], v141
	ds_read_b128 v[140:143], v142
	ds_read_b128 v[24:27], v131 offset:32768
	ds_read_b128 v[160:163], v131 offset:33792
	ds_read_b128 v[182:185], v134 offset:32768
	ds_read_b128 v[186:189], v134 offset:33792
	ds_read_b128 v[190:193], v133 offset:32768
	ds_read_b128 v[194:197], v133 offset:33792
	ds_read_b128 v[198:201], v132 offset:32768
	ds_read_b128 v[202:205], v132 offset:33792
	s_waitcnt vmcnt(2)
	s_barrier
	s_waitcnt lgkmcnt(0)
	v_mfma_f32_16x16x32_bf16 v[64:67], v[0:3], v[24:27], v[124:127]
	v_mfma_f32_16x16x32_bf16 v[72:75], v[16:19], v[24:27], v[120:123]
	v_mfma_f32_16x16x32_bf16 v[80:83], v[0:3], v[182:185], v[116:119]
	v_mfma_f32_16x16x32_bf16 v[88:91], v[16:19], v[182:185], v[112:115]
	v_mfma_f32_16x16x32_bf16 v[108:111], v[0:3], v[190:193], v[108:111]
	v_mfma_f32_16x16x32_bf16 v[116:119], v[16:19], v[190:193], v[104:107]
	v_mfma_f32_16x16x32_bf16 v[100:103], v[0:3], v[198:201], v[100:103]
	v_mfma_f32_16x16x32_bf16 v[124:127], v[16:19], v[198:201], v[96:99]
	v_mfma_f32_16x16x32_bf16 v[120:123], v[8:11], v[160:163], v[64:67]
	v_mfma_f32_16x16x32_bf16 v[112:115], v[140:143], v[160:163], v[72:75]
	v_mfma_f32_16x16x32_bf16 v[104:107], v[8:11], v[186:189], v[80:83]
	v_mfma_f32_16x16x32_bf16 v[96:99], v[140:143], v[186:189], v[88:91]
	v_mfma_f32_16x16x32_bf16 v[88:91], v[8:11], v[194:197], v[108:111]
	v_mfma_f32_16x16x32_bf16 v[80:83], v[140:143], v[194:197], v[116:119]
	v_mfma_f32_16x16x32_bf16 v[72:75], v[8:11], v[202:205], v[100:103]
	v_mfma_f32_16x16x32_bf16 v[64:67], v[140:143], v[202:205], v[124:127]
	s_barrier
; #define LDA(dst, b, h) _Pragma("unroll") for (int m = 0; m < 4; ++m) _Pragma("unroll") for (int k = 0; k < 2; ++k) \
;     dst[m][k] = *reinterpret_cast<const bf16x8*>(SA(b, h) + lds_byte(wr * 64 + m * 16 + fr, k * 32 + fq * 8))
; #define LDB(dst, b, h) _Pragma("unroll") for (int n = 0; n < 2; ++n) _Pragma("unroll") for (int k = 0; k < 2; ++k) \
;     dst[n][k] = *reinterpret_cast<const bf16x8*>(SB(b, h) + lds_byte(wc * 32 + n * 16 + fr, k * 32 + fq * 8))
; #define WAIT_V(n) asm volatile("s_waitcnt vmcnt(" #n ")" ::: "memory")
; #define WAIT_L(n) asm volatile("s_waitcnt lgkmcnt(" #n ")" ::: "memory")
; #define BAR __builtin_amdgcn_s_barrier()
;     ...
;       LDB(B1, 1, 1); WAIT_V(0); BAR; WAIT_L(0); MMA(0, 1, At, B1); BAR;
;       LDA(At, 1, 1); BAR; WAIT_L(0); MMA(1, 0, At, B0); MMA(1, 1, At, B1); BAR; }
;     if (wr == 0) BAR;
	ds_read_b128 v[206:209], v135
	ds_read_b128 v[210:213], v136
	ds_read_b128 v[214:217], v137
	ds_read_b128 v[136:139], v138
	s_waitcnt vmcnt(0)
	s_barrier
	s_waitcnt lgkmcnt(0)
	v_mfma_f32_16x16x32_bf16 v[92:95], v[206:209], v[24:27], v[92:95]
	v_mfma_f32_16x16x32_bf16 v[24:27], v[214:217], v[24:27], v[166:169]
	v_mfma_f32_16x16x32_bf16 v[84:87], v[206:209], v[182:185], v[84:87]
	v_mfma_f32_16x16x32_bf16 v[100:103], v[214:217], v[182:185], v[170:173]
	v_mfma_f32_16x16x32_bf16 v[76:79], v[206:209], v[190:193], v[76:79]
	v_mfma_f32_16x16x32_bf16 v[164:167], v[214:217], v[190:193], v[174:177]
	v_mfma_f32_16x16x32_bf16 v[68:71], v[206:209], v[198:201], v[68:71]
	v_mfma_f32_16x16x32_bf16 v[168:171], v[214:217], v[198:201], v[178:181]
	v_mfma_f32_16x16x32_bf16 v[124:127], v[210:213], v[160:163], v[92:95]
	v_mfma_f32_16x16x32_bf16 v[116:119], v[136:139], v[160:163], v[24:27]
	v_mfma_f32_16x16x32_bf16 v[108:111], v[210:213], v[186:189], v[84:87]
	v_mfma_f32_16x16x32_bf16 v[100:103], v[136:139], v[186:189], v[100:103]
	v_mfma_f32_16x16x32_bf16 v[92:95], v[210:213], v[194:197], v[76:79]
	v_mfma_f32_16x16x32_bf16 v[84:87], v[136:139], v[194:197], v[164:167]
	v_mfma_f32_16x16x32_bf16 v[76:79], v[210:213], v[202:205], v[68:71]
	v_mfma_f32_16x16x32_bf16 v[68:71], v[136:139], v[202:205], v[168:171]
	s_barrier
	ds_read_b128 v[160:163], v131 offset:49152
	ds_read_b128 v[164:167], v131 offset:50176
	ds_read_b128 v[168:171], v134 offset:49152
	ds_read_b128 v[172:175], v134 offset:50176
	ds_read_b128 v[176:179], v133 offset:49152
	ds_read_b128 v[180:183], v133 offset:50176
	ds_read_b128 v[184:187], v132 offset:49152
	ds_read_b128 v[132:135], v132 offset:50176
	s_barrier
	s_waitcnt lgkmcnt(0)
	v_mfma_f32_16x16x32_bf16 v[24:27], v[0:3], v[160:163], v[60:63]
	v_mfma_f32_16x16x32_bf16 v[60:63], v[16:19], v[160:163], v[56:59]
	v_mfma_f32_16x16x32_bf16 v[52:55], v[0:3], v[168:171], v[52:55]
	v_mfma_f32_16x16x32_bf16 v[188:191], v[16:19], v[168:171], v[48:51]
	v_mfma_f32_16x16x32_bf16 v[44:47], v[0:3], v[176:179], v[44:47]
	v_mfma_f32_16x16x32_bf16 v[192:195], v[16:19], v[176:179], v[40:43]
	v_mfma_f32_16x16x32_bf16 v[0:3], v[0:3], v[184:187], v[36:39]
	v_mfma_f32_16x16x32_bf16 v[36:39], v[16:19], v[184:187], v[32:35]
	v_mfma_f32_16x16x32_bf16 v[56:59], v[8:11], v[164:167], v[24:27]
	v_mfma_f32_16x16x32_bf16 v[48:51], v[140:143], v[164:167], v[60:63]
	v_mfma_f32_16x16x32_bf16 v[40:43], v[8:11], v[172:175], v[52:55]
	v_mfma_f32_16x16x32_bf16 v[32:35], v[140:143], v[172:175], v[188:191]
	v_mfma_f32_16x16x32_bf16 v[24:27], v[8:11], v[180:183], v[44:47]
	v_mfma_f32_16x16x32_bf16 v[16:19], v[140:143], v[180:183], v[192:195]
	v_mfma_f32_16x16x32_bf16 v[8:11], v[8:11], v[132:135], v[0:3]
	v_mfma_f32_16x16x32_bf16 v[0:3], v[140:143], v[132:135], v[36:39]
	v_mfma_f32_16x16x32_bf16 v[28:31], v[206:209], v[160:163], v[28:31]
	v_mfma_f32_16x16x32_bf16 v[36:39], v[214:217], v[160:163], v[144:147]
	v_mfma_f32_16x16x32_bf16 v[20:23], v[206:209], v[168:171], v[20:23]
	v_mfma_f32_16x16x32_bf16 v[140:143], v[214:217], v[168:171], v[148:151]
	v_mfma_f32_16x16x32_bf16 v[12:15], v[206:209], v[176:179], v[12:15]
	v_mfma_f32_16x16x32_bf16 v[144:147], v[214:217], v[176:179], v[152:155]
	v_mfma_f32_16x16x32_bf16 v[4:7], v[206:209], v[184:187], v[4:7]
	v_mfma_f32_16x16x32_bf16 v[148:151], v[214:217], v[184:187], v[156:159]
	v_mfma_f32_16x16x32_bf16 v[60:63], v[210:213], v[164:167], v[28:31]
	v_mfma_f32_16x16x32_bf16 v[52:55], v[136:139], v[164:167], v[36:39]
	v_mfma_f32_16x16x32_bf16 v[44:47], v[210:213], v[172:175], v[20:23]
	v_mfma_f32_16x16x32_bf16 v[36:39], v[136:139], v[172:175], v[140:143]
	v_mfma_f32_16x16x32_bf16 v[28:31], v[210:213], v[180:183], v[12:15]
	v_mfma_f32_16x16x32_bf16 v[20:23], v[136:139], v[180:183], v[144:147]
	v_mfma_f32_16x16x32_bf16 v[12:15], v[210:213], v[132:135], v[4:7]
	v_mfma_f32_16x16x32_bf16 v[4:7], v[136:139], v[132:135], v[148:151]
	v_cmp_gt_u32_e32 vcc, s35, v130
	s_barrier
	s_and_saveexec_b64 s[10:11], vcc
	s_cbranch_execz .LBB0_98
	s_barrier

; #define WAIT_V(n) asm volatile("s_waitcnt vmcnt(" #n ")" ::: "memory")
; #define BAR __builtin_amdgcn_s_barrier()
;     ...
;     const int tid = opaque_tid(wave);
;     const int wid = tid >> 6, lane = tid & 63, wr = wid >> 2, wc = wid & 3, fr = lane & 15, fq = lane >> 4;
;     int offA[2], offB[2];
;     _Pragma("unroll") for (int i = 0; i < 2; ++i) {
;       int r, c; stage_rc(tid * 16 + i * 8192, r, c);
;       offA[i] = (r * lda + c) * 2; offB[i] = (r * ldb + c) * 2;
;     }
;     const int brow = pm * BM;
;     f32x4 acc[2][2][4][2];
;     _Pragma("unroll") for (int a = 0; a < 2; ++a) _Pragma("unroll") for (int b = 0; b < 2; ++b) _Pragma("unroll") for (int m = 0; m < 4; ++m) _Pragma("unroll") for (int n = 0; n < 2; ++n)
;       acc[a][b][m][n] = f32x4{0.f, 0.f, 0.f, 0.f};
;     bf16x8 At[4][2], B0[2][2], B1[2][2];
;     if (wr == 1) BAR;
;     if (first_tile) { WAIT_V(0); }
;     else if constexpr (mode == MODE_RESID_LN) { WAIT_V(0); }
;     else if constexpr (mode == MODE_SWIGLU) { WAIT_V(6); }
;     else if constexpr (mode == MODE_V) { WAIT_V(24); }
;     else { WAIT_V(12); }
;     first_tile = false;
;     BAR;
;     BAR;
.LBB0_109:
	v_bfe_i32 v4, v136, 27, 1
	v_lshlrev_b32_e32 v2, 4, v136
	v_lshrrev_b32_e32 v4, 22, v4
	v_add_u32_e32 v4, v2, v4
	v_and_b32_e32 v4, 0xfffffc00, v4
	v_sub_u32_e32 v4, v2, v4
	v_lshrrev_b32_e32 v5, 4, v4
	v_ashrrev_i32_e32 v3, 31, v136
	v_bitop3_b32 v4, v5, v4, 32 bitop3:0x6c
	v_lshrrev_b32_e32 v3, 26, v3
	v_ashrrev_i32_e32 v6, 31, v4
	v_add_u32_e32 v3, v136, v3
	v_lshrrev_b32_e32 v6, 26, v6
	v_ashrrev_i32_e32 v3, 6, v3
	v_add_u32_e32 v6, v4, v6
	v_lshlrev_b32_e32 v5, 3, v3
	v_ashrrev_i32_e32 v7, 6, v6
	v_and_b32_e32 v6, 0xc0, v6
	v_and_b32_e32 v5, -16, v5
	v_lshlrev_b32_e32 v3, 5, v3
	v_sub_u32_e32 v4, v4, v6
	v_add_u32_e32 v5, v7, v5
	v_and_b32_e32 v3, 32, v3
	v_ashrrev_i16_sdwa v4, v129, sext(v4) dst_sel:DWORD dst_unused:UNUSED_PAD src0_sel:DWORD src1_sel:BYTE_0
	v_add_u32_sdwa v3, v3, sext(v4) dst_sel:DWORD dst_unused:UNUSED_PAD src0_sel:DWORD src1_sel:WORD_0
	v_lshlrev_b32_e32 v4, 10, v5
	v_add_u32_e32 v2, 0x2000, v2
	v_lshl_add_u32 v128, v3, 1, v4
	v_ashrrev_i32_e32 v3, 31, v2
	v_lshrrev_b32_e32 v3, 22, v3
	v_add_u32_e32 v3, v2, v3
	v_ashrrev_i32_e32 v3, 10, v3
	v_mul_i32_i24_e32 v4, 0x400, v3
	v_sub_u32_e32 v2, v2, v4
	v_lshrrev_b32_e32 v4, 4, v2
	v_bitop3_b32 v2, v4, v2, 32 bitop3:0x6c
	v_mad_u64_u32 v[130:131], s[10:11], v5, s1, v[128:129]
	v_ashrrev_i32_e32 v5, 31, v2
	v_lshrrev_b32_e32 v5, 26, v5
	v_add_u32_e32 v5, v2, v5
	v_lshlrev_b32_e32 v4, 3, v3
	v_ashrrev_i32_e32 v6, 6, v5
	v_and_b32_e32 v5, 0xc0, v5
	v_and_b32_e32 v4, -16, v4
	v_lshlrev_b32_e32 v3, 5, v3
	v_sub_u32_e32 v2, v2, v5
	v_add_u32_e32 v4, v6, v4
	v_and_b32_e32 v3, 32, v3
	v_ashrrev_i16_sdwa v2, v129, sext(v2) dst_sel:DWORD dst_unused:UNUSED_PAD src0_sel:DWORD src1_sel:BYTE_0
	v_add_u32_sdwa v2, v3, sext(v2) dst_sel:DWORD dst_unused:UNUSED_PAD src0_sel:DWORD src1_sel:WORD_0
	v_lshlrev_b32_e32 v3, 10, v4
	v_lshl_add_u32 v132, v2, 1, v3
	v_and_b32_e32 v3, 15, v0
	v_lshlrev_b32_e32 v5, 2, v0
	v_and_b32_e32 v2, 48, v0
	v_lshlrev_b32_e32 v3, 6, v3
	v_and_b32_e32 v5, 32, v5
	v_lshlrev_b32_e32 v0, 6, v0
	v_mad_u64_u32 v[134:135], s[10:11], v4, s1, v[132:133]
	v_or_b32_e32 v4, v3, v2
	v_bitop3_b32 v3, v3, v5, v2 bitop3:0x36
	v_lshlrev_b32_e32 v6, 6, v136
	v_lshlrev_b32_e32 v1, 13, v1
	v_and_or_b32 v0, v0, s35, v2
	v_and_or_b32 v3, v6, s34, v3
	v_bitop3_b32 v0, v1, v0, v5 bitop3:0xf6
	v_or_b32_e32 v6, 0x400, v3
	v_or_b32_e32 v7, 0x800, v3
	v_or_b32_e32 v8, 0xc00, v3
	v_or_b32_e32 v138, 0x800, v0
	v_or_b32_e32 v137, 0x1000, v0
	v_or_b32_e32 v135, 0x1800, v0
	v_mov_b32_e32 v0, 0
	v_bitop3_b32 v131, v4, v1, v5 bitop3:0xde
	s_mov_b32 s16, -2
	s_mov_b32 s17, 0
	v_or_b32_e32 v151, 0x10000, v3
	v_or_b32_e32 v152, 0x10000, v6
	v_or_b32_e32 v153, 0x10000, v7
	v_or_b32_e32 v154, 0x10000, v8
	v_or_b32_e32 v147, 0x14000, v3
	v_or_b32_e32 v148, 0x14000, v6
	v_or_b32_e32 v149, 0x14000, v7
	v_or_b32_e32 v150, 0x14000, v8
	v_or_b32_e32 v143, 0x18000, v3
	v_or_b32_e32 v144, 0x18000, v6
	v_or_b32_e32 v145, 0x18000, v7
	v_or_b32_e32 v146, 0x18000, v8
	v_or_b32_e32 v139, 0x1c000, v3
	v_or_b32_e32 v140, 0x1c000, v6
	v_or_b32_e32 v141, 0x1c000, v7
	v_or_b32_e32 v142, 0x1c000, v8
	v_mov_b32_e32 v1, v0
	v_mov_b32_e32 v2, v0
	v_mov_b32_e32 v3, v0
	v_mov_b32_e32 v4, v0
	v_mov_b32_e32 v5, v0
	v_mov_b32_e32 v6, v0
	v_mov_b32_e32 v7, v0
	v_mov_b32_e32 v8, v0
	v_mov_b32_e32 v9, v0
	v_mov_b32_e32 v10, v0
	v_mov_b32_e32 v11, v0
	v_mov_b32_e32 v12, v0
	v_mov_b32_e32 v13, v0
	v_mov_b32_e32 v14, v0
	v_mov_b32_e32 v15, v0
	v_mov_b32_e32 v16, v0
	v_mov_b32_e32 v17, v0
	v_mov_b32_e32 v18, v0
	v_mov_b32_e32 v19, v0
	v_mov_b32_e32 v20, v0
	v_mov_b32_e32 v21, v0
	v_mov_b32_e32 v22, v0
	v_mov_b32_e32 v23, v0
	v_mov_b32_e32 v24, v0
	v_mov_b32_e32 v25, v0
	v_mov_b32_e32 v26, v0
	v_mov_b32_e32 v27, v0
	v_mov_b32_e32 v28, v0
	v_mov_b32_e32 v29, v0
	v_mov_b32_e32 v30, v0
	v_mov_b32_e32 v31, v0
	v_mov_b32_e32 v32, v0
	v_mov_b32_e32 v33, v0
	v_mov_b32_e32 v34, v0
	v_mov_b32_e32 v35, v0
	v_mov_b32_e32 v36, v0
	v_mov_b32_e32 v37, v0
	v_mov_b32_e32 v38, v0
	v_mov_b32_e32 v39, v0
	v_mov_b32_e32 v40, v0
	v_mov_b32_e32 v41, v0
	v_mov_b32_e32 v42, v0
	v_mov_b32_e32 v43, v0
	v_mov_b32_e32 v44, v0
	v_mov_b32_e32 v45, v0
	v_mov_b32_e32 v46, v0
	v_mov_b32_e32 v47, v0
	v_mov_b32_e32 v48, v0
	v_mov_b32_e32 v49, v0
	v_mov_b32_e32 v50, v0
	v_mov_b32_e32 v51, v0
	v_mov_b32_e32 v52, v0
	v_mov_b32_e32 v53, v0
	v_mov_b32_e32 v54, v0
	v_mov_b32_e32 v55, v0
	v_mov_b32_e32 v56, v0
	v_mov_b32_e32 v57, v0
	v_mov_b32_e32 v58, v0
	v_mov_b32_e32 v59, v0
	v_mov_b32_e32 v60, v0
	v_mov_b32_e32 v61, v0
	v_mov_b32_e32 v62, v0
	v_mov_b32_e32 v63, v0
	v_mov_b32_e32 v64, v0
	v_mov_b32_e32 v65, v0
	v_mov_b32_e32 v66, v0
	v_mov_b32_e32 v67, v0
	v_mov_b32_e32 v68, v0
	v_mov_b32_e32 v69, v0
	v_mov_b32_e32 v70, v0
	v_mov_b32_e32 v71, v0
	v_mov_b32_e32 v72, v0
	v_mov_b32_e32 v73, v0
	v_mov_b32_e32 v74, v0
	v_mov_b32_e32 v75, v0
	v_mov_b32_e32 v76, v0
	v_mov_b32_e32 v77, v0
	v_mov_b32_e32 v78, v0
	v_mov_b32_e32 v79, v0
	v_mov_b32_e32 v80, v0
	v_mov_b32_e32 v81, v0
	v_mov_b32_e32 v82, v0
	v_mov_b32_e32 v83, v0
	v_mov_b32_e32 v84, v0
	v_mov_b32_e32 v85, v0
	v_mov_b32_e32 v86, v0
	v_mov_b32_e32 v87, v0
	v_mov_b32_e32 v88, v0
	v_mov_b32_e32 v89, v0
	v_mov_b32_e32 v90, v0
	v_mov_b32_e32 v91, v0
	v_mov_b32_e32 v92, v0
	v_mov_b32_e32 v93, v0
	v_mov_b32_e32 v94, v0
	v_mov_b32_e32 v95, v0
	v_mov_b32_e32 v96, v0
	v_mov_b32_e32 v97, v0
	v_mov_b32_e32 v98, v0
	v_mov_b32_e32 v99, v0
	v_mov_b32_e32 v100, v0
	v_mov_b32_e32 v101, v0
	v_mov_b32_e32 v102, v0
	v_mov_b32_e32 v103, v0
	v_mov_b32_e32 v104, v0
	v_mov_b32_e32 v105, v0
	v_mov_b32_e32 v106, v0
	v_mov_b32_e32 v107, v0
	v_mov_b32_e32 v108, v0
	v_mov_b32_e32 v109, v0
	v_mov_b32_e32 v110, v0
	v_mov_b32_e32 v111, v0
	v_mov_b32_e32 v112, v0
	v_mov_b32_e32 v113, v0
	v_mov_b32_e32 v114, v0
	v_mov_b32_e32 v115, v0
	v_mov_b32_e32 v116, v0
	v_mov_b32_e32 v117, v0
	v_mov_b32_e32 v118, v0
	v_mov_b32_e32 v119, v0
	v_mov_b32_e32 v120, v0
	v_mov_b32_e32 v121, v0
	v_mov_b32_e32 v122, v0
	v_mov_b32_e32 v123, v0
	v_mov_b32_e32 v124, v0
	v_mov_b32_e32 v125, v0
	v_mov_b32_e32 v126, v0
	v_mov_b32_e32 v127, v0
	s_barrier
	s_barrier
	s_branch .Lmy_rot_110
; #define STAGE(P, RS, SOFF, OFF, kt) do { const int _so = (SOFF) + (kt) * (BK * 2); \
;     _Pragma("unroll") for (int _i = 0; _i < 2; ++_i) { \
;       __builtin_amdgcn_raw_ptr_buffer_load_lds(RS, (__attribute__((address_space(3))) void*)((P) + wave * 1024 + _i * 8192), 16, OFF[_i], _so, 0, 0); } } while (0)
; #define LDA(dst, b, h) _Pragma("unroll") for (int m = 0; m < 4; ++m) _Pragma("unroll") for (int k = 0; k < 2; ++k) \
;     dst[m][k] = *reinterpret_cast<const bf16x8*>(SA(b, h) + lds_byte(wr * 64 + m * 16 + fr, k * 32 + fq * 8))
; #define LDB(dst, b, h) _Pragma("unroll") for (int n = 0; n < 2; ++n) _Pragma("unroll") for (int k = 0; k < 2; ++k) \
;     dst[n][k] = *reinterpret_cast<const bf16x8*>(SB(b, h) + lds_byte(wc * 32 + n * 16 + fr, k * 32 + fq * 8))
; #define WAIT_V(n) asm volatile("s_waitcnt vmcnt(" #n ")" ::: "memory")
; #define WAIT_L(n) asm volatile("s_waitcnt lgkmcnt(" #n ")" ::: "memory")
; #define BAR __builtin_amdgcn_s_barrier()
; #define SCHED __builtin_amdgcn_sched_barrier(0)
;     ...
;       LDB(B0, 0, 0); SCHED; LDA(At, 0, 0); STAGE(SA(1, 1), rsA, sA1, offA, t + 1);
;       WAIT_L(8); BAR; WAIT_L(0); MMA(0, 0, At, B0); BAR; SCHED;
;       LDB(B1, 0, 1); STAGE(SB(0, 0), rsB, sB0, offB, t + 2);
;       BAR; WAIT_L(0); MMA(0, 1, At, B1); BAR;
;       LDA(At, 0, 1); STAGE(SA(0, 0), rsA, sA0, offA, t + 2);
;       BAR; WAIT_L(0); MMA(1, 0, At, B0); BAR; SCHED;
;     ...
;       WAIT_V(6); BAR; MMA(1, 1, At, B1); BAR;
.LBB0_110:
	s_waitcnt vmcnt(6)
	s_barrier
	v_mfma_f32_16x16x32_bf16 v[28:31], v[204:207], v[172:175], v[28:31]
	v_mfma_f32_16x16x32_bf16 v[28:31], v[208:211], v[176:179], v[28:31]
	v_mfma_f32_16x16x32_bf16 v[24:27], v[212:215], v[172:175], v[24:27]
	v_mfma_f32_16x16x32_bf16 v[24:27], v[216:219], v[176:179], v[24:27]
	v_mfma_f32_16x16x32_bf16 v[20:23], v[204:207], v[180:183], v[20:23]
	v_mfma_f32_16x16x32_bf16 v[20:23], v[208:211], v[184:187], v[20:23]
	v_mfma_f32_16x16x32_bf16 v[16:19], v[212:215], v[180:183], v[16:19]
	v_mfma_f32_16x16x32_bf16 v[16:19], v[216:219], v[184:187], v[16:19]
	v_mfma_f32_16x16x32_bf16 v[12:15], v[204:207], v[188:191], v[12:15]
	v_mfma_f32_16x16x32_bf16 v[12:15], v[208:211], v[192:195], v[12:15]
	v_mfma_f32_16x16x32_bf16 v[8:11], v[212:215], v[188:191], v[8:11]
	v_mfma_f32_16x16x32_bf16 v[8:11], v[216:219], v[192:195], v[8:11]
	v_mfma_f32_16x16x32_bf16 v[4:7], v[204:207], v[196:199], v[4:7]
	v_mfma_f32_16x16x32_bf16 v[4:7], v[208:211], v[200:203], v[4:7]
	v_mfma_f32_16x16x32_bf16 v[0:3], v[212:215], v[196:199], v[0:3]
	v_mfma_f32_16x16x32_bf16 v[0:3], v[216:219], v[200:203], v[0:3]
	s_barrier
.Lmy_rot_110:
	ds_read_b128 v[156:159], v151
	ds_read_b128 v[160:163], v152
	ds_read_b128 v[164:167], v153
	ds_read_b128 v[168:171], v154
	s_add_i32 s44, s38, s17
	s_add_i32 s10, s44, 0x80
	s_mov_b32 m0, s31
	ds_read_b128 v[172:175], v131
	ds_read_b128 v[176:179], v131 offset:1024
	ds_read_b128 v[180:183], v138
	ds_read_b128 v[184:187], v138 offset:1024
	ds_read_b128 v[188:191], v137
	ds_read_b128 v[192:195], v137 offset:1024
	ds_read_b128 v[196:199], v135
	ds_read_b128 v[200:203], v135 offset:1024
	buffer_load_dwordx4 v128, s[4:7], s10 offen lds
	s_mov_b32 m0, s33
	s_nop 0
	buffer_load_dwordx4 v132, s[4:7], s10 offen lds
	s_waitcnt lgkmcnt(8)
	s_barrier
	s_waitcnt lgkmcnt(0)
	v_mfma_f32_16x16x32_bf16 v[124:127], v[156:159], v[172:175], v[124:127]
	v_mfma_f32_16x16x32_bf16 v[124:127], v[160:163], v[176:179], v[124:127]
	v_mfma_f32_16x16x32_bf16 v[120:123], v[164:167], v[172:175], v[120:123]
	v_mfma_f32_16x16x32_bf16 v[120:123], v[168:171], v[176:179], v[120:123]
	v_mfma_f32_16x16x32_bf16 v[116:119], v[156:159], v[180:183], v[116:119]
	v_mfma_f32_16x16x32_bf16 v[116:119], v[160:163], v[184:187], v[116:119]
	v_mfma_f32_16x16x32_bf16 v[112:115], v[164:167], v[180:183], v[112:115]
	v_mfma_f32_16x16x32_bf16 v[112:115], v[168:171], v[184:187], v[112:115]
	v_mfma_f32_16x16x32_bf16 v[108:111], v[156:159], v[188:191], v[108:111]
	v_mfma_f32_16x16x32_bf16 v[108:111], v[160:163], v[192:195], v[108:111]
	v_mfma_f32_16x16x32_bf16 v[104:107], v[164:167], v[188:191], v[104:107]
	v_mfma_f32_16x16x32_bf16 v[104:107], v[168:171], v[192:195], v[104:107]
	v_mfma_f32_16x16x32_bf16 v[100:103], v[156:159], v[196:199], v[100:103]
	v_mfma_f32_16x16x32_bf16 v[100:103], v[160:163], v[200:203], v[100:103]
	v_mfma_f32_16x16x32_bf16 v[96:99], v[164:167], v[196:199], v[96:99]
	v_mfma_f32_16x16x32_bf16 v[96:99], v[168:171], v[200:203], v[96:99]
	s_barrier
	s_add_i32 s45, s40, s17
	s_add_i32 s46, s45, 0x100
	s_mov_b32 s10, s6
	s_mov_b32 s11, s7
	s_mov_b32 m0, s3
	ds_read_b128 v[204:207], v147
	ds_read_b128 v[208:211], v148
	ds_read_b128 v[212:215], v149
	ds_read_b128 v[216:219], v150
	buffer_load_dwordx4 v130, s[8:11], s46 offen lds
	s_mov_b32 m0, s18
	s_nop 0
	buffer_load_dwordx4 v134, s[8:11], s46 offen lds
	s_barrier
	s_waitcnt lgkmcnt(0)
	v_mfma_f32_16x16x32_bf16 v[92:95], v[204:207], v[172:175], v[92:95]
	v_mfma_f32_16x16x32_bf16 v[92:95], v[208:211], v[176:179], v[92:95]
	v_mfma_f32_16x16x32_bf16 v[88:91], v[212:215], v[172:175], v[88:91]
	v_mfma_f32_16x16x32_bf16 v[88:91], v[216:219], v[176:179], v[88:91]
	v_mfma_f32_16x16x32_bf16 v[84:87], v[204:207], v[180:183], v[84:87]
	v_mfma_f32_16x16x32_bf16 v[84:87], v[208:211], v[184:187], v[84:87]
	v_mfma_f32_16x16x32_bf16 v[80:83], v[212:215], v[180:183], v[80:83]
	v_mfma_f32_16x16x32_bf16 v[80:83], v[216:219], v[184:187], v[80:83]
	v_mfma_f32_16x16x32_bf16 v[76:79], v[204:207], v[188:191], v[76:79]
	v_mfma_f32_16x16x32_bf16 v[76:79], v[208:211], v[192:195], v[76:79]
	v_mfma_f32_16x16x32_bf16 v[72:75], v[212:215], v[188:191], v[72:75]
	v_mfma_f32_16x16x32_bf16 v[72:75], v[216:219], v[192:195], v[72:75]
	v_mfma_f32_16x16x32_bf16 v[68:71], v[204:207], v[196:199], v[68:71]
	v_mfma_f32_16x16x32_bf16 v[68:71], v[208:211], v[200:203], v[68:71]
	v_mfma_f32_16x16x32_bf16 v[64:67], v[212:215], v[196:199], v[64:67]
	v_mfma_f32_16x16x32_bf16 v[64:67], v[216:219], v[200:203], v[64:67]
	s_barrier
	s_add_i32 s46, s39, s17
	s_add_i32 s47, s46, 0x100
	s_mov_b32 m0, s0
	ds_read_b128 v[172:175], v131 offset:16384
	ds_read_b128 v[176:179], v131 offset:17408
	ds_read_b128 v[180:183], v138 offset:16384
	ds_read_b128 v[184:187], v138 offset:17408
	ds_read_b128 v[188:191], v137 offset:16384
	ds_read_b128 v[192:195], v137 offset:17408
	ds_read_b128 v[196:199], v135 offset:16384
	ds_read_b128 v[200:203], v135 offset:17408
	buffer_load_dwordx4 v128, s[4:7], s47 offen lds
	s_mov_b32 m0, s19
	s_nop 0
	buffer_load_dwordx4 v132, s[4:7], s47 offen lds
	s_barrier
	s_waitcnt lgkmcnt(0)
	v_mfma_f32_16x16x32_bf16 v[60:63], v[156:159], v[172:175], v[60:63]
	v_mfma_f32_16x16x32_bf16 v[60:63], v[160:163], v[176:179], v[60:63]
	v_mfma_f32_16x16x32_bf16 v[56:59], v[164:167], v[172:175], v[56:59]
	v_mfma_f32_16x16x32_bf16 v[56:59], v[168:171], v[176:179], v[56:59]
	v_mfma_f32_16x16x32_bf16 v[52:55], v[156:159], v[180:183], v[52:55]
	v_mfma_f32_16x16x32_bf16 v[52:55], v[160:163], v[184:187], v[52:55]
	v_mfma_f32_16x16x32_bf16 v[48:51], v[164:167], v[180:183], v[48:51]
	v_mfma_f32_16x16x32_bf16 v[48:51], v[168:171], v[184:187], v[48:51]
	v_mfma_f32_16x16x32_bf16 v[44:47], v[156:159], v[188:191], v[44:47]
	v_mfma_f32_16x16x32_bf16 v[44:47], v[160:163], v[192:195], v[44:47]
	v_mfma_f32_16x16x32_bf16 v[40:43], v[164:167], v[188:191], v[40:43]
	v_mfma_f32_16x16x32_bf16 v[40:43], v[168:171], v[192:195], v[40:43]
	v_mfma_f32_16x16x32_bf16 v[36:39], v[156:159], v[196:199], v[36:39]
	v_mfma_f32_16x16x32_bf16 v[36:39], v[160:163], v[200:203], v[36:39]
	v_mfma_f32_16x16x32_bf16 v[32:35], v[164:167], v[196:199], v[32:35]
	v_mfma_f32_16x16x32_bf16 v[32:35], v[168:171], v[200:203], v[32:35]
	s_barrier
; #define STAGE(P, RS, SOFF, OFF, kt) do { const int _so = (SOFF) + (kt) * (BK * 2); \
;     _Pragma("unroll") for (int _i = 0; _i < 2; ++_i) { \
;       __builtin_amdgcn_raw_ptr_buffer_load_lds(RS, (__attribute__((address_space(3))) void*)((P) + wave * 1024 + _i * 8192), 16, OFF[_i], _so, 0, 0); } } while (0)
; #define LDA(dst, b, h) _Pragma("unroll") for (int m = 0; m < 4; ++m) _Pragma("unroll") for (int k = 0; k < 2; ++k) \
;     dst[m][k] = *reinterpret_cast<const bf16x8*>(SA(b, h) + lds_byte(wr * 64 + m * 16 + fr, k * 32 + fq * 8))
; #define LDB(dst, b, h) _Pragma("unroll") for (int n = 0; n < 2; ++n) _Pragma("unroll") for (int k = 0; k < 2; ++k) \
;     dst[n][k] = *reinterpret_cast<const bf16x8*>(SB(b, h) + lds_byte(wc * 32 + n * 16 + fr, k * 32 + fq * 8))
; #define WAIT_V(n) asm volatile("s_waitcnt vmcnt(" #n ")" ::: "memory")
; #define WAIT_L(n) asm volatile("s_waitcnt lgkmcnt(" #n ")" ::: "memory")
; #define BAR __builtin_amdgcn_s_barrier()
; #define SCHED __builtin_amdgcn_sched_barrier(0)
;     ...
;       STAGE(SB(0, 1), rsB, sB1, offB, t + 2);
;       WAIT_V(6); BAR; MMA(1, 1, At, B1); BAR;
;       LDB(B0, 1, 0); SCHED; LDA(At, 1, 0); STAGE(SA(0, 1), rsA, sA1, offA, t + 2);
;       WAIT_L(8); BAR; WAIT_L(0); MMA(0, 0, At, B0); BAR; SCHED;
;       LDB(B1, 1, 1); STAGE(SB(1, 0), rsB, sB0, offB, t + 3);
;       BAR; WAIT_L(0); MMA(0, 1, At, B1); BAR;
;       LDA(At, 1, 1); STAGE(SA(1, 0), rsA, sA0, offA, t + 3);
	s_add_i32 s47, s41, s17
	s_add_i32 s48, s47, 0x100
	s_mov_b32 m0, s20
	s_nop 0
	buffer_load_dwordx4 v130, s[8:11], s48 offen lds
	s_mov_b32 m0, s21
	s_nop 0
	buffer_load_dwordx4 v134, s[8:11], s48 offen lds
	s_waitcnt vmcnt(6)
	s_barrier
	v_mfma_f32_16x16x32_bf16 v[28:31], v[204:207], v[172:175], v[28:31]
	v_mfma_f32_16x16x32_bf16 v[28:31], v[208:211], v[176:179], v[28:31]
	v_mfma_f32_16x16x32_bf16 v[24:27], v[212:215], v[172:175], v[24:27]
	v_mfma_f32_16x16x32_bf16 v[24:27], v[216:219], v[176:179], v[24:27]
	v_mfma_f32_16x16x32_bf16 v[20:23], v[204:207], v[180:183], v[20:23]
	v_mfma_f32_16x16x32_bf16 v[20:23], v[208:211], v[184:187], v[20:23]
	v_mfma_f32_16x16x32_bf16 v[16:19], v[212:215], v[180:183], v[16:19]
	v_mfma_f32_16x16x32_bf16 v[16:19], v[216:219], v[184:187], v[16:19]
	v_mfma_f32_16x16x32_bf16 v[12:15], v[204:207], v[188:191], v[12:15]
	v_mfma_f32_16x16x32_bf16 v[12:15], v[208:211], v[192:195], v[12:15]
	v_mfma_f32_16x16x32_bf16 v[8:11], v[212:215], v[188:191], v[8:11]
	v_mfma_f32_16x16x32_bf16 v[8:11], v[216:219], v[192:195], v[8:11]
	v_mfma_f32_16x16x32_bf16 v[4:7], v[204:207], v[196:199], v[4:7]
	v_mfma_f32_16x16x32_bf16 v[4:7], v[208:211], v[200:203], v[4:7]
	v_mfma_f32_16x16x32_bf16 v[0:3], v[212:215], v[196:199], v[0:3]
	v_mfma_f32_16x16x32_bf16 v[0:3], v[216:219], v[200:203], v[0:3]
	s_barrier
	ds_read_b128 v[156:159], v143
	ds_read_b128 v[160:163], v144
	ds_read_b128 v[164:167], v145
	ds_read_b128 v[168:171], v146
	s_addk_i32 s44, 0x100
	s_mov_b32 m0, s22
	ds_read_b128 v[172:175], v131 offset:32768
	ds_read_b128 v[176:179], v131 offset:33792
	ds_read_b128 v[180:183], v138 offset:32768
	ds_read_b128 v[184:187], v138 offset:33792
	ds_read_b128 v[188:191], v137 offset:32768
	ds_read_b128 v[192:195], v137 offset:33792
	ds_read_b128 v[196:199], v135 offset:32768
	ds_read_b128 v[200:203], v135 offset:33792
	buffer_load_dwordx4 v128, s[4:7], s44 offen lds
	s_mov_b32 m0, s23
	s_nop 0
	buffer_load_dwordx4 v132, s[4:7], s44 offen lds
	s_waitcnt lgkmcnt(8)
	s_barrier
	s_waitcnt lgkmcnt(0)
	v_mfma_f32_16x16x32_bf16 v[124:127], v[156:159], v[172:175], v[124:127]
	v_mfma_f32_16x16x32_bf16 v[124:127], v[160:163], v[176:179], v[124:127]
	v_mfma_f32_16x16x32_bf16 v[120:123], v[164:167], v[172:175], v[120:123]
	v_mfma_f32_16x16x32_bf16 v[120:123], v[168:171], v[176:179], v[120:123]
	v_mfma_f32_16x16x32_bf16 v[116:119], v[156:159], v[180:183], v[116:119]
	v_mfma_f32_16x16x32_bf16 v[116:119], v[160:163], v[184:187], v[116:119]
	v_mfma_f32_16x16x32_bf16 v[112:115], v[164:167], v[180:183], v[112:115]
	v_mfma_f32_16x16x32_bf16 v[112:115], v[168:171], v[184:187], v[112:115]
	v_mfma_f32_16x16x32_bf16 v[108:111], v[156:159], v[188:191], v[108:111]
	v_mfma_f32_16x16x32_bf16 v[108:111], v[160:163], v[192:195], v[108:111]
	v_mfma_f32_16x16x32_bf16 v[104:107], v[164:167], v[188:191], v[104:107]
	v_mfma_f32_16x16x32_bf16 v[104:107], v[168:171], v[192:195], v[104:107]
	v_mfma_f32_16x16x32_bf16 v[100:103], v[156:159], v[196:199], v[100:103]
	v_mfma_f32_16x16x32_bf16 v[100:103], v[160:163], v[200:203], v[100:103]
	v_mfma_f32_16x16x32_bf16 v[96:99], v[164:167], v[196:199], v[96:99]
	v_mfma_f32_16x16x32_bf16 v[96:99], v[168:171], v[200:203], v[96:99]
	s_barrier
	s_addk_i32 s45, 0x180
	s_mov_b32 m0, s24
	ds_read_b128 v[204:207], v139
	ds_read_b128 v[208:211], v140
	ds_read_b128 v[212:215], v141
	ds_read_b128 v[216:219], v142
	buffer_load_dwordx4 v130, s[8:11], s45 offen lds
	s_mov_b32 m0, s25
	s_nop 0
	buffer_load_dwordx4 v134, s[8:11], s45 offen lds
	s_barrier
	s_waitcnt lgkmcnt(0)
	v_mfma_f32_16x16x32_bf16 v[92:95], v[204:207], v[172:175], v[92:95]
	v_mfma_f32_16x16x32_bf16 v[92:95], v[208:211], v[176:179], v[92:95]
	v_mfma_f32_16x16x32_bf16 v[88:91], v[212:215], v[172:175], v[88:91]
	v_mfma_f32_16x16x32_bf16 v[88:91], v[216:219], v[176:179], v[88:91]
	v_mfma_f32_16x16x32_bf16 v[84:87], v[204:207], v[180:183], v[84:87]
	v_mfma_f32_16x16x32_bf16 v[84:87], v[208:211], v[184:187], v[84:87]
	v_mfma_f32_16x16x32_bf16 v[80:83], v[212:215], v[180:183], v[80:83]
	v_mfma_f32_16x16x32_bf16 v[80:83], v[216:219], v[184:187], v[80:83]
	v_mfma_f32_16x16x32_bf16 v[76:79], v[204:207], v[188:191], v[76:79]
	v_mfma_f32_16x16x32_bf16 v[76:79], v[208:211], v[192:195], v[76:79]
	v_mfma_f32_16x16x32_bf16 v[72:75], v[212:215], v[188:191], v[72:75]
	v_mfma_f32_16x16x32_bf16 v[72:75], v[216:219], v[192:195], v[72:75]
	v_mfma_f32_16x16x32_bf16 v[68:71], v[204:207], v[196:199], v[68:71]
	v_mfma_f32_16x16x32_bf16 v[68:71], v[208:211], v[200:203], v[68:71]
	v_mfma_f32_16x16x32_bf16 v[64:67], v[212:215], v[196:199], v[64:67]
	v_mfma_f32_16x16x32_bf16 v[64:67], v[216:219], v[200:203], v[64:67]
	s_barrier
	s_addk_i32 s46, 0x180
	s_mov_b32 m0, s26
	ds_read_b128 v[172:175], v131 offset:49152
	ds_read_b128 v[176:179], v131 offset:50176
	ds_read_b128 v[180:183], v138 offset:49152
	ds_read_b128 v[184:187], v138 offset:50176
	ds_read_b128 v[188:191], v137 offset:49152
	ds_read_b128 v[192:195], v137 offset:50176
	ds_read_b128 v[196:199], v135 offset:49152
	ds_read_b128 v[200:203], v135 offset:50176
	buffer_load_dwordx4 v128, s[4:7], s46 offen lds
	s_mov_b32 m0, s27
	s_nop 0
	buffer_load_dwordx4 v132, s[4:7], s46 offen lds
	s_barrier
; #define STAGE(P, RS, SOFF, OFF, kt) do { const int _so = (SOFF) + (kt) * (BK * 2); \
;     _Pragma("unroll") for (int _i = 0; _i < 2; ++_i) { \
;       __builtin_amdgcn_raw_ptr_buffer_load_lds(RS, (__attribute__((address_space(3))) void*)((P) + wave * 1024 + _i * 8192), 16, OFF[_i], _so, 0, 0); } } while (0)
; #define LDA(dst, b, h) _Pragma("unroll") for (int m = 0; m < 4; ++m) _Pragma("unroll") for (int k = 0; k < 2; ++k) \
;     dst[m][k] = *reinterpret_cast<const bf16x8*>(SA(b, h) + lds_byte(wr * 64 + m * 16 + fr, k * 32 + fq * 8))
; #define LDB(dst, b, h) _Pragma("unroll") for (int n = 0; n < 2; ++n) _Pragma("unroll") for (int k = 0; k < 2; ++k) \
;     dst[n][k] = *reinterpret_cast<const bf16x8*>(SB(b, h) + lds_byte(wc * 32 + n * 16 + fr, k * 32 + fq * 8))
; #define WAIT_V(n) asm volatile("s_waitcnt vmcnt(" #n ")" ::: "memory")
; #define WAIT_L(n) asm volatile("s_waitcnt lgkmcnt(" #n ")" ::: "memory")
; #define BAR __builtin_amdgcn_s_barrier()
; #define SCHED __builtin_amdgcn_sched_barrier(0)
;     ...
;       LDA(At, 1, 1); STAGE(SA(1, 0), rsA, sA0, offA, t + 3);
;       BAR; WAIT_L(0); MMA(1, 0, At, B0); BAR; SCHED;
;       STAGE(SB(1, 1), rsB, sB1, offB, t + 3);
;       WAIT_V(6); BAR; MMA(1, 1, At, B1); BAR;
;     }
;     { LDB(B0, 0, 0); LDA(At, 0, 0); STAGE(SA(1, 1), rsA, sA1, offA, nt - 1);
;       BAR; WAIT_L(0); MMA(0, 0, At, B0); BAR;
;       LDB(B1, 0, 1); BAR; WAIT_L(0); MMA(0, 1, At, B1); BAR;
	s_waitcnt lgkmcnt(0)
	v_mfma_f32_16x16x32_bf16 v[60:63], v[156:159], v[172:175], v[60:63]
	v_mfma_f32_16x16x32_bf16 v[60:63], v[160:163], v[176:179], v[60:63]
	v_mfma_f32_16x16x32_bf16 v[56:59], v[164:167], v[172:175], v[56:59]
	v_mfma_f32_16x16x32_bf16 v[56:59], v[168:171], v[176:179], v[56:59]
	v_mfma_f32_16x16x32_bf16 v[52:55], v[156:159], v[180:183], v[52:55]
	v_mfma_f32_16x16x32_bf16 v[52:55], v[160:163], v[184:187], v[52:55]
	v_mfma_f32_16x16x32_bf16 v[48:51], v[164:167], v[180:183], v[48:51]
	v_mfma_f32_16x16x32_bf16 v[48:51], v[168:171], v[184:187], v[48:51]
	v_mfma_f32_16x16x32_bf16 v[44:47], v[156:159], v[188:191], v[44:47]
	v_mfma_f32_16x16x32_bf16 v[44:47], v[160:163], v[192:195], v[44:47]
	v_mfma_f32_16x16x32_bf16 v[40:43], v[164:167], v[188:191], v[40:43]
	v_mfma_f32_16x16x32_bf16 v[40:43], v[168:171], v[192:195], v[40:43]
	v_mfma_f32_16x16x32_bf16 v[36:39], v[156:159], v[196:199], v[36:39]
	v_mfma_f32_16x16x32_bf16 v[36:39], v[160:163], v[200:203], v[36:39]
	v_mfma_f32_16x16x32_bf16 v[32:35], v[164:167], v[196:199], v[32:35]
	v_mfma_f32_16x16x32_bf16 v[32:35], v[168:171], v[200:203], v[32:35]
	s_barrier
	s_addk_i32 s47, 0x180
	s_mov_b32 m0, s28
	s_nop 0
	buffer_load_dwordx4 v130, s[8:11], s47 offen lds
	s_mov_b32 m0, s29
	s_nop 0
	buffer_load_dwordx4 v134, s[8:11], s47 offen lds
	s_add_i32 s16, s16, 2
	s_addk_i32 s17, 0x100
	s_cmp_gt_u32 s16, 3
	s_cbranch_scc0 .LBB0_110
	s_waitcnt vmcnt(6)
	s_barrier
	v_mfma_f32_16x16x32_bf16 v[28:31], v[204:207], v[172:175], v[28:31]
	v_mfma_f32_16x16x32_bf16 v[28:31], v[208:211], v[176:179], v[28:31]
	v_mfma_f32_16x16x32_bf16 v[24:27], v[212:215], v[172:175], v[24:27]
	v_mfma_f32_16x16x32_bf16 v[24:27], v[216:219], v[176:179], v[24:27]
	v_mfma_f32_16x16x32_bf16 v[20:23], v[204:207], v[180:183], v[20:23]
	v_mfma_f32_16x16x32_bf16 v[20:23], v[208:211], v[184:187], v[20:23]
	v_mfma_f32_16x16x32_bf16 v[16:19], v[212:215], v[180:183], v[16:19]
	v_mfma_f32_16x16x32_bf16 v[16:19], v[216:219], v[184:187], v[16:19]
	v_mfma_f32_16x16x32_bf16 v[12:15], v[204:207], v[188:191], v[12:15]
	v_mfma_f32_16x16x32_bf16 v[12:15], v[208:211], v[192:195], v[12:15]
	v_mfma_f32_16x16x32_bf16 v[8:11], v[212:215], v[188:191], v[8:11]
	v_mfma_f32_16x16x32_bf16 v[8:11], v[216:219], v[192:195], v[8:11]
	v_mfma_f32_16x16x32_bf16 v[4:7], v[204:207], v[196:199], v[4:7]
	v_mfma_f32_16x16x32_bf16 v[4:7], v[208:211], v[200:203], v[4:7]
	v_mfma_f32_16x16x32_bf16 v[0:3], v[212:215], v[196:199], v[0:3]
	v_mfma_f32_16x16x32_bf16 v[0:3], v[216:219], v[200:203], v[0:3]
	s_barrier
	s_add_i32 s10, s38, 0x380
	s_mov_b32 m0, s31
	ds_read_b128 v[156:159], v151
	ds_read_b128 v[160:163], v152
	ds_read_b128 v[164:167], v153
	ds_read_b128 v[152:155], v154
	ds_read_b128 v[168:171], v131
	ds_read_b128 v[172:175], v131 offset:1024
	ds_read_b128 v[176:179], v138
	ds_read_b128 v[180:183], v138 offset:1024
	ds_read_b128 v[184:187], v137
	ds_read_b128 v[188:191], v137 offset:1024
	ds_read_b128 v[192:195], v135
	ds_read_b128 v[196:199], v135 offset:1024
	buffer_load_dwordx4 v128, s[4:7], s10 offen lds
	s_mov_b32 m0, s33
	s_nop 0
	buffer_load_dwordx4 v132, s[4:7], s10 offen lds
	s_barrier
	s_waitcnt lgkmcnt(0)
	v_mfma_f32_16x16x32_bf16 v[124:127], v[156:159], v[168:171], v[124:127]
	v_mfma_f32_16x16x32_bf16 v[124:127], v[160:163], v[172:175], v[124:127]
	v_mfma_f32_16x16x32_bf16 v[120:123], v[164:167], v[168:171], v[120:123]
	v_mfma_f32_16x16x32_bf16 v[120:123], v[152:155], v[172:175], v[120:123]
	v_mfma_f32_16x16x32_bf16 v[116:119], v[156:159], v[176:179], v[116:119]
	v_mfma_f32_16x16x32_bf16 v[116:119], v[160:163], v[180:183], v[116:119]
	v_mfma_f32_16x16x32_bf16 v[112:115], v[164:167], v[176:179], v[112:115]
	v_mfma_f32_16x16x32_bf16 v[112:115], v[152:155], v[180:183], v[112:115]
	v_mfma_f32_16x16x32_bf16 v[108:111], v[156:159], v[184:187], v[108:111]
	v_mfma_f32_16x16x32_bf16 v[108:111], v[160:163], v[188:191], v[108:111]
	v_mfma_f32_16x16x32_bf16 v[104:107], v[164:167], v[184:187], v[104:107]
	v_mfma_f32_16x16x32_bf16 v[104:107], v[152:155], v[188:191], v[104:107]
	v_mfma_f32_16x16x32_bf16 v[100:103], v[156:159], v[192:195], v[100:103]
	v_mfma_f32_16x16x32_bf16 v[100:103], v[160:163], v[196:199], v[100:103]
	v_mfma_f32_16x16x32_bf16 v[96:99], v[164:167], v[192:195], v[96:99]
	v_mfma_f32_16x16x32_bf16 v[96:99], v[152:155], v[196:199], v[96:99]
	s_barrier
	ds_read_b128 v[200:203], v147
	ds_read_b128 v[204:207], v148
	ds_read_b128 v[208:211], v149
	ds_read_b128 v[148:151], v150
	s_barrier
	s_waitcnt lgkmcnt(0)
	v_mfma_f32_16x16x32_bf16 v[92:95], v[200:203], v[168:171], v[92:95]
	v_mfma_f32_16x16x32_bf16 v[92:95], v[204:207], v[172:175], v[92:95]
	v_mfma_f32_16x16x32_bf16 v[88:91], v[208:211], v[168:171], v[88:91]
	v_mfma_f32_16x16x32_bf16 v[88:91], v[148:151], v[172:175], v[88:91]
	v_mfma_f32_16x16x32_bf16 v[84:87], v[200:203], v[176:179], v[84:87]
	v_mfma_f32_16x16x32_bf16 v[84:87], v[204:207], v[180:183], v[84:87]
	v_mfma_f32_16x16x32_bf16 v[80:83], v[208:211], v[176:179], v[80:83]
	v_mfma_f32_16x16x32_bf16 v[80:83], v[148:151], v[180:183], v[80:83]
	v_mfma_f32_16x16x32_bf16 v[76:79], v[200:203], v[184:187], v[76:79]
	v_mfma_f32_16x16x32_bf16 v[76:79], v[204:207], v[188:191], v[76:79]
	v_mfma_f32_16x16x32_bf16 v[72:75], v[208:211], v[184:187], v[72:75]
	v_mfma_f32_16x16x32_bf16 v[72:75], v[148:151], v[188:191], v[72:75]
	v_mfma_f32_16x16x32_bf16 v[68:71], v[200:203], v[192:195], v[68:71]
	v_mfma_f32_16x16x32_bf16 v[68:71], v[204:207], v[196:199], v[68:71]
	v_mfma_f32_16x16x32_bf16 v[64:67], v[208:211], v[192:195], v[64:67]
	v_mfma_f32_16x16x32_bf16 v[64:67], v[148:151], v[196:199], v[64:67]
	s_barrier
; #define LDA(dst, b, h) _Pragma("unroll") for (int m = 0; m < 4; ++m) _Pragma("unroll") for (int k = 0; k < 2; ++k) \
;     dst[m][k] = *reinterpret_cast<const bf16x8*>(SA(b, h) + lds_byte(wr * 64 + m * 16 + fr, k * 32 + fq * 8))
; #define LDB(dst, b, h) _Pragma("unroll") for (int n = 0; n < 2; ++n) _Pragma("unroll") for (int k = 0; k < 2; ++k) \
;     dst[n][k] = *reinterpret_cast<const bf16x8*>(SB(b, h) + lds_byte(wc * 32 + n * 16 + fr, k * 32 + fq * 8))
; #define WAIT_V(n) asm volatile("s_waitcnt vmcnt(" #n ")" ::: "memory")
; #define WAIT_L(n) asm volatile("s_waitcnt lgkmcnt(" #n ")" ::: "memory")
; #define BAR __builtin_amdgcn_s_barrier()
;     ...
;       LDA(At, 0, 1); WAIT_V(4); BAR; WAIT_L(0); MMA(1, 0, At, B0); MMA(1, 1, At, B1); BAR; }
;     { LDB(B0, 1, 0); LDA(At, 1, 0); WAIT_V(2); BAR; WAIT_L(0); MMA(0, 0, At, B0); BAR;
	ds_read_b128 v[168:171], v131 offset:16384
	ds_read_b128 v[172:175], v131 offset:17408
	ds_read_b128 v[176:179], v138 offset:16384
	ds_read_b128 v[180:183], v138 offset:17408
	ds_read_b128 v[184:187], v137 offset:16384
	ds_read_b128 v[188:191], v137 offset:17408
	ds_read_b128 v[192:195], v135 offset:16384
	ds_read_b128 v[196:199], v135 offset:17408
	s_waitcnt vmcnt(4)
	s_barrier
	s_waitcnt lgkmcnt(0)
	v_mfma_f32_16x16x32_bf16 v[60:63], v[156:159], v[168:171], v[60:63]
	v_mfma_f32_16x16x32_bf16 v[60:63], v[160:163], v[172:175], v[60:63]
	v_mfma_f32_16x16x32_bf16 v[56:59], v[164:167], v[168:171], v[56:59]
	v_mfma_f32_16x16x32_bf16 v[56:59], v[152:155], v[172:175], v[56:59]
	v_mfma_f32_16x16x32_bf16 v[52:55], v[156:159], v[176:179], v[52:55]
	v_mfma_f32_16x16x32_bf16 v[52:55], v[160:163], v[180:183], v[52:55]
	v_mfma_f32_16x16x32_bf16 v[48:51], v[164:167], v[176:179], v[48:51]
	v_mfma_f32_16x16x32_bf16 v[48:51], v[152:155], v[180:183], v[48:51]
	v_mfma_f32_16x16x32_bf16 v[44:47], v[156:159], v[184:187], v[44:47]
	v_mfma_f32_16x16x32_bf16 v[44:47], v[160:163], v[188:191], v[44:47]
	v_mfma_f32_16x16x32_bf16 v[40:43], v[164:167], v[184:187], v[40:43]
	v_mfma_f32_16x16x32_bf16 v[40:43], v[152:155], v[188:191], v[40:43]
	v_mfma_f32_16x16x32_bf16 v[36:39], v[156:159], v[192:195], v[36:39]
	v_mfma_f32_16x16x32_bf16 v[36:39], v[160:163], v[196:199], v[36:39]
	v_mfma_f32_16x16x32_bf16 v[32:35], v[164:167], v[192:195], v[32:35]
	v_mfma_f32_16x16x32_bf16 v[32:35], v[152:155], v[196:199], v[32:35]
	v_mfma_f32_16x16x32_bf16 v[28:31], v[200:203], v[168:171], v[28:31]
	v_mfma_f32_16x16x32_bf16 v[28:31], v[204:207], v[172:175], v[28:31]
	v_mfma_f32_16x16x32_bf16 v[24:27], v[208:211], v[168:171], v[24:27]
	v_mfma_f32_16x16x32_bf16 v[24:27], v[148:151], v[172:175], v[24:27]
	v_mfma_f32_16x16x32_bf16 v[20:23], v[200:203], v[176:179], v[20:23]
	v_mfma_f32_16x16x32_bf16 v[20:23], v[204:207], v[180:183], v[20:23]
	v_mfma_f32_16x16x32_bf16 v[16:19], v[208:211], v[176:179], v[16:19]
	v_mfma_f32_16x16x32_bf16 v[16:19], v[148:151], v[180:183], v[16:19]
	v_mfma_f32_16x16x32_bf16 v[12:15], v[200:203], v[184:187], v[12:15]
	v_mfma_f32_16x16x32_bf16 v[12:15], v[204:207], v[188:191], v[12:15]
	v_mfma_f32_16x16x32_bf16 v[8:11], v[208:211], v[184:187], v[8:11]
	v_mfma_f32_16x16x32_bf16 v[8:11], v[148:151], v[188:191], v[8:11]
	v_mfma_f32_16x16x32_bf16 v[4:7], v[200:203], v[192:195], v[4:7]
	v_mfma_f32_16x16x32_bf16 v[4:7], v[204:207], v[196:199], v[4:7]
	v_mfma_f32_16x16x32_bf16 v[0:3], v[208:211], v[192:195], v[0:3]
	v_mfma_f32_16x16x32_bf16 v[0:3], v[148:151], v[196:199], v[0:3]
	s_barrier
	ds_read_b128 v[148:151], v143
	ds_read_b128 v[152:155], v144
	ds_read_b128 v[156:159], v145
	ds_read_b128 v[144:147], v146
	ds_read_b128 v[160:163], v131 offset:32768
	ds_read_b128 v[164:167], v131 offset:33792
	ds_read_b128 v[168:171], v138 offset:32768
	ds_read_b128 v[172:175], v138 offset:33792
	ds_read_b128 v[176:179], v137 offset:32768
	ds_read_b128 v[180:183], v137 offset:33792
	ds_read_b128 v[184:187], v135 offset:32768
	ds_read_b128 v[188:191], v135 offset:33792
	s_waitcnt vmcnt(2)
	s_barrier
	s_waitcnt lgkmcnt(0)
	v_mfma_f32_16x16x32_bf16 v[124:127], v[148:151], v[160:163], v[124:127]
	v_mfma_f32_16x16x32_bf16 v[124:127], v[152:155], v[164:167], v[124:127]
	v_mfma_f32_16x16x32_bf16 v[120:123], v[156:159], v[160:163], v[120:123]
	v_mfma_f32_16x16x32_bf16 v[120:123], v[144:147], v[164:167], v[120:123]
	v_mfma_f32_16x16x32_bf16 v[116:119], v[148:151], v[168:171], v[116:119]
	v_mfma_f32_16x16x32_bf16 v[116:119], v[152:155], v[172:175], v[116:119]
	v_mfma_f32_16x16x32_bf16 v[112:115], v[156:159], v[168:171], v[112:115]
	v_mfma_f32_16x16x32_bf16 v[112:115], v[144:147], v[172:175], v[112:115]
	v_mfma_f32_16x16x32_bf16 v[108:111], v[148:151], v[176:179], v[108:111]
	v_mfma_f32_16x16x32_bf16 v[108:111], v[152:155], v[180:183], v[108:111]
	v_mfma_f32_16x16x32_bf16 v[104:107], v[156:159], v[176:179], v[104:107]
	v_mfma_f32_16x16x32_bf16 v[104:107], v[144:147], v[180:183], v[104:107]
	v_mfma_f32_16x16x32_bf16 v[100:103], v[148:151], v[184:187], v[100:103]
	v_mfma_f32_16x16x32_bf16 v[100:103], v[152:155], v[188:191], v[100:103]
	v_mfma_f32_16x16x32_bf16 v[96:99], v[156:159], v[184:187], v[96:99]
	v_mfma_f32_16x16x32_bf16 v[96:99], v[144:147], v[188:191], v[96:99]
	s_barrier
; #define LDA(dst, b, h) _Pragma("unroll") for (int m = 0; m < 4; ++m) _Pragma("unroll") for (int k = 0; k < 2; ++k) \
;     dst[m][k] = *reinterpret_cast<const bf16x8*>(SA(b, h) + lds_byte(wr * 64 + m * 16 + fr, k * 32 + fq * 8))
; #define LDB(dst, b, h) _Pragma("unroll") for (int n = 0; n < 2; ++n) _Pragma("unroll") for (int k = 0; k < 2; ++k) \
;     dst[n][k] = *reinterpret_cast<const bf16x8*>(SB(b, h) + lds_byte(wc * 32 + n * 16 + fr, k * 32 + fq * 8))
; #define WAIT_V(n) asm volatile("s_waitcnt vmcnt(" #n ")" ::: "memory")
; #define WAIT_L(n) asm volatile("s_waitcnt lgkmcnt(" #n ")" ::: "memory")
; #define BAR __builtin_amdgcn_s_barrier()
;     ...
;     { LDB(B0, 1, 0); LDA(At, 1, 0); WAIT_V(2); BAR; WAIT_L(0); MMA(0, 0, At, B0); BAR;
;       LDB(B1, 1, 1); WAIT_V(0); BAR; WAIT_L(0); MMA(0, 1, At, B1); BAR;
;       LDA(At, 1, 1); BAR; WAIT_L(0); MMA(1, 0, At, B0); MMA(1, 1, At, B1); BAR; }
;     if (wr == 0) BAR;
	ds_read_b128 v[192:195], v139
	ds_read_b128 v[196:199], v140
	ds_read_b128 v[200:203], v141
	ds_read_b128 v[140:143], v142
	s_waitcnt vmcnt(0)
	s_barrier
	s_waitcnt lgkmcnt(0)
	v_mfma_f32_16x16x32_bf16 v[92:95], v[192:195], v[160:163], v[92:95]
	v_mfma_f32_16x16x32_bf16 v[92:95], v[196:199], v[164:167], v[92:95]
	v_mfma_f32_16x16x32_bf16 v[88:91], v[200:203], v[160:163], v[88:91]
	v_mfma_f32_16x16x32_bf16 v[88:91], v[140:143], v[164:167], v[88:91]
	v_mfma_f32_16x16x32_bf16 v[84:87], v[192:195], v[168:171], v[84:87]
	v_mfma_f32_16x16x32_bf16 v[84:87], v[196:199], v[172:175], v[84:87]
	v_mfma_f32_16x16x32_bf16 v[80:83], v[200:203], v[168:171], v[80:83]
	v_mfma_f32_16x16x32_bf16 v[80:83], v[140:143], v[172:175], v[80:83]
	v_mfma_f32_16x16x32_bf16 v[76:79], v[192:195], v[176:179], v[76:79]
	v_mfma_f32_16x16x32_bf16 v[76:79], v[196:199], v[180:183], v[76:79]
	v_mfma_f32_16x16x32_bf16 v[72:75], v[200:203], v[176:179], v[72:75]
	v_mfma_f32_16x16x32_bf16 v[72:75], v[140:143], v[180:183], v[72:75]
	v_mfma_f32_16x16x32_bf16 v[68:71], v[192:195], v[184:187], v[68:71]
	v_mfma_f32_16x16x32_bf16 v[68:71], v[196:199], v[188:191], v[68:71]
	v_mfma_f32_16x16x32_bf16 v[64:67], v[200:203], v[184:187], v[64:67]
	v_mfma_f32_16x16x32_bf16 v[64:67], v[140:143], v[188:191], v[64:67]
	s_barrier
	ds_read_b128 v[160:163], v131 offset:49152
	ds_read_b128 v[164:167], v131 offset:50176
	ds_read_b128 v[168:171], v138 offset:49152
	ds_read_b128 v[172:175], v138 offset:50176
	ds_read_b128 v[176:179], v137 offset:49152
	ds_read_b128 v[180:183], v137 offset:50176
	ds_read_b128 v[184:187], v135 offset:49152
	ds_read_b128 v[188:191], v135 offset:50176
	s_barrier
	s_waitcnt lgkmcnt(0)
	v_mfma_f32_16x16x32_bf16 v[60:63], v[148:151], v[160:163], v[60:63]
	v_mfma_f32_16x16x32_bf16 v[60:63], v[152:155], v[164:167], v[60:63]
	v_mfma_f32_16x16x32_bf16 v[56:59], v[156:159], v[160:163], v[56:59]
	v_mfma_f32_16x16x32_bf16 v[56:59], v[144:147], v[164:167], v[56:59]
	v_mfma_f32_16x16x32_bf16 v[52:55], v[148:151], v[168:171], v[52:55]
	v_mfma_f32_16x16x32_bf16 v[52:55], v[152:155], v[172:175], v[52:55]
	v_mfma_f32_16x16x32_bf16 v[48:51], v[156:159], v[168:171], v[48:51]
	v_mfma_f32_16x16x32_bf16 v[48:51], v[144:147], v[172:175], v[48:51]
	v_mfma_f32_16x16x32_bf16 v[44:47], v[148:151], v[176:179], v[44:47]
	v_mfma_f32_16x16x32_bf16 v[44:47], v[152:155], v[180:183], v[44:47]
	v_mfma_f32_16x16x32_bf16 v[40:43], v[156:159], v[176:179], v[40:43]
	v_mfma_f32_16x16x32_bf16 v[40:43], v[144:147], v[180:183], v[40:43]
	v_mfma_f32_16x16x32_bf16 v[36:39], v[148:151], v[184:187], v[36:39]
	v_mfma_f32_16x16x32_bf16 v[36:39], v[152:155], v[188:191], v[36:39]
	v_mfma_f32_16x16x32_bf16 v[32:35], v[156:159], v[184:187], v[32:35]
	v_mfma_f32_16x16x32_bf16 v[32:35], v[144:147], v[188:191], v[32:35]
	v_mfma_f32_16x16x32_bf16 v[28:31], v[192:195], v[160:163], v[28:31]
	v_mfma_f32_16x16x32_bf16 v[28:31], v[196:199], v[164:167], v[28:31]
	v_mfma_f32_16x16x32_bf16 v[24:27], v[200:203], v[160:163], v[24:27]
	v_mfma_f32_16x16x32_bf16 v[24:27], v[140:143], v[164:167], v[24:27]
	v_mfma_f32_16x16x32_bf16 v[20:23], v[192:195], v[168:171], v[20:23]
	v_mfma_f32_16x16x32_bf16 v[20:23], v[196:199], v[172:175], v[20:23]
	v_mfma_f32_16x16x32_bf16 v[16:19], v[200:203], v[168:171], v[16:19]
	v_mfma_f32_16x16x32_bf16 v[16:19], v[140:143], v[172:175], v[16:19]
	v_mfma_f32_16x16x32_bf16 v[12:15], v[192:195], v[176:179], v[12:15]
	v_mfma_f32_16x16x32_bf16 v[12:15], v[196:199], v[180:183], v[12:15]
	v_mfma_f32_16x16x32_bf16 v[8:11], v[200:203], v[176:179], v[8:11]
	v_mfma_f32_16x16x32_bf16 v[8:11], v[140:143], v[180:183], v[8:11]
	v_mfma_f32_16x16x32_bf16 v[4:7], v[192:195], v[184:187], v[4:7]
	v_mfma_f32_16x16x32_bf16 v[4:7], v[196:199], v[188:191], v[4:7]
	v_mfma_f32_16x16x32_bf16 v[0:3], v[200:203], v[184:187], v[0:3]
	v_mfma_f32_16x16x32_bf16 v[0:3], v[140:143], v[188:191], v[0:3]
	v_cmp_gt_u32_e32 vcc, s36, v136
	s_barrier
	s_and_saveexec_b64 s[10:11], vcc
	s_cbranch_execz .LBB0_113
	s_barrier

; #define WAIT_V(n) asm volatile("s_waitcnt vmcnt(" #n ")" ::: "memory")
; #define BAR __builtin_amdgcn_s_barrier()
;     ...
;     const int tid = opaque_tid(wave);
;     const int wid = tid >> 6, lane = tid & 63, wr = wid >> 2, wc = wid & 3, fr = lane & 15, fq = lane >> 4;
;     int offA[2], offB[2];
;     _Pragma("unroll") for (int i = 0; i < 2; ++i) {
;       int r, c; stage_rc(tid * 16 + i * 8192, r, c);
;       offA[i] = (r * lda + c) * 2; offB[i] = (r * ldb + c) * 2;
;     }
;     const int brow = pm * BM;
;     f32x4 acc[2][2][4][2];
;     _Pragma("unroll") for (int a = 0; a < 2; ++a) _Pragma("unroll") for (int b = 0; b < 2; ++b) _Pragma("unroll") for (int m = 0; m < 4; ++m) _Pragma("unroll") for (int n = 0; n < 2; ++n)
;       acc[a][b][m][n] = f32x4{0.f, 0.f, 0.f, 0.f};
;     bf16x8 At[4][2], B0[2][2], B1[2][2];
;     if (wr == 1) BAR;
;     if (first_tile) { WAIT_V(0); }
;     else if constexpr (mode == MODE_RESID_LN) { WAIT_V(0); }
;     else if constexpr (mode == MODE_SWIGLU) { WAIT_V(6); }
;     else if constexpr (mode == MODE_V) { WAIT_V(24); }
;     else { WAIT_V(12); }
;     first_tile = false;
;     BAR;
;     BAR;
.LBB0_147:
	v_bfe_i32 v4, v128, 27, 1
	v_lshlrev_b32_e32 v2, 4, v128
	v_lshrrev_b32_e32 v4, 22, v4
	v_add_u32_e32 v4, v2, v4
	v_and_b32_e32 v4, 0xfffffc00, v4
	v_sub_u32_e32 v4, v2, v4
	v_lshrrev_b32_e32 v5, 4, v4
	v_bitop3_b32 v4, v5, v4, 32 bitop3:0x6c
	v_ashrrev_i32_e32 v3, 31, v128
	v_ashrrev_i32_e32 v6, 31, v4
	v_lshrrev_b32_e32 v3, 26, v3
	v_lshrrev_b32_e32 v6, 26, v6
	v_add_u32_e32 v3, v128, v3
	v_add_u32_e32 v6, v4, v6
	v_ashrrev_i32_e32 v3, 6, v3
	v_lshrrev_b32_e32 v7, 6, v6
	v_and_b32_e32 v6, 0xc0, v6
	v_lshlrev_b32_e32 v5, 3, v3
	v_lshlrev_b32_e32 v3, 5, v3
	v_sub_u32_e32 v4, v4, v6
	v_and_b32_e32 v5, 0x7fff0, v5
	v_and_b32_e32 v3, 32, v3
	v_ashrrev_i16_sdwa v4, v244, sext(v4) dst_sel:DWORD dst_unused:UNUSED_PAD src0_sel:DWORD src1_sel:BYTE_0
	v_add_u32_sdwa v3, v3, sext(v4) dst_sel:DWORD dst_unused:UNUSED_PAD src0_sel:DWORD src1_sel:WORD_0
	v_add_lshl_u32 v4, v7, v5, 13
	v_add_u32_e32 v2, 0x2000, v2
	v_lshl_add_u32 v141, v3, 1, v4
	v_ashrrev_i32_e32 v3, 31, v2
	v_lshrrev_b32_e32 v3, 22, v3
	v_add_u32_e32 v3, v2, v3
	v_ashrrev_i32_e32 v3, 10, v3
	v_mul_i32_i24_e32 v4, 0x400, v3
	v_sub_u32_e32 v2, v2, v4
	v_lshrrev_b32_e32 v4, 4, v2
	v_bitop3_b32 v2, v4, v2, 32 bitop3:0x6c
	v_ashrrev_i32_e32 v5, 31, v2
	v_lshrrev_b32_e32 v5, 26, v5
	v_add_u32_e32 v5, v2, v5
	v_lshrrev_b32_e32 v6, 6, v5
	v_and_b32_e32 v5, 0xc0, v5
	v_lshlrev_b32_e32 v4, 3, v3
	v_lshlrev_b32_e32 v3, 5, v3
	v_sub_u32_e32 v2, v2, v5
	v_and_b32_e32 v4, 0x7fff0, v4
	v_and_b32_e32 v3, 32, v3
	v_ashrrev_i16_sdwa v2, v244, sext(v2) dst_sel:DWORD dst_unused:UNUSED_PAD src0_sel:DWORD src1_sel:BYTE_0
	v_add_u32_sdwa v2, v3, sext(v2) dst_sel:DWORD dst_unused:UNUSED_PAD src0_sel:DWORD src1_sel:WORD_0
	v_add_lshl_u32 v3, v6, v4, 13
	v_lshl_add_u32 v142, v2, 1, v3
	v_and_b32_e32 v3, 15, v0
	v_lshlrev_b32_e32 v5, 2, v0
	v_and_b32_e32 v2, 48, v0
	v_lshlrev_b32_e32 v3, 6, v3
	v_and_b32_e32 v5, 32, v5
	v_or_b32_e32 v4, v3, v2
	v_bitop3_b32 v3, v3, v5, v2 bitop3:0x36
	v_lshlrev_b32_e32 v6, 6, v128
	s_movk_i32 s1, 0x3000
	v_and_or_b32 v3, v6, s1, v3
	v_lshlrev_b32_e32 v0, 6, v0
	s_movk_i32 s1, 0x3c0
	v_lshlrev_b32_e32 v1, 13, v1
	v_and_or_b32 v0, v0, s1, v2
	v_bitop3_b32 v0, v1, v0, v5 bitop3:0xf6
	v_or_b32_e32 v6, 0x400, v3
	v_or_b32_e32 v7, 0x800, v3
	v_or_b32_e32 v8, 0xc00, v3
	v_or_b32_e32 v132, 0x800, v0
	v_or_b32_e32 v131, 0x1000, v0
	v_or_b32_e32 v130, 0x1800, v0
	v_mov_b32_e32 v0, 0
	v_bitop3_b32 v129, v4, v1, v5 bitop3:0xde
	s_mov_b32 s1, -2
	s_mov_b32 s3, 0
	v_or_b32_e32 v147, 0x10000, v3
	v_or_b32_e32 v148, 0x10000, v6
	v_or_b32_e32 v149, 0x10000, v7
	v_or_b32_e32 v150, 0x10000, v8
	v_or_b32_e32 v143, 0x14000, v3
	v_or_b32_e32 v144, 0x14000, v6
	v_or_b32_e32 v145, 0x14000, v7
	v_or_b32_e32 v146, 0x14000, v8
	v_or_b32_e32 v137, 0x18000, v3
	v_or_b32_e32 v138, 0x18000, v6
	v_or_b32_e32 v139, 0x18000, v7
	v_or_b32_e32 v140, 0x18000, v8
	v_or_b32_e32 v133, 0x1c000, v3
	v_or_b32_e32 v134, 0x1c000, v6
	v_or_b32_e32 v135, 0x1c000, v7
	v_or_b32_e32 v136, 0x1c000, v8
	v_mov_b32_e32 v1, v0
	v_mov_b32_e32 v2, v0
	v_mov_b32_e32 v3, v0
	v_mov_b32_e32 v4, v0
	v_mov_b32_e32 v5, v0
	v_mov_b32_e32 v6, v0
	v_mov_b32_e32 v7, v0
	v_mov_b32_e32 v8, v0
	v_mov_b32_e32 v9, v0
	v_mov_b32_e32 v10, v0
	v_mov_b32_e32 v11, v0
	v_mov_b32_e32 v12, v0
	v_mov_b32_e32 v13, v0
	v_mov_b32_e32 v14, v0
	v_mov_b32_e32 v15, v0
	v_mov_b32_e32 v16, v0
	v_mov_b32_e32 v17, v0
	v_mov_b32_e32 v18, v0
	v_mov_b32_e32 v19, v0
	v_mov_b32_e32 v20, v0
	v_mov_b32_e32 v21, v0
	v_mov_b32_e32 v22, v0
	v_mov_b32_e32 v23, v0
	v_mov_b32_e32 v24, v0
	v_mov_b32_e32 v25, v0
	v_mov_b32_e32 v26, v0
	v_mov_b32_e32 v27, v0
	v_mov_b32_e32 v28, v0
	v_mov_b32_e32 v29, v0
	v_mov_b32_e32 v30, v0
	v_mov_b32_e32 v31, v0
	v_mov_b32_e32 v32, v0
	v_mov_b32_e32 v33, v0
	v_mov_b32_e32 v34, v0
	v_mov_b32_e32 v35, v0
	v_mov_b32_e32 v36, v0
	v_mov_b32_e32 v37, v0
	v_mov_b32_e32 v38, v0
	v_mov_b32_e32 v39, v0
	v_mov_b32_e32 v40, v0
	v_mov_b32_e32 v41, v0
	v_mov_b32_e32 v42, v0
	v_mov_b32_e32 v43, v0
	v_mov_b32_e32 v44, v0
	v_mov_b32_e32 v45, v0
	v_mov_b32_e32 v46, v0
	v_mov_b32_e32 v47, v0
	v_mov_b32_e32 v48, v0
	v_mov_b32_e32 v49, v0
	v_mov_b32_e32 v50, v0
	v_mov_b32_e32 v51, v0
	v_mov_b32_e32 v52, v0
	v_mov_b32_e32 v53, v0
	v_mov_b32_e32 v54, v0
	v_mov_b32_e32 v55, v0
	v_mov_b32_e32 v56, v0
	v_mov_b32_e32 v57, v0
	v_mov_b32_e32 v58, v0
	v_mov_b32_e32 v59, v0
	v_mov_b32_e32 v60, v0
	v_mov_b32_e32 v61, v0
	v_mov_b32_e32 v62, v0
	v_mov_b32_e32 v63, v0
	v_mov_b32_e32 v68, v0
	v_mov_b32_e32 v69, v0
	v_mov_b32_e32 v70, v0
	v_mov_b32_e32 v71, v0
	v_mov_b32_e32 v80, v0
	v_mov_b32_e32 v81, v0
	v_mov_b32_e32 v82, v0
	v_mov_b32_e32 v83, v0
	v_mov_b32_e32 v88, v0
	v_mov_b32_e32 v89, v0
	v_mov_b32_e32 v90, v0
	v_mov_b32_e32 v91, v0
	v_mov_b32_e32 v92, v0
	v_mov_b32_e32 v93, v0
	v_mov_b32_e32 v94, v0
	v_mov_b32_e32 v95, v0
	v_mov_b32_e32 v96, v0
	v_mov_b32_e32 v97, v0
	v_mov_b32_e32 v98, v0
	v_mov_b32_e32 v99, v0
	v_mov_b32_e32 v100, v0
	v_mov_b32_e32 v101, v0
	v_mov_b32_e32 v102, v0
	v_mov_b32_e32 v103, v0
	v_mov_b32_e32 v104, v0
	v_mov_b32_e32 v105, v0
	v_mov_b32_e32 v106, v0
	v_mov_b32_e32 v107, v0
	v_mov_b32_e32 v108, v0
	v_mov_b32_e32 v109, v0
	v_mov_b32_e32 v110, v0
	v_mov_b32_e32 v111, v0
	v_mov_b32_e32 v112, v0
	v_mov_b32_e32 v113, v0
	v_mov_b32_e32 v114, v0
	v_mov_b32_e32 v115, v0
	v_mov_b32_e32 v116, v0
	v_mov_b32_e32 v117, v0
	v_mov_b32_e32 v118, v0
	v_mov_b32_e32 v119, v0
	v_mov_b32_e32 v120, v0
	v_mov_b32_e32 v121, v0
	v_mov_b32_e32 v122, v0
	v_mov_b32_e32 v123, v0
	v_mov_b32_e32 v124, v0
	v_mov_b32_e32 v125, v0
	v_mov_b32_e32 v126, v0
	v_mov_b32_e32 v127, v0
	v_mov_b32_e32 v64, v0
	v_mov_b32_e32 v65, v0
	v_mov_b32_e32 v66, v0
	v_mov_b32_e32 v67, v0
	v_mov_b32_e32 v72, v0
	v_mov_b32_e32 v73, v0
	v_mov_b32_e32 v74, v0
	v_mov_b32_e32 v75, v0
	v_mov_b32_e32 v76, v0
	v_mov_b32_e32 v77, v0
	v_mov_b32_e32 v78, v0
	v_mov_b32_e32 v79, v0
	v_mov_b32_e32 v84, v0
	v_mov_b32_e32 v85, v0
	v_mov_b32_e32 v86, v0
	v_mov_b32_e32 v87, v0
	s_barrier
	s_barrier
	s_branch .Lmy_rot_148
; #define STAGE(P, RS, SOFF, OFF, kt) do { const int _so = (SOFF) + (kt) * (BK * 2); \
;     _Pragma("unroll") for (int _i = 0; _i < 2; ++_i) { \
;       __builtin_amdgcn_raw_ptr_buffer_load_lds(RS, (__attribute__((address_space(3))) void*)((P) + wave * 1024 + _i * 8192), 16, OFF[_i], _so, 0, 0); } } while (0)
; #define LDA(dst, b, h) _Pragma("unroll") for (int m = 0; m < 4; ++m) _Pragma("unroll") for (int k = 0; k < 2; ++k) \
;     dst[m][k] = *reinterpret_cast<const bf16x8*>(SA(b, h) + lds_byte(wr * 64 + m * 16 + fr, k * 32 + fq * 8))
; #define LDB(dst, b, h) _Pragma("unroll") for (int n = 0; n < 2; ++n) _Pragma("unroll") for (int k = 0; k < 2; ++k) \
;     dst[n][k] = *reinterpret_cast<const bf16x8*>(SB(b, h) + lds_byte(wc * 32 + n * 16 + fr, k * 32 + fq * 8))
; #define WAIT_V(n) asm volatile("s_waitcnt vmcnt(" #n ")" ::: "memory")
; #define WAIT_L(n) asm volatile("s_waitcnt lgkmcnt(" #n ")" ::: "memory")
; #define BAR __builtin_amdgcn_s_barrier()
; #define SCHED __builtin_amdgcn_sched_barrier(0)
;     ...
;       LDB(B0, 0, 0); SCHED; LDA(At, 0, 0); STAGE(SA(1, 1), rsA, sA1, offA, t + 1);
;       WAIT_L(8); BAR; WAIT_L(0); MMA(0, 0, At, B0); BAR; SCHED;
;       LDB(B1, 0, 1); STAGE(SB(0, 0), rsB, sB0, offB, t + 2);
;       BAR; WAIT_L(0); MMA(0, 1, At, B1); BAR;
;       LDA(At, 0, 1); STAGE(SA(0, 0), rsA, sA0, offA, t + 2);
;       BAR; WAIT_L(0); MMA(1, 0, At, B0); BAR; SCHED;
;     ...
;       WAIT_V(6); BAR; MMA(1, 1, At, B1); BAR;
.LBB0_148:
	s_waitcnt vmcnt(6)
	s_barrier
	v_mfma_f32_16x16x32_bf16 v[12:15], v[200:203], v[168:171], v[12:15]
	v_mfma_f32_16x16x32_bf16 v[12:15], v[204:207], v[172:175], v[12:15]
	v_mfma_f32_16x16x32_bf16 v[8:11], v[208:211], v[168:171], v[8:11]
	v_mfma_f32_16x16x32_bf16 v[8:11], v[212:215], v[172:175], v[8:11]
	v_mfma_f32_16x16x32_bf16 v[4:7], v[200:203], v[176:179], v[4:7]
	v_mfma_f32_16x16x32_bf16 v[4:7], v[204:207], v[180:183], v[4:7]
	v_mfma_f32_16x16x32_bf16 v[0:3], v[208:211], v[176:179], v[0:3]
	v_mfma_f32_16x16x32_bf16 v[0:3], v[212:215], v[180:183], v[0:3]
	v_mfma_f32_16x16x32_bf16 v[64:67], v[200:203], v[184:187], v[64:67]
	v_mfma_f32_16x16x32_bf16 v[64:67], v[204:207], v[188:191], v[64:67]
	v_mfma_f32_16x16x32_bf16 v[72:75], v[208:211], v[184:187], v[72:75]
	v_mfma_f32_16x16x32_bf16 v[72:75], v[212:215], v[188:191], v[72:75]
	v_mfma_f32_16x16x32_bf16 v[76:79], v[200:203], v[192:195], v[76:79]
	v_mfma_f32_16x16x32_bf16 v[76:79], v[204:207], v[196:199], v[76:79]
	v_mfma_f32_16x16x32_bf16 v[84:87], v[208:211], v[192:195], v[84:87]
	v_mfma_f32_16x16x32_bf16 v[84:87], v[212:215], v[196:199], v[84:87]
	s_barrier
.Lmy_rot_148:
	ds_read_b128 v[152:155], v147
	ds_read_b128 v[156:159], v148
	ds_read_b128 v[160:163], v149
	ds_read_b128 v[164:167], v150
	s_add_i32 s4, s82, s3
	s_add_i32 s5, s4, 0x80
	s_mov_b32 m0, s31
	ds_read_b128 v[168:171], v129
	ds_read_b128 v[172:175], v129 offset:1024
	ds_read_b128 v[176:179], v132
	ds_read_b128 v[180:183], v132 offset:1024
	ds_read_b128 v[184:187], v131
	ds_read_b128 v[188:191], v131 offset:1024
	ds_read_b128 v[192:195], v130
	ds_read_b128 v[196:199], v130 offset:1024
	buffer_load_dwordx4 v141, s[8:11], s5 offen lds
	s_mov_b32 m0, s58
	s_nop 0
	buffer_load_dwordx4 v142, s[8:11], s5 offen lds
	s_waitcnt lgkmcnt(8)
	s_barrier
	s_waitcnt lgkmcnt(0)
	v_mfma_f32_16x16x32_bf16 v[124:127], v[152:155], v[168:171], v[124:127]
	v_mfma_f32_16x16x32_bf16 v[124:127], v[156:159], v[172:175], v[124:127]
	v_mfma_f32_16x16x32_bf16 v[120:123], v[160:163], v[168:171], v[120:123]
	v_mfma_f32_16x16x32_bf16 v[120:123], v[164:167], v[172:175], v[120:123]
	v_mfma_f32_16x16x32_bf16 v[116:119], v[152:155], v[176:179], v[116:119]
	v_mfma_f32_16x16x32_bf16 v[116:119], v[156:159], v[180:183], v[116:119]
	v_mfma_f32_16x16x32_bf16 v[112:115], v[160:163], v[176:179], v[112:115]
	v_mfma_f32_16x16x32_bf16 v[112:115], v[164:167], v[180:183], v[112:115]
	v_mfma_f32_16x16x32_bf16 v[108:111], v[152:155], v[184:187], v[108:111]
	v_mfma_f32_16x16x32_bf16 v[108:111], v[156:159], v[188:191], v[108:111]
	v_mfma_f32_16x16x32_bf16 v[104:107], v[160:163], v[184:187], v[104:107]
	v_mfma_f32_16x16x32_bf16 v[104:107], v[164:167], v[188:191], v[104:107]
	v_mfma_f32_16x16x32_bf16 v[100:103], v[152:155], v[192:195], v[100:103]
	v_mfma_f32_16x16x32_bf16 v[100:103], v[156:159], v[196:199], v[100:103]
	v_mfma_f32_16x16x32_bf16 v[96:99], v[160:163], v[192:195], v[96:99]
	v_mfma_f32_16x16x32_bf16 v[96:99], v[164:167], v[196:199], v[96:99]
	s_barrier
	s_add_i32 s5, s84, s3
	s_add_i32 s6, s5, 0x100
	s_mov_b32 s14, s10
	s_mov_b32 s15, s11
	s_mov_b32 m0, s34
	ds_read_b128 v[200:203], v143
	ds_read_b128 v[204:207], v144
	ds_read_b128 v[208:211], v145
	ds_read_b128 v[212:215], v146
	buffer_load_dwordx4 v141, s[12:15], s6 offen lds
	s_mov_b32 m0, s43
	s_nop 0
	buffer_load_dwordx4 v142, s[12:15], s6 offen lds
	s_barrier
	s_waitcnt lgkmcnt(0)
	v_mfma_f32_16x16x32_bf16 v[92:95], v[200:203], v[168:171], v[92:95]
	v_mfma_f32_16x16x32_bf16 v[92:95], v[204:207], v[172:175], v[92:95]
	v_mfma_f32_16x16x32_bf16 v[88:91], v[208:211], v[168:171], v[88:91]
	v_mfma_f32_16x16x32_bf16 v[88:91], v[212:215], v[172:175], v[88:91]
	v_mfma_f32_16x16x32_bf16 v[80:83], v[200:203], v[176:179], v[80:83]
	v_mfma_f32_16x16x32_bf16 v[80:83], v[204:207], v[180:183], v[80:83]
	v_mfma_f32_16x16x32_bf16 v[68:71], v[208:211], v[176:179], v[68:71]
	v_mfma_f32_16x16x32_bf16 v[68:71], v[212:215], v[180:183], v[68:71]
	v_mfma_f32_16x16x32_bf16 v[60:63], v[200:203], v[184:187], v[60:63]
	v_mfma_f32_16x16x32_bf16 v[60:63], v[204:207], v[188:191], v[60:63]
	v_mfma_f32_16x16x32_bf16 v[56:59], v[208:211], v[184:187], v[56:59]
	v_mfma_f32_16x16x32_bf16 v[56:59], v[212:215], v[188:191], v[56:59]
	v_mfma_f32_16x16x32_bf16 v[52:55], v[200:203], v[192:195], v[52:55]
	v_mfma_f32_16x16x32_bf16 v[52:55], v[204:207], v[196:199], v[52:55]
	v_mfma_f32_16x16x32_bf16 v[48:51], v[208:211], v[192:195], v[48:51]
	v_mfma_f32_16x16x32_bf16 v[48:51], v[212:215], v[196:199], v[48:51]
	s_barrier
	s_add_i32 s6, s83, s3
	s_add_i32 s7, s6, 0x100
	s_mov_b32 m0, s30
	ds_read_b128 v[168:171], v129 offset:16384
	ds_read_b128 v[172:175], v129 offset:17408
	ds_read_b128 v[176:179], v132 offset:16384
	ds_read_b128 v[180:183], v132 offset:17408
	ds_read_b128 v[184:187], v131 offset:16384
	ds_read_b128 v[188:191], v131 offset:17408
	ds_read_b128 v[192:195], v130 offset:16384
	ds_read_b128 v[196:199], v130 offset:17408
	buffer_load_dwordx4 v141, s[8:11], s7 offen lds
	s_mov_b32 m0, s44
	s_nop 0
	buffer_load_dwordx4 v142, s[8:11], s7 offen lds
	s_barrier
	s_waitcnt lgkmcnt(0)
	v_mfma_f32_16x16x32_bf16 v[44:47], v[152:155], v[168:171], v[44:47]
	v_mfma_f32_16x16x32_bf16 v[44:47], v[156:159], v[172:175], v[44:47]
	v_mfma_f32_16x16x32_bf16 v[40:43], v[160:163], v[168:171], v[40:43]
	v_mfma_f32_16x16x32_bf16 v[40:43], v[164:167], v[172:175], v[40:43]
	v_mfma_f32_16x16x32_bf16 v[36:39], v[152:155], v[176:179], v[36:39]
	v_mfma_f32_16x16x32_bf16 v[36:39], v[156:159], v[180:183], v[36:39]
	v_mfma_f32_16x16x32_bf16 v[32:35], v[160:163], v[176:179], v[32:35]
	v_mfma_f32_16x16x32_bf16 v[32:35], v[164:167], v[180:183], v[32:35]
	v_mfma_f32_16x16x32_bf16 v[28:31], v[152:155], v[184:187], v[28:31]
	v_mfma_f32_16x16x32_bf16 v[28:31], v[156:159], v[188:191], v[28:31]
	v_mfma_f32_16x16x32_bf16 v[24:27], v[160:163], v[184:187], v[24:27]
	v_mfma_f32_16x16x32_bf16 v[24:27], v[164:167], v[188:191], v[24:27]
	v_mfma_f32_16x16x32_bf16 v[20:23], v[152:155], v[192:195], v[20:23]
	v_mfma_f32_16x16x32_bf16 v[20:23], v[156:159], v[196:199], v[20:23]
	v_mfma_f32_16x16x32_bf16 v[16:19], v[160:163], v[192:195], v[16:19]
	v_mfma_f32_16x16x32_bf16 v[16:19], v[164:167], v[196:199], v[16:19]
	s_barrier
; #define STAGE(P, RS, SOFF, OFF, kt) do { const int _so = (SOFF) + (kt) * (BK * 2); \
;     _Pragma("unroll") for (int _i = 0; _i < 2; ++_i) { \
;       __builtin_amdgcn_raw_ptr_buffer_load_lds(RS, (__attribute__((address_space(3))) void*)((P) + wave * 1024 + _i * 8192), 16, OFF[_i], _so, 0, 0); } } while (0)
; #define LDA(dst, b, h) _Pragma("unroll") for (int m = 0; m < 4; ++m) _Pragma("unroll") for (int k = 0; k < 2; ++k) \
;     dst[m][k] = *reinterpret_cast<const bf16x8*>(SA(b, h) + lds_byte(wr * 64 + m * 16 + fr, k * 32 + fq * 8))
; #define LDB(dst, b, h) _Pragma("unroll") for (int n = 0; n < 2; ++n) _Pragma("unroll") for (int k = 0; k < 2; ++k) \
;     dst[n][k] = *reinterpret_cast<const bf16x8*>(SB(b, h) + lds_byte(wc * 32 + n * 16 + fr, k * 32 + fq * 8))
; #define WAIT_V(n) asm volatile("s_waitcnt vmcnt(" #n ")" ::: "memory")
; #define WAIT_L(n) asm volatile("s_waitcnt lgkmcnt(" #n ")" ::: "memory")
; #define BAR __builtin_amdgcn_s_barrier()
; #define SCHED __builtin_amdgcn_sched_barrier(0)
;     ...
;       STAGE(SB(0, 1), rsB, sB1, offB, t + 2);
;       WAIT_V(6); BAR; MMA(1, 1, At, B1); BAR;
;       LDB(B0, 1, 0); SCHED; LDA(At, 1, 0); STAGE(SA(0, 1), rsA, sA1, offA, t + 2);
;       WAIT_L(8); BAR; WAIT_L(0); MMA(0, 0, At, B0); BAR; SCHED;
;       LDB(B1, 1, 1); STAGE(SB(1, 0), rsB, sB0, offB, t + 3);
;       BAR; WAIT_L(0); MMA(0, 1, At, B1); BAR;
;       LDA(At, 1, 1); STAGE(SA(1, 0), rsA, sA0, offA, t + 3);
	s_add_i32 s7, s85, s3
	s_add_i32 s19, s7, 0x100
	s_mov_b32 m0, s35
	s_nop 0
	buffer_load_dwordx4 v141, s[12:15], s19 offen lds
	s_mov_b32 m0, s45
	s_nop 0
	buffer_load_dwordx4 v142, s[12:15], s19 offen lds
	s_waitcnt vmcnt(6)
	s_barrier
	v_mfma_f32_16x16x32_bf16 v[12:15], v[200:203], v[168:171], v[12:15]
	v_mfma_f32_16x16x32_bf16 v[12:15], v[204:207], v[172:175], v[12:15]
	v_mfma_f32_16x16x32_bf16 v[8:11], v[208:211], v[168:171], v[8:11]
	v_mfma_f32_16x16x32_bf16 v[8:11], v[212:215], v[172:175], v[8:11]
	v_mfma_f32_16x16x32_bf16 v[4:7], v[200:203], v[176:179], v[4:7]
	v_mfma_f32_16x16x32_bf16 v[4:7], v[204:207], v[180:183], v[4:7]
	v_mfma_f32_16x16x32_bf16 v[0:3], v[208:211], v[176:179], v[0:3]
	v_mfma_f32_16x16x32_bf16 v[0:3], v[212:215], v[180:183], v[0:3]
	v_mfma_f32_16x16x32_bf16 v[64:67], v[200:203], v[184:187], v[64:67]
	v_mfma_f32_16x16x32_bf16 v[64:67], v[204:207], v[188:191], v[64:67]
	v_mfma_f32_16x16x32_bf16 v[72:75], v[208:211], v[184:187], v[72:75]
	v_mfma_f32_16x16x32_bf16 v[72:75], v[212:215], v[188:191], v[72:75]
	v_mfma_f32_16x16x32_bf16 v[76:79], v[200:203], v[192:195], v[76:79]
	v_mfma_f32_16x16x32_bf16 v[76:79], v[204:207], v[196:199], v[76:79]
	v_mfma_f32_16x16x32_bf16 v[84:87], v[208:211], v[192:195], v[84:87]
	v_mfma_f32_16x16x32_bf16 v[84:87], v[212:215], v[196:199], v[84:87]
	s_barrier
	ds_read_b128 v[152:155], v137
	ds_read_b128 v[156:159], v138
	ds_read_b128 v[160:163], v139
	ds_read_b128 v[164:167], v140
	s_addk_i32 s4, 0x100
	s_mov_b32 m0, s36
	ds_read_b128 v[168:171], v129 offset:32768
	ds_read_b128 v[172:175], v129 offset:33792
	ds_read_b128 v[176:179], v132 offset:32768
	ds_read_b128 v[180:183], v132 offset:33792
	ds_read_b128 v[184:187], v131 offset:32768
	ds_read_b128 v[188:191], v131 offset:33792
	ds_read_b128 v[192:195], v130 offset:32768
	ds_read_b128 v[196:199], v130 offset:33792
	buffer_load_dwordx4 v141, s[8:11], s4 offen lds
	s_mov_b32 m0, s48
	s_nop 0
	buffer_load_dwordx4 v142, s[8:11], s4 offen lds
	s_waitcnt lgkmcnt(8)
	s_barrier
	s_waitcnt lgkmcnt(0)
	v_mfma_f32_16x16x32_bf16 v[124:127], v[152:155], v[168:171], v[124:127]
	v_mfma_f32_16x16x32_bf16 v[124:127], v[156:159], v[172:175], v[124:127]
	v_mfma_f32_16x16x32_bf16 v[120:123], v[160:163], v[168:171], v[120:123]
	v_mfma_f32_16x16x32_bf16 v[120:123], v[164:167], v[172:175], v[120:123]
	v_mfma_f32_16x16x32_bf16 v[116:119], v[152:155], v[176:179], v[116:119]
	v_mfma_f32_16x16x32_bf16 v[116:119], v[156:159], v[180:183], v[116:119]
	v_mfma_f32_16x16x32_bf16 v[112:115], v[160:163], v[176:179], v[112:115]
	v_mfma_f32_16x16x32_bf16 v[112:115], v[164:167], v[180:183], v[112:115]
	v_mfma_f32_16x16x32_bf16 v[108:111], v[152:155], v[184:187], v[108:111]
	v_mfma_f32_16x16x32_bf16 v[108:111], v[156:159], v[188:191], v[108:111]
	v_mfma_f32_16x16x32_bf16 v[104:107], v[160:163], v[184:187], v[104:107]
	v_mfma_f32_16x16x32_bf16 v[104:107], v[164:167], v[188:191], v[104:107]
	v_mfma_f32_16x16x32_bf16 v[100:103], v[152:155], v[192:195], v[100:103]
	v_mfma_f32_16x16x32_bf16 v[100:103], v[156:159], v[196:199], v[100:103]
	v_mfma_f32_16x16x32_bf16 v[96:99], v[160:163], v[192:195], v[96:99]
	v_mfma_f32_16x16x32_bf16 v[96:99], v[164:167], v[196:199], v[96:99]
	s_barrier
	s_addk_i32 s5, 0x180
	s_mov_b32 m0, s37
	ds_read_b128 v[200:203], v133
	ds_read_b128 v[204:207], v134
	ds_read_b128 v[208:211], v135
	ds_read_b128 v[212:215], v136
	buffer_load_dwordx4 v141, s[12:15], s5 offen lds
	s_mov_b32 m0, s49
	s_nop 0
	buffer_load_dwordx4 v142, s[12:15], s5 offen lds
	s_barrier
	s_waitcnt lgkmcnt(0)
	v_mfma_f32_16x16x32_bf16 v[92:95], v[200:203], v[168:171], v[92:95]
	v_mfma_f32_16x16x32_bf16 v[92:95], v[204:207], v[172:175], v[92:95]
	v_mfma_f32_16x16x32_bf16 v[88:91], v[208:211], v[168:171], v[88:91]
	v_mfma_f32_16x16x32_bf16 v[88:91], v[212:215], v[172:175], v[88:91]
	v_mfma_f32_16x16x32_bf16 v[80:83], v[200:203], v[176:179], v[80:83]
	v_mfma_f32_16x16x32_bf16 v[80:83], v[204:207], v[180:183], v[80:83]
	v_mfma_f32_16x16x32_bf16 v[68:71], v[208:211], v[176:179], v[68:71]
	v_mfma_f32_16x16x32_bf16 v[68:71], v[212:215], v[180:183], v[68:71]
	v_mfma_f32_16x16x32_bf16 v[60:63], v[200:203], v[184:187], v[60:63]
	v_mfma_f32_16x16x32_bf16 v[60:63], v[204:207], v[188:191], v[60:63]
	v_mfma_f32_16x16x32_bf16 v[56:59], v[208:211], v[184:187], v[56:59]
	v_mfma_f32_16x16x32_bf16 v[56:59], v[212:215], v[188:191], v[56:59]
	v_mfma_f32_16x16x32_bf16 v[52:55], v[200:203], v[192:195], v[52:55]
	v_mfma_f32_16x16x32_bf16 v[52:55], v[204:207], v[196:199], v[52:55]
	v_mfma_f32_16x16x32_bf16 v[48:51], v[208:211], v[192:195], v[48:51]
	v_mfma_f32_16x16x32_bf16 v[48:51], v[212:215], v[196:199], v[48:51]
	s_barrier
	s_addk_i32 s6, 0x180
	s_mov_b32 m0, s38
	ds_read_b128 v[168:171], v129 offset:49152
	ds_read_b128 v[172:175], v129 offset:50176
	ds_read_b128 v[176:179], v132 offset:49152
	ds_read_b128 v[180:183], v132 offset:50176
	ds_read_b128 v[184:187], v131 offset:49152
	ds_read_b128 v[188:191], v131 offset:50176
	ds_read_b128 v[192:195], v130 offset:49152
	ds_read_b128 v[196:199], v130 offset:50176
	buffer_load_dwordx4 v141, s[8:11], s6 offen lds
	s_mov_b32 m0, s54
	s_nop 0
	buffer_load_dwordx4 v142, s[8:11], s6 offen lds
	s_barrier
; #define STAGE(P, RS, SOFF, OFF, kt) do { const int _so = (SOFF) + (kt) * (BK * 2); \
;     _Pragma("unroll") for (int _i = 0; _i < 2; ++_i) { \
;       __builtin_amdgcn_raw_ptr_buffer_load_lds(RS, (__attribute__((address_space(3))) void*)((P) + wave * 1024 + _i * 8192), 16, OFF[_i], _so, 0, 0); } } while (0)
; #define LDA(dst, b, h) _Pragma("unroll") for (int m = 0; m < 4; ++m) _Pragma("unroll") for (int k = 0; k < 2; ++k) \
;     dst[m][k] = *reinterpret_cast<const bf16x8*>(SA(b, h) + lds_byte(wr * 64 + m * 16 + fr, k * 32 + fq * 8))
; #define LDB(dst, b, h) _Pragma("unroll") for (int n = 0; n < 2; ++n) _Pragma("unroll") for (int k = 0; k < 2; ++k) \
;     dst[n][k] = *reinterpret_cast<const bf16x8*>(SB(b, h) + lds_byte(wc * 32 + n * 16 + fr, k * 32 + fq * 8))
; #define WAIT_V(n) asm volatile("s_waitcnt vmcnt(" #n ")" ::: "memory")
; #define WAIT_L(n) asm volatile("s_waitcnt lgkmcnt(" #n ")" ::: "memory")
; #define BAR __builtin_amdgcn_s_barrier()
; #define SCHED __builtin_amdgcn_sched_barrier(0)
;     ...
;       LDA(At, 1, 1); STAGE(SA(1, 0), rsA, sA0, offA, t + 3);
;       BAR; WAIT_L(0); MMA(1, 0, At, B0); BAR; SCHED;
;       STAGE(SB(1, 1), rsB, sB1, offB, t + 3);
;       WAIT_V(6); BAR; MMA(1, 1, At, B1); BAR;
;     }
;     { LDB(B0, 0, 0); LDA(At, 0, 0); STAGE(SA(1, 1), rsA, sA1, offA, nt - 1);
;       BAR; WAIT_L(0); MMA(0, 0, At, B0); BAR;
;       LDB(B1, 0, 1); BAR; WAIT_L(0); MMA(0, 1, At, B1); BAR;
	s_waitcnt lgkmcnt(0)
	v_mfma_f32_16x16x32_bf16 v[44:47], v[152:155], v[168:171], v[44:47]
	v_mfma_f32_16x16x32_bf16 v[44:47], v[156:159], v[172:175], v[44:47]
	v_mfma_f32_16x16x32_bf16 v[40:43], v[160:163], v[168:171], v[40:43]
	v_mfma_f32_16x16x32_bf16 v[40:43], v[164:167], v[172:175], v[40:43]
	v_mfma_f32_16x16x32_bf16 v[36:39], v[152:155], v[176:179], v[36:39]
	v_mfma_f32_16x16x32_bf16 v[36:39], v[156:159], v[180:183], v[36:39]
	v_mfma_f32_16x16x32_bf16 v[32:35], v[160:163], v[176:179], v[32:35]
	v_mfma_f32_16x16x32_bf16 v[32:35], v[164:167], v[180:183], v[32:35]
	v_mfma_f32_16x16x32_bf16 v[28:31], v[152:155], v[184:187], v[28:31]
	v_mfma_f32_16x16x32_bf16 v[28:31], v[156:159], v[188:191], v[28:31]
	v_mfma_f32_16x16x32_bf16 v[24:27], v[160:163], v[184:187], v[24:27]
	v_mfma_f32_16x16x32_bf16 v[24:27], v[164:167], v[188:191], v[24:27]
	v_mfma_f32_16x16x32_bf16 v[20:23], v[152:155], v[192:195], v[20:23]
	v_mfma_f32_16x16x32_bf16 v[20:23], v[156:159], v[196:199], v[20:23]
	v_mfma_f32_16x16x32_bf16 v[16:19], v[160:163], v[192:195], v[16:19]
	v_mfma_f32_16x16x32_bf16 v[16:19], v[164:167], v[196:199], v[16:19]
	s_barrier
	s_addk_i32 s7, 0x180
	s_mov_b32 m0, s39
	s_nop 0
	buffer_load_dwordx4 v141, s[12:15], s7 offen lds
	s_mov_b32 m0, s55
	s_nop 0
	buffer_load_dwordx4 v142, s[12:15], s7 offen lds
	s_add_i32 s1, s1, 2
	s_addk_i32 s3, 0x100
	s_cmp_gt_u32 s1, 59
	s_cbranch_scc0 .LBB0_148
	s_waitcnt vmcnt(6)
	s_barrier
	v_mfma_f32_16x16x32_bf16 v[12:15], v[200:203], v[168:171], v[12:15]
	v_mfma_f32_16x16x32_bf16 v[12:15], v[204:207], v[172:175], v[12:15]
	v_mfma_f32_16x16x32_bf16 v[8:11], v[208:211], v[168:171], v[8:11]
	v_mfma_f32_16x16x32_bf16 v[8:11], v[212:215], v[172:175], v[8:11]
	v_mfma_f32_16x16x32_bf16 v[4:7], v[200:203], v[176:179], v[4:7]
	v_mfma_f32_16x16x32_bf16 v[4:7], v[204:207], v[180:183], v[4:7]
	v_mfma_f32_16x16x32_bf16 v[0:3], v[208:211], v[176:179], v[0:3]
	v_mfma_f32_16x16x32_bf16 v[0:3], v[212:215], v[180:183], v[0:3]
	v_mfma_f32_16x16x32_bf16 v[64:67], v[200:203], v[184:187], v[64:67]
	v_mfma_f32_16x16x32_bf16 v[64:67], v[204:207], v[188:191], v[64:67]
	v_mfma_f32_16x16x32_bf16 v[72:75], v[208:211], v[184:187], v[72:75]
	v_mfma_f32_16x16x32_bf16 v[72:75], v[212:215], v[188:191], v[72:75]
	v_mfma_f32_16x16x32_bf16 v[76:79], v[200:203], v[192:195], v[76:79]
	v_mfma_f32_16x16x32_bf16 v[76:79], v[204:207], v[196:199], v[76:79]
	v_mfma_f32_16x16x32_bf16 v[84:87], v[208:211], v[192:195], v[84:87]
	v_mfma_f32_16x16x32_bf16 v[84:87], v[212:215], v[196:199], v[84:87]
	s_barrier
	s_add_i32 s1, s82, 0x1f80
	s_mov_b32 m0, s31
	ds_read_b128 v[152:155], v147
	ds_read_b128 v[156:159], v148
	ds_read_b128 v[160:163], v149
	ds_read_b128 v[148:151], v150
	ds_read_b128 v[164:167], v129
	ds_read_b128 v[168:171], v129 offset:1024
	ds_read_b128 v[172:175], v132
	ds_read_b128 v[176:179], v132 offset:1024
	ds_read_b128 v[180:183], v131
	ds_read_b128 v[184:187], v131 offset:1024
	ds_read_b128 v[188:191], v130
	ds_read_b128 v[192:195], v130 offset:1024
	buffer_load_dwordx4 v141, s[8:11], s1 offen lds
	s_mov_b32 m0, s58
	s_nop 0
	buffer_load_dwordx4 v142, s[8:11], s1 offen lds
	s_barrier
	s_waitcnt lgkmcnt(0)
	v_mfma_f32_16x16x32_bf16 v[124:127], v[152:155], v[164:167], v[124:127]
	v_mfma_f32_16x16x32_bf16 v[124:127], v[156:159], v[168:171], v[124:127]
	v_mfma_f32_16x16x32_bf16 v[120:123], v[160:163], v[164:167], v[120:123]
	v_mfma_f32_16x16x32_bf16 v[120:123], v[148:151], v[168:171], v[120:123]
	v_mfma_f32_16x16x32_bf16 v[116:119], v[152:155], v[172:175], v[116:119]
	v_mfma_f32_16x16x32_bf16 v[116:119], v[156:159], v[176:179], v[116:119]
	v_mfma_f32_16x16x32_bf16 v[112:115], v[160:163], v[172:175], v[112:115]
	v_mfma_f32_16x16x32_bf16 v[112:115], v[148:151], v[176:179], v[112:115]
	v_mfma_f32_16x16x32_bf16 v[108:111], v[152:155], v[180:183], v[108:111]
	v_mfma_f32_16x16x32_bf16 v[108:111], v[156:159], v[184:187], v[108:111]
	v_mfma_f32_16x16x32_bf16 v[104:107], v[160:163], v[180:183], v[104:107]
	v_mfma_f32_16x16x32_bf16 v[104:107], v[148:151], v[184:187], v[104:107]
	v_mfma_f32_16x16x32_bf16 v[100:103], v[152:155], v[188:191], v[100:103]
	v_mfma_f32_16x16x32_bf16 v[100:103], v[156:159], v[192:195], v[100:103]
	v_mfma_f32_16x16x32_bf16 v[96:99], v[160:163], v[188:191], v[96:99]
	v_mfma_f32_16x16x32_bf16 v[96:99], v[148:151], v[192:195], v[96:99]
	s_barrier
	ds_read_b128 v[196:199], v143
	ds_read_b128 v[200:203], v144
	ds_read_b128 v[142:145], v145
	ds_read_b128 v[204:207], v146
	s_barrier
	s_waitcnt lgkmcnt(0)
	v_mfma_f32_16x16x32_bf16 v[88:91], v[142:145], v[164:167], v[88:91]
	v_mfma_f32_16x16x32_bf16 v[80:83], v[196:199], v[172:175], v[80:83]
	v_mfma_f32_16x16x32_bf16 v[60:63], v[196:199], v[180:183], v[60:63]
	v_mfma_f32_16x16x32_bf16 v[56:59], v[142:145], v[180:183], v[56:59]
	v_mfma_f32_16x16x32_bf16 v[52:55], v[196:199], v[188:191], v[52:55]
	v_mfma_f32_16x16x32_bf16 v[48:51], v[142:145], v[188:191], v[48:51]
	v_mfma_f32_16x16x32_bf16 v[92:95], v[196:199], v[164:167], v[92:95]
	v_mfma_f32_16x16x32_bf16 v[68:71], v[142:145], v[172:175], v[68:71]
	v_mfma_f32_16x16x32_bf16 v[88:91], v[204:207], v[168:171], v[88:91]
	v_mfma_f32_16x16x32_bf16 v[80:83], v[200:203], v[176:179], v[80:83]
	v_mfma_f32_16x16x32_bf16 v[60:63], v[200:203], v[184:187], v[60:63]
	v_mfma_f32_16x16x32_bf16 v[56:59], v[204:207], v[184:187], v[56:59]
	v_mfma_f32_16x16x32_bf16 v[52:55], v[200:203], v[192:195], v[52:55]
	v_mfma_f32_16x16x32_bf16 v[48:51], v[204:207], v[192:195], v[48:51]
	v_mfma_f32_16x16x32_bf16 v[164:167], v[200:203], v[168:171], v[92:95]
	v_mfma_f32_16x16x32_bf16 v[168:171], v[204:207], v[176:179], v[68:71]
	s_barrier
; #define LDA(dst, b, h) _Pragma("unroll") for (int m = 0; m < 4; ++m) _Pragma("unroll") for (int k = 0; k < 2; ++k) \
;     dst[m][k] = *reinterpret_cast<const bf16x8*>(SA(b, h) + lds_byte(wr * 64 + m * 16 + fr, k * 32 + fq * 8))
; #define LDB(dst, b, h) _Pragma("unroll") for (int n = 0; n < 2; ++n) _Pragma("unroll") for (int k = 0; k < 2; ++k) \
;     dst[n][k] = *reinterpret_cast<const bf16x8*>(SB(b, h) + lds_byte(wc * 32 + n * 16 + fr, k * 32 + fq * 8))
; #define WAIT_V(n) asm volatile("s_waitcnt vmcnt(" #n ")" ::: "memory")
; #define WAIT_L(n) asm volatile("s_waitcnt lgkmcnt(" #n ")" ::: "memory")
; #define BAR __builtin_amdgcn_s_barrier()
;     ...
;       LDA(At, 0, 1); WAIT_V(4); BAR; WAIT_L(0); MMA(1, 0, At, B0); MMA(1, 1, At, B1); BAR; }
;     { LDB(B0, 1, 0); LDA(At, 1, 0); WAIT_V(2); BAR; WAIT_L(0); MMA(0, 0, At, B0); BAR;
	s_nop 0
	ds_read_b128 v[68:71], v129 offset:16384
	ds_read_b128 v[92:95], v129 offset:17408
	ds_read_b128 v[172:175], v132 offset:16384
	ds_read_b128 v[176:179], v132 offset:17408
	ds_read_b128 v[180:183], v131 offset:16384
	ds_read_b128 v[184:187], v131 offset:17408
	ds_read_b128 v[188:191], v130 offset:16384
	ds_read_b128 v[192:195], v130 offset:17408
	s_waitcnt vmcnt(4)
	s_barrier
	s_waitcnt lgkmcnt(0)
	v_mfma_f32_16x16x32_bf16 v[44:47], v[152:155], v[68:71], v[44:47]
	v_mfma_f32_16x16x32_bf16 v[40:43], v[160:163], v[68:71], v[40:43]
	v_mfma_f32_16x16x32_bf16 v[36:39], v[152:155], v[172:175], v[36:39]
	v_mfma_f32_16x16x32_bf16 v[32:35], v[160:163], v[172:175], v[32:35]
	v_mfma_f32_16x16x32_bf16 v[28:31], v[152:155], v[180:183], v[28:31]
	v_mfma_f32_16x16x32_bf16 v[24:27], v[160:163], v[180:183], v[24:27]
	v_mfma_f32_16x16x32_bf16 v[20:23], v[152:155], v[188:191], v[20:23]
	v_mfma_f32_16x16x32_bf16 v[16:19], v[160:163], v[188:191], v[16:19]
	v_mfma_f32_16x16x32_bf16 v[44:47], v[156:159], v[92:95], v[44:47]
	v_mfma_f32_16x16x32_bf16 v[40:43], v[148:151], v[92:95], v[40:43]
	v_mfma_f32_16x16x32_bf16 v[36:39], v[156:159], v[176:179], v[36:39]
	v_mfma_f32_16x16x32_bf16 v[32:35], v[148:151], v[176:179], v[32:35]
	v_mfma_f32_16x16x32_bf16 v[28:31], v[156:159], v[184:187], v[28:31]
	v_mfma_f32_16x16x32_bf16 v[24:27], v[148:151], v[184:187], v[24:27]
	v_mfma_f32_16x16x32_bf16 v[20:23], v[156:159], v[192:195], v[20:23]
	v_mfma_f32_16x16x32_bf16 v[16:19], v[148:151], v[192:195], v[16:19]
	v_mfma_f32_16x16x32_bf16 v[8:11], v[142:145], v[68:71], v[8:11]
	v_mfma_f32_16x16x32_bf16 v[0:3], v[142:145], v[172:175], v[0:3]
	v_mfma_f32_16x16x32_bf16 v[12:15], v[196:199], v[68:71], v[12:15]
	v_mfma_f32_16x16x32_bf16 v[4:7], v[196:199], v[172:175], v[4:7]
	v_mfma_f32_16x16x32_bf16 v[64:67], v[196:199], v[180:183], v[64:67]
	v_mfma_f32_16x16x32_bf16 v[68:71], v[142:145], v[180:183], v[72:75]
	v_mfma_f32_16x16x32_bf16 v[72:75], v[196:199], v[188:191], v[76:79]
	v_mfma_f32_16x16x32_bf16 v[76:79], v[142:145], v[188:191], v[84:87]
	v_mfma_f32_16x16x32_bf16 v[8:11], v[204:207], v[92:95], v[8:11]
	v_mfma_f32_16x16x32_bf16 v[0:3], v[204:207], v[176:179], v[0:3]
	v_mfma_f32_16x16x32_bf16 v[160:163], v[200:203], v[92:95], v[12:15]
	v_mfma_f32_16x16x32_bf16 v[172:175], v[200:203], v[176:179], v[4:7]
	v_mfma_f32_16x16x32_bf16 v[176:179], v[200:203], v[184:187], v[64:67]
	v_mfma_f32_16x16x32_bf16 v[180:183], v[204:207], v[184:187], v[68:71]
	v_mfma_f32_16x16x32_bf16 v[184:187], v[200:203], v[192:195], v[72:75]
	v_mfma_f32_16x16x32_bf16 v[188:191], v[204:207], v[192:195], v[76:79]
	s_barrier
	ds_read_b128 v[4:7], v137
	ds_read_b128 v[12:15], v138
	ds_read_b128 v[192:195], v139
	ds_read_b128 v[138:141], v140
	ds_read_b128 v[72:75], v129 offset:32768
	ds_read_b128 v[142:145], v129 offset:33792
	ds_read_b128 v[76:79], v132 offset:32768
	ds_read_b128 v[196:199], v132 offset:33792
	ds_read_b128 v[152:155], v131 offset:32768
	ds_read_b128 v[200:203], v131 offset:33792
	ds_read_b128 v[204:207], v130 offset:32768
	ds_read_b128 v[208:211], v130 offset:33792
	s_waitcnt vmcnt(2)
	s_barrier
	s_waitcnt lgkmcnt(0)
	v_mfma_f32_16x16x32_bf16 v[64:67], v[4:7], v[72:75], v[124:127]
	v_mfma_f32_16x16x32_bf16 v[84:87], v[192:195], v[72:75], v[120:123]
	v_mfma_f32_16x16x32_bf16 v[92:95], v[4:7], v[76:79], v[116:119]
	v_mfma_f32_16x16x32_bf16 v[112:115], v[192:195], v[76:79], v[112:115]
	v_mfma_f32_16x16x32_bf16 v[108:111], v[4:7], v[152:155], v[108:111]
	v_mfma_f32_16x16x32_bf16 v[104:107], v[192:195], v[152:155], v[104:107]
	v_mfma_f32_16x16x32_bf16 v[100:103], v[4:7], v[204:207], v[100:103]
	v_mfma_f32_16x16x32_bf16 v[96:99], v[192:195], v[204:207], v[96:99]
	v_mfma_f32_16x16x32_bf16 v[68:71], v[12:15], v[142:145], v[64:67]
	v_mfma_f32_16x16x32_bf16 v[64:67], v[138:141], v[142:145], v[84:87]
	v_mfma_f32_16x16x32_bf16 v[156:159], v[12:15], v[196:199], v[92:95]
	v_mfma_f32_16x16x32_bf16 v[148:151], v[138:141], v[196:199], v[112:115]
	v_mfma_f32_16x16x32_bf16 v[124:127], v[12:15], v[200:203], v[108:111]
	v_mfma_f32_16x16x32_bf16 v[116:119], v[138:141], v[200:203], v[104:107]
	v_mfma_f32_16x16x32_bf16 v[92:95], v[12:15], v[208:211], v[100:103]
	v_mfma_f32_16x16x32_bf16 v[84:87], v[138:141], v[208:211], v[96:99]
	s_barrier
; #define LDA(dst, b, h) _Pragma("unroll") for (int m = 0; m < 4; ++m) _Pragma("unroll") for (int k = 0; k < 2; ++k) \
;     dst[m][k] = *reinterpret_cast<const bf16x8*>(SA(b, h) + lds_byte(wr * 64 + m * 16 + fr, k * 32 + fq * 8))
; #define LDB(dst, b, h) _Pragma("unroll") for (int n = 0; n < 2; ++n) _Pragma("unroll") for (int k = 0; k < 2; ++k) \
;     dst[n][k] = *reinterpret_cast<const bf16x8*>(SB(b, h) + lds_byte(wc * 32 + n * 16 + fr, k * 32 + fq * 8))
; #define WAIT_V(n) asm volatile("s_waitcnt vmcnt(" #n ")" ::: "memory")
; #define WAIT_L(n) asm volatile("s_waitcnt lgkmcnt(" #n ")" ::: "memory")
; #define BAR __builtin_amdgcn_s_barrier()
;     ...
;       LDB(B1, 1, 1); WAIT_V(0); BAR; WAIT_L(0); MMA(0, 1, At, B1); BAR;
;       LDA(At, 1, 1); BAR; WAIT_L(0); MMA(1, 0, At, B0); MMA(1, 1, At, B1); BAR; }
;     if (wr == 0) BAR;
	s_nop 0
	ds_read_b128 v[96:99], v133
	ds_read_b128 v[100:103], v134
	ds_read_b128 v[104:107], v135
	ds_read_b128 v[108:111], v136
	s_waitcnt vmcnt(0)
	s_barrier
	s_waitcnt lgkmcnt(0)
	v_mfma_f32_16x16x32_bf16 v[112:115], v[96:99], v[72:75], v[164:167]
	v_mfma_f32_16x16x32_bf16 v[72:75], v[104:107], v[72:75], v[88:91]
	v_mfma_f32_16x16x32_bf16 v[80:83], v[96:99], v[76:79], v[80:83]
	v_mfma_f32_16x16x32_bf16 v[88:91], v[104:107], v[76:79], v[168:171]
	v_mfma_f32_16x16x32_bf16 v[60:63], v[96:99], v[152:155], v[60:63]
	v_mfma_f32_16x16x32_bf16 v[56:59], v[104:107], v[152:155], v[56:59]
	v_mfma_f32_16x16x32_bf16 v[52:55], v[96:99], v[204:207], v[52:55]
	v_mfma_f32_16x16x32_bf16 v[48:51], v[104:107], v[204:207], v[48:51]
	v_mfma_f32_16x16x32_bf16 v[76:79], v[100:103], v[142:145], v[112:115]
	v_mfma_f32_16x16x32_bf16 v[72:75], v[108:111], v[142:145], v[72:75]
	v_mfma_f32_16x16x32_bf16 v[152:155], v[100:103], v[196:199], v[80:83]
	v_mfma_f32_16x16x32_bf16 v[144:147], v[108:111], v[196:199], v[88:91]
	v_mfma_f32_16x16x32_bf16 v[120:123], v[100:103], v[200:203], v[60:63]
	v_mfma_f32_16x16x32_bf16 v[112:115], v[108:111], v[200:203], v[56:59]
	v_mfma_f32_16x16x32_bf16 v[88:91], v[100:103], v[208:211], v[52:55]
	v_mfma_f32_16x16x32_bf16 v[80:83], v[108:111], v[208:211], v[48:51]
	s_barrier
	s_nop 0
	ds_read_b128 v[48:51], v129 offset:49152
	ds_read_b128 v[134:137], v129 offset:50176
	ds_read_b128 v[56:59], v132 offset:49152
	ds_read_b128 v[164:167], v132 offset:50176
	ds_read_b128 v[168:171], v131 offset:49152
	ds_read_b128 v[196:199], v131 offset:50176
	ds_read_b128 v[200:203], v130 offset:49152
	ds_read_b128 v[130:133], v130 offset:50176
	s_barrier
	s_waitcnt lgkmcnt(0)
	v_mfma_f32_16x16x32_bf16 v[44:47], v[4:7], v[48:51], v[44:47]
	v_mfma_f32_16x16x32_bf16 v[40:43], v[192:195], v[48:51], v[40:43]
	v_mfma_f32_16x16x32_bf16 v[36:39], v[4:7], v[56:59], v[36:39]
	v_mfma_f32_16x16x32_bf16 v[32:35], v[192:195], v[56:59], v[32:35]
	v_mfma_f32_16x16x32_bf16 v[28:31], v[4:7], v[168:171], v[28:31]
	v_mfma_f32_16x16x32_bf16 v[24:27], v[192:195], v[168:171], v[24:27]
	v_mfma_f32_16x16x32_bf16 v[4:7], v[4:7], v[200:203], v[20:23]
	v_mfma_f32_16x16x32_bf16 v[16:19], v[192:195], v[200:203], v[16:19]
	v_mfma_f32_16x16x32_bf16 v[60:63], v[12:15], v[134:137], v[44:47]
	v_mfma_f32_16x16x32_bf16 v[52:55], v[138:141], v[134:137], v[40:43]
	v_mfma_f32_16x16x32_bf16 v[44:47], v[12:15], v[164:167], v[36:39]
	v_mfma_f32_16x16x32_bf16 v[36:39], v[138:141], v[164:167], v[32:35]
	v_mfma_f32_16x16x32_bf16 v[28:31], v[12:15], v[196:199], v[28:31]
	v_mfma_f32_16x16x32_bf16 v[20:23], v[138:141], v[196:199], v[24:27]
	v_mfma_f32_16x16x32_bf16 v[12:15], v[12:15], v[130:133], v[4:7]
	v_mfma_f32_16x16x32_bf16 v[4:7], v[138:141], v[130:133], v[16:19]
	v_mfma_f32_16x16x32_bf16 v[16:19], v[96:99], v[48:51], v[160:163]
	v_mfma_f32_16x16x32_bf16 v[8:11], v[104:107], v[48:51], v[8:11]
	v_mfma_f32_16x16x32_bf16 v[24:27], v[96:99], v[56:59], v[172:175]
	v_mfma_f32_16x16x32_bf16 v[0:3], v[104:107], v[56:59], v[0:3]
	v_mfma_f32_16x16x32_bf16 v[138:141], v[96:99], v[168:171], v[176:179]
	v_mfma_f32_16x16x32_bf16 v[160:163], v[104:107], v[168:171], v[180:183]
	v_mfma_f32_16x16x32_bf16 v[96:99], v[96:99], v[200:203], v[184:187]
	v_mfma_f32_16x16x32_bf16 v[104:107], v[104:107], v[200:203], v[188:191]
	v_mfma_f32_16x16x32_bf16 v[56:59], v[100:103], v[134:137], v[16:19]
	v_mfma_f32_16x16x32_bf16 v[48:51], v[108:111], v[134:137], v[8:11]
	v_mfma_f32_16x16x32_bf16 v[40:43], v[100:103], v[164:167], v[24:27]
	v_mfma_f32_16x16x32_bf16 v[32:35], v[108:111], v[164:167], v[0:3]
	v_mfma_f32_16x16x32_bf16 v[24:27], v[100:103], v[196:199], v[138:141]
	v_mfma_f32_16x16x32_bf16 v[16:19], v[108:111], v[196:199], v[160:163]
	v_mfma_f32_16x16x32_bf16 v[8:11], v[100:103], v[130:133], v[96:99]
	v_mfma_f32_16x16x32_bf16 v[0:3], v[108:111], v[130:133], v[104:107]
	v_cmp_gt_u32_e32 vcc, s60, v128
	s_barrier
	s_and_saveexec_b64 s[4:5], vcc
	s_cbranch_execz .LBB0_151
	s_barrier

; #define WAIT_V(n) asm volatile("s_waitcnt vmcnt(" #n ")" ::: "memory")
; #define BAR __builtin_amdgcn_s_barrier()
;     ...
;     const int tid = opaque_tid(wave);
;     const int wid = tid >> 6, lane = tid & 63, wr = wid >> 2, wc = wid & 3, fr = lane & 15, fq = lane >> 4;
;     int offA[2], offB[2];
;     _Pragma("unroll") for (int i = 0; i < 2; ++i) {
;       int r, c; stage_rc(tid * 16 + i * 8192, r, c);
;       offA[i] = (r * lda + c) * 2; offB[i] = (r * ldb + c) * 2;
;     }
;     const int brow = pm * BM;
;     f32x4 acc[2][2][4][2];
;     _Pragma("unroll") for (int a = 0; a < 2; ++a) _Pragma("unroll") for (int b = 0; b < 2; ++b) _Pragma("unroll") for (int m = 0; m < 4; ++m) _Pragma("unroll") for (int n = 0; n < 2; ++n)
;       acc[a][b][m][n] = f32x4{0.f, 0.f, 0.f, 0.f};
;     bf16x8 At[4][2], B0[2][2], B1[2][2];
;     if (wr == 1) BAR;
;     if (first_tile) { WAIT_V(0); }
;     else if constexpr (mode == MODE_RESID_LN) { WAIT_V(0); }
;     else if constexpr (mode == MODE_SWIGLU) { WAIT_V(6); }
;     else if constexpr (mode == MODE_V) { WAIT_V(24); }
;     else { WAIT_V(12); }
;     first_tile = false;
;     BAR;
;     BAR;
.LBB0_209:
	v_bfe_i32 v4, v130, 27, 1
	v_lshlrev_b32_e32 v2, 4, v130
	v_lshrrev_b32_e32 v4, 22, v4
	v_add_u32_e32 v4, v2, v4
	v_and_b32_e32 v4, 0xfffffc00, v4
	v_sub_u32_e32 v4, v2, v4
	v_lshrrev_b32_e32 v5, 4, v4
	v_bitop3_b32 v4, v5, v4, 32 bitop3:0x6c
	v_ashrrev_i32_e32 v3, 31, v130
	v_ashrrev_i32_e32 v6, 31, v4
	v_lshrrev_b32_e32 v3, 26, v3
	v_lshrrev_b32_e32 v6, 26, v6
	v_add_u32_e32 v3, v130, v3
	v_add_u32_e32 v6, v4, v6
	v_ashrrev_i32_e32 v3, 6, v3
	v_lshrrev_b32_e32 v7, 6, v6
	v_and_b32_e32 v6, 0xc0, v6
	v_lshlrev_b32_e32 v5, 3, v3
	v_lshlrev_b32_e32 v3, 5, v3
	v_sub_u32_e32 v4, v4, v6
	v_and_b32_e32 v5, 0xffff0, v5
	v_and_b32_e32 v3, 32, v3
	v_ashrrev_i16_sdwa v4, v128, sext(v4) dst_sel:DWORD dst_unused:UNUSED_PAD src0_sel:DWORD src1_sel:BYTE_0
	v_add_u32_sdwa v3, v3, sext(v4) dst_sel:DWORD dst_unused:UNUSED_PAD src0_sel:DWORD src1_sel:WORD_0
	v_add_lshl_u32 v4, v7, v5, 12
	v_add_u32_e32 v2, 0x2000, v2
	v_lshl_add_u32 v143, v3, 1, v4
	v_ashrrev_i32_e32 v3, 31, v2
	v_lshrrev_b32_e32 v3, 22, v3
	v_add_u32_e32 v3, v2, v3
	v_ashrrev_i32_e32 v3, 10, v3
	v_mul_i32_i24_e32 v4, 0x400, v3
	v_sub_u32_e32 v2, v2, v4
	v_lshrrev_b32_e32 v4, 4, v2
	v_bitop3_b32 v2, v4, v2, 32 bitop3:0x6c
	v_ashrrev_i32_e32 v5, 31, v2
	v_lshrrev_b32_e32 v5, 26, v5
	v_add_u32_e32 v5, v2, v5
	v_lshrrev_b32_e32 v6, 6, v5
	v_and_b32_e32 v5, 0xc0, v5
	v_lshlrev_b32_e32 v4, 3, v3
	v_lshlrev_b32_e32 v3, 5, v3
	v_sub_u32_e32 v2, v2, v5
	v_and_b32_e32 v4, 0xffff0, v4
	v_and_b32_e32 v3, 32, v3
	v_ashrrev_i16_sdwa v2, v128, sext(v2) dst_sel:DWORD dst_unused:UNUSED_PAD src0_sel:DWORD src1_sel:BYTE_0
	v_add_u32_sdwa v2, v3, sext(v2) dst_sel:DWORD dst_unused:UNUSED_PAD src0_sel:DWORD src1_sel:WORD_0
	v_add_lshl_u32 v3, v6, v4, 12
	v_lshl_add_u32 v144, v2, 1, v3
	v_and_b32_e32 v3, 15, v0
	v_lshlrev_b32_e32 v5, 2, v0
	v_and_b32_e32 v2, 48, v0
	v_lshlrev_b32_e32 v3, 6, v3
	v_and_b32_e32 v5, 32, v5
	v_lshlrev_b32_e32 v0, 6, v0
	v_or_b32_e32 v4, v3, v2
	v_bitop3_b32 v3, v3, v5, v2 bitop3:0x36
	v_lshlrev_b32_e32 v6, 6, v130
	v_lshlrev_b32_e32 v1, 13, v1
	v_and_or_b32 v0, v0, s34, v2
	v_and_or_b32 v3, v6, s33, v3
	v_bitop3_b32 v0, v1, v0, v5 bitop3:0xf6
	v_or_b32_e32 v6, 0x400, v3
	v_or_b32_e32 v7, 0x800, v3
	v_or_b32_e32 v8, 0xc00, v3
	v_or_b32_e32 v134, 0x800, v0
	v_or_b32_e32 v133, 0x1000, v0
	v_or_b32_e32 v132, 0x1800, v0
	v_mov_b32_e32 v0, 0
	v_bitop3_b32 v131, v4, v1, v5 bitop3:0xde
	s_mov_b32 s16, -2
	s_mov_b32 s17, 0
	v_or_b32_e32 v149, 0x10000, v3
	v_or_b32_e32 v150, 0x10000, v6
	v_or_b32_e32 v151, 0x10000, v7
	v_or_b32_e32 v152, 0x10000, v8
	v_or_b32_e32 v145, 0x14000, v3
	v_or_b32_e32 v146, 0x14000, v6
	v_or_b32_e32 v147, 0x14000, v7
	v_or_b32_e32 v148, 0x14000, v8
	v_or_b32_e32 v139, 0x18000, v3
	v_or_b32_e32 v140, 0x18000, v6
	v_or_b32_e32 v141, 0x18000, v7
	v_or_b32_e32 v142, 0x18000, v8
	v_or_b32_e32 v135, 0x1c000, v3
	v_or_b32_e32 v136, 0x1c000, v6
	v_or_b32_e32 v137, 0x1c000, v7
	v_or_b32_e32 v138, 0x1c000, v8
	v_mov_b32_e32 v1, v0
	v_mov_b32_e32 v2, v0
	v_mov_b32_e32 v3, v0
	v_mov_b32_e32 v4, v0
	v_mov_b32_e32 v5, v0
	v_mov_b32_e32 v6, v0
	v_mov_b32_e32 v7, v0
	v_mov_b32_e32 v8, v0
	v_mov_b32_e32 v9, v0
	v_mov_b32_e32 v10, v0
	v_mov_b32_e32 v11, v0
	v_mov_b32_e32 v12, v0
	v_mov_b32_e32 v13, v0
	v_mov_b32_e32 v14, v0
	v_mov_b32_e32 v15, v0
	v_mov_b32_e32 v16, v0
	v_mov_b32_e32 v17, v0
	v_mov_b32_e32 v18, v0
	v_mov_b32_e32 v19, v0
	v_mov_b32_e32 v20, v0
	v_mov_b32_e32 v21, v0
	v_mov_b32_e32 v22, v0
	v_mov_b32_e32 v23, v0
	v_mov_b32_e32 v24, v0
	v_mov_b32_e32 v25, v0
	v_mov_b32_e32 v26, v0
	v_mov_b32_e32 v27, v0
	v_mov_b32_e32 v28, v0
	v_mov_b32_e32 v29, v0
	v_mov_b32_e32 v30, v0
	v_mov_b32_e32 v31, v0
	v_mov_b32_e32 v32, v0
	v_mov_b32_e32 v33, v0
	v_mov_b32_e32 v34, v0
	v_mov_b32_e32 v35, v0
	v_mov_b32_e32 v36, v0
	v_mov_b32_e32 v37, v0
	v_mov_b32_e32 v38, v0
	v_mov_b32_e32 v39, v0
	v_mov_b32_e32 v40, v0
	v_mov_b32_e32 v41, v0
	v_mov_b32_e32 v42, v0
	v_mov_b32_e32 v43, v0
	v_mov_b32_e32 v44, v0
	v_mov_b32_e32 v45, v0
	v_mov_b32_e32 v46, v0
	v_mov_b32_e32 v47, v0
	v_mov_b32_e32 v48, v0
	v_mov_b32_e32 v49, v0
	v_mov_b32_e32 v50, v0
	v_mov_b32_e32 v51, v0
	v_mov_b32_e32 v52, v0
	v_mov_b32_e32 v53, v0
	v_mov_b32_e32 v54, v0
	v_mov_b32_e32 v55, v0
	v_mov_b32_e32 v56, v0
	v_mov_b32_e32 v57, v0
	v_mov_b32_e32 v58, v0
	v_mov_b32_e32 v59, v0
	v_mov_b32_e32 v60, v0
	v_mov_b32_e32 v61, v0
	v_mov_b32_e32 v62, v0
	v_mov_b32_e32 v63, v0
	v_mov_b32_e32 v64, v0
	v_mov_b32_e32 v65, v0
	v_mov_b32_e32 v66, v0
	v_mov_b32_e32 v67, v0
	v_mov_b32_e32 v68, v0
	v_mov_b32_e32 v69, v0
	v_mov_b32_e32 v70, v0
	v_mov_b32_e32 v71, v0
	v_mov_b32_e32 v72, v0
	v_mov_b32_e32 v73, v0
	v_mov_b32_e32 v74, v0
	v_mov_b32_e32 v75, v0
	v_mov_b32_e32 v76, v0
	v_mov_b32_e32 v77, v0
	v_mov_b32_e32 v78, v0
	v_mov_b32_e32 v79, v0
	v_mov_b32_e32 v80, v0
	v_mov_b32_e32 v81, v0
	v_mov_b32_e32 v82, v0
	v_mov_b32_e32 v83, v0
	v_mov_b32_e32 v84, v0
	v_mov_b32_e32 v85, v0
	v_mov_b32_e32 v86, v0
	v_mov_b32_e32 v87, v0
	v_mov_b32_e32 v88, v0
	v_mov_b32_e32 v89, v0
	v_mov_b32_e32 v90, v0
	v_mov_b32_e32 v91, v0
	v_mov_b32_e32 v92, v0
	v_mov_b32_e32 v93, v0
	v_mov_b32_e32 v94, v0
	v_mov_b32_e32 v95, v0
	v_mov_b32_e32 v96, v0
	v_mov_b32_e32 v97, v0
	v_mov_b32_e32 v98, v0
	v_mov_b32_e32 v99, v0
	v_mov_b32_e32 v100, v0
	v_mov_b32_e32 v101, v0
	v_mov_b32_e32 v102, v0
	v_mov_b32_e32 v103, v0
	v_mov_b32_e32 v104, v0
	v_mov_b32_e32 v105, v0
	v_mov_b32_e32 v106, v0
	v_mov_b32_e32 v107, v0
	v_mov_b32_e32 v108, v0
	v_mov_b32_e32 v109, v0
	v_mov_b32_e32 v110, v0
	v_mov_b32_e32 v111, v0
	v_mov_b32_e32 v112, v0
	v_mov_b32_e32 v113, v0
	v_mov_b32_e32 v114, v0
	v_mov_b32_e32 v115, v0
	v_mov_b32_e32 v116, v0
	v_mov_b32_e32 v117, v0
	v_mov_b32_e32 v118, v0
	v_mov_b32_e32 v119, v0
	v_mov_b32_e32 v120, v0
	v_mov_b32_e32 v121, v0
	v_mov_b32_e32 v122, v0
	v_mov_b32_e32 v123, v0
	v_mov_b32_e32 v124, v0
	v_mov_b32_e32 v125, v0
	v_mov_b32_e32 v126, v0
	v_mov_b32_e32 v127, v0
	s_barrier
	s_barrier
	s_branch .Lmy_rot_210

; #define STAGE(P, RS, SOFF, OFF, kt) do { const int _so = (SOFF) + (kt) * (BK * 2); \
;     _Pragma("unroll") for (int _i = 0; _i < 2; ++_i) { \
;       __builtin_amdgcn_raw_ptr_buffer_load_lds(RS, (__attribute__((address_space(3))) void*)((P) + wave * 1024 + _i * 8192), 16, OFF[_i], _so, 0, 0); } } while (0)
; #define LDA(dst, b, h) _Pragma("unroll") for (int m = 0; m < 4; ++m) _Pragma("unroll") for (int k = 0; k < 2; ++k) \
;     dst[m][k] = *reinterpret_cast<const bf16x8*>(SA(b, h) + lds_byte(wr * 64 + m * 16 + fr, k * 32 + fq * 8))
; #define LDB(dst, b, h) _Pragma("unroll") for (int n = 0; n < 2; ++n) _Pragma("unroll") for (int k = 0; k < 2; ++k) \
;     dst[n][k] = *reinterpret_cast<const bf16x8*>(SB(b, h) + lds_byte(wc * 32 + n * 16 + fr, k * 32 + fq * 8))
; #define WAIT_V(n) asm volatile("s_waitcnt vmcnt(" #n ")" ::: "memory")
; #define WAIT_L(n) asm volatile("s_waitcnt lgkmcnt(" #n ")" ::: "memory")
; #define BAR __builtin_amdgcn_s_barrier()
; #define SCHED __builtin_amdgcn_sched_barrier(0)
;     ...
;       LDB(B0, 0, 0); SCHED; LDA(At, 0, 0); STAGE(SA(1, 1), rsA, sA1, offA, t + 1);
;       WAIT_L(8); BAR; WAIT_L(0); MMA(0, 0, At, B0); BAR; SCHED;
;       LDB(B1, 0, 1); STAGE(SB(0, 0), rsB, sB0, offB, t + 2);
;       BAR; WAIT_L(0); MMA(0, 1, At, B1); BAR;
;       LDA(At, 0, 1); STAGE(SA(0, 0), rsA, sA0, offA, t + 2);
;       BAR; WAIT_L(0); MMA(1, 0, At, B0); BAR; SCHED;
;       STAGE(SB(0, 1), rsB, sB1, offB, t + 2);
;       WAIT_V(6); BAR; MMA(1, 1, At, B1); BAR;
;       LDB(B0, 1, 0); SCHED; LDA(At, 1, 0); STAGE(SA(0, 1), rsA, sA1, offA, t + 2);
;       WAIT_L(8); BAR; WAIT_L(0); MMA(0, 0, At, B0); BAR; SCHED;
;       LDB(B1, 1, 1); STAGE(SB(1, 0), rsB, sB0, offB, t + 3);
;       BAR; WAIT_L(0); MMA(0, 1, At, B1); BAR;
;       LDA(At, 1, 1); STAGE(SA(1, 0), rsA, sA0, offA, t + 3);
.Lmy_rot_210:
	ds_read_b128 v[154:157], v149
	ds_read_b128 v[158:161], v150
	ds_read_b128 v[162:165], v151
	ds_read_b128 v[166:169], v152
	s_add_i32 s44, s38, s17
	s_add_i32 s10, s44, 0x80
	s_mov_b32 m0, s30
	ds_read_b128 v[170:173], v131
	ds_read_b128 v[174:177], v131 offset:1024
	ds_read_b128 v[178:181], v134
	ds_read_b128 v[182:185], v134 offset:1024
	ds_read_b128 v[186:189], v133
	ds_read_b128 v[190:193], v133 offset:1024
	ds_read_b128 v[194:197], v132
	ds_read_b128 v[198:201], v132 offset:1024
	buffer_load_dwordx4 v143, s[4:7], s10 offen lds
	s_mov_b32 m0, s31
	s_nop 0
	buffer_load_dwordx4 v144, s[4:7], s10 offen lds
	s_waitcnt lgkmcnt(8)
	s_barrier
	s_waitcnt lgkmcnt(0)
	v_mfma_f32_16x16x32_bf16 v[124:127], v[154:157], v[170:173], v[124:127]
	v_mfma_f32_16x16x32_bf16 v[124:127], v[158:161], v[174:177], v[124:127]
	v_mfma_f32_16x16x32_bf16 v[120:123], v[162:165], v[170:173], v[120:123]
	v_mfma_f32_16x16x32_bf16 v[120:123], v[166:169], v[174:177], v[120:123]
	v_mfma_f32_16x16x32_bf16 v[116:119], v[154:157], v[178:181], v[116:119]
	v_mfma_f32_16x16x32_bf16 v[116:119], v[158:161], v[182:185], v[116:119]
	v_mfma_f32_16x16x32_bf16 v[112:115], v[162:165], v[178:181], v[112:115]
	v_mfma_f32_16x16x32_bf16 v[112:115], v[166:169], v[182:185], v[112:115]
	v_mfma_f32_16x16x32_bf16 v[108:111], v[154:157], v[186:189], v[108:111]
	v_mfma_f32_16x16x32_bf16 v[108:111], v[158:161], v[190:193], v[108:111]
	v_mfma_f32_16x16x32_bf16 v[104:107], v[162:165], v[186:189], v[104:107]
	v_mfma_f32_16x16x32_bf16 v[104:107], v[166:169], v[190:193], v[104:107]
	v_mfma_f32_16x16x32_bf16 v[100:103], v[154:157], v[194:197], v[100:103]
	v_mfma_f32_16x16x32_bf16 v[100:103], v[158:161], v[198:201], v[100:103]
	v_mfma_f32_16x16x32_bf16 v[96:99], v[162:165], v[194:197], v[96:99]
	v_mfma_f32_16x16x32_bf16 v[96:99], v[166:169], v[198:201], v[96:99]
	s_barrier
	s_add_i32 s45, s40, s17
	s_add_i32 s46, s45, 0x100
	s_mov_b32 s10, s6
	s_mov_b32 s11, s7
	s_mov_b32 m0, s1
	ds_read_b128 v[202:205], v145
	ds_read_b128 v[206:209], v146
	ds_read_b128 v[210:213], v147
	ds_read_b128 v[214:217], v148
	buffer_load_dwordx4 v143, s[8:11], s46 offen lds
	s_mov_b32 m0, s3
	s_nop 0
	buffer_load_dwordx4 v144, s[8:11], s46 offen lds
	s_barrier
	s_waitcnt lgkmcnt(0)
	v_mfma_f32_16x16x32_bf16 v[92:95], v[202:205], v[170:173], v[92:95]
	v_mfma_f32_16x16x32_bf16 v[92:95], v[206:209], v[174:177], v[92:95]
	v_mfma_f32_16x16x32_bf16 v[88:91], v[210:213], v[170:173], v[88:91]
	v_mfma_f32_16x16x32_bf16 v[88:91], v[214:217], v[174:177], v[88:91]
	v_mfma_f32_16x16x32_bf16 v[84:87], v[202:205], v[178:181], v[84:87]
	v_mfma_f32_16x16x32_bf16 v[84:87], v[206:209], v[182:185], v[84:87]
	v_mfma_f32_16x16x32_bf16 v[80:83], v[210:213], v[178:181], v[80:83]
	v_mfma_f32_16x16x32_bf16 v[80:83], v[214:217], v[182:185], v[80:83]
	v_mfma_f32_16x16x32_bf16 v[76:79], v[202:205], v[186:189], v[76:79]
	v_mfma_f32_16x16x32_bf16 v[76:79], v[206:209], v[190:193], v[76:79]
	v_mfma_f32_16x16x32_bf16 v[72:75], v[210:213], v[186:189], v[72:75]
	v_mfma_f32_16x16x32_bf16 v[72:75], v[214:217], v[190:193], v[72:75]
	v_mfma_f32_16x16x32_bf16 v[68:71], v[202:205], v[194:197], v[68:71]
	v_mfma_f32_16x16x32_bf16 v[68:71], v[206:209], v[198:201], v[68:71]
	v_mfma_f32_16x16x32_bf16 v[64:67], v[210:213], v[194:197], v[64:67]
	v_mfma_f32_16x16x32_bf16 v[64:67], v[214:217], v[198:201], v[64:67]
	s_barrier
	s_add_i32 s46, s39, s17
	s_add_i32 s47, s46, 0x100
	s_mov_b32 m0, s0
	ds_read_b128 v[170:173], v131 offset:16384
	ds_read_b128 v[174:177], v131 offset:17408
	ds_read_b128 v[178:181], v134 offset:16384
	ds_read_b128 v[182:185], v134 offset:17408
	ds_read_b128 v[186:189], v133 offset:16384
	ds_read_b128 v[190:193], v133 offset:17408
	ds_read_b128 v[194:197], v132 offset:16384
	ds_read_b128 v[198:201], v132 offset:17408
	buffer_load_dwordx4 v143, s[4:7], s47 offen lds
	s_mov_b32 m0, s18
	s_nop 0
	buffer_load_dwordx4 v144, s[4:7], s47 offen lds
	s_barrier
	s_waitcnt lgkmcnt(0)
	v_mfma_f32_16x16x32_bf16 v[60:63], v[154:157], v[170:173], v[60:63]
	v_mfma_f32_16x16x32_bf16 v[60:63], v[158:161], v[174:177], v[60:63]
	v_mfma_f32_16x16x32_bf16 v[56:59], v[162:165], v[170:173], v[56:59]
	v_mfma_f32_16x16x32_bf16 v[56:59], v[166:169], v[174:177], v[56:59]
	v_mfma_f32_16x16x32_bf16 v[52:55], v[154:157], v[178:181], v[52:55]
	v_mfma_f32_16x16x32_bf16 v[52:55], v[158:161], v[182:185], v[52:55]
	v_mfma_f32_16x16x32_bf16 v[48:51], v[162:165], v[178:181], v[48:51]
	v_mfma_f32_16x16x32_bf16 v[48:51], v[166:169], v[182:185], v[48:51]
	v_mfma_f32_16x16x32_bf16 v[44:47], v[154:157], v[186:189], v[44:47]
	v_mfma_f32_16x16x32_bf16 v[44:47], v[158:161], v[190:193], v[44:47]
	v_mfma_f32_16x16x32_bf16 v[40:43], v[162:165], v[186:189], v[40:43]
	v_mfma_f32_16x16x32_bf16 v[40:43], v[166:169], v[190:193], v[40:43]
	v_mfma_f32_16x16x32_bf16 v[36:39], v[154:157], v[194:197], v[36:39]
	v_mfma_f32_16x16x32_bf16 v[36:39], v[158:161], v[198:201], v[36:39]
	v_mfma_f32_16x16x32_bf16 v[32:35], v[162:165], v[194:197], v[32:35]
	v_mfma_f32_16x16x32_bf16 v[32:35], v[166:169], v[198:201], v[32:35]
	s_barrier
	s_add_i32 s47, s41, s17
	s_add_i32 s48, s47, 0x100
	s_mov_b32 m0, s19
	s_nop 0
	buffer_load_dwordx4 v143, s[8:11], s48 offen lds
	s_mov_b32 m0, s20
	s_nop 0
	buffer_load_dwordx4 v144, s[8:11], s48 offen lds
	s_waitcnt vmcnt(6)
	s_barrier
; #define STAGE(P, RS, SOFF, OFF, kt) do { const int _so = (SOFF) + (kt) * (BK * 2); \
;     _Pragma("unroll") for (int _i = 0; _i < 2; ++_i) { \
;       __builtin_amdgcn_raw_ptr_buffer_load_lds(RS, (__attribute__((address_space(3))) void*)((P) + wave * 1024 + _i * 8192), 16, OFF[_i], _so, 0, 0); } } while (0)
; #define LDA(dst, b, h) _Pragma("unroll") for (int m = 0; m < 4; ++m) _Pragma("unroll") for (int k = 0; k < 2; ++k) \
;     dst[m][k] = *reinterpret_cast<const bf16x8*>(SA(b, h) + lds_byte(wr * 64 + m * 16 + fr, k * 32 + fq * 8))
; #define LDB(dst, b, h) _Pragma("unroll") for (int n = 0; n < 2; ++n) _Pragma("unroll") for (int k = 0; k < 2; ++k) \
;     dst[n][k] = *reinterpret_cast<const bf16x8*>(SB(b, h) + lds_byte(wc * 32 + n * 16 + fr, k * 32 + fq * 8))
; #define WAIT_V(n) asm volatile("s_waitcnt vmcnt(" #n ")" ::: "memory")
; #define WAIT_L(n) asm volatile("s_waitcnt lgkmcnt(" #n ")" ::: "memory")
; #define BAR __builtin_amdgcn_s_barrier()
; #define SCHED __builtin_amdgcn_sched_barrier(0)
;     ...
;       WAIT_V(6); BAR; MMA(1, 1, At, B1); BAR;
;       LDB(B0, 1, 0); SCHED; LDA(At, 1, 0); STAGE(SA(0, 1), rsA, sA1, offA, t + 2);
;       WAIT_L(8); BAR; WAIT_L(0); MMA(0, 0, At, B0); BAR; SCHED;
;       LDB(B1, 1, 1); STAGE(SB(1, 0), rsB, sB0, offB, t + 3);
;       BAR; WAIT_L(0); MMA(0, 1, At, B1); BAR;
;       LDA(At, 1, 1); STAGE(SA(1, 0), rsA, sA0, offA, t + 3);
	v_mfma_f32_16x16x32_bf16 v[28:31], v[202:205], v[170:173], v[28:31]
	v_mfma_f32_16x16x32_bf16 v[28:31], v[206:209], v[174:177], v[28:31]
	v_mfma_f32_16x16x32_bf16 v[24:27], v[210:213], v[170:173], v[24:27]
	v_mfma_f32_16x16x32_bf16 v[24:27], v[214:217], v[174:177], v[24:27]
	v_mfma_f32_16x16x32_bf16 v[20:23], v[202:205], v[178:181], v[20:23]
	v_mfma_f32_16x16x32_bf16 v[20:23], v[206:209], v[182:185], v[20:23]
	v_mfma_f32_16x16x32_bf16 v[16:19], v[210:213], v[178:181], v[16:19]
	v_mfma_f32_16x16x32_bf16 v[16:19], v[214:217], v[182:185], v[16:19]
	v_mfma_f32_16x16x32_bf16 v[12:15], v[202:205], v[186:189], v[12:15]
	v_mfma_f32_16x16x32_bf16 v[12:15], v[206:209], v[190:193], v[12:15]
	v_mfma_f32_16x16x32_bf16 v[8:11], v[210:213], v[186:189], v[8:11]
	v_mfma_f32_16x16x32_bf16 v[8:11], v[214:217], v[190:193], v[8:11]
	v_mfma_f32_16x16x32_bf16 v[4:7], v[202:205], v[194:197], v[4:7]
	v_mfma_f32_16x16x32_bf16 v[4:7], v[206:209], v[198:201], v[4:7]
	v_mfma_f32_16x16x32_bf16 v[0:3], v[210:213], v[194:197], v[0:3]
	v_mfma_f32_16x16x32_bf16 v[0:3], v[214:217], v[198:201], v[0:3]
	s_barrier
	ds_read_b128 v[154:157], v139
	ds_read_b128 v[158:161], v140
	ds_read_b128 v[162:165], v141
	ds_read_b128 v[166:169], v142
	s_addk_i32 s44, 0x100
	s_mov_b32 m0, s21
	ds_read_b128 v[170:173], v131 offset:32768
	ds_read_b128 v[174:177], v131 offset:33792
	ds_read_b128 v[178:181], v134 offset:32768
	ds_read_b128 v[182:185], v134 offset:33792
	ds_read_b128 v[186:189], v133 offset:32768
	ds_read_b128 v[190:193], v133 offset:33792
	ds_read_b128 v[194:197], v132 offset:32768
	ds_read_b128 v[198:201], v132 offset:33792
	buffer_load_dwordx4 v143, s[4:7], s44 offen lds
	s_mov_b32 m0, s22
	s_nop 0
	buffer_load_dwordx4 v144, s[4:7], s44 offen lds
	s_waitcnt lgkmcnt(8)
	s_barrier
	s_waitcnt lgkmcnt(0)
	v_mfma_f32_16x16x32_bf16 v[124:127], v[154:157], v[170:173], v[124:127]
	v_mfma_f32_16x16x32_bf16 v[124:127], v[158:161], v[174:177], v[124:127]
	v_mfma_f32_16x16x32_bf16 v[120:123], v[162:165], v[170:173], v[120:123]
	v_mfma_f32_16x16x32_bf16 v[120:123], v[166:169], v[174:177], v[120:123]
	v_mfma_f32_16x16x32_bf16 v[116:119], v[154:157], v[178:181], v[116:119]
	v_mfma_f32_16x16x32_bf16 v[116:119], v[158:161], v[182:185], v[116:119]
	v_mfma_f32_16x16x32_bf16 v[112:115], v[162:165], v[178:181], v[112:115]
	v_mfma_f32_16x16x32_bf16 v[112:115], v[166:169], v[182:185], v[112:115]
	v_mfma_f32_16x16x32_bf16 v[108:111], v[154:157], v[186:189], v[108:111]
	v_mfma_f32_16x16x32_bf16 v[108:111], v[158:161], v[190:193], v[108:111]
	v_mfma_f32_16x16x32_bf16 v[104:107], v[162:165], v[186:189], v[104:107]
	v_mfma_f32_16x16x32_bf16 v[104:107], v[166:169], v[190:193], v[104:107]
	v_mfma_f32_16x16x32_bf16 v[100:103], v[154:157], v[194:197], v[100:103]
	v_mfma_f32_16x16x32_bf16 v[100:103], v[158:161], v[198:201], v[100:103]
	v_mfma_f32_16x16x32_bf16 v[96:99], v[162:165], v[194:197], v[96:99]
	v_mfma_f32_16x16x32_bf16 v[96:99], v[166:169], v[198:201], v[96:99]
	s_barrier
	s_addk_i32 s45, 0x180
	s_mov_b32 m0, s23
	ds_read_b128 v[202:205], v135
	ds_read_b128 v[206:209], v136
	ds_read_b128 v[210:213], v137
	ds_read_b128 v[214:217], v138
	buffer_load_dwordx4 v143, s[8:11], s45 offen lds
	s_mov_b32 m0, s24
	s_nop 0
	buffer_load_dwordx4 v144, s[8:11], s45 offen lds
	s_barrier
	s_waitcnt lgkmcnt(0)
	v_mfma_f32_16x16x32_bf16 v[92:95], v[202:205], v[170:173], v[92:95]
	v_mfma_f32_16x16x32_bf16 v[92:95], v[206:209], v[174:177], v[92:95]
	v_mfma_f32_16x16x32_bf16 v[88:91], v[210:213], v[170:173], v[88:91]
	v_mfma_f32_16x16x32_bf16 v[88:91], v[214:217], v[174:177], v[88:91]
	v_mfma_f32_16x16x32_bf16 v[84:87], v[202:205], v[178:181], v[84:87]
	v_mfma_f32_16x16x32_bf16 v[84:87], v[206:209], v[182:185], v[84:87]
	v_mfma_f32_16x16x32_bf16 v[80:83], v[210:213], v[178:181], v[80:83]
	v_mfma_f32_16x16x32_bf16 v[80:83], v[214:217], v[182:185], v[80:83]
	v_mfma_f32_16x16x32_bf16 v[76:79], v[202:205], v[186:189], v[76:79]
	v_mfma_f32_16x16x32_bf16 v[76:79], v[206:209], v[190:193], v[76:79]
	v_mfma_f32_16x16x32_bf16 v[72:75], v[210:213], v[186:189], v[72:75]
	v_mfma_f32_16x16x32_bf16 v[72:75], v[214:217], v[190:193], v[72:75]
	v_mfma_f32_16x16x32_bf16 v[68:71], v[202:205], v[194:197], v[68:71]
	v_mfma_f32_16x16x32_bf16 v[68:71], v[206:209], v[198:201], v[68:71]
	v_mfma_f32_16x16x32_bf16 v[64:67], v[210:213], v[194:197], v[64:67]
	v_mfma_f32_16x16x32_bf16 v[64:67], v[214:217], v[198:201], v[64:67]
	s_barrier
	s_addk_i32 s46, 0x180
	s_mov_b32 m0, s25
	ds_read_b128 v[170:173], v131 offset:49152
	ds_read_b128 v[174:177], v131 offset:50176
	ds_read_b128 v[178:181], v134 offset:49152
	ds_read_b128 v[182:185], v134 offset:50176
	ds_read_b128 v[186:189], v133 offset:49152
	ds_read_b128 v[190:193], v133 offset:50176
	ds_read_b128 v[194:197], v132 offset:49152
	ds_read_b128 v[198:201], v132 offset:50176
	buffer_load_dwordx4 v143, s[4:7], s46 offen lds
	s_mov_b32 m0, s26
	s_nop 0
	buffer_load_dwordx4 v144, s[4:7], s46 offen lds
	s_barrier
	s_waitcnt lgkmcnt(0)
	v_mfma_f32_16x16x32_bf16 v[60:63], v[154:157], v[170:173], v[60:63]
	v_mfma_f32_16x16x32_bf16 v[60:63], v[158:161], v[174:177], v[60:63]
	v_mfma_f32_16x16x32_bf16 v[56:59], v[162:165], v[170:173], v[56:59]
	v_mfma_f32_16x16x32_bf16 v[56:59], v[166:169], v[174:177], v[56:59]
	v_mfma_f32_16x16x32_bf16 v[52:55], v[154:157], v[178:181], v[52:55]
	v_mfma_f32_16x16x32_bf16 v[52:55], v[158:161], v[182:185], v[52:55]
	v_mfma_f32_16x16x32_bf16 v[48:51], v[162:165], v[178:181], v[48:51]
	v_mfma_f32_16x16x32_bf16 v[48:51], v[166:169], v[182:185], v[48:51]
	v_mfma_f32_16x16x32_bf16 v[44:47], v[154:157], v[186:189], v[44:47]
	v_mfma_f32_16x16x32_bf16 v[44:47], v[158:161], v[190:193], v[44:47]
	v_mfma_f32_16x16x32_bf16 v[40:43], v[162:165], v[186:189], v[40:43]
	v_mfma_f32_16x16x32_bf16 v[40:43], v[166:169], v[190:193], v[40:43]
	v_mfma_f32_16x16x32_bf16 v[36:39], v[154:157], v[194:197], v[36:39]
	v_mfma_f32_16x16x32_bf16 v[36:39], v[158:161], v[198:201], v[36:39]
	v_mfma_f32_16x16x32_bf16 v[32:35], v[162:165], v[194:197], v[32:35]
	v_mfma_f32_16x16x32_bf16 v[32:35], v[166:169], v[198:201], v[32:35]
	s_barrier
; #define STAGE(P, RS, SOFF, OFF, kt) do { const int _so = (SOFF) + (kt) * (BK * 2); \
;     _Pragma("unroll") for (int _i = 0; _i < 2; ++_i) { \
;       __builtin_amdgcn_raw_ptr_buffer_load_lds(RS, (__attribute__((address_space(3))) void*)((P) + wave * 1024 + _i * 8192), 16, OFF[_i], _so, 0, 0); } } while (0)
; #define LDA(dst, b, h) _Pragma("unroll") for (int m = 0; m < 4; ++m) _Pragma("unroll") for (int k = 0; k < 2; ++k) \
;     dst[m][k] = *reinterpret_cast<const bf16x8*>(SA(b, h) + lds_byte(wr * 64 + m * 16 + fr, k * 32 + fq * 8))
; #define LDB(dst, b, h) _Pragma("unroll") for (int n = 0; n < 2; ++n) _Pragma("unroll") for (int k = 0; k < 2; ++k) \
;     dst[n][k] = *reinterpret_cast<const bf16x8*>(SB(b, h) + lds_byte(wc * 32 + n * 16 + fr, k * 32 + fq * 8))
; #define WAIT_V(n) asm volatile("s_waitcnt vmcnt(" #n ")" ::: "memory")
; #define WAIT_L(n) asm volatile("s_waitcnt lgkmcnt(" #n ")" ::: "memory")
; #define BAR __builtin_amdgcn_s_barrier()
;     ...
;       STAGE(SB(1, 1), rsB, sB1, offB, t + 3);
;       WAIT_V(6); BAR; MMA(1, 1, At, B1); BAR;
;     }
;     { LDB(B0, 0, 0); LDA(At, 0, 0); STAGE(SA(1, 1), rsA, sA1, offA, nt - 1);
;       BAR; WAIT_L(0); MMA(0, 0, At, B0); BAR;
;       LDB(B1, 0, 1); BAR; WAIT_L(0); MMA(0, 1, At, B1); BAR;
;       LDA(At, 0, 1); WAIT_V(4); BAR; WAIT_L(0); MMA(1, 0, At, B0); MMA(1, 1, At, B1); BAR; }
	s_addk_i32 s47, 0x180
	s_mov_b32 m0, s27
	s_nop 0
	buffer_load_dwordx4 v143, s[8:11], s47 offen lds
	s_mov_b32 m0, s28
	s_nop 0
	buffer_load_dwordx4 v144, s[8:11], s47 offen lds
	s_add_i32 s16, s16, 2
	s_addk_i32 s17, 0x100
	s_cmp_gt_u32 s16, 27
	s_cbranch_scc0 .LBB0_210
	s_waitcnt vmcnt(6)
	s_barrier
	v_mfma_f32_16x16x32_bf16 v[28:31], v[202:205], v[170:173], v[28:31]
	v_mfma_f32_16x16x32_bf16 v[28:31], v[206:209], v[174:177], v[28:31]
	v_mfma_f32_16x16x32_bf16 v[24:27], v[210:213], v[170:173], v[24:27]
	v_mfma_f32_16x16x32_bf16 v[24:27], v[214:217], v[174:177], v[24:27]
	v_mfma_f32_16x16x32_bf16 v[20:23], v[202:205], v[178:181], v[20:23]
	v_mfma_f32_16x16x32_bf16 v[20:23], v[206:209], v[182:185], v[20:23]
	v_mfma_f32_16x16x32_bf16 v[16:19], v[210:213], v[178:181], v[16:19]
	v_mfma_f32_16x16x32_bf16 v[16:19], v[214:217], v[182:185], v[16:19]
	v_mfma_f32_16x16x32_bf16 v[12:15], v[202:205], v[186:189], v[12:15]
	v_mfma_f32_16x16x32_bf16 v[12:15], v[206:209], v[190:193], v[12:15]
	v_mfma_f32_16x16x32_bf16 v[8:11], v[210:213], v[186:189], v[8:11]
	v_mfma_f32_16x16x32_bf16 v[8:11], v[214:217], v[190:193], v[8:11]
	v_mfma_f32_16x16x32_bf16 v[4:7], v[202:205], v[194:197], v[4:7]
	v_mfma_f32_16x16x32_bf16 v[4:7], v[206:209], v[198:201], v[4:7]
	v_mfma_f32_16x16x32_bf16 v[0:3], v[210:213], v[194:197], v[0:3]
	v_mfma_f32_16x16x32_bf16 v[0:3], v[214:217], v[198:201], v[0:3]
	s_barrier
	s_add_i32 s10, s38, 0xf80
	s_mov_b32 m0, s30
	ds_read_b128 v[154:157], v149
	ds_read_b128 v[158:161], v150
	ds_read_b128 v[162:165], v151
	ds_read_b128 v[150:153], v152
	ds_read_b128 v[166:169], v131
	ds_read_b128 v[170:173], v131 offset:1024
	ds_read_b128 v[174:177], v134
	ds_read_b128 v[178:181], v134 offset:1024
	ds_read_b128 v[182:185], v133
	ds_read_b128 v[186:189], v133 offset:1024
	ds_read_b128 v[190:193], v132
	ds_read_b128 v[194:197], v132 offset:1024
	buffer_load_dwordx4 v143, s[4:7], s10 offen lds
	s_mov_b32 m0, s31
	s_nop 0
	buffer_load_dwordx4 v144, s[4:7], s10 offen lds
	s_barrier
	s_waitcnt lgkmcnt(0)
	v_mfma_f32_16x16x32_bf16 v[124:127], v[154:157], v[166:169], v[124:127]
	v_mfma_f32_16x16x32_bf16 v[124:127], v[158:161], v[170:173], v[124:127]
	v_mfma_f32_16x16x32_bf16 v[120:123], v[162:165], v[166:169], v[120:123]
	v_mfma_f32_16x16x32_bf16 v[120:123], v[150:153], v[170:173], v[120:123]
	v_mfma_f32_16x16x32_bf16 v[116:119], v[154:157], v[174:177], v[116:119]
	v_mfma_f32_16x16x32_bf16 v[116:119], v[158:161], v[178:181], v[116:119]
	v_mfma_f32_16x16x32_bf16 v[112:115], v[162:165], v[174:177], v[112:115]
	v_mfma_f32_16x16x32_bf16 v[112:115], v[150:153], v[178:181], v[112:115]
	v_mfma_f32_16x16x32_bf16 v[108:111], v[154:157], v[182:185], v[108:111]
	v_mfma_f32_16x16x32_bf16 v[108:111], v[158:161], v[186:189], v[108:111]
	v_mfma_f32_16x16x32_bf16 v[104:107], v[162:165], v[182:185], v[104:107]
	v_mfma_f32_16x16x32_bf16 v[104:107], v[150:153], v[186:189], v[104:107]
	v_mfma_f32_16x16x32_bf16 v[100:103], v[154:157], v[190:193], v[100:103]
	v_mfma_f32_16x16x32_bf16 v[100:103], v[158:161], v[194:197], v[100:103]
	v_mfma_f32_16x16x32_bf16 v[96:99], v[162:165], v[190:193], v[96:99]
	v_mfma_f32_16x16x32_bf16 v[96:99], v[150:153], v[194:197], v[96:99]
	s_barrier
	ds_read_b128 v[198:201], v145
	ds_read_b128 v[202:205], v146
	ds_read_b128 v[144:147], v147
	ds_read_b128 v[206:209], v148
	s_barrier
	s_waitcnt lgkmcnt(0)
	v_mfma_f32_16x16x32_bf16 v[92:95], v[198:201], v[166:169], v[92:95]
	v_mfma_f32_16x16x32_bf16 v[92:95], v[202:205], v[170:173], v[92:95]
	v_mfma_f32_16x16x32_bf16 v[88:91], v[144:147], v[166:169], v[88:91]
	v_mfma_f32_16x16x32_bf16 v[88:91], v[206:209], v[170:173], v[88:91]
	v_mfma_f32_16x16x32_bf16 v[84:87], v[198:201], v[174:177], v[84:87]
	v_mfma_f32_16x16x32_bf16 v[84:87], v[202:205], v[178:181], v[84:87]
	v_mfma_f32_16x16x32_bf16 v[80:83], v[144:147], v[174:177], v[80:83]
	v_mfma_f32_16x16x32_bf16 v[80:83], v[206:209], v[178:181], v[80:83]
	v_mfma_f32_16x16x32_bf16 v[76:79], v[198:201], v[182:185], v[76:79]
	v_mfma_f32_16x16x32_bf16 v[76:79], v[202:205], v[186:189], v[76:79]
	v_mfma_f32_16x16x32_bf16 v[72:75], v[144:147], v[182:185], v[72:75]
	v_mfma_f32_16x16x32_bf16 v[72:75], v[206:209], v[186:189], v[72:75]
	v_mfma_f32_16x16x32_bf16 v[68:71], v[198:201], v[190:193], v[68:71]
	v_mfma_f32_16x16x32_bf16 v[68:71], v[202:205], v[194:197], v[68:71]
	v_mfma_f32_16x16x32_bf16 v[64:67], v[144:147], v[190:193], v[64:67]
	v_mfma_f32_16x16x32_bf16 v[64:67], v[206:209], v[194:197], v[64:67]
	s_barrier
	ds_read_b128 v[166:169], v131 offset:16384
	ds_read_b128 v[170:173], v131 offset:17408
	ds_read_b128 v[174:177], v134 offset:16384
	ds_read_b128 v[178:181], v134 offset:17408
	ds_read_b128 v[182:185], v133 offset:16384
	ds_read_b128 v[186:189], v133 offset:17408
	ds_read_b128 v[190:193], v132 offset:16384
	ds_read_b128 v[194:197], v132 offset:17408
	s_waitcnt vmcnt(4)
	s_barrier
; #define LDA(dst, b, h) _Pragma("unroll") for (int m = 0; m < 4; ++m) _Pragma("unroll") for (int k = 0; k < 2; ++k) \
;     dst[m][k] = *reinterpret_cast<const bf16x8*>(SA(b, h) + lds_byte(wr * 64 + m * 16 + fr, k * 32 + fq * 8))
; #define LDB(dst, b, h) _Pragma("unroll") for (int n = 0; n < 2; ++n) _Pragma("unroll") for (int k = 0; k < 2; ++k) \
;     dst[n][k] = *reinterpret_cast<const bf16x8*>(SB(b, h) + lds_byte(wc * 32 + n * 16 + fr, k * 32 + fq * 8))
; #define WAIT_V(n) asm volatile("s_waitcnt vmcnt(" #n ")" ::: "memory")
; #define WAIT_L(n) asm volatile("s_waitcnt lgkmcnt(" #n ")" ::: "memory")
; #define BAR __builtin_amdgcn_s_barrier()
;     ...
;       LDA(At, 0, 1); WAIT_V(4); BAR; WAIT_L(0); MMA(1, 0, At, B0); MMA(1, 1, At, B1); BAR; }
;     { LDB(B0, 1, 0); LDA(At, 1, 0); WAIT_V(2); BAR; WAIT_L(0); MMA(0, 0, At, B0); BAR;
	s_waitcnt lgkmcnt(0)
	v_mfma_f32_16x16x32_bf16 v[60:63], v[154:157], v[166:169], v[60:63]
	v_mfma_f32_16x16x32_bf16 v[60:63], v[158:161], v[170:173], v[60:63]
	v_mfma_f32_16x16x32_bf16 v[56:59], v[162:165], v[166:169], v[56:59]
	v_mfma_f32_16x16x32_bf16 v[56:59], v[150:153], v[170:173], v[56:59]
	v_mfma_f32_16x16x32_bf16 v[52:55], v[154:157], v[174:177], v[52:55]
	v_mfma_f32_16x16x32_bf16 v[52:55], v[158:161], v[178:181], v[52:55]
	v_mfma_f32_16x16x32_bf16 v[48:51], v[162:165], v[174:177], v[48:51]
	v_mfma_f32_16x16x32_bf16 v[48:51], v[150:153], v[178:181], v[48:51]
	v_mfma_f32_16x16x32_bf16 v[44:47], v[154:157], v[182:185], v[44:47]
	v_mfma_f32_16x16x32_bf16 v[44:47], v[158:161], v[186:189], v[44:47]
	v_mfma_f32_16x16x32_bf16 v[40:43], v[162:165], v[182:185], v[40:43]
	v_mfma_f32_16x16x32_bf16 v[40:43], v[150:153], v[186:189], v[40:43]
	v_mfma_f32_16x16x32_bf16 v[36:39], v[154:157], v[190:193], v[36:39]
	v_mfma_f32_16x16x32_bf16 v[36:39], v[158:161], v[194:197], v[36:39]
	v_mfma_f32_16x16x32_bf16 v[32:35], v[162:165], v[190:193], v[32:35]
	v_mfma_f32_16x16x32_bf16 v[32:35], v[150:153], v[194:197], v[32:35]
	v_mfma_f32_16x16x32_bf16 v[28:31], v[198:201], v[166:169], v[28:31]
	v_mfma_f32_16x16x32_bf16 v[28:31], v[202:205], v[170:173], v[28:31]
	v_mfma_f32_16x16x32_bf16 v[24:27], v[144:147], v[166:169], v[24:27]
	v_mfma_f32_16x16x32_bf16 v[24:27], v[206:209], v[170:173], v[24:27]
	v_mfma_f32_16x16x32_bf16 v[20:23], v[198:201], v[174:177], v[20:23]
	v_mfma_f32_16x16x32_bf16 v[20:23], v[202:205], v[178:181], v[20:23]
	v_mfma_f32_16x16x32_bf16 v[16:19], v[144:147], v[174:177], v[16:19]
	v_mfma_f32_16x16x32_bf16 v[16:19], v[206:209], v[178:181], v[16:19]
	v_mfma_f32_16x16x32_bf16 v[12:15], v[198:201], v[182:185], v[12:15]
	v_mfma_f32_16x16x32_bf16 v[12:15], v[202:205], v[186:189], v[12:15]
	v_mfma_f32_16x16x32_bf16 v[8:11], v[144:147], v[182:185], v[8:11]
	v_mfma_f32_16x16x32_bf16 v[8:11], v[206:209], v[186:189], v[8:11]
	v_mfma_f32_16x16x32_bf16 v[4:7], v[198:201], v[190:193], v[4:7]
	v_mfma_f32_16x16x32_bf16 v[4:7], v[202:205], v[194:197], v[4:7]
	v_mfma_f32_16x16x32_bf16 v[0:3], v[144:147], v[190:193], v[0:3]
	v_mfma_f32_16x16x32_bf16 v[0:3], v[206:209], v[194:197], v[0:3]
	s_barrier
	ds_read_b128 v[144:147], v139
	ds_read_b128 v[148:151], v140
	ds_read_b128 v[152:155], v141
	ds_read_b128 v[140:143], v142
	ds_read_b128 v[156:159], v131 offset:32768
	ds_read_b128 v[160:163], v131 offset:33792
	ds_read_b128 v[164:167], v134 offset:32768
	ds_read_b128 v[168:171], v134 offset:33792
	ds_read_b128 v[172:175], v133 offset:32768
	ds_read_b128 v[176:179], v133 offset:33792
	ds_read_b128 v[180:183], v132 offset:32768
	ds_read_b128 v[184:187], v132 offset:33792
	s_waitcnt vmcnt(2)
	s_barrier
	s_waitcnt lgkmcnt(0)
	v_mfma_f32_16x16x32_bf16 v[124:127], v[144:147], v[156:159], v[124:127]
	v_mfma_f32_16x16x32_bf16 v[124:127], v[148:151], v[160:163], v[124:127]
	v_mfma_f32_16x16x32_bf16 v[120:123], v[152:155], v[156:159], v[120:123]
	v_mfma_f32_16x16x32_bf16 v[120:123], v[140:143], v[160:163], v[120:123]
	v_mfma_f32_16x16x32_bf16 v[116:119], v[144:147], v[164:167], v[116:119]
	v_mfma_f32_16x16x32_bf16 v[116:119], v[148:151], v[168:171], v[116:119]
	v_mfma_f32_16x16x32_bf16 v[112:115], v[152:155], v[164:167], v[112:115]
	v_mfma_f32_16x16x32_bf16 v[112:115], v[140:143], v[168:171], v[112:115]
	v_mfma_f32_16x16x32_bf16 v[108:111], v[144:147], v[172:175], v[108:111]
	v_mfma_f32_16x16x32_bf16 v[108:111], v[148:151], v[176:179], v[108:111]
	v_mfma_f32_16x16x32_bf16 v[104:107], v[152:155], v[172:175], v[104:107]
	v_mfma_f32_16x16x32_bf16 v[104:107], v[140:143], v[176:179], v[104:107]
	v_mfma_f32_16x16x32_bf16 v[100:103], v[144:147], v[180:183], v[100:103]
	v_mfma_f32_16x16x32_bf16 v[100:103], v[148:151], v[184:187], v[100:103]
	v_mfma_f32_16x16x32_bf16 v[96:99], v[152:155], v[180:183], v[96:99]
	v_mfma_f32_16x16x32_bf16 v[96:99], v[140:143], v[184:187], v[96:99]
	s_barrier
; #define LDA(dst, b, h) _Pragma("unroll") for (int m = 0; m < 4; ++m) _Pragma("unroll") for (int k = 0; k < 2; ++k) \
;     dst[m][k] = *reinterpret_cast<const bf16x8*>(SA(b, h) + lds_byte(wr * 64 + m * 16 + fr, k * 32 + fq * 8))
; #define LDB(dst, b, h) _Pragma("unroll") for (int n = 0; n < 2; ++n) _Pragma("unroll") for (int k = 0; k < 2; ++k) \
;     dst[n][k] = *reinterpret_cast<const bf16x8*>(SB(b, h) + lds_byte(wc * 32 + n * 16 + fr, k * 32 + fq * 8))
; #define WAIT_V(n) asm volatile("s_waitcnt vmcnt(" #n ")" ::: "memory")
; #define WAIT_L(n) asm volatile("s_waitcnt lgkmcnt(" #n ")" ::: "memory")
; #define BAR __builtin_amdgcn_s_barrier()
;     ...
;     { LDB(B0, 1, 0); LDA(At, 1, 0); WAIT_V(2); BAR; WAIT_L(0); MMA(0, 0, At, B0); BAR;
;       LDB(B1, 1, 1); WAIT_V(0); BAR; WAIT_L(0); MMA(0, 1, At, B1); BAR;
;       LDA(At, 1, 1); BAR; WAIT_L(0); MMA(1, 0, At, B0); MMA(1, 1, At, B1); BAR; }
;     if (wr == 0) BAR;
	ds_read_b128 v[188:191], v135
	ds_read_b128 v[192:195], v136
	ds_read_b128 v[196:199], v137
	ds_read_b128 v[136:139], v138
	s_waitcnt vmcnt(0)
	s_barrier
	s_waitcnt lgkmcnt(0)
	v_mfma_f32_16x16x32_bf16 v[92:95], v[188:191], v[156:159], v[92:95]
	v_mfma_f32_16x16x32_bf16 v[92:95], v[192:195], v[160:163], v[92:95]
	v_mfma_f32_16x16x32_bf16 v[88:91], v[196:199], v[156:159], v[88:91]
	v_mfma_f32_16x16x32_bf16 v[88:91], v[136:139], v[160:163], v[88:91]
	v_mfma_f32_16x16x32_bf16 v[84:87], v[188:191], v[164:167], v[84:87]
	v_mfma_f32_16x16x32_bf16 v[84:87], v[192:195], v[168:171], v[84:87]
	v_mfma_f32_16x16x32_bf16 v[80:83], v[196:199], v[164:167], v[80:83]
	v_mfma_f32_16x16x32_bf16 v[80:83], v[136:139], v[168:171], v[80:83]
	v_mfma_f32_16x16x32_bf16 v[76:79], v[188:191], v[172:175], v[76:79]
	v_mfma_f32_16x16x32_bf16 v[76:79], v[192:195], v[176:179], v[76:79]
	v_mfma_f32_16x16x32_bf16 v[72:75], v[196:199], v[172:175], v[72:75]
	v_mfma_f32_16x16x32_bf16 v[72:75], v[136:139], v[176:179], v[72:75]
	v_mfma_f32_16x16x32_bf16 v[68:71], v[188:191], v[180:183], v[68:71]
	v_mfma_f32_16x16x32_bf16 v[68:71], v[192:195], v[184:187], v[68:71]
	v_mfma_f32_16x16x32_bf16 v[64:67], v[196:199], v[180:183], v[64:67]
	v_mfma_f32_16x16x32_bf16 v[64:67], v[136:139], v[184:187], v[64:67]
	s_barrier
	ds_read_b128 v[156:159], v131 offset:49152
	ds_read_b128 v[160:163], v131 offset:50176
	ds_read_b128 v[164:167], v134 offset:49152
	ds_read_b128 v[168:171], v134 offset:50176
	ds_read_b128 v[172:175], v133 offset:49152
	ds_read_b128 v[176:179], v133 offset:50176
	ds_read_b128 v[180:183], v132 offset:49152
	ds_read_b128 v[132:135], v132 offset:50176
	s_barrier
	s_waitcnt lgkmcnt(0)
	v_mfma_f32_16x16x32_bf16 v[60:63], v[144:147], v[156:159], v[60:63]
	v_mfma_f32_16x16x32_bf16 v[60:63], v[148:151], v[160:163], v[60:63]
	v_mfma_f32_16x16x32_bf16 v[56:59], v[152:155], v[156:159], v[56:59]
	v_mfma_f32_16x16x32_bf16 v[56:59], v[140:143], v[160:163], v[56:59]
	v_mfma_f32_16x16x32_bf16 v[52:55], v[144:147], v[164:167], v[52:55]
	v_mfma_f32_16x16x32_bf16 v[52:55], v[148:151], v[168:171], v[52:55]
	v_mfma_f32_16x16x32_bf16 v[48:51], v[152:155], v[164:167], v[48:51]
	v_mfma_f32_16x16x32_bf16 v[48:51], v[140:143], v[168:171], v[48:51]
	v_mfma_f32_16x16x32_bf16 v[44:47], v[144:147], v[172:175], v[44:47]
	v_mfma_f32_16x16x32_bf16 v[44:47], v[148:151], v[176:179], v[44:47]
	v_mfma_f32_16x16x32_bf16 v[40:43], v[152:155], v[172:175], v[40:43]
	v_mfma_f32_16x16x32_bf16 v[40:43], v[140:143], v[176:179], v[40:43]
	v_mfma_f32_16x16x32_bf16 v[36:39], v[144:147], v[180:183], v[36:39]
	v_mfma_f32_16x16x32_bf16 v[36:39], v[148:151], v[132:135], v[36:39]
	v_mfma_f32_16x16x32_bf16 v[32:35], v[152:155], v[180:183], v[32:35]
	v_mfma_f32_16x16x32_bf16 v[32:35], v[140:143], v[132:135], v[32:35]
	v_mfma_f32_16x16x32_bf16 v[28:31], v[188:191], v[156:159], v[28:31]
	v_mfma_f32_16x16x32_bf16 v[28:31], v[192:195], v[160:163], v[28:31]
	v_mfma_f32_16x16x32_bf16 v[24:27], v[196:199], v[156:159], v[24:27]
	v_mfma_f32_16x16x32_bf16 v[24:27], v[136:139], v[160:163], v[24:27]
	v_mfma_f32_16x16x32_bf16 v[20:23], v[188:191], v[164:167], v[20:23]
	v_mfma_f32_16x16x32_bf16 v[20:23], v[192:195], v[168:171], v[20:23]
	v_mfma_f32_16x16x32_bf16 v[16:19], v[196:199], v[164:167], v[16:19]
	v_mfma_f32_16x16x32_bf16 v[16:19], v[136:139], v[168:171], v[16:19]
	v_mfma_f32_16x16x32_bf16 v[12:15], v[188:191], v[172:175], v[12:15]
	v_mfma_f32_16x16x32_bf16 v[12:15], v[192:195], v[176:179], v[12:15]
	v_mfma_f32_16x16x32_bf16 v[8:11], v[196:199], v[172:175], v[8:11]
	v_mfma_f32_16x16x32_bf16 v[8:11], v[136:139], v[176:179], v[8:11]
	v_mfma_f32_16x16x32_bf16 v[4:7], v[188:191], v[180:183], v[4:7]
	v_mfma_f32_16x16x32_bf16 v[4:7], v[192:195], v[132:135], v[4:7]
	v_mfma_f32_16x16x32_bf16 v[0:3], v[196:199], v[180:183], v[0:3]
	v_mfma_f32_16x16x32_bf16 v[0:3], v[136:139], v[132:135], v[0:3]
	v_cmp_gt_u32_e32 vcc, s35, v130
	s_barrier
	s_and_saveexec_b64 s[10:11], vcc
	s_cbranch_execz .LBB0_213
	s_barrier

; #define WAIT_V(n) asm volatile("s_waitcnt vmcnt(" #n ")" ::: "memory")
; #define BAR __builtin_amdgcn_s_barrier()
;     ...
;     const int tid = opaque_tid(wave);
;     const int wid = tid >> 6, lane = tid & 63, wr = wid >> 2, wc = wid & 3, fr = lane & 15, fq = lane >> 4;
;     int offA[2], offB[2];
;     _Pragma("unroll") for (int i = 0; i < 2; ++i) {
;       int r, c; stage_rc(tid * 16 + i * 8192, r, c);
;       offA[i] = (r * lda + c) * 2; offB[i] = (r * ldb + c) * 2;
;     }
;     const int brow = pm * BM;
;     f32x4 acc[2][2][4][2];
;     _Pragma("unroll") for (int a = 0; a < 2; ++a) _Pragma("unroll") for (int b = 0; b < 2; ++b) _Pragma("unroll") for (int m = 0; m < 4; ++m) _Pragma("unroll") for (int n = 0; n < 2; ++n)
;       acc[a][b][m][n] = f32x4{0.f, 0.f, 0.f, 0.f};
;     bf16x8 At[4][2], B0[2][2], B1[2][2];
;     if (wr == 1) BAR;
;     if (first_tile) { WAIT_V(0); }
;     else if constexpr (mode == MODE_RESID_LN) { WAIT_V(0); }
;     else if constexpr (mode == MODE_SWIGLU) { WAIT_V(6); }
;     else if constexpr (mode == MODE_V) { WAIT_V(24); }
;     else { WAIT_V(12); }
;     first_tile = false;
;     BAR;
;     BAR;
.LBB0_224:
	v_bfe_i32 v4, v129, 27, 1
	v_lshlrev_b32_e32 v2, 4, v129
	v_lshrrev_b32_e32 v4, 22, v4
	v_add_u32_e32 v4, v2, v4
	v_and_b32_e32 v4, 0xfffffc00, v4
	v_sub_u32_e32 v4, v2, v4
	v_lshrrev_b32_e32 v5, 4, v4
	v_bitop3_b32 v4, v5, v4, 32 bitop3:0x6c
	v_ashrrev_i32_e32 v3, 31, v129
	v_ashrrev_i32_e32 v6, 31, v4
	v_lshrrev_b32_e32 v3, 26, v3
	v_lshrrev_b32_e32 v6, 26, v6
	v_add_u32_e32 v3, v129, v3
	v_add_u32_e32 v6, v4, v6
	v_ashrrev_i32_e32 v3, 6, v3
	v_lshrrev_b32_e32 v7, 6, v6
	v_and_b32_e32 v6, 0xc0, v6
	v_lshlrev_b32_e32 v5, 3, v3
	v_lshlrev_b32_e32 v3, 5, v3
	v_sub_u32_e32 v4, v4, v6
	v_and_b32_e32 v5, 0xffff0, v5
	v_and_b32_e32 v3, 32, v3
	v_ashrrev_i16_sdwa v4, v128, sext(v4) dst_sel:DWORD dst_unused:UNUSED_PAD src0_sel:DWORD src1_sel:BYTE_0
	v_add_u32_sdwa v3, v3, sext(v4) dst_sel:DWORD dst_unused:UNUSED_PAD src0_sel:DWORD src1_sel:WORD_0
	v_add_lshl_u32 v4, v7, v5, 12
	v_add_u32_e32 v2, 0x2000, v2
	v_lshl_add_u32 v142, v3, 1, v4
	v_ashrrev_i32_e32 v3, 31, v2
	v_lshrrev_b32_e32 v3, 22, v3
	v_add_u32_e32 v3, v2, v3
	v_ashrrev_i32_e32 v3, 10, v3
	v_mul_i32_i24_e32 v4, 0x400, v3
	v_sub_u32_e32 v2, v2, v4
	v_lshrrev_b32_e32 v4, 4, v2
	v_bitop3_b32 v2, v4, v2, 32 bitop3:0x6c
	v_ashrrev_i32_e32 v5, 31, v2
	v_lshrrev_b32_e32 v5, 26, v5
	v_add_u32_e32 v5, v2, v5
	v_lshrrev_b32_e32 v6, 6, v5
	v_and_b32_e32 v5, 0xc0, v5
	v_lshlrev_b32_e32 v4, 3, v3
	v_lshlrev_b32_e32 v3, 5, v3
	v_sub_u32_e32 v2, v2, v5
	v_and_b32_e32 v4, 0xffff0, v4
	v_and_b32_e32 v3, 32, v3
	v_ashrrev_i16_sdwa v2, v128, sext(v2) dst_sel:DWORD dst_unused:UNUSED_PAD src0_sel:DWORD src1_sel:BYTE_0
	v_add_u32_sdwa v2, v3, sext(v2) dst_sel:DWORD dst_unused:UNUSED_PAD src0_sel:DWORD src1_sel:WORD_0
	v_add_lshl_u32 v3, v6, v4, 12
	v_lshl_add_u32 v143, v2, 1, v3
	v_and_b32_e32 v3, 15, v0
	v_lshlrev_b32_e32 v5, 2, v0
	v_and_b32_e32 v2, 48, v0
	v_lshlrev_b32_e32 v3, 6, v3
	v_and_b32_e32 v5, 32, v5
	v_lshlrev_b32_e32 v0, 6, v0
	v_or_b32_e32 v4, v3, v2
	v_bitop3_b32 v3, v3, v5, v2 bitop3:0x36
	v_lshlrev_b32_e32 v6, 6, v129
	v_lshlrev_b32_e32 v1, 13, v1
	v_and_or_b32 v0, v0, s36, v2
	v_and_or_b32 v3, v6, s35, v3
	v_bitop3_b32 v0, v1, v0, v5 bitop3:0xf6
	v_or_b32_e32 v6, 0x400, v3
	v_or_b32_e32 v7, 0x800, v3
	v_or_b32_e32 v8, 0xc00, v3
	v_or_b32_e32 v133, 0x800, v0
	v_or_b32_e32 v132, 0x1000, v0
	v_or_b32_e32 v131, 0x1800, v0
	v_mov_b32_e32 v0, 0
	v_bitop3_b32 v130, v4, v1, v5 bitop3:0xde
	s_mov_b32 s16, -2
	s_mov_b32 s17, 0
	v_or_b32_e32 v148, 0x10000, v3
	v_or_b32_e32 v149, 0x10000, v6
	v_or_b32_e32 v150, 0x10000, v7
	v_or_b32_e32 v151, 0x10000, v8
	v_or_b32_e32 v144, 0x14000, v3
	v_or_b32_e32 v145, 0x14000, v6
	v_or_b32_e32 v146, 0x14000, v7
	v_or_b32_e32 v147, 0x14000, v8
	v_or_b32_e32 v138, 0x18000, v3
	v_or_b32_e32 v139, 0x18000, v6
	v_or_b32_e32 v140, 0x18000, v7
	v_or_b32_e32 v141, 0x18000, v8
	v_or_b32_e32 v134, 0x1c000, v3
	v_or_b32_e32 v135, 0x1c000, v6
	v_or_b32_e32 v136, 0x1c000, v7
	v_or_b32_e32 v137, 0x1c000, v8
	v_mov_b32_e32 v1, v0
	v_mov_b32_e32 v2, v0
	v_mov_b32_e32 v3, v0
	v_mov_b32_e32 v4, v0
	v_mov_b32_e32 v5, v0
	v_mov_b32_e32 v6, v0
	v_mov_b32_e32 v7, v0
	v_mov_b32_e32 v8, v0
	v_mov_b32_e32 v9, v0
	v_mov_b32_e32 v10, v0
	v_mov_b32_e32 v11, v0
	v_mov_b32_e32 v12, v0
	v_mov_b32_e32 v13, v0
	v_mov_b32_e32 v14, v0
	v_mov_b32_e32 v15, v0
	v_mov_b32_e32 v16, v0
	v_mov_b32_e32 v17, v0
	v_mov_b32_e32 v18, v0
	v_mov_b32_e32 v19, v0
	v_mov_b32_e32 v20, v0
	v_mov_b32_e32 v21, v0
	v_mov_b32_e32 v22, v0
	v_mov_b32_e32 v23, v0
	v_mov_b32_e32 v24, v0
	v_mov_b32_e32 v25, v0
	v_mov_b32_e32 v26, v0
	v_mov_b32_e32 v27, v0
	v_mov_b32_e32 v28, v0
	v_mov_b32_e32 v29, v0
	v_mov_b32_e32 v30, v0
	v_mov_b32_e32 v31, v0
	v_mov_b32_e32 v32, v0
	v_mov_b32_e32 v33, v0
	v_mov_b32_e32 v34, v0
	v_mov_b32_e32 v35, v0
	v_mov_b32_e32 v36, v0
	v_mov_b32_e32 v37, v0
	v_mov_b32_e32 v38, v0
	v_mov_b32_e32 v39, v0
	v_mov_b32_e32 v40, v0
	v_mov_b32_e32 v41, v0
	v_mov_b32_e32 v42, v0
	v_mov_b32_e32 v43, v0
	v_mov_b32_e32 v44, v0
	v_mov_b32_e32 v45, v0
	v_mov_b32_e32 v46, v0
	v_mov_b32_e32 v47, v0
	v_mov_b32_e32 v48, v0
	v_mov_b32_e32 v49, v0
	v_mov_b32_e32 v50, v0
	v_mov_b32_e32 v51, v0
	v_mov_b32_e32 v52, v0
	v_mov_b32_e32 v53, v0
	v_mov_b32_e32 v54, v0
	v_mov_b32_e32 v55, v0
	v_mov_b32_e32 v56, v0
	v_mov_b32_e32 v57, v0
	v_mov_b32_e32 v58, v0
	v_mov_b32_e32 v59, v0
	v_mov_b32_e32 v60, v0
	v_mov_b32_e32 v61, v0
	v_mov_b32_e32 v62, v0
	v_mov_b32_e32 v63, v0
	v_mov_b32_e32 v64, v0
	v_mov_b32_e32 v65, v0
	v_mov_b32_e32 v66, v0
	v_mov_b32_e32 v67, v0
	v_mov_b32_e32 v68, v0
	v_mov_b32_e32 v69, v0
	v_mov_b32_e32 v70, v0
	v_mov_b32_e32 v71, v0
	v_mov_b32_e32 v72, v0
	v_mov_b32_e32 v73, v0
	v_mov_b32_e32 v74, v0
	v_mov_b32_e32 v75, v0
	v_mov_b32_e32 v76, v0
	v_mov_b32_e32 v77, v0
	v_mov_b32_e32 v78, v0
	v_mov_b32_e32 v79, v0
	v_mov_b32_e32 v80, v0
	v_mov_b32_e32 v81, v0
	v_mov_b32_e32 v82, v0
	v_mov_b32_e32 v83, v0
	v_mov_b32_e32 v84, v0
	v_mov_b32_e32 v85, v0
	v_mov_b32_e32 v86, v0
	v_mov_b32_e32 v87, v0
	v_mov_b32_e32 v88, v0
	v_mov_b32_e32 v89, v0
	v_mov_b32_e32 v90, v0
	v_mov_b32_e32 v91, v0
	v_mov_b32_e32 v92, v0
	v_mov_b32_e32 v93, v0
	v_mov_b32_e32 v94, v0
	v_mov_b32_e32 v95, v0
	v_mov_b32_e32 v96, v0
	v_mov_b32_e32 v97, v0
	v_mov_b32_e32 v98, v0
	v_mov_b32_e32 v99, v0
	v_mov_b32_e32 v100, v0
	v_mov_b32_e32 v101, v0
	v_mov_b32_e32 v102, v0
	v_mov_b32_e32 v103, v0
	v_mov_b32_e32 v104, v0
	v_mov_b32_e32 v105, v0
	v_mov_b32_e32 v106, v0
	v_mov_b32_e32 v107, v0
	v_mov_b32_e32 v108, v0
	v_mov_b32_e32 v109, v0
	v_mov_b32_e32 v110, v0
	v_mov_b32_e32 v111, v0
	v_mov_b32_e32 v112, v0
	v_mov_b32_e32 v113, v0
	v_mov_b32_e32 v114, v0
	v_mov_b32_e32 v115, v0
	v_mov_b32_e32 v116, v0
	v_mov_b32_e32 v117, v0
	v_mov_b32_e32 v118, v0
	v_mov_b32_e32 v119, v0
	v_mov_b32_e32 v120, v0
	v_mov_b32_e32 v121, v0
	v_mov_b32_e32 v122, v0
	v_mov_b32_e32 v123, v0
	v_mov_b32_e32 v124, v0
	v_mov_b32_e32 v125, v0
	v_mov_b32_e32 v126, v0
	v_mov_b32_e32 v127, v0
	s_barrier
	s_barrier
	s_branch .Lmy_rot_225
; #define STAGE(P, RS, SOFF, OFF, kt) do { const int _so = (SOFF) + (kt) * (BK * 2); \
;     _Pragma("unroll") for (int _i = 0; _i < 2; ++_i) { \
;       __builtin_amdgcn_raw_ptr_buffer_load_lds(RS, (__attribute__((address_space(3))) void*)((P) + wave * 1024 + _i * 8192), 16, OFF[_i], _so, 0, 0); } } while (0)
; #define LDA(dst, b, h) _Pragma("unroll") for (int m = 0; m < 4; ++m) _Pragma("unroll") for (int k = 0; k < 2; ++k) \
;     dst[m][k] = *reinterpret_cast<const bf16x8*>(SA(b, h) + lds_byte(wr * 64 + m * 16 + fr, k * 32 + fq * 8))
; #define LDB(dst, b, h) _Pragma("unroll") for (int n = 0; n < 2; ++n) _Pragma("unroll") for (int k = 0; k < 2; ++k) \
;     dst[n][k] = *reinterpret_cast<const bf16x8*>(SB(b, h) + lds_byte(wc * 32 + n * 16 + fr, k * 32 + fq * 8))
; #define WAIT_V(n) asm volatile("s_waitcnt vmcnt(" #n ")" ::: "memory")
; #define WAIT_L(n) asm volatile("s_waitcnt lgkmcnt(" #n ")" ::: "memory")
; #define BAR __builtin_amdgcn_s_barrier()
; #define SCHED __builtin_amdgcn_sched_barrier(0)
;     ...
;       LDB(B0, 0, 0); SCHED; LDA(At, 0, 0); STAGE(SA(1, 1), rsA, sA1, offA, t + 1);
;       WAIT_L(8); BAR; WAIT_L(0); MMA(0, 0, At, B0); BAR; SCHED;
;       LDB(B1, 0, 1); STAGE(SB(0, 0), rsB, sB0, offB, t + 2);
;       BAR; WAIT_L(0); MMA(0, 1, At, B1); BAR;
;       LDA(At, 0, 1); STAGE(SA(0, 0), rsA, sA0, offA, t + 2);
;       BAR; WAIT_L(0); MMA(1, 0, At, B0); BAR; SCHED;
;       STAGE(SB(0, 1), rsB, sB1, offB, t + 2);
;       WAIT_V(6); BAR; MMA(1, 1, At, B1); BAR;
;     ...
;       WAIT_V(6); BAR; MMA(1, 1, At, B1); BAR;
.LBB0_225:
	s_waitcnt vmcnt(6)
	s_barrier
	v_mfma_f32_16x16x32_bf16 v[28:31], v[168:171], v[200:203], v[28:31]
	v_mfma_f32_16x16x32_bf16 v[28:31], v[172:175], v[204:207], v[28:31]
	v_mfma_f32_16x16x32_bf16 v[24:27], v[168:171], v[208:211], v[24:27]
	v_mfma_f32_16x16x32_bf16 v[24:27], v[172:175], v[212:215], v[24:27]
	v_mfma_f32_16x16x32_bf16 v[20:23], v[176:179], v[200:203], v[20:23]
	v_mfma_f32_16x16x32_bf16 v[20:23], v[180:183], v[204:207], v[20:23]
	v_mfma_f32_16x16x32_bf16 v[16:19], v[176:179], v[208:211], v[16:19]
	v_mfma_f32_16x16x32_bf16 v[16:19], v[180:183], v[212:215], v[16:19]
	v_mfma_f32_16x16x32_bf16 v[12:15], v[184:187], v[200:203], v[12:15]
	v_mfma_f32_16x16x32_bf16 v[12:15], v[188:191], v[204:207], v[12:15]
	v_mfma_f32_16x16x32_bf16 v[8:11], v[184:187], v[208:211], v[8:11]
	v_mfma_f32_16x16x32_bf16 v[8:11], v[188:191], v[212:215], v[8:11]
	v_mfma_f32_16x16x32_bf16 v[4:7], v[192:195], v[200:203], v[4:7]
	v_mfma_f32_16x16x32_bf16 v[4:7], v[196:199], v[204:207], v[4:7]
	v_mfma_f32_16x16x32_bf16 v[0:3], v[192:195], v[208:211], v[0:3]
	v_mfma_f32_16x16x32_bf16 v[0:3], v[196:199], v[212:215], v[0:3]
	s_barrier
.Lmy_rot_225:
	ds_read_b128 v[152:155], v148
	ds_read_b128 v[156:159], v149
	ds_read_b128 v[160:163], v150
	ds_read_b128 v[164:167], v151
	s_add_i32 s18, s41, s17
	s_add_i32 s19, s18, 0x80
	s_mov_b32 m0, s33
	ds_read_b128 v[168:171], v130
	ds_read_b128 v[172:175], v130 offset:1024
	ds_read_b128 v[176:179], v133
	ds_read_b128 v[180:183], v133 offset:1024
	ds_read_b128 v[184:187], v132
	ds_read_b128 v[188:191], v132 offset:1024
	ds_read_b128 v[192:195], v131
	ds_read_b128 v[196:199], v131 offset:1024
	buffer_load_dwordx4 v142, s[4:7], s19 offen lds
	s_mov_b32 m0, s34
	s_nop 0
	buffer_load_dwordx4 v143, s[4:7], s19 offen lds
	s_waitcnt lgkmcnt(8)
	s_barrier
	s_waitcnt lgkmcnt(0)
	v_mfma_f32_16x16x32_bf16 v[124:127], v[168:171], v[152:155], v[124:127]
	v_mfma_f32_16x16x32_bf16 v[124:127], v[172:175], v[156:159], v[124:127]
	v_mfma_f32_16x16x32_bf16 v[120:123], v[168:171], v[160:163], v[120:123]
	v_mfma_f32_16x16x32_bf16 v[120:123], v[172:175], v[164:167], v[120:123]
	v_mfma_f32_16x16x32_bf16 v[116:119], v[176:179], v[152:155], v[116:119]
	v_mfma_f32_16x16x32_bf16 v[116:119], v[180:183], v[156:159], v[116:119]
	v_mfma_f32_16x16x32_bf16 v[112:115], v[176:179], v[160:163], v[112:115]
	v_mfma_f32_16x16x32_bf16 v[112:115], v[180:183], v[164:167], v[112:115]
	v_mfma_f32_16x16x32_bf16 v[108:111], v[184:187], v[152:155], v[108:111]
	v_mfma_f32_16x16x32_bf16 v[108:111], v[188:191], v[156:159], v[108:111]
	v_mfma_f32_16x16x32_bf16 v[104:107], v[184:187], v[160:163], v[104:107]
	v_mfma_f32_16x16x32_bf16 v[104:107], v[188:191], v[164:167], v[104:107]
	v_mfma_f32_16x16x32_bf16 v[100:103], v[192:195], v[152:155], v[100:103]
	v_mfma_f32_16x16x32_bf16 v[100:103], v[196:199], v[156:159], v[100:103]
	v_mfma_f32_16x16x32_bf16 v[96:99], v[192:195], v[160:163], v[96:99]
	v_mfma_f32_16x16x32_bf16 v[96:99], v[196:199], v[164:167], v[96:99]
	s_barrier
	s_add_i32 s19, s43, s17
	s_add_i32 s47, s19, 0x100
	s_mov_b32 m0, s1
	ds_read_b128 v[200:203], v144
	ds_read_b128 v[204:207], v145
	ds_read_b128 v[208:211], v146
	ds_read_b128 v[212:215], v147
	buffer_load_dwordx4 v142, s[8:11], s47 offen lds
	s_mov_b32 m0, s3
	s_nop 0
	buffer_load_dwordx4 v143, s[8:11], s47 offen lds
	s_barrier
	s_waitcnt lgkmcnt(0)
	v_mfma_f32_16x16x32_bf16 v[92:95], v[168:171], v[200:203], v[92:95]
	v_mfma_f32_16x16x32_bf16 v[92:95], v[172:175], v[204:207], v[92:95]
	v_mfma_f32_16x16x32_bf16 v[88:91], v[168:171], v[208:211], v[88:91]
	v_mfma_f32_16x16x32_bf16 v[88:91], v[172:175], v[212:215], v[88:91]
	v_mfma_f32_16x16x32_bf16 v[84:87], v[176:179], v[200:203], v[84:87]
	v_mfma_f32_16x16x32_bf16 v[84:87], v[180:183], v[204:207], v[84:87]
	v_mfma_f32_16x16x32_bf16 v[80:83], v[176:179], v[208:211], v[80:83]
	v_mfma_f32_16x16x32_bf16 v[80:83], v[180:183], v[212:215], v[80:83]
	v_mfma_f32_16x16x32_bf16 v[76:79], v[184:187], v[200:203], v[76:79]
	v_mfma_f32_16x16x32_bf16 v[76:79], v[188:191], v[204:207], v[76:79]
	v_mfma_f32_16x16x32_bf16 v[72:75], v[184:187], v[208:211], v[72:75]
	v_mfma_f32_16x16x32_bf16 v[72:75], v[188:191], v[212:215], v[72:75]
	v_mfma_f32_16x16x32_bf16 v[68:71], v[192:195], v[200:203], v[68:71]
	v_mfma_f32_16x16x32_bf16 v[68:71], v[196:199], v[204:207], v[68:71]
	v_mfma_f32_16x16x32_bf16 v[64:67], v[192:195], v[208:211], v[64:67]
	v_mfma_f32_16x16x32_bf16 v[64:67], v[196:199], v[212:215], v[64:67]
	s_barrier
	s_add_i32 s47, s42, s17
	s_add_i32 s48, s47, 0x100
	s_mov_b32 m0, s0
	ds_read_b128 v[168:171], v130 offset:16384
	ds_read_b128 v[172:175], v130 offset:17408
	ds_read_b128 v[176:179], v133 offset:16384
	ds_read_b128 v[180:183], v133 offset:17408
	ds_read_b128 v[184:187], v132 offset:16384
	ds_read_b128 v[188:191], v132 offset:17408
	ds_read_b128 v[192:195], v131 offset:16384
	ds_read_b128 v[196:199], v131 offset:17408
	buffer_load_dwordx4 v142, s[4:7], s48 offen lds
	s_mov_b32 m0, s20
	s_nop 0
	buffer_load_dwordx4 v143, s[4:7], s48 offen lds
	s_barrier
	s_waitcnt lgkmcnt(0)
	v_mfma_f32_16x16x32_bf16 v[60:63], v[168:171], v[152:155], v[60:63]
	v_mfma_f32_16x16x32_bf16 v[60:63], v[172:175], v[156:159], v[60:63]
	v_mfma_f32_16x16x32_bf16 v[56:59], v[168:171], v[160:163], v[56:59]
	v_mfma_f32_16x16x32_bf16 v[56:59], v[172:175], v[164:167], v[56:59]
	v_mfma_f32_16x16x32_bf16 v[52:55], v[176:179], v[152:155], v[52:55]
	v_mfma_f32_16x16x32_bf16 v[52:55], v[180:183], v[156:159], v[52:55]
	v_mfma_f32_16x16x32_bf16 v[48:51], v[176:179], v[160:163], v[48:51]
	v_mfma_f32_16x16x32_bf16 v[48:51], v[180:183], v[164:167], v[48:51]
	v_mfma_f32_16x16x32_bf16 v[44:47], v[184:187], v[152:155], v[44:47]
	v_mfma_f32_16x16x32_bf16 v[44:47], v[188:191], v[156:159], v[44:47]
	v_mfma_f32_16x16x32_bf16 v[40:43], v[184:187], v[160:163], v[40:43]
	v_mfma_f32_16x16x32_bf16 v[40:43], v[188:191], v[164:167], v[40:43]
	v_mfma_f32_16x16x32_bf16 v[36:39], v[192:195], v[152:155], v[36:39]
	v_mfma_f32_16x16x32_bf16 v[36:39], v[196:199], v[156:159], v[36:39]
	v_mfma_f32_16x16x32_bf16 v[32:35], v[192:195], v[160:163], v[32:35]
	v_mfma_f32_16x16x32_bf16 v[32:35], v[196:199], v[164:167], v[32:35]
	s_barrier
; #define STAGE(P, RS, SOFF, OFF, kt) do { const int _so = (SOFF) + (kt) * (BK * 2); \
;     _Pragma("unroll") for (int _i = 0; _i < 2; ++_i) { \
;       __builtin_amdgcn_raw_ptr_buffer_load_lds(RS, (__attribute__((address_space(3))) void*)((P) + wave * 1024 + _i * 8192), 16, OFF[_i], _so, 0, 0); } } while (0)
; #define LDA(dst, b, h) _Pragma("unroll") for (int m = 0; m < 4; ++m) _Pragma("unroll") for (int k = 0; k < 2; ++k) \
;     dst[m][k] = *reinterpret_cast<const bf16x8*>(SA(b, h) + lds_byte(wr * 64 + m * 16 + fr, k * 32 + fq * 8))
; #define LDB(dst, b, h) _Pragma("unroll") for (int n = 0; n < 2; ++n) _Pragma("unroll") for (int k = 0; k < 2; ++k) \
;     dst[n][k] = *reinterpret_cast<const bf16x8*>(SB(b, h) + lds_byte(wc * 32 + n * 16 + fr, k * 32 + fq * 8))
; #define WAIT_V(n) asm volatile("s_waitcnt vmcnt(" #n ")" ::: "memory")
; #define WAIT_L(n) asm volatile("s_waitcnt lgkmcnt(" #n ")" ::: "memory")
; #define BAR __builtin_amdgcn_s_barrier()
; #define SCHED __builtin_amdgcn_sched_barrier(0)
;     ...
;       WAIT_V(6); BAR; MMA(1, 1, At, B1); BAR;
;       LDB(B0, 1, 0); SCHED; LDA(At, 1, 0); STAGE(SA(0, 1), rsA, sA1, offA, t + 2);
;       WAIT_L(8); BAR; WAIT_L(0); MMA(0, 0, At, B0); BAR; SCHED;
;       LDB(B1, 1, 1); STAGE(SB(1, 0), rsB, sB0, offB, t + 3);
;       BAR; WAIT_L(0); MMA(0, 1, At, B1); BAR;
;       LDA(At, 1, 1); STAGE(SA(1, 0), rsA, sA0, offA, t + 3);
;       BAR; WAIT_L(0); MMA(1, 0, At, B0); BAR; SCHED;
	s_add_i32 s48, s44, s17
	s_add_i32 s49, s48, 0x100
	s_mov_b32 m0, s21
	s_nop 0
	buffer_load_dwordx4 v142, s[8:11], s49 offen lds
	s_mov_b32 m0, s22
	s_nop 0
	buffer_load_dwordx4 v143, s[8:11], s49 offen lds
	s_waitcnt vmcnt(6)
	s_barrier
	v_mfma_f32_16x16x32_bf16 v[28:31], v[168:171], v[200:203], v[28:31]
	v_mfma_f32_16x16x32_bf16 v[28:31], v[172:175], v[204:207], v[28:31]
	v_mfma_f32_16x16x32_bf16 v[24:27], v[168:171], v[208:211], v[24:27]
	v_mfma_f32_16x16x32_bf16 v[24:27], v[172:175], v[212:215], v[24:27]
	v_mfma_f32_16x16x32_bf16 v[20:23], v[176:179], v[200:203], v[20:23]
	v_mfma_f32_16x16x32_bf16 v[20:23], v[180:183], v[204:207], v[20:23]
	v_mfma_f32_16x16x32_bf16 v[16:19], v[176:179], v[208:211], v[16:19]
	v_mfma_f32_16x16x32_bf16 v[16:19], v[180:183], v[212:215], v[16:19]
	v_mfma_f32_16x16x32_bf16 v[12:15], v[184:187], v[200:203], v[12:15]
	v_mfma_f32_16x16x32_bf16 v[12:15], v[188:191], v[204:207], v[12:15]
	v_mfma_f32_16x16x32_bf16 v[8:11], v[184:187], v[208:211], v[8:11]
	v_mfma_f32_16x16x32_bf16 v[8:11], v[188:191], v[212:215], v[8:11]
	v_mfma_f32_16x16x32_bf16 v[4:7], v[192:195], v[200:203], v[4:7]
	v_mfma_f32_16x16x32_bf16 v[4:7], v[196:199], v[204:207], v[4:7]
	v_mfma_f32_16x16x32_bf16 v[0:3], v[192:195], v[208:211], v[0:3]
	v_mfma_f32_16x16x32_bf16 v[0:3], v[196:199], v[212:215], v[0:3]
	s_barrier
	ds_read_b128 v[152:155], v138
	ds_read_b128 v[156:159], v139
	ds_read_b128 v[160:163], v140
	ds_read_b128 v[164:167], v141
	s_addk_i32 s18, 0x100
	s_mov_b32 m0, s23
	ds_read_b128 v[168:171], v130 offset:32768
	ds_read_b128 v[172:175], v130 offset:33792
	ds_read_b128 v[176:179], v133 offset:32768
	ds_read_b128 v[180:183], v133 offset:33792
	ds_read_b128 v[184:187], v132 offset:32768
	ds_read_b128 v[188:191], v132 offset:33792
	ds_read_b128 v[192:195], v131 offset:32768
	ds_read_b128 v[196:199], v131 offset:33792
	buffer_load_dwordx4 v142, s[4:7], s18 offen lds
	s_mov_b32 m0, s24
	s_nop 0
	buffer_load_dwordx4 v143, s[4:7], s18 offen lds
	s_waitcnt lgkmcnt(8)
	s_barrier
	s_waitcnt lgkmcnt(0)
	v_mfma_f32_16x16x32_bf16 v[124:127], v[168:171], v[152:155], v[124:127]
	v_mfma_f32_16x16x32_bf16 v[124:127], v[172:175], v[156:159], v[124:127]
	v_mfma_f32_16x16x32_bf16 v[120:123], v[168:171], v[160:163], v[120:123]
	v_mfma_f32_16x16x32_bf16 v[120:123], v[172:175], v[164:167], v[120:123]
	v_mfma_f32_16x16x32_bf16 v[116:119], v[176:179], v[152:155], v[116:119]
	v_mfma_f32_16x16x32_bf16 v[116:119], v[180:183], v[156:159], v[116:119]
	v_mfma_f32_16x16x32_bf16 v[112:115], v[176:179], v[160:163], v[112:115]
	v_mfma_f32_16x16x32_bf16 v[112:115], v[180:183], v[164:167], v[112:115]
	v_mfma_f32_16x16x32_bf16 v[108:111], v[184:187], v[152:155], v[108:111]
	v_mfma_f32_16x16x32_bf16 v[108:111], v[188:191], v[156:159], v[108:111]
	v_mfma_f32_16x16x32_bf16 v[104:107], v[184:187], v[160:163], v[104:107]
	v_mfma_f32_16x16x32_bf16 v[104:107], v[188:191], v[164:167], v[104:107]
	v_mfma_f32_16x16x32_bf16 v[100:103], v[192:195], v[152:155], v[100:103]
	v_mfma_f32_16x16x32_bf16 v[100:103], v[196:199], v[156:159], v[100:103]
	v_mfma_f32_16x16x32_bf16 v[96:99], v[192:195], v[160:163], v[96:99]
	v_mfma_f32_16x16x32_bf16 v[96:99], v[196:199], v[164:167], v[96:99]
	s_barrier
	s_addk_i32 s19, 0x180
	s_mov_b32 m0, s25
	ds_read_b128 v[200:203], v134
	ds_read_b128 v[204:207], v135
	ds_read_b128 v[208:211], v136
	ds_read_b128 v[212:215], v137
	buffer_load_dwordx4 v142, s[8:11], s19 offen lds
	s_mov_b32 m0, s26
	s_nop 0
	buffer_load_dwordx4 v143, s[8:11], s19 offen lds
	s_barrier
	s_waitcnt lgkmcnt(0)
	v_mfma_f32_16x16x32_bf16 v[92:95], v[168:171], v[200:203], v[92:95]
	v_mfma_f32_16x16x32_bf16 v[92:95], v[172:175], v[204:207], v[92:95]
	v_mfma_f32_16x16x32_bf16 v[88:91], v[168:171], v[208:211], v[88:91]
	v_mfma_f32_16x16x32_bf16 v[88:91], v[172:175], v[212:215], v[88:91]
	v_mfma_f32_16x16x32_bf16 v[84:87], v[176:179], v[200:203], v[84:87]
	v_mfma_f32_16x16x32_bf16 v[84:87], v[180:183], v[204:207], v[84:87]
	v_mfma_f32_16x16x32_bf16 v[80:83], v[176:179], v[208:211], v[80:83]
	v_mfma_f32_16x16x32_bf16 v[80:83], v[180:183], v[212:215], v[80:83]
	v_mfma_f32_16x16x32_bf16 v[76:79], v[184:187], v[200:203], v[76:79]
	v_mfma_f32_16x16x32_bf16 v[76:79], v[188:191], v[204:207], v[76:79]
	v_mfma_f32_16x16x32_bf16 v[72:75], v[184:187], v[208:211], v[72:75]
	v_mfma_f32_16x16x32_bf16 v[72:75], v[188:191], v[212:215], v[72:75]
	v_mfma_f32_16x16x32_bf16 v[68:71], v[192:195], v[200:203], v[68:71]
	v_mfma_f32_16x16x32_bf16 v[68:71], v[196:199], v[204:207], v[68:71]
	v_mfma_f32_16x16x32_bf16 v[64:67], v[192:195], v[208:211], v[64:67]
	v_mfma_f32_16x16x32_bf16 v[64:67], v[196:199], v[212:215], v[64:67]
	s_barrier
	s_addk_i32 s47, 0x180
	s_mov_b32 m0, s27
	ds_read_b128 v[168:171], v130 offset:49152
	ds_read_b128 v[172:175], v130 offset:50176
	ds_read_b128 v[176:179], v133 offset:49152
	ds_read_b128 v[180:183], v133 offset:50176
	ds_read_b128 v[184:187], v132 offset:49152
	ds_read_b128 v[188:191], v132 offset:50176
	ds_read_b128 v[192:195], v131 offset:49152
	ds_read_b128 v[196:199], v131 offset:50176
	buffer_load_dwordx4 v142, s[4:7], s47 offen lds
	s_mov_b32 m0, s28
	s_nop 0
	buffer_load_dwordx4 v143, s[4:7], s47 offen lds
	s_barrier
; #define STAGE(P, RS, SOFF, OFF, kt) do { const int _so = (SOFF) + (kt) * (BK * 2); \
;     _Pragma("unroll") for (int _i = 0; _i < 2; ++_i) { \
;       __builtin_amdgcn_raw_ptr_buffer_load_lds(RS, (__attribute__((address_space(3))) void*)((P) + wave * 1024 + _i * 8192), 16, OFF[_i], _so, 0, 0); } } while (0)
; #define LDA(dst, b, h) _Pragma("unroll") for (int m = 0; m < 4; ++m) _Pragma("unroll") for (int k = 0; k < 2; ++k) \
;     dst[m][k] = *reinterpret_cast<const bf16x8*>(SA(b, h) + lds_byte(wr * 64 + m * 16 + fr, k * 32 + fq * 8))
; #define LDB(dst, b, h) _Pragma("unroll") for (int n = 0; n < 2; ++n) _Pragma("unroll") for (int k = 0; k < 2; ++k) \
;     dst[n][k] = *reinterpret_cast<const bf16x8*>(SB(b, h) + lds_byte(wc * 32 + n * 16 + fr, k * 32 + fq * 8))
; #define WAIT_V(n) asm volatile("s_waitcnt vmcnt(" #n ")" ::: "memory")
; #define WAIT_L(n) asm volatile("s_waitcnt lgkmcnt(" #n ")" ::: "memory")
; #define BAR __builtin_amdgcn_s_barrier()
; #define SCHED __builtin_amdgcn_sched_barrier(0)
;     ...
;       BAR; WAIT_L(0); MMA(1, 0, At, B0); BAR; SCHED;
;       STAGE(SB(1, 1), rsB, sB1, offB, t + 3);
;       WAIT_V(6); BAR; MMA(1, 1, At, B1); BAR;
;     }
;     { LDB(B0, 0, 0); LDA(At, 0, 0); STAGE(SA(1, 1), rsA, sA1, offA, nt - 1);
;       BAR; WAIT_L(0); MMA(0, 0, At, B0); BAR;
;       LDB(B1, 0, 1); BAR; WAIT_L(0); MMA(0, 1, At, B1); BAR;
;       LDA(At, 0, 1); WAIT_V(4); BAR; WAIT_L(0); MMA(1, 0, At, B0); MMA(1, 1, At, B1); BAR; }
	s_waitcnt lgkmcnt(0)
	v_mfma_f32_16x16x32_bf16 v[60:63], v[168:171], v[152:155], v[60:63]
	v_mfma_f32_16x16x32_bf16 v[60:63], v[172:175], v[156:159], v[60:63]
	v_mfma_f32_16x16x32_bf16 v[56:59], v[168:171], v[160:163], v[56:59]
	v_mfma_f32_16x16x32_bf16 v[56:59], v[172:175], v[164:167], v[56:59]
	v_mfma_f32_16x16x32_bf16 v[52:55], v[176:179], v[152:155], v[52:55]
	v_mfma_f32_16x16x32_bf16 v[52:55], v[180:183], v[156:159], v[52:55]
	v_mfma_f32_16x16x32_bf16 v[48:51], v[176:179], v[160:163], v[48:51]
	v_mfma_f32_16x16x32_bf16 v[48:51], v[180:183], v[164:167], v[48:51]
	v_mfma_f32_16x16x32_bf16 v[44:47], v[184:187], v[152:155], v[44:47]
	v_mfma_f32_16x16x32_bf16 v[44:47], v[188:191], v[156:159], v[44:47]
	v_mfma_f32_16x16x32_bf16 v[40:43], v[184:187], v[160:163], v[40:43]
	v_mfma_f32_16x16x32_bf16 v[40:43], v[188:191], v[164:167], v[40:43]
	v_mfma_f32_16x16x32_bf16 v[36:39], v[192:195], v[152:155], v[36:39]
	v_mfma_f32_16x16x32_bf16 v[36:39], v[196:199], v[156:159], v[36:39]
	v_mfma_f32_16x16x32_bf16 v[32:35], v[192:195], v[160:163], v[32:35]
	v_mfma_f32_16x16x32_bf16 v[32:35], v[196:199], v[164:167], v[32:35]
	s_barrier
	s_addk_i32 s48, 0x180
	s_mov_b32 m0, s29
	s_nop 0
	buffer_load_dwordx4 v142, s[8:11], s48 offen lds
	s_mov_b32 m0, s30
	s_nop 0
	buffer_load_dwordx4 v143, s[8:11], s48 offen lds
	s_add_i32 s16, s16, 2
	s_addk_i32 s17, 0x100
	s_cmp_gt_u32 s16, 27
	s_cbranch_scc0 .LBB0_225
	s_waitcnt vmcnt(6)
	s_barrier
	v_mfma_f32_16x16x32_bf16 v[28:31], v[168:171], v[200:203], v[28:31]
	v_mfma_f32_16x16x32_bf16 v[28:31], v[172:175], v[204:207], v[28:31]
	v_mfma_f32_16x16x32_bf16 v[24:27], v[168:171], v[208:211], v[24:27]
	v_mfma_f32_16x16x32_bf16 v[24:27], v[172:175], v[212:215], v[24:27]
	v_mfma_f32_16x16x32_bf16 v[20:23], v[176:179], v[200:203], v[20:23]
	v_mfma_f32_16x16x32_bf16 v[20:23], v[180:183], v[204:207], v[20:23]
	v_mfma_f32_16x16x32_bf16 v[16:19], v[176:179], v[208:211], v[16:19]
	v_mfma_f32_16x16x32_bf16 v[16:19], v[180:183], v[212:215], v[16:19]
	v_mfma_f32_16x16x32_bf16 v[12:15], v[184:187], v[200:203], v[12:15]
	v_mfma_f32_16x16x32_bf16 v[12:15], v[188:191], v[204:207], v[12:15]
	v_mfma_f32_16x16x32_bf16 v[8:11], v[184:187], v[208:211], v[8:11]
	v_mfma_f32_16x16x32_bf16 v[8:11], v[188:191], v[212:215], v[8:11]
	v_mfma_f32_16x16x32_bf16 v[4:7], v[192:195], v[200:203], v[4:7]
	v_mfma_f32_16x16x32_bf16 v[4:7], v[196:199], v[204:207], v[4:7]
	v_mfma_f32_16x16x32_bf16 v[0:3], v[192:195], v[208:211], v[0:3]
	v_mfma_f32_16x16x32_bf16 v[0:3], v[196:199], v[212:215], v[0:3]
	s_barrier
	s_add_i32 s16, s41, 0xf80
	s_mov_b32 m0, s33
	ds_read_b128 v[152:155], v148
	ds_read_b128 v[156:159], v149
	ds_read_b128 v[160:163], v150
	ds_read_b128 v[148:151], v151
	ds_read_b128 v[164:167], v130
	ds_read_b128 v[168:171], v130 offset:1024
	ds_read_b128 v[172:175], v133
	ds_read_b128 v[176:179], v133 offset:1024
	ds_read_b128 v[180:183], v132
	ds_read_b128 v[184:187], v132 offset:1024
	ds_read_b128 v[188:191], v131
	ds_read_b128 v[192:195], v131 offset:1024
	buffer_load_dwordx4 v142, s[4:7], s16 offen lds
	s_mov_b32 m0, s34
	s_nop 0
	buffer_load_dwordx4 v143, s[4:7], s16 offen lds
	s_barrier
	s_waitcnt lgkmcnt(0)
	v_mfma_f32_16x16x32_bf16 v[124:127], v[164:167], v[152:155], v[124:127]
	v_mfma_f32_16x16x32_bf16 v[124:127], v[168:171], v[156:159], v[124:127]
	v_mfma_f32_16x16x32_bf16 v[120:123], v[164:167], v[160:163], v[120:123]
	v_mfma_f32_16x16x32_bf16 v[120:123], v[168:171], v[148:151], v[120:123]
	v_mfma_f32_16x16x32_bf16 v[116:119], v[172:175], v[152:155], v[116:119]
	v_mfma_f32_16x16x32_bf16 v[116:119], v[176:179], v[156:159], v[116:119]
	v_mfma_f32_16x16x32_bf16 v[112:115], v[172:175], v[160:163], v[112:115]
	v_mfma_f32_16x16x32_bf16 v[112:115], v[176:179], v[148:151], v[112:115]
	v_mfma_f32_16x16x32_bf16 v[108:111], v[180:183], v[152:155], v[108:111]
	v_mfma_f32_16x16x32_bf16 v[108:111], v[184:187], v[156:159], v[108:111]
	v_mfma_f32_16x16x32_bf16 v[104:107], v[180:183], v[160:163], v[104:107]
	v_mfma_f32_16x16x32_bf16 v[104:107], v[184:187], v[148:151], v[104:107]
	v_mfma_f32_16x16x32_bf16 v[100:103], v[188:191], v[152:155], v[100:103]
	v_mfma_f32_16x16x32_bf16 v[100:103], v[192:195], v[156:159], v[100:103]
	v_mfma_f32_16x16x32_bf16 v[96:99], v[188:191], v[160:163], v[96:99]
	v_mfma_f32_16x16x32_bf16 v[96:99], v[192:195], v[148:151], v[96:99]
	s_barrier
	ds_read_b128 v[196:199], v144
	ds_read_b128 v[142:145], v145
	ds_read_b128 v[200:203], v146
	ds_read_b128 v[204:207], v147
	s_barrier
	s_waitcnt lgkmcnt(0)
	v_mfma_f32_16x16x32_bf16 v[88:91], v[164:167], v[200:203], v[88:91]
	v_mfma_f32_16x16x32_bf16 v[84:87], v[172:175], v[196:199], v[84:87]
	v_mfma_f32_16x16x32_bf16 v[80:83], v[172:175], v[200:203], v[80:83]
	v_mfma_f32_16x16x32_bf16 v[76:79], v[180:183], v[196:199], v[76:79]
	v_mfma_f32_16x16x32_bf16 v[72:75], v[180:183], v[200:203], v[72:75]
	v_mfma_f32_16x16x32_bf16 v[68:71], v[188:191], v[196:199], v[68:71]
	v_mfma_f32_16x16x32_bf16 v[64:67], v[188:191], v[200:203], v[64:67]
	v_mfma_f32_16x16x32_bf16 v[92:95], v[164:167], v[196:199], v[92:95]
	v_mfma_f32_16x16x32_bf16 v[88:91], v[168:171], v[204:207], v[88:91]
	v_mfma_f32_16x16x32_bf16 v[84:87], v[176:179], v[142:145], v[84:87]
	v_mfma_f32_16x16x32_bf16 v[80:83], v[176:179], v[204:207], v[80:83]
	v_mfma_f32_16x16x32_bf16 v[76:79], v[184:187], v[142:145], v[76:79]
	v_mfma_f32_16x16x32_bf16 v[72:75], v[184:187], v[204:207], v[72:75]
	v_mfma_f32_16x16x32_bf16 v[68:71], v[192:195], v[142:145], v[68:71]
	v_mfma_f32_16x16x32_bf16 v[64:67], v[192:195], v[204:207], v[64:67]
	v_mfma_f32_16x16x32_bf16 v[164:167], v[168:171], v[142:145], v[92:95]
	s_barrier
; #define LDA(dst, b, h) _Pragma("unroll") for (int m = 0; m < 4; ++m) _Pragma("unroll") for (int k = 0; k < 2; ++k) \
;     dst[m][k] = *reinterpret_cast<const bf16x8*>(SA(b, h) + lds_byte(wr * 64 + m * 16 + fr, k * 32 + fq * 8))
; #define LDB(dst, b, h) _Pragma("unroll") for (int n = 0; n < 2; ++n) _Pragma("unroll") for (int k = 0; k < 2; ++k) \
;     dst[n][k] = *reinterpret_cast<const bf16x8*>(SB(b, h) + lds_byte(wc * 32 + n * 16 + fr, k * 32 + fq * 8))
; #define WAIT_V(n) asm volatile("s_waitcnt vmcnt(" #n ")" ::: "memory")
; #define WAIT_L(n) asm volatile("s_waitcnt lgkmcnt(" #n ")" ::: "memory")
; #define BAR __builtin_amdgcn_s_barrier()
;     ...
;       BAR; WAIT_L(0); MMA(0, 0, At, B0); BAR;
;       LDB(B1, 0, 1); BAR; WAIT_L(0); MMA(0, 1, At, B1); BAR;
;       LDA(At, 0, 1); WAIT_V(4); BAR; WAIT_L(0); MMA(1, 0, At, B0); MMA(1, 1, At, B1); BAR; }
;     { LDB(B0, 1, 0); LDA(At, 1, 0); WAIT_V(2); BAR; WAIT_L(0); MMA(0, 0, At, B0); BAR;
	s_nop 0
	ds_read_b128 v[92:95], v130 offset:16384
	ds_read_b128 v[168:171], v130 offset:17408
	ds_read_b128 v[172:175], v133 offset:16384
	ds_read_b128 v[176:179], v133 offset:17408
	ds_read_b128 v[180:183], v132 offset:16384
	ds_read_b128 v[184:187], v132 offset:17408
	ds_read_b128 v[188:191], v131 offset:16384
	ds_read_b128 v[192:195], v131 offset:17408
	s_waitcnt vmcnt(4)
	s_barrier
	s_waitcnt lgkmcnt(0)
	v_mfma_f32_16x16x32_bf16 v[60:63], v[92:95], v[152:155], v[60:63]
	v_mfma_f32_16x16x32_bf16 v[60:63], v[168:171], v[156:159], v[60:63]
	v_mfma_f32_16x16x32_bf16 v[56:59], v[92:95], v[160:163], v[56:59]
	v_mfma_f32_16x16x32_bf16 v[56:59], v[168:171], v[148:151], v[56:59]
	v_mfma_f32_16x16x32_bf16 v[52:55], v[172:175], v[152:155], v[52:55]
	v_mfma_f32_16x16x32_bf16 v[52:55], v[176:179], v[156:159], v[52:55]
	v_mfma_f32_16x16x32_bf16 v[48:51], v[172:175], v[160:163], v[48:51]
	v_mfma_f32_16x16x32_bf16 v[48:51], v[176:179], v[148:151], v[48:51]
	v_mfma_f32_16x16x32_bf16 v[44:47], v[180:183], v[152:155], v[44:47]
	v_mfma_f32_16x16x32_bf16 v[44:47], v[184:187], v[156:159], v[44:47]
	v_mfma_f32_16x16x32_bf16 v[40:43], v[180:183], v[160:163], v[40:43]
	v_mfma_f32_16x16x32_bf16 v[40:43], v[184:187], v[148:151], v[40:43]
	v_mfma_f32_16x16x32_bf16 v[36:39], v[188:191], v[152:155], v[36:39]
	v_mfma_f32_16x16x32_bf16 v[36:39], v[192:195], v[156:159], v[36:39]
	v_mfma_f32_16x16x32_bf16 v[32:35], v[188:191], v[160:163], v[32:35]
	v_mfma_f32_16x16x32_bf16 v[32:35], v[192:195], v[148:151], v[32:35]
	v_mfma_f32_16x16x32_bf16 v[28:31], v[92:95], v[196:199], v[28:31]
	v_mfma_f32_16x16x32_bf16 v[28:31], v[168:171], v[142:145], v[28:31]
	v_mfma_f32_16x16x32_bf16 v[24:27], v[92:95], v[200:203], v[24:27]
	v_mfma_f32_16x16x32_bf16 v[24:27], v[168:171], v[204:207], v[24:27]
	v_mfma_f32_16x16x32_bf16 v[20:23], v[172:175], v[196:199], v[20:23]
	v_mfma_f32_16x16x32_bf16 v[20:23], v[176:179], v[142:145], v[20:23]
	v_mfma_f32_16x16x32_bf16 v[16:19], v[172:175], v[200:203], v[16:19]
	v_mfma_f32_16x16x32_bf16 v[16:19], v[176:179], v[204:207], v[16:19]
	v_mfma_f32_16x16x32_bf16 v[12:15], v[180:183], v[196:199], v[12:15]
	v_mfma_f32_16x16x32_bf16 v[12:15], v[184:187], v[142:145], v[12:15]
	v_mfma_f32_16x16x32_bf16 v[8:11], v[180:183], v[200:203], v[8:11]
	v_mfma_f32_16x16x32_bf16 v[8:11], v[184:187], v[204:207], v[8:11]
	v_mfma_f32_16x16x32_bf16 v[4:7], v[188:191], v[196:199], v[4:7]
	v_mfma_f32_16x16x32_bf16 v[4:7], v[192:195], v[142:145], v[4:7]
	v_mfma_f32_16x16x32_bf16 v[0:3], v[188:191], v[200:203], v[0:3]
	v_mfma_f32_16x16x32_bf16 v[0:3], v[192:195], v[204:207], v[0:3]
	s_barrier
	ds_read_b128 v[142:145], v138
	ds_read_b128 v[146:149], v139
	ds_read_b128 v[150:153], v140
	ds_read_b128 v[138:141], v141
	ds_read_b128 v[154:157], v130 offset:32768
	ds_read_b128 v[158:161], v130 offset:33792
	ds_read_b128 v[168:171], v133 offset:32768
	ds_read_b128 v[172:175], v133 offset:33792
	ds_read_b128 v[176:179], v132 offset:32768
	ds_read_b128 v[180:183], v132 offset:33792
	ds_read_b128 v[184:187], v131 offset:32768
	ds_read_b128 v[188:191], v131 offset:33792
	s_waitcnt vmcnt(2)
	s_barrier
	s_waitcnt lgkmcnt(0)
	v_mfma_f32_16x16x32_bf16 v[92:95], v[154:157], v[142:145], v[124:127]
	v_mfma_f32_16x16x32_bf16 v[120:123], v[154:157], v[150:153], v[120:123]
	v_mfma_f32_16x16x32_bf16 v[116:119], v[168:171], v[142:145], v[116:119]
	v_mfma_f32_16x16x32_bf16 v[112:115], v[168:171], v[150:153], v[112:115]
	v_mfma_f32_16x16x32_bf16 v[108:111], v[176:179], v[142:145], v[108:111]
	v_mfma_f32_16x16x32_bf16 v[104:107], v[176:179], v[150:153], v[104:107]
	v_mfma_f32_16x16x32_bf16 v[100:103], v[184:187], v[142:145], v[100:103]
	v_mfma_f32_16x16x32_bf16 v[96:99], v[184:187], v[150:153], v[96:99]
	v_mfma_f32_16x16x32_bf16 v[124:127], v[158:161], v[146:149], v[92:95]
	v_mfma_f32_16x16x32_bf16 v[120:123], v[158:161], v[138:141], v[120:123]
	v_mfma_f32_16x16x32_bf16 v[116:119], v[172:175], v[146:149], v[116:119]
	v_mfma_f32_16x16x32_bf16 v[112:115], v[172:175], v[138:141], v[112:115]
	v_mfma_f32_16x16x32_bf16 v[108:111], v[180:183], v[146:149], v[108:111]
	v_mfma_f32_16x16x32_bf16 v[104:107], v[180:183], v[138:141], v[104:107]
	v_mfma_f32_16x16x32_bf16 v[100:103], v[188:191], v[146:149], v[100:103]
	v_mfma_f32_16x16x32_bf16 v[92:95], v[188:191], v[138:141], v[96:99]
	s_barrier
; #define LDA(dst, b, h) _Pragma("unroll") for (int m = 0; m < 4; ++m) _Pragma("unroll") for (int k = 0; k < 2; ++k) \
;     dst[m][k] = *reinterpret_cast<const bf16x8*>(SA(b, h) + lds_byte(wr * 64 + m * 16 + fr, k * 32 + fq * 8))
; #define LDB(dst, b, h) _Pragma("unroll") for (int n = 0; n < 2; ++n) _Pragma("unroll") for (int k = 0; k < 2; ++k) \
;     dst[n][k] = *reinterpret_cast<const bf16x8*>(SB(b, h) + lds_byte(wc * 32 + n * 16 + fr, k * 32 + fq * 8))
; #define WAIT_V(n) asm volatile("s_waitcnt vmcnt(" #n ")" ::: "memory")
; #define WAIT_L(n) asm volatile("s_waitcnt lgkmcnt(" #n ")" ::: "memory")
; #define BAR __builtin_amdgcn_s_barrier()
;     ...
;     { LDB(B0, 1, 0); LDA(At, 1, 0); WAIT_V(2); BAR; WAIT_L(0); MMA(0, 0, At, B0); BAR;
;       LDB(B1, 1, 1); WAIT_V(0); BAR; WAIT_L(0); MMA(0, 1, At, B1); BAR;
;       LDA(At, 1, 1); BAR; WAIT_L(0); MMA(1, 0, At, B0); MMA(1, 1, At, B1); BAR; }
;     if (wr == 0) BAR;
	ds_read_b128 v[192:195], v134
	ds_read_b128 v[196:199], v135
	ds_read_b128 v[200:203], v136
	ds_read_b128 v[134:137], v137
	s_waitcnt vmcnt(0)
	s_barrier
	s_waitcnt lgkmcnt(0)
	v_mfma_f32_16x16x32_bf16 v[96:99], v[154:157], v[192:195], v[164:167]
	v_mfma_f32_16x16x32_bf16 v[88:91], v[154:157], v[200:203], v[88:91]
	v_mfma_f32_16x16x32_bf16 v[84:87], v[168:171], v[192:195], v[84:87]
	v_mfma_f32_16x16x32_bf16 v[80:83], v[168:171], v[200:203], v[80:83]
	v_mfma_f32_16x16x32_bf16 v[76:79], v[176:179], v[192:195], v[76:79]
	v_mfma_f32_16x16x32_bf16 v[72:75], v[176:179], v[200:203], v[72:75]
	v_mfma_f32_16x16x32_bf16 v[68:71], v[184:187], v[192:195], v[68:71]
	v_mfma_f32_16x16x32_bf16 v[64:67], v[184:187], v[200:203], v[64:67]
	v_mfma_f32_16x16x32_bf16 v[96:99], v[158:161], v[196:199], v[96:99]
	v_mfma_f32_16x16x32_bf16 v[88:91], v[158:161], v[134:137], v[88:91]
	v_mfma_f32_16x16x32_bf16 v[84:87], v[172:175], v[196:199], v[84:87]
	v_mfma_f32_16x16x32_bf16 v[80:83], v[172:175], v[134:137], v[80:83]
	v_mfma_f32_16x16x32_bf16 v[76:79], v[180:183], v[196:199], v[76:79]
	v_mfma_f32_16x16x32_bf16 v[72:75], v[180:183], v[134:137], v[72:75]
	v_mfma_f32_16x16x32_bf16 v[68:71], v[188:191], v[196:199], v[68:71]
	v_mfma_f32_16x16x32_bf16 v[64:67], v[188:191], v[134:137], v[64:67]
	s_barrier
	ds_read_b128 v[154:157], v130 offset:49152
	ds_read_b128 v[158:161], v130 offset:50176
	ds_read_b128 v[162:165], v133 offset:49152
	ds_read_b128 v[166:169], v133 offset:50176
	ds_read_b128 v[170:173], v132 offset:49152
	ds_read_b128 v[174:177], v132 offset:50176
	ds_read_b128 v[178:181], v131 offset:49152
	ds_read_b128 v[130:133], v131 offset:50176
	s_barrier
	s_waitcnt lgkmcnt(0)
	v_mfma_f32_16x16x32_bf16 v[60:63], v[154:157], v[142:145], v[60:63]
	v_mfma_f32_16x16x32_bf16 v[60:63], v[158:161], v[146:149], v[60:63]
	v_mfma_f32_16x16x32_bf16 v[56:59], v[154:157], v[150:153], v[56:59]
	v_mfma_f32_16x16x32_bf16 v[56:59], v[158:161], v[138:141], v[56:59]
	v_mfma_f32_16x16x32_bf16 v[52:55], v[162:165], v[142:145], v[52:55]
	v_mfma_f32_16x16x32_bf16 v[52:55], v[166:169], v[146:149], v[52:55]
	v_mfma_f32_16x16x32_bf16 v[48:51], v[162:165], v[150:153], v[48:51]
	v_mfma_f32_16x16x32_bf16 v[48:51], v[166:169], v[138:141], v[48:51]
	v_mfma_f32_16x16x32_bf16 v[44:47], v[170:173], v[142:145], v[44:47]
	v_mfma_f32_16x16x32_bf16 v[44:47], v[174:177], v[146:149], v[44:47]
	v_mfma_f32_16x16x32_bf16 v[40:43], v[170:173], v[150:153], v[40:43]
	v_mfma_f32_16x16x32_bf16 v[40:43], v[174:177], v[138:141], v[40:43]
	v_mfma_f32_16x16x32_bf16 v[36:39], v[178:181], v[142:145], v[36:39]
	v_mfma_f32_16x16x32_bf16 v[36:39], v[130:133], v[146:149], v[36:39]
	v_mfma_f32_16x16x32_bf16 v[32:35], v[178:181], v[150:153], v[32:35]
	v_mfma_f32_16x16x32_bf16 v[32:35], v[130:133], v[138:141], v[32:35]
	v_mfma_f32_16x16x32_bf16 v[28:31], v[154:157], v[192:195], v[28:31]
	v_mfma_f32_16x16x32_bf16 v[28:31], v[158:161], v[196:199], v[28:31]
	v_mfma_f32_16x16x32_bf16 v[24:27], v[154:157], v[200:203], v[24:27]
	v_mfma_f32_16x16x32_bf16 v[24:27], v[158:161], v[134:137], v[24:27]
	v_mfma_f32_16x16x32_bf16 v[20:23], v[162:165], v[192:195], v[20:23]
	v_mfma_f32_16x16x32_bf16 v[20:23], v[166:169], v[196:199], v[20:23]
	v_mfma_f32_16x16x32_bf16 v[16:19], v[162:165], v[200:203], v[16:19]
	v_mfma_f32_16x16x32_bf16 v[16:19], v[166:169], v[134:137], v[16:19]
	v_mfma_f32_16x16x32_bf16 v[12:15], v[170:173], v[192:195], v[12:15]
	v_mfma_f32_16x16x32_bf16 v[12:15], v[174:177], v[196:199], v[12:15]
	v_mfma_f32_16x16x32_bf16 v[8:11], v[170:173], v[200:203], v[8:11]
	v_mfma_f32_16x16x32_bf16 v[8:11], v[174:177], v[134:137], v[8:11]
	v_mfma_f32_16x16x32_bf16 v[4:7], v[178:181], v[192:195], v[4:7]
	v_mfma_f32_16x16x32_bf16 v[4:7], v[130:133], v[196:199], v[4:7]
	v_mfma_f32_16x16x32_bf16 v[0:3], v[178:181], v[200:203], v[0:3]
	v_mfma_f32_16x16x32_bf16 v[0:3], v[130:133], v[134:137], v[0:3]
	v_cmp_gt_u32_e32 vcc, s37, v129
	s_barrier
	s_and_saveexec_b64 s[16:17], vcc
	s_cbranch_execz .LBB0_228
	s_barrier

; #define WAIT_V(n) asm volatile("s_waitcnt vmcnt(" #n ")" ::: "memory")
; #define BAR __builtin_amdgcn_s_barrier()
;     ...
;     const int tid = opaque_tid(wave);
;     const int wid = tid >> 6, lane = tid & 63, wr = wid >> 2, wc = wid & 3, fr = lane & 15, fq = lane >> 4;
;     int offA[2], offB[2];
;     _Pragma("unroll") for (int i = 0; i < 2; ++i) {
;       int r, c; stage_rc(tid * 16 + i * 8192, r, c);
;       offA[i] = (r * lda + c) * 2; offB[i] = (r * ldb + c) * 2;
;     }
;     const int brow = pm * BM;
;     f32x4 acc[2][2][4][2];
;     _Pragma("unroll") for (int a = 0; a < 2; ++a) _Pragma("unroll") for (int b = 0; b < 2; ++b) _Pragma("unroll") for (int m = 0; m < 4; ++m) _Pragma("unroll") for (int n = 0; n < 2; ++n)
;       acc[a][b][m][n] = f32x4{0.f, 0.f, 0.f, 0.f};
;     bf16x8 At[4][2], B0[2][2], B1[2][2];
;     if (wr == 1) BAR;
;     if (first_tile) { WAIT_V(0); }
;     else if constexpr (mode == MODE_RESID_LN) { WAIT_V(0); }
;     else if constexpr (mode == MODE_SWIGLU) { WAIT_V(6); }
;     else if constexpr (mode == MODE_V) { WAIT_V(24); }
;     else { WAIT_V(12); }
;     first_tile = false;
;     BAR;
;     BAR;
.LBB0_290:
	v_bfe_i32 v4, v128, 27, 1
	v_lshlrev_b32_e32 v2, 4, v128
	v_lshrrev_b32_e32 v4, 22, v4
	v_add_u32_e32 v4, v2, v4
	v_and_b32_e32 v4, 0xfffffc00, v4
	v_sub_u32_e32 v4, v2, v4
	v_lshrrev_b32_e32 v5, 4, v4
	v_bitop3_b32 v4, v5, v4, 32 bitop3:0x6c
	v_ashrrev_i32_e32 v3, 31, v128
	v_ashrrev_i32_e32 v6, 31, v4
	v_lshrrev_b32_e32 v3, 26, v3
	v_lshrrev_b32_e32 v6, 26, v6
	v_add_u32_e32 v3, v128, v3
	v_add_u32_e32 v6, v4, v6
	v_ashrrev_i32_e32 v3, 6, v3
	v_lshrrev_b32_e32 v7, 6, v6
	v_and_b32_e32 v6, 0xc0, v6
	v_lshlrev_b32_e32 v5, 3, v3
	v_lshlrev_b32_e32 v3, 5, v3
	v_sub_u32_e32 v4, v4, v6
	v_and_b32_e32 v5, 0x1ffff0, v5
	v_and_b32_e32 v3, 32, v3
	v_ashrrev_i16_sdwa v4, v216, sext(v4) dst_sel:DWORD dst_unused:UNUSED_PAD src0_sel:DWORD src1_sel:BYTE_0
	v_add_u32_sdwa v3, v3, sext(v4) dst_sel:DWORD dst_unused:UNUSED_PAD src0_sel:DWORD src1_sel:WORD_0
	v_add_lshl_u32 v4, v7, v5, 11
	v_add_u32_e32 v2, 0x2000, v2
	v_lshl_add_u32 v141, v3, 1, v4
	v_ashrrev_i32_e32 v3, 31, v2
	v_lshrrev_b32_e32 v3, 22, v3
	v_add_u32_e32 v3, v2, v3
	v_ashrrev_i32_e32 v3, 10, v3
	v_mul_i32_i24_e32 v4, 0x400, v3
	v_sub_u32_e32 v2, v2, v4
	v_lshrrev_b32_e32 v4, 4, v2
	v_bitop3_b32 v2, v4, v2, 32 bitop3:0x6c
	v_ashrrev_i32_e32 v5, 31, v2
	v_lshrrev_b32_e32 v5, 26, v5
	v_add_u32_e32 v5, v2, v5
	v_lshrrev_b32_e32 v6, 6, v5
	v_and_b32_e32 v5, 0xc0, v5
	v_lshlrev_b32_e32 v4, 3, v3
	v_lshlrev_b32_e32 v3, 5, v3
	v_sub_u32_e32 v2, v2, v5
	v_and_b32_e32 v4, 0x1ffff0, v4
	v_and_b32_e32 v3, 32, v3
	v_ashrrev_i16_sdwa v2, v216, sext(v2) dst_sel:DWORD dst_unused:UNUSED_PAD src0_sel:DWORD src1_sel:BYTE_0
	v_add_u32_sdwa v2, v3, sext(v2) dst_sel:DWORD dst_unused:UNUSED_PAD src0_sel:DWORD src1_sel:WORD_0
	v_add_lshl_u32 v3, v6, v4, 11
	v_lshl_add_u32 v142, v2, 1, v3
	v_and_b32_e32 v3, 15, v0
	v_lshlrev_b32_e32 v5, 2, v0
	v_and_b32_e32 v2, 48, v0
	v_lshlrev_b32_e32 v3, 6, v3
	v_and_b32_e32 v5, 32, v5
	v_or_b32_e32 v4, v3, v2
	v_bitop3_b32 v3, v3, v5, v2 bitop3:0x36
	v_lshlrev_b32_e32 v6, 6, v128
	s_movk_i32 s1, 0x3000
	v_and_or_b32 v3, v6, s1, v3
	v_lshlrev_b32_e32 v0, 6, v0
	s_movk_i32 s1, 0x3c0
	v_lshlrev_b32_e32 v1, 13, v1
	v_and_or_b32 v0, v0, s1, v2
	v_bitop3_b32 v0, v1, v0, v5 bitop3:0xf6
	v_or_b32_e32 v6, 0x400, v3
	v_or_b32_e32 v7, 0x800, v3
	v_or_b32_e32 v8, 0xc00, v3
	v_or_b32_e32 v132, 0x800, v0
	v_or_b32_e32 v131, 0x1000, v0
	v_or_b32_e32 v130, 0x1800, v0
	v_mov_b32_e32 v0, 0
	v_bitop3_b32 v129, v4, v1, v5 bitop3:0xde
	s_mov_b32 s1, -2
	s_mov_b32 s3, 0
	v_or_b32_e32 v147, 0x10000, v3
	v_or_b32_e32 v148, 0x10000, v6
	v_or_b32_e32 v149, 0x10000, v7
	v_or_b32_e32 v150, 0x10000, v8
	v_or_b32_e32 v143, 0x14000, v3
	v_or_b32_e32 v144, 0x14000, v6
	v_or_b32_e32 v145, 0x14000, v7
	v_or_b32_e32 v146, 0x14000, v8
	v_or_b32_e32 v137, 0x18000, v3
	v_or_b32_e32 v138, 0x18000, v6
	v_or_b32_e32 v139, 0x18000, v7
	v_or_b32_e32 v140, 0x18000, v8
	v_or_b32_e32 v133, 0x1c000, v3
	v_or_b32_e32 v134, 0x1c000, v6
	v_or_b32_e32 v135, 0x1c000, v7
	v_or_b32_e32 v136, 0x1c000, v8
	v_mov_b32_e32 v1, v0
	v_mov_b32_e32 v2, v0
	v_mov_b32_e32 v3, v0
	v_mov_b32_e32 v4, v0
	v_mov_b32_e32 v5, v0
	v_mov_b32_e32 v6, v0
	v_mov_b32_e32 v7, v0
	v_mov_b32_e32 v8, v0
	v_mov_b32_e32 v9, v0
	v_mov_b32_e32 v10, v0
	v_mov_b32_e32 v11, v0
	v_mov_b32_e32 v12, v0
	v_mov_b32_e32 v13, v0
	v_mov_b32_e32 v14, v0
	v_mov_b32_e32 v15, v0
	v_mov_b32_e32 v16, v0
	v_mov_b32_e32 v17, v0
	v_mov_b32_e32 v18, v0
	v_mov_b32_e32 v19, v0
	v_mov_b32_e32 v20, v0
	v_mov_b32_e32 v21, v0
	v_mov_b32_e32 v22, v0
	v_mov_b32_e32 v23, v0
	v_mov_b32_e32 v24, v0
	v_mov_b32_e32 v25, v0
	v_mov_b32_e32 v26, v0
	v_mov_b32_e32 v27, v0
	v_mov_b32_e32 v28, v0
	v_mov_b32_e32 v29, v0
	v_mov_b32_e32 v30, v0
	v_mov_b32_e32 v31, v0
	v_mov_b32_e32 v32, v0
	v_mov_b32_e32 v33, v0
	v_mov_b32_e32 v34, v0
	v_mov_b32_e32 v35, v0
	v_mov_b32_e32 v36, v0
	v_mov_b32_e32 v37, v0
	v_mov_b32_e32 v38, v0
	v_mov_b32_e32 v39, v0
	v_mov_b32_e32 v40, v0
	v_mov_b32_e32 v41, v0
	v_mov_b32_e32 v42, v0
	v_mov_b32_e32 v43, v0
	v_mov_b32_e32 v44, v0
	v_mov_b32_e32 v45, v0
	v_mov_b32_e32 v46, v0
	v_mov_b32_e32 v47, v0
	v_mov_b32_e32 v48, v0
	v_mov_b32_e32 v49, v0
	v_mov_b32_e32 v50, v0
	v_mov_b32_e32 v51, v0
	v_mov_b32_e32 v52, v0
	v_mov_b32_e32 v53, v0
	v_mov_b32_e32 v54, v0
	v_mov_b32_e32 v55, v0
	v_mov_b32_e32 v56, v0
	v_mov_b32_e32 v57, v0
	v_mov_b32_e32 v58, v0
	v_mov_b32_e32 v59, v0
	v_mov_b32_e32 v60, v0
	v_mov_b32_e32 v61, v0
	v_mov_b32_e32 v62, v0
	v_mov_b32_e32 v63, v0
	v_mov_b32_e32 v68, v0
	v_mov_b32_e32 v69, v0
	v_mov_b32_e32 v70, v0
	v_mov_b32_e32 v71, v0
	v_mov_b32_e32 v80, v0
	v_mov_b32_e32 v81, v0
	v_mov_b32_e32 v82, v0
	v_mov_b32_e32 v83, v0
	v_mov_b32_e32 v88, v0
	v_mov_b32_e32 v89, v0
	v_mov_b32_e32 v90, v0
	v_mov_b32_e32 v91, v0
	v_mov_b32_e32 v92, v0
	v_mov_b32_e32 v93, v0
	v_mov_b32_e32 v94, v0
	v_mov_b32_e32 v95, v0
	v_mov_b32_e32 v96, v0
	v_mov_b32_e32 v97, v0
	v_mov_b32_e32 v98, v0
	v_mov_b32_e32 v99, v0
	v_mov_b32_e32 v100, v0
	v_mov_b32_e32 v101, v0
	v_mov_b32_e32 v102, v0
	v_mov_b32_e32 v103, v0
	v_mov_b32_e32 v104, v0
	v_mov_b32_e32 v105, v0
	v_mov_b32_e32 v106, v0
	v_mov_b32_e32 v107, v0
	v_mov_b32_e32 v108, v0
	v_mov_b32_e32 v109, v0
	v_mov_b32_e32 v110, v0
	v_mov_b32_e32 v111, v0
	v_mov_b32_e32 v112, v0
	v_mov_b32_e32 v113, v0
	v_mov_b32_e32 v114, v0
	v_mov_b32_e32 v115, v0
	v_mov_b32_e32 v116, v0
	v_mov_b32_e32 v117, v0
	v_mov_b32_e32 v118, v0
	v_mov_b32_e32 v119, v0
	v_mov_b32_e32 v120, v0
	v_mov_b32_e32 v121, v0
	v_mov_b32_e32 v122, v0
	v_mov_b32_e32 v123, v0
	v_mov_b32_e32 v124, v0
	v_mov_b32_e32 v125, v0
	v_mov_b32_e32 v126, v0
	v_mov_b32_e32 v127, v0
	v_mov_b32_e32 v64, v0
	v_mov_b32_e32 v65, v0
	v_mov_b32_e32 v66, v0
	v_mov_b32_e32 v67, v0
	v_mov_b32_e32 v72, v0
	v_mov_b32_e32 v73, v0
	v_mov_b32_e32 v74, v0
	v_mov_b32_e32 v75, v0
	v_mov_b32_e32 v76, v0
	v_mov_b32_e32 v77, v0
	v_mov_b32_e32 v78, v0
	v_mov_b32_e32 v79, v0
	v_mov_b32_e32 v84, v0
	v_mov_b32_e32 v85, v0
	v_mov_b32_e32 v86, v0
	v_mov_b32_e32 v87, v0
	s_barrier
	s_barrier
	s_branch .Lmy_rot_291

; #define STAGE(P, RS, SOFF, OFF, kt) do { const int _so = (SOFF) + (kt) * (BK * 2); \
;     _Pragma("unroll") for (int _i = 0; _i < 2; ++_i) { \
;       __builtin_amdgcn_raw_ptr_buffer_load_lds(RS, (__attribute__((address_space(3))) void*)((P) + wave * 1024 + _i * 8192), 16, OFF[_i], _so, 0, 0); } } while (0)
; #define LDA(dst, b, h) _Pragma("unroll") for (int m = 0; m < 4; ++m) _Pragma("unroll") for (int k = 0; k < 2; ++k) \
;     dst[m][k] = *reinterpret_cast<const bf16x8*>(SA(b, h) + lds_byte(wr * 64 + m * 16 + fr, k * 32 + fq * 8))
; #define LDB(dst, b, h) _Pragma("unroll") for (int n = 0; n < 2; ++n) _Pragma("unroll") for (int k = 0; k < 2; ++k) \
;     dst[n][k] = *reinterpret_cast<const bf16x8*>(SB(b, h) + lds_byte(wc * 32 + n * 16 + fr, k * 32 + fq * 8))
; #define WAIT_V(n) asm volatile("s_waitcnt vmcnt(" #n ")" ::: "memory")
; #define WAIT_L(n) asm volatile("s_waitcnt lgkmcnt(" #n ")" ::: "memory")
; #define BAR __builtin_amdgcn_s_barrier()
; #define SCHED __builtin_amdgcn_sched_barrier(0)
;     ...
;       LDB(B0, 0, 0); SCHED; LDA(At, 0, 0); STAGE(SA(1, 1), rsA, sA1, offA, t + 1);
;       WAIT_L(8); BAR; WAIT_L(0); MMA(0, 0, At, B0); BAR; SCHED;
;       LDB(B1, 0, 1); STAGE(SB(0, 0), rsB, sB0, offB, t + 2);
;       BAR; WAIT_L(0); MMA(0, 1, At, B1); BAR;
;       LDA(At, 0, 1); STAGE(SA(0, 0), rsA, sA0, offA, t + 2);
;       BAR; WAIT_L(0); MMA(1, 0, At, B0); BAR; SCHED;
;       STAGE(SB(0, 1), rsB, sB1, offB, t + 2);
;       WAIT_V(6); BAR; MMA(1, 1, At, B1); BAR;
.Lmy_rot_291:
	ds_read_b128 v[152:155], v147
	ds_read_b128 v[156:159], v148
	ds_read_b128 v[160:163], v149
	ds_read_b128 v[164:167], v150
	s_add_i32 s5, s94, s3
	s_add_i32 s6, s5, 0x80
	s_mov_b32 m0, s36
	ds_read_b128 v[168:171], v129
	ds_read_b128 v[172:175], v129 offset:1024
	ds_read_b128 v[176:179], v132
	ds_read_b128 v[180:183], v132 offset:1024
	ds_read_b128 v[184:187], v131
	ds_read_b128 v[188:191], v131 offset:1024
	ds_read_b128 v[192:195], v130
	ds_read_b128 v[196:199], v130 offset:1024
	buffer_load_dwordx4 v141, s[8:11], s6 offen lds
	s_mov_b32 m0, s61
	s_nop 0
	buffer_load_dwordx4 v142, s[8:11], s6 offen lds
	s_waitcnt lgkmcnt(8)
	s_barrier
	s_waitcnt lgkmcnt(0)
	v_mfma_f32_16x16x32_bf16 v[124:127], v[152:155], v[168:171], v[124:127]
	v_mfma_f32_16x16x32_bf16 v[124:127], v[156:159], v[172:175], v[124:127]
	v_mfma_f32_16x16x32_bf16 v[120:123], v[160:163], v[168:171], v[120:123]
	v_mfma_f32_16x16x32_bf16 v[120:123], v[164:167], v[172:175], v[120:123]
	v_mfma_f32_16x16x32_bf16 v[116:119], v[152:155], v[176:179], v[116:119]
	v_mfma_f32_16x16x32_bf16 v[116:119], v[156:159], v[180:183], v[116:119]
	v_mfma_f32_16x16x32_bf16 v[112:115], v[160:163], v[176:179], v[112:115]
	v_mfma_f32_16x16x32_bf16 v[112:115], v[164:167], v[180:183], v[112:115]
	v_mfma_f32_16x16x32_bf16 v[108:111], v[152:155], v[184:187], v[108:111]
	v_mfma_f32_16x16x32_bf16 v[108:111], v[156:159], v[188:191], v[108:111]
	v_mfma_f32_16x16x32_bf16 v[104:107], v[160:163], v[184:187], v[104:107]
	v_mfma_f32_16x16x32_bf16 v[104:107], v[164:167], v[188:191], v[104:107]
	v_mfma_f32_16x16x32_bf16 v[100:103], v[152:155], v[192:195], v[100:103]
	v_mfma_f32_16x16x32_bf16 v[100:103], v[156:159], v[196:199], v[100:103]
	v_mfma_f32_16x16x32_bf16 v[96:99], v[160:163], v[192:195], v[96:99]
	v_mfma_f32_16x16x32_bf16 v[96:99], v[164:167], v[196:199], v[96:99]
	s_barrier
	s_add_i32 s6, s96, s3
	s_add_i32 s7, s6, 0x100
	s_mov_b32 s14, s10
	s_mov_b32 s15, s11
	s_mov_b32 m0, s37
	ds_read_b128 v[200:203], v143
	ds_read_b128 v[204:207], v144
	ds_read_b128 v[208:211], v145
	ds_read_b128 v[212:215], v146
	buffer_load_dwordx4 v141, s[12:15], s7 offen lds
	s_mov_b32 m0, s48
	s_nop 0
	buffer_load_dwordx4 v142, s[12:15], s7 offen lds
	s_barrier
	s_waitcnt lgkmcnt(0)
	v_mfma_f32_16x16x32_bf16 v[92:95], v[200:203], v[168:171], v[92:95]
	v_mfma_f32_16x16x32_bf16 v[92:95], v[204:207], v[172:175], v[92:95]
	v_mfma_f32_16x16x32_bf16 v[88:91], v[208:211], v[168:171], v[88:91]
	v_mfma_f32_16x16x32_bf16 v[88:91], v[212:215], v[172:175], v[88:91]
	v_mfma_f32_16x16x32_bf16 v[80:83], v[200:203], v[176:179], v[80:83]
	v_mfma_f32_16x16x32_bf16 v[80:83], v[204:207], v[180:183], v[80:83]
	v_mfma_f32_16x16x32_bf16 v[68:71], v[208:211], v[176:179], v[68:71]
	v_mfma_f32_16x16x32_bf16 v[68:71], v[212:215], v[180:183], v[68:71]
	v_mfma_f32_16x16x32_bf16 v[60:63], v[200:203], v[184:187], v[60:63]
	v_mfma_f32_16x16x32_bf16 v[60:63], v[204:207], v[188:191], v[60:63]
	v_mfma_f32_16x16x32_bf16 v[56:59], v[208:211], v[184:187], v[56:59]
	v_mfma_f32_16x16x32_bf16 v[56:59], v[212:215], v[188:191], v[56:59]
	v_mfma_f32_16x16x32_bf16 v[52:55], v[200:203], v[192:195], v[52:55]
	v_mfma_f32_16x16x32_bf16 v[52:55], v[204:207], v[196:199], v[52:55]
	v_mfma_f32_16x16x32_bf16 v[48:51], v[208:211], v[192:195], v[48:51]
	v_mfma_f32_16x16x32_bf16 v[48:51], v[212:215], v[196:199], v[48:51]
	s_barrier
	s_add_i32 s7, s95, s3
	s_add_i32 s22, s7, 0x100
	s_mov_b32 m0, s35
	ds_read_b128 v[168:171], v129 offset:16384
	ds_read_b128 v[172:175], v129 offset:17408
	ds_read_b128 v[176:179], v132 offset:16384
	ds_read_b128 v[180:183], v132 offset:17408
	ds_read_b128 v[184:187], v131 offset:16384
	ds_read_b128 v[188:191], v131 offset:17408
	ds_read_b128 v[192:195], v130 offset:16384
	ds_read_b128 v[196:199], v130 offset:17408
	buffer_load_dwordx4 v141, s[8:11], s22 offen lds
	s_mov_b32 m0, s49
	s_nop 0
	buffer_load_dwordx4 v142, s[8:11], s22 offen lds
	s_barrier
	s_waitcnt lgkmcnt(0)
	v_mfma_f32_16x16x32_bf16 v[44:47], v[152:155], v[168:171], v[44:47]
	v_mfma_f32_16x16x32_bf16 v[44:47], v[156:159], v[172:175], v[44:47]
	v_mfma_f32_16x16x32_bf16 v[40:43], v[160:163], v[168:171], v[40:43]
	v_mfma_f32_16x16x32_bf16 v[40:43], v[164:167], v[172:175], v[40:43]
	v_mfma_f32_16x16x32_bf16 v[36:39], v[152:155], v[176:179], v[36:39]
	v_mfma_f32_16x16x32_bf16 v[36:39], v[156:159], v[180:183], v[36:39]
	v_mfma_f32_16x16x32_bf16 v[32:35], v[160:163], v[176:179], v[32:35]
	v_mfma_f32_16x16x32_bf16 v[32:35], v[164:167], v[180:183], v[32:35]
	v_mfma_f32_16x16x32_bf16 v[28:31], v[152:155], v[184:187], v[28:31]
	v_mfma_f32_16x16x32_bf16 v[28:31], v[156:159], v[188:191], v[28:31]
	v_mfma_f32_16x16x32_bf16 v[24:27], v[160:163], v[184:187], v[24:27]
	v_mfma_f32_16x16x32_bf16 v[24:27], v[164:167], v[188:191], v[24:27]
	v_mfma_f32_16x16x32_bf16 v[20:23], v[152:155], v[192:195], v[20:23]
	v_mfma_f32_16x16x32_bf16 v[20:23], v[156:159], v[196:199], v[20:23]
	v_mfma_f32_16x16x32_bf16 v[16:19], v[160:163], v[192:195], v[16:19]
	v_mfma_f32_16x16x32_bf16 v[16:19], v[164:167], v[196:199], v[16:19]
	s_barrier
	s_add_i32 s22, s97, s3
	s_add_i32 s23, s22, 0x100
	s_mov_b32 m0, s38
	s_nop 0
	buffer_load_dwordx4 v141, s[12:15], s23 offen lds
	s_mov_b32 m0, s54
	s_nop 0
	buffer_load_dwordx4 v142, s[12:15], s23 offen lds
	s_waitcnt vmcnt(6)
	s_barrier
; #define STAGE(P, RS, SOFF, OFF, kt) do { const int _so = (SOFF) + (kt) * (BK * 2); \
;     _Pragma("unroll") for (int _i = 0; _i < 2; ++_i) { \
;       __builtin_amdgcn_raw_ptr_buffer_load_lds(RS, (__attribute__((address_space(3))) void*)((P) + wave * 1024 + _i * 8192), 16, OFF[_i], _so, 0, 0); } } while (0)
; #define LDA(dst, b, h) _Pragma("unroll") for (int m = 0; m < 4; ++m) _Pragma("unroll") for (int k = 0; k < 2; ++k) \
;     dst[m][k] = *reinterpret_cast<const bf16x8*>(SA(b, h) + lds_byte(wr * 64 + m * 16 + fr, k * 32 + fq * 8))
; #define LDB(dst, b, h) _Pragma("unroll") for (int n = 0; n < 2; ++n) _Pragma("unroll") for (int k = 0; k < 2; ++k) \
;     dst[n][k] = *reinterpret_cast<const bf16x8*>(SB(b, h) + lds_byte(wc * 32 + n * 16 + fr, k * 32 + fq * 8))
; #define WAIT_V(n) asm volatile("s_waitcnt vmcnt(" #n ")" ::: "memory")
; #define WAIT_L(n) asm volatile("s_waitcnt lgkmcnt(" #n ")" ::: "memory")
; #define BAR __builtin_amdgcn_s_barrier()
; #define SCHED __builtin_amdgcn_sched_barrier(0)
;     ...
;       WAIT_V(6); BAR; MMA(1, 1, At, B1); BAR;
;       LDB(B0, 1, 0); SCHED; LDA(At, 1, 0); STAGE(SA(0, 1), rsA, sA1, offA, t + 2);
;       WAIT_L(8); BAR; WAIT_L(0); MMA(0, 0, At, B0); BAR; SCHED;
;       LDB(B1, 1, 1); STAGE(SB(1, 0), rsB, sB0, offB, t + 3);
;       BAR; WAIT_L(0); MMA(0, 1, At, B1); BAR;
;       LDA(At, 1, 1); STAGE(SA(1, 0), rsA, sA0, offA, t + 3);
;       BAR; WAIT_L(0); MMA(1, 0, At, B0); BAR; SCHED;
	v_mfma_f32_16x16x32_bf16 v[12:15], v[200:203], v[168:171], v[12:15]
	v_mfma_f32_16x16x32_bf16 v[12:15], v[204:207], v[172:175], v[12:15]
	v_mfma_f32_16x16x32_bf16 v[8:11], v[208:211], v[168:171], v[8:11]
	v_mfma_f32_16x16x32_bf16 v[8:11], v[212:215], v[172:175], v[8:11]
	v_mfma_f32_16x16x32_bf16 v[4:7], v[200:203], v[176:179], v[4:7]
	v_mfma_f32_16x16x32_bf16 v[4:7], v[204:207], v[180:183], v[4:7]
	v_mfma_f32_16x16x32_bf16 v[0:3], v[208:211], v[176:179], v[0:3]
	v_mfma_f32_16x16x32_bf16 v[0:3], v[212:215], v[180:183], v[0:3]
	v_mfma_f32_16x16x32_bf16 v[64:67], v[200:203], v[184:187], v[64:67]
	v_mfma_f32_16x16x32_bf16 v[64:67], v[204:207], v[188:191], v[64:67]
	v_mfma_f32_16x16x32_bf16 v[72:75], v[208:211], v[184:187], v[72:75]
	v_mfma_f32_16x16x32_bf16 v[72:75], v[212:215], v[188:191], v[72:75]
	v_mfma_f32_16x16x32_bf16 v[76:79], v[200:203], v[192:195], v[76:79]
	v_mfma_f32_16x16x32_bf16 v[76:79], v[204:207], v[196:199], v[76:79]
	v_mfma_f32_16x16x32_bf16 v[84:87], v[208:211], v[192:195], v[84:87]
	v_mfma_f32_16x16x32_bf16 v[84:87], v[212:215], v[196:199], v[84:87]
	s_barrier
	ds_read_b128 v[152:155], v137
	ds_read_b128 v[156:159], v138
	ds_read_b128 v[160:163], v139
	ds_read_b128 v[164:167], v140
	s_addk_i32 s5, 0x100
	s_mov_b32 m0, s39
	ds_read_b128 v[168:171], v129 offset:32768
	ds_read_b128 v[172:175], v129 offset:33792
	ds_read_b128 v[176:179], v132 offset:32768
	ds_read_b128 v[180:183], v132 offset:33792
	ds_read_b128 v[184:187], v131 offset:32768
	ds_read_b128 v[188:191], v131 offset:33792
	ds_read_b128 v[192:195], v130 offset:32768
	ds_read_b128 v[196:199], v130 offset:33792
	buffer_load_dwordx4 v141, s[8:11], s5 offen lds
	s_mov_b32 m0, s55
	s_nop 0
	buffer_load_dwordx4 v142, s[8:11], s5 offen lds
	s_waitcnt lgkmcnt(8)
	s_barrier
	s_waitcnt lgkmcnt(0)
	v_mfma_f32_16x16x32_bf16 v[124:127], v[152:155], v[168:171], v[124:127]
	v_mfma_f32_16x16x32_bf16 v[124:127], v[156:159], v[172:175], v[124:127]
	v_mfma_f32_16x16x32_bf16 v[120:123], v[160:163], v[168:171], v[120:123]
	v_mfma_f32_16x16x32_bf16 v[120:123], v[164:167], v[172:175], v[120:123]
	v_mfma_f32_16x16x32_bf16 v[116:119], v[152:155], v[176:179], v[116:119]
	v_mfma_f32_16x16x32_bf16 v[116:119], v[156:159], v[180:183], v[116:119]
	v_mfma_f32_16x16x32_bf16 v[112:115], v[160:163], v[176:179], v[112:115]
	v_mfma_f32_16x16x32_bf16 v[112:115], v[164:167], v[180:183], v[112:115]
	v_mfma_f32_16x16x32_bf16 v[108:111], v[152:155], v[184:187], v[108:111]
	v_mfma_f32_16x16x32_bf16 v[108:111], v[156:159], v[188:191], v[108:111]
	v_mfma_f32_16x16x32_bf16 v[104:107], v[160:163], v[184:187], v[104:107]
	v_mfma_f32_16x16x32_bf16 v[104:107], v[164:167], v[188:191], v[104:107]
	v_mfma_f32_16x16x32_bf16 v[100:103], v[152:155], v[192:195], v[100:103]
	v_mfma_f32_16x16x32_bf16 v[100:103], v[156:159], v[196:199], v[100:103]
	v_mfma_f32_16x16x32_bf16 v[96:99], v[160:163], v[192:195], v[96:99]
	v_mfma_f32_16x16x32_bf16 v[96:99], v[164:167], v[196:199], v[96:99]
	s_barrier
	s_addk_i32 s6, 0x180
	s_mov_b32 m0, s42
	ds_read_b128 v[200:203], v133
	ds_read_b128 v[204:207], v134
	ds_read_b128 v[208:211], v135
	ds_read_b128 v[212:215], v136
	buffer_load_dwordx4 v141, s[12:15], s6 offen lds
	s_mov_b32 m0, s58
	s_nop 0
	buffer_load_dwordx4 v142, s[12:15], s6 offen lds
	s_barrier
	s_waitcnt lgkmcnt(0)
	v_mfma_f32_16x16x32_bf16 v[92:95], v[200:203], v[168:171], v[92:95]
	v_mfma_f32_16x16x32_bf16 v[92:95], v[204:207], v[172:175], v[92:95]
	v_mfma_f32_16x16x32_bf16 v[88:91], v[208:211], v[168:171], v[88:91]
	v_mfma_f32_16x16x32_bf16 v[88:91], v[212:215], v[172:175], v[88:91]
	v_mfma_f32_16x16x32_bf16 v[80:83], v[200:203], v[176:179], v[80:83]
	v_mfma_f32_16x16x32_bf16 v[80:83], v[204:207], v[180:183], v[80:83]
	v_mfma_f32_16x16x32_bf16 v[68:71], v[208:211], v[176:179], v[68:71]
	v_mfma_f32_16x16x32_bf16 v[68:71], v[212:215], v[180:183], v[68:71]
	v_mfma_f32_16x16x32_bf16 v[60:63], v[200:203], v[184:187], v[60:63]
	v_mfma_f32_16x16x32_bf16 v[60:63], v[204:207], v[188:191], v[60:63]
	v_mfma_f32_16x16x32_bf16 v[56:59], v[208:211], v[184:187], v[56:59]
	v_mfma_f32_16x16x32_bf16 v[56:59], v[212:215], v[188:191], v[56:59]
	v_mfma_f32_16x16x32_bf16 v[52:55], v[200:203], v[192:195], v[52:55]
	v_mfma_f32_16x16x32_bf16 v[52:55], v[204:207], v[196:199], v[52:55]
	v_mfma_f32_16x16x32_bf16 v[48:51], v[208:211], v[192:195], v[48:51]
	v_mfma_f32_16x16x32_bf16 v[48:51], v[212:215], v[196:199], v[48:51]
	s_barrier
	s_addk_i32 s7, 0x180
	s_mov_b32 m0, s43
	ds_read_b128 v[168:171], v129 offset:49152
	ds_read_b128 v[172:175], v129 offset:50176
	ds_read_b128 v[176:179], v132 offset:49152
	ds_read_b128 v[180:183], v132 offset:50176
	ds_read_b128 v[184:187], v131 offset:49152
	ds_read_b128 v[188:191], v131 offset:50176
	ds_read_b128 v[192:195], v130 offset:49152
	ds_read_b128 v[196:199], v130 offset:50176
	buffer_load_dwordx4 v141, s[8:11], s7 offen lds
	s_mov_b32 m0, s59
	s_nop 0
	buffer_load_dwordx4 v142, s[8:11], s7 offen lds
	s_barrier
	s_waitcnt lgkmcnt(0)
	v_mfma_f32_16x16x32_bf16 v[44:47], v[152:155], v[168:171], v[44:47]
	v_mfma_f32_16x16x32_bf16 v[44:47], v[156:159], v[172:175], v[44:47]
	v_mfma_f32_16x16x32_bf16 v[40:43], v[160:163], v[168:171], v[40:43]
	v_mfma_f32_16x16x32_bf16 v[40:43], v[164:167], v[172:175], v[40:43]
	v_mfma_f32_16x16x32_bf16 v[36:39], v[152:155], v[176:179], v[36:39]
	v_mfma_f32_16x16x32_bf16 v[36:39], v[156:159], v[180:183], v[36:39]
	v_mfma_f32_16x16x32_bf16 v[32:35], v[160:163], v[176:179], v[32:35]
	v_mfma_f32_16x16x32_bf16 v[32:35], v[164:167], v[180:183], v[32:35]
	v_mfma_f32_16x16x32_bf16 v[28:31], v[152:155], v[184:187], v[28:31]
	v_mfma_f32_16x16x32_bf16 v[28:31], v[156:159], v[188:191], v[28:31]
	v_mfma_f32_16x16x32_bf16 v[24:27], v[160:163], v[184:187], v[24:27]
	v_mfma_f32_16x16x32_bf16 v[24:27], v[164:167], v[188:191], v[24:27]
	v_mfma_f32_16x16x32_bf16 v[20:23], v[152:155], v[192:195], v[20:23]
	v_mfma_f32_16x16x32_bf16 v[20:23], v[156:159], v[196:199], v[20:23]
	v_mfma_f32_16x16x32_bf16 v[16:19], v[160:163], v[192:195], v[16:19]
	v_mfma_f32_16x16x32_bf16 v[16:19], v[164:167], v[196:199], v[16:19]
	s_barrier
; #define STAGE(P, RS, SOFF, OFF, kt) do { const int _so = (SOFF) + (kt) * (BK * 2); \
;     _Pragma("unroll") for (int _i = 0; _i < 2; ++_i) { \
;       __builtin_amdgcn_raw_ptr_buffer_load_lds(RS, (__attribute__((address_space(3))) void*)((P) + wave * 1024 + _i * 8192), 16, OFF[_i], _so, 0, 0); } } while (0)
; #define LDA(dst, b, h) _Pragma("unroll") for (int m = 0; m < 4; ++m) _Pragma("unroll") for (int k = 0; k < 2; ++k) \
;     dst[m][k] = *reinterpret_cast<const bf16x8*>(SA(b, h) + lds_byte(wr * 64 + m * 16 + fr, k * 32 + fq * 8))
; #define LDB(dst, b, h) _Pragma("unroll") for (int n = 0; n < 2; ++n) _Pragma("unroll") for (int k = 0; k < 2; ++k) \
;     dst[n][k] = *reinterpret_cast<const bf16x8*>(SB(b, h) + lds_byte(wc * 32 + n * 16 + fr, k * 32 + fq * 8))
; #define WAIT_V(n) asm volatile("s_waitcnt vmcnt(" #n ")" ::: "memory")
; #define WAIT_L(n) asm volatile("s_waitcnt lgkmcnt(" #n ")" ::: "memory")
; #define BAR __builtin_amdgcn_s_barrier()
;     ...
;       STAGE(SB(1, 1), rsB, sB1, offB, t + 3);
;       WAIT_V(6); BAR; MMA(1, 1, At, B1); BAR;
;     }
;     { LDB(B0, 0, 0); LDA(At, 0, 0); STAGE(SA(1, 1), rsA, sA1, offA, nt - 1);
;       BAR; WAIT_L(0); MMA(0, 0, At, B0); BAR;
;       LDB(B1, 0, 1); BAR; WAIT_L(0); MMA(0, 1, At, B1); BAR;
;       LDA(At, 0, 1); WAIT_V(4); BAR; WAIT_L(0); MMA(1, 0, At, B0); MMA(1, 1, At, B1); BAR; }
	s_addk_i32 s22, 0x180
	s_mov_b32 m0, s44
	s_nop 0
	buffer_load_dwordx4 v141, s[12:15], s22 offen lds
	s_mov_b32 m0, s60
	s_nop 0
	buffer_load_dwordx4 v142, s[12:15], s22 offen lds
	s_add_i32 s1, s1, 2
	s_addk_i32 s3, 0x100
	s_cmp_gt_u32 s1, 11
	s_cbranch_scc0 .LBB0_291
	s_waitcnt vmcnt(6)
	s_barrier
	v_mfma_f32_16x16x32_bf16 v[12:15], v[200:203], v[168:171], v[12:15]
	v_mfma_f32_16x16x32_bf16 v[12:15], v[204:207], v[172:175], v[12:15]
	v_mfma_f32_16x16x32_bf16 v[8:11], v[208:211], v[168:171], v[8:11]
	v_mfma_f32_16x16x32_bf16 v[8:11], v[212:215], v[172:175], v[8:11]
	v_mfma_f32_16x16x32_bf16 v[4:7], v[200:203], v[176:179], v[4:7]
	v_mfma_f32_16x16x32_bf16 v[4:7], v[204:207], v[180:183], v[4:7]
	v_mfma_f32_16x16x32_bf16 v[0:3], v[208:211], v[176:179], v[0:3]
	v_mfma_f32_16x16x32_bf16 v[0:3], v[212:215], v[180:183], v[0:3]
	v_mfma_f32_16x16x32_bf16 v[64:67], v[200:203], v[184:187], v[64:67]
	v_mfma_f32_16x16x32_bf16 v[64:67], v[204:207], v[188:191], v[64:67]
	v_mfma_f32_16x16x32_bf16 v[72:75], v[208:211], v[184:187], v[72:75]
	v_mfma_f32_16x16x32_bf16 v[72:75], v[212:215], v[188:191], v[72:75]
	v_mfma_f32_16x16x32_bf16 v[76:79], v[200:203], v[192:195], v[76:79]
	v_mfma_f32_16x16x32_bf16 v[76:79], v[204:207], v[196:199], v[76:79]
	v_mfma_f32_16x16x32_bf16 v[84:87], v[208:211], v[192:195], v[84:87]
	v_mfma_f32_16x16x32_bf16 v[84:87], v[212:215], v[196:199], v[84:87]
	s_barrier
	s_add_i32 s1, s94, 0x780
	s_mov_b32 m0, s36
	ds_read_b128 v[152:155], v147
	ds_read_b128 v[156:159], v148
	ds_read_b128 v[160:163], v149
	ds_read_b128 v[148:151], v150
	ds_read_b128 v[164:167], v129
	ds_read_b128 v[168:171], v129 offset:1024
	ds_read_b128 v[172:175], v132
	ds_read_b128 v[176:179], v132 offset:1024
	ds_read_b128 v[180:183], v131
	ds_read_b128 v[184:187], v131 offset:1024
	ds_read_b128 v[188:191], v130
	ds_read_b128 v[192:195], v130 offset:1024
	buffer_load_dwordx4 v141, s[8:11], s1 offen lds
	s_mov_b32 m0, s61
	s_nop 0
	buffer_load_dwordx4 v142, s[8:11], s1 offen lds
	s_barrier
	s_waitcnt lgkmcnt(0)
	v_mfma_f32_16x16x32_bf16 v[124:127], v[152:155], v[164:167], v[124:127]
	v_mfma_f32_16x16x32_bf16 v[124:127], v[156:159], v[168:171], v[124:127]
	v_mfma_f32_16x16x32_bf16 v[120:123], v[160:163], v[164:167], v[120:123]
	v_mfma_f32_16x16x32_bf16 v[120:123], v[148:151], v[168:171], v[120:123]
	v_mfma_f32_16x16x32_bf16 v[116:119], v[152:155], v[172:175], v[116:119]
	v_mfma_f32_16x16x32_bf16 v[116:119], v[156:159], v[176:179], v[116:119]
	v_mfma_f32_16x16x32_bf16 v[112:115], v[160:163], v[172:175], v[112:115]
	v_mfma_f32_16x16x32_bf16 v[112:115], v[148:151], v[176:179], v[112:115]
	v_mfma_f32_16x16x32_bf16 v[108:111], v[152:155], v[180:183], v[108:111]
	v_mfma_f32_16x16x32_bf16 v[108:111], v[156:159], v[184:187], v[108:111]
	v_mfma_f32_16x16x32_bf16 v[104:107], v[160:163], v[180:183], v[104:107]
	v_mfma_f32_16x16x32_bf16 v[104:107], v[148:151], v[184:187], v[104:107]
	v_mfma_f32_16x16x32_bf16 v[100:103], v[152:155], v[188:191], v[100:103]
	v_mfma_f32_16x16x32_bf16 v[100:103], v[156:159], v[192:195], v[100:103]
	v_mfma_f32_16x16x32_bf16 v[96:99], v[160:163], v[188:191], v[96:99]
	v_mfma_f32_16x16x32_bf16 v[96:99], v[148:151], v[192:195], v[96:99]
	s_barrier
	ds_read_b128 v[196:199], v143
	ds_read_b128 v[200:203], v144
	ds_read_b128 v[142:145], v145
	ds_read_b128 v[204:207], v146
	s_barrier
	s_waitcnt lgkmcnt(0)
	v_mfma_f32_16x16x32_bf16 v[88:91], v[142:145], v[164:167], v[88:91]
	v_mfma_f32_16x16x32_bf16 v[80:83], v[196:199], v[172:175], v[80:83]
	v_mfma_f32_16x16x32_bf16 v[60:63], v[196:199], v[180:183], v[60:63]
	v_mfma_f32_16x16x32_bf16 v[56:59], v[142:145], v[180:183], v[56:59]
	v_mfma_f32_16x16x32_bf16 v[52:55], v[196:199], v[188:191], v[52:55]
	v_mfma_f32_16x16x32_bf16 v[48:51], v[142:145], v[188:191], v[48:51]
	v_mfma_f32_16x16x32_bf16 v[92:95], v[196:199], v[164:167], v[92:95]
	v_mfma_f32_16x16x32_bf16 v[68:71], v[142:145], v[172:175], v[68:71]
	v_mfma_f32_16x16x32_bf16 v[88:91], v[204:207], v[168:171], v[88:91]
	v_mfma_f32_16x16x32_bf16 v[80:83], v[200:203], v[176:179], v[80:83]
	v_mfma_f32_16x16x32_bf16 v[60:63], v[200:203], v[184:187], v[60:63]
	v_mfma_f32_16x16x32_bf16 v[56:59], v[204:207], v[184:187], v[56:59]
	v_mfma_f32_16x16x32_bf16 v[52:55], v[200:203], v[192:195], v[52:55]
	v_mfma_f32_16x16x32_bf16 v[48:51], v[204:207], v[192:195], v[48:51]
	v_mfma_f32_16x16x32_bf16 v[164:167], v[200:203], v[168:171], v[92:95]
	v_mfma_f32_16x16x32_bf16 v[168:171], v[204:207], v[176:179], v[68:71]
	s_barrier
	s_nop 0
	ds_read_b128 v[68:71], v129 offset:16384
	ds_read_b128 v[92:95], v129 offset:17408
	ds_read_b128 v[172:175], v132 offset:16384
	ds_read_b128 v[176:179], v132 offset:17408
	ds_read_b128 v[180:183], v131 offset:16384
	ds_read_b128 v[184:187], v131 offset:17408
	ds_read_b128 v[188:191], v130 offset:16384
	ds_read_b128 v[192:195], v130 offset:17408
	s_waitcnt vmcnt(4)
	s_barrier
; #define LDA(dst, b, h) _Pragma("unroll") for (int m = 0; m < 4; ++m) _Pragma("unroll") for (int k = 0; k < 2; ++k) \
;     dst[m][k] = *reinterpret_cast<const bf16x8*>(SA(b, h) + lds_byte(wr * 64 + m * 16 + fr, k * 32 + fq * 8))
; #define LDB(dst, b, h) _Pragma("unroll") for (int n = 0; n < 2; ++n) _Pragma("unroll") for (int k = 0; k < 2; ++k) \
;     dst[n][k] = *reinterpret_cast<const bf16x8*>(SB(b, h) + lds_byte(wc * 32 + n * 16 + fr, k * 32 + fq * 8))
; #define WAIT_V(n) asm volatile("s_waitcnt vmcnt(" #n ")" ::: "memory")
; #define WAIT_L(n) asm volatile("s_waitcnt lgkmcnt(" #n ")" ::: "memory")
; #define BAR __builtin_amdgcn_s_barrier()
;     ...
;       LDA(At, 0, 1); WAIT_V(4); BAR; WAIT_L(0); MMA(1, 0, At, B0); MMA(1, 1, At, B1); BAR; }
;     { LDB(B0, 1, 0); LDA(At, 1, 0); WAIT_V(2); BAR; WAIT_L(0); MMA(0, 0, At, B0); BAR;
	s_waitcnt lgkmcnt(0)
	v_mfma_f32_16x16x32_bf16 v[44:47], v[152:155], v[68:71], v[44:47]
	v_mfma_f32_16x16x32_bf16 v[40:43], v[160:163], v[68:71], v[40:43]
	v_mfma_f32_16x16x32_bf16 v[36:39], v[152:155], v[172:175], v[36:39]
	v_mfma_f32_16x16x32_bf16 v[32:35], v[160:163], v[172:175], v[32:35]
	v_mfma_f32_16x16x32_bf16 v[28:31], v[152:155], v[180:183], v[28:31]
	v_mfma_f32_16x16x32_bf16 v[24:27], v[160:163], v[180:183], v[24:27]
	v_mfma_f32_16x16x32_bf16 v[20:23], v[152:155], v[188:191], v[20:23]
	v_mfma_f32_16x16x32_bf16 v[16:19], v[160:163], v[188:191], v[16:19]
	v_mfma_f32_16x16x32_bf16 v[44:47], v[156:159], v[92:95], v[44:47]
	v_mfma_f32_16x16x32_bf16 v[40:43], v[148:151], v[92:95], v[40:43]
	v_mfma_f32_16x16x32_bf16 v[36:39], v[156:159], v[176:179], v[36:39]
	v_mfma_f32_16x16x32_bf16 v[32:35], v[148:151], v[176:179], v[32:35]
	v_mfma_f32_16x16x32_bf16 v[28:31], v[156:159], v[184:187], v[28:31]
	v_mfma_f32_16x16x32_bf16 v[24:27], v[148:151], v[184:187], v[24:27]
	v_mfma_f32_16x16x32_bf16 v[20:23], v[156:159], v[192:195], v[20:23]
	v_mfma_f32_16x16x32_bf16 v[16:19], v[148:151], v[192:195], v[16:19]
	v_mfma_f32_16x16x32_bf16 v[4:7], v[196:199], v[172:175], v[4:7]
	v_mfma_f32_16x16x32_bf16 v[0:3], v[142:145], v[172:175], v[0:3]
	v_mfma_f32_16x16x32_bf16 v[12:15], v[196:199], v[68:71], v[12:15]
	v_mfma_f32_16x16x32_bf16 v[8:11], v[142:145], v[68:71], v[8:11]
	v_mfma_f32_16x16x32_bf16 v[64:67], v[196:199], v[180:183], v[64:67]
	v_mfma_f32_16x16x32_bf16 v[68:71], v[142:145], v[180:183], v[72:75]
	v_mfma_f32_16x16x32_bf16 v[72:75], v[196:199], v[188:191], v[76:79]
	v_mfma_f32_16x16x32_bf16 v[76:79], v[142:145], v[188:191], v[84:87]
	v_mfma_f32_16x16x32_bf16 v[4:7], v[200:203], v[176:179], v[4:7]
	v_mfma_f32_16x16x32_bf16 v[0:3], v[204:207], v[176:179], v[0:3]
	v_mfma_f32_16x16x32_bf16 v[142:145], v[200:203], v[92:95], v[12:15]
	v_mfma_f32_16x16x32_bf16 v[146:149], v[204:207], v[92:95], v[8:11]
	v_mfma_f32_16x16x32_bf16 v[150:153], v[200:203], v[184:187], v[64:67]
	v_mfma_f32_16x16x32_bf16 v[154:157], v[204:207], v[184:187], v[68:71]
	v_mfma_f32_16x16x32_bf16 v[158:161], v[200:203], v[192:195], v[72:75]
	v_mfma_f32_16x16x32_bf16 v[172:175], v[204:207], v[192:195], v[76:79]
	s_barrier
	ds_read_b128 v[8:11], v137
	ds_read_b128 v[12:15], v138
	ds_read_b128 v[176:179], v139
	ds_read_b128 v[138:141], v140
	ds_read_b128 v[64:67], v129 offset:32768
	ds_read_b128 v[72:75], v129 offset:33792
	ds_read_b128 v[180:183], v132 offset:32768
	ds_read_b128 v[184:187], v132 offset:33792
	ds_read_b128 v[188:191], v131 offset:32768
	ds_read_b128 v[192:195], v131 offset:33792
	ds_read_b128 v[196:199], v130 offset:32768
	ds_read_b128 v[200:203], v130 offset:33792
	s_waitcnt vmcnt(2)
	s_barrier
	s_waitcnt lgkmcnt(0)
	v_mfma_f32_16x16x32_bf16 v[68:71], v[8:11], v[64:67], v[124:127]
	v_mfma_f32_16x16x32_bf16 v[76:79], v[176:179], v[64:67], v[120:123]
	v_mfma_f32_16x16x32_bf16 v[84:87], v[8:11], v[180:183], v[116:119]
	v_mfma_f32_16x16x32_bf16 v[92:95], v[176:179], v[180:183], v[112:115]
	v_mfma_f32_16x16x32_bf16 v[112:115], v[8:11], v[188:191], v[108:111]
	v_mfma_f32_16x16x32_bf16 v[104:107], v[176:179], v[188:191], v[104:107]
	v_mfma_f32_16x16x32_bf16 v[120:123], v[8:11], v[196:199], v[100:103]
	v_mfma_f32_16x16x32_bf16 v[96:99], v[176:179], v[196:199], v[96:99]
	v_mfma_f32_16x16x32_bf16 v[124:127], v[12:15], v[72:75], v[68:71]
	v_mfma_f32_16x16x32_bf16 v[116:119], v[138:141], v[72:75], v[76:79]
	v_mfma_f32_16x16x32_bf16 v[108:111], v[12:15], v[184:187], v[84:87]
	v_mfma_f32_16x16x32_bf16 v[100:103], v[138:141], v[184:187], v[92:95]
	v_mfma_f32_16x16x32_bf16 v[92:95], v[12:15], v[192:195], v[112:115]
	v_mfma_f32_16x16x32_bf16 v[84:87], v[138:141], v[192:195], v[104:107]
	v_mfma_f32_16x16x32_bf16 v[76:79], v[12:15], v[200:203], v[120:123]
	v_mfma_f32_16x16x32_bf16 v[68:71], v[138:141], v[200:203], v[96:99]
	s_barrier
; #define LDA(dst, b, h) _Pragma("unroll") for (int m = 0; m < 4; ++m) _Pragma("unroll") for (int k = 0; k < 2; ++k) \
;     dst[m][k] = *reinterpret_cast<const bf16x8*>(SA(b, h) + lds_byte(wr * 64 + m * 16 + fr, k * 32 + fq * 8))
; #define LDB(dst, b, h) _Pragma("unroll") for (int n = 0; n < 2; ++n) _Pragma("unroll") for (int k = 0; k < 2; ++k) \
;     dst[n][k] = *reinterpret_cast<const bf16x8*>(SB(b, h) + lds_byte(wc * 32 + n * 16 + fr, k * 32 + fq * 8))
; #define WAIT_V(n) asm volatile("s_waitcnt vmcnt(" #n ")" ::: "memory")
; #define WAIT_L(n) asm volatile("s_waitcnt lgkmcnt(" #n ")" ::: "memory")
; #define BAR __builtin_amdgcn_s_barrier()
;     ...
;     { LDB(B0, 1, 0); LDA(At, 1, 0); WAIT_V(2); BAR; WAIT_L(0); MMA(0, 0, At, B0); BAR;
;       LDB(B1, 1, 1); WAIT_V(0); BAR; WAIT_L(0); MMA(0, 1, At, B1); BAR;
;       LDA(At, 1, 1); BAR; WAIT_L(0); MMA(1, 0, At, B0); MMA(1, 1, At, B1); BAR; }
;     if (wr == 0) BAR;
	ds_read_b128 v[204:207], v133
	ds_read_b128 v[208:211], v134
	ds_read_b128 v[212:215], v135
	ds_read_b128 v[134:137], v136
	s_waitcnt vmcnt(0)
	s_barrier
	s_waitcnt lgkmcnt(0)
	v_mfma_f32_16x16x32_bf16 v[96:99], v[204:207], v[64:67], v[164:167]
	v_mfma_f32_16x16x32_bf16 v[64:67], v[212:215], v[64:67], v[88:91]
	v_mfma_f32_16x16x32_bf16 v[80:83], v[204:207], v[180:183], v[80:83]
	v_mfma_f32_16x16x32_bf16 v[88:91], v[212:215], v[180:183], v[168:171]
	v_mfma_f32_16x16x32_bf16 v[60:63], v[204:207], v[188:191], v[60:63]
	v_mfma_f32_16x16x32_bf16 v[56:59], v[212:215], v[188:191], v[56:59]
	v_mfma_f32_16x16x32_bf16 v[52:55], v[204:207], v[196:199], v[52:55]
	v_mfma_f32_16x16x32_bf16 v[48:51], v[212:215], v[196:199], v[48:51]
	v_mfma_f32_16x16x32_bf16 v[120:123], v[208:211], v[72:75], v[96:99]
	v_mfma_f32_16x16x32_bf16 v[112:115], v[134:137], v[72:75], v[64:67]
	v_mfma_f32_16x16x32_bf16 v[104:107], v[208:211], v[184:187], v[80:83]
	v_mfma_f32_16x16x32_bf16 v[96:99], v[134:137], v[184:187], v[88:91]
	v_mfma_f32_16x16x32_bf16 v[88:91], v[208:211], v[192:195], v[60:63]
	v_mfma_f32_16x16x32_bf16 v[80:83], v[134:137], v[192:195], v[56:59]
	v_mfma_f32_16x16x32_bf16 v[72:75], v[208:211], v[200:203], v[52:55]
	v_mfma_f32_16x16x32_bf16 v[64:67], v[134:137], v[200:203], v[48:51]
	s_barrier
	s_nop 0
	ds_read_b128 v[48:51], v129 offset:49152
	ds_read_b128 v[162:165], v129 offset:50176
	ds_read_b128 v[52:55], v132 offset:49152
	ds_read_b128 v[166:169], v132 offset:50176
	ds_read_b128 v[180:183], v131 offset:49152
	ds_read_b128 v[184:187], v131 offset:50176
	ds_read_b128 v[188:191], v130 offset:49152
	ds_read_b128 v[130:133], v130 offset:50176
	s_barrier
	s_waitcnt lgkmcnt(0)
	v_mfma_f32_16x16x32_bf16 v[44:47], v[8:11], v[48:51], v[44:47]
	v_mfma_f32_16x16x32_bf16 v[40:43], v[176:179], v[48:51], v[40:43]
	v_mfma_f32_16x16x32_bf16 v[36:39], v[8:11], v[52:55], v[36:39]
	v_mfma_f32_16x16x32_bf16 v[32:35], v[176:179], v[52:55], v[32:35]
	v_mfma_f32_16x16x32_bf16 v[28:31], v[8:11], v[180:183], v[28:31]
	v_mfma_f32_16x16x32_bf16 v[24:27], v[176:179], v[180:183], v[24:27]
	v_mfma_f32_16x16x32_bf16 v[8:11], v[8:11], v[188:191], v[20:23]
	v_mfma_f32_16x16x32_bf16 v[16:19], v[176:179], v[188:191], v[16:19]
	v_mfma_f32_16x16x32_bf16 v[60:63], v[12:15], v[162:165], v[44:47]
	v_mfma_f32_16x16x32_bf16 v[56:59], v[138:141], v[162:165], v[40:43]
	v_mfma_f32_16x16x32_bf16 v[44:47], v[12:15], v[166:169], v[36:39]
	v_mfma_f32_16x16x32_bf16 v[40:43], v[138:141], v[166:169], v[32:35]
	v_mfma_f32_16x16x32_bf16 v[28:31], v[12:15], v[184:187], v[28:31]
	v_mfma_f32_16x16x32_bf16 v[24:27], v[138:141], v[184:187], v[24:27]
	v_mfma_f32_16x16x32_bf16 v[12:15], v[12:15], v[130:133], v[8:11]
	v_mfma_f32_16x16x32_bf16 v[8:11], v[138:141], v[130:133], v[16:19]
	v_mfma_f32_16x16x32_bf16 v[16:19], v[204:207], v[48:51], v[142:145]
	v_mfma_f32_16x16x32_bf16 v[20:23], v[212:215], v[48:51], v[146:149]
	v_mfma_f32_16x16x32_bf16 v[4:7], v[204:207], v[52:55], v[4:7]
	v_mfma_f32_16x16x32_bf16 v[0:3], v[212:215], v[52:55], v[0:3]
	v_mfma_f32_16x16x32_bf16 v[138:141], v[204:207], v[180:183], v[150:153]
	v_mfma_f32_16x16x32_bf16 v[142:145], v[212:215], v[180:183], v[154:157]
	v_mfma_f32_16x16x32_bf16 v[146:149], v[204:207], v[188:191], v[158:161]
	v_mfma_f32_16x16x32_bf16 v[150:153], v[212:215], v[188:191], v[172:175]
	v_mfma_f32_16x16x32_bf16 v[52:55], v[208:211], v[162:165], v[16:19]
	v_mfma_f32_16x16x32_bf16 v[48:51], v[134:137], v[162:165], v[20:23]
	v_mfma_f32_16x16x32_bf16 v[36:39], v[208:211], v[166:169], v[4:7]
	v_mfma_f32_16x16x32_bf16 v[32:35], v[134:137], v[166:169], v[0:3]
	v_mfma_f32_16x16x32_bf16 v[20:23], v[208:211], v[184:187], v[138:141]
	v_mfma_f32_16x16x32_bf16 v[16:19], v[134:137], v[184:187], v[142:145]
	v_mfma_f32_16x16x32_bf16 v[4:7], v[208:211], v[130:133], v[146:149]
	v_mfma_f32_16x16x32_bf16 v[0:3], v[134:137], v[130:133], v[150:153]
	v_cmp_gt_u32_e32 vcc, s46, v128
	s_barrier
	s_and_saveexec_b64 s[6:7], vcc
	s_cbranch_execz .LBB0_294
	s_barrier

; #define STAGE(P, RS, SOFF, OFF, kt) do { const int _so = (SOFF) + (kt) * (BK * 2); \
;     _Pragma("unroll") for (int _i = 0; _i < 2; ++_i) { \
;       __builtin_amdgcn_raw_ptr_buffer_load_lds(RS, (__attribute__((address_space(3))) void*)((P) + wave * 1024 + _i * 8192), 16, OFF[_i], _so, 0, 0); } } while (0)
; #define LDA(dst, b, h) _Pragma("unroll") for (int m = 0; m < 4; ++m) _Pragma("unroll") for (int k = 0; k < 2; ++k) \
;     dst[m][k] = *reinterpret_cast<const bf16x8*>(SA(b, h) + lds_byte(wr * 64 + m * 16 + fr, k * 32 + fq * 8))
; #define LDB(dst, b, h) _Pragma("unroll") for (int n = 0; n < 2; ++n) _Pragma("unroll") for (int k = 0; k < 2; ++k) \
;     dst[n][k] = *reinterpret_cast<const bf16x8*>(SB(b, h) + lds_byte(wc * 32 + n * 16 + fr, k * 32 + fq * 8))
; #define WAIT_V(n) asm volatile("s_waitcnt vmcnt(" #n ")" ::: "memory")
; #define WAIT_L(n) asm volatile("s_waitcnt lgkmcnt(" #n ")" ::: "memory")
; #define BAR __builtin_amdgcn_s_barrier()
; #define SCHED __builtin_amdgcn_sched_barrier(0)
;     ...
;       LDB(B0, 0, 0); SCHED; LDA(At, 0, 0); STAGE(SA(1, 1), rsA, sA1, offA, t + 1);
;       WAIT_L(8); BAR; WAIT_L(0); MMA(0, 0, At, B0); BAR; SCHED;
;       LDB(B1, 0, 1); STAGE(SB(0, 0), rsB, sB0, offB, t + 2);
;       BAR; WAIT_L(0); MMA(0, 1, At, B1); BAR;
;       LDA(At, 0, 1); STAGE(SA(0, 0), rsA, sA0, offA, t + 2);
;       BAR; WAIT_L(0); MMA(1, 0, At, B0); BAR; SCHED;
;       STAGE(SB(0, 1), rsB, sB1, offB, t + 2);
;       WAIT_V(6); BAR; MMA(1, 1, At, B1); BAR;
.Lmy_rot_354:
	ds_read_b128 v[154:157], v149
	ds_read_b128 v[158:161], v150
	ds_read_b128 v[162:165], v151
	ds_read_b128 v[166:169], v152
	s_add_i32 s43, s37, s17
	s_add_i32 s10, s43, 0x80
	s_mov_b32 m0, s30
	ds_read_b128 v[170:173], v131
	ds_read_b128 v[174:177], v131 offset:1024
	ds_read_b128 v[178:181], v134
	ds_read_b128 v[182:185], v134 offset:1024
	ds_read_b128 v[186:189], v133
	ds_read_b128 v[190:193], v133 offset:1024
	ds_read_b128 v[194:197], v132
	ds_read_b128 v[198:201], v132 offset:1024
	buffer_load_dwordx4 v143, s[4:7], s10 offen lds
	s_mov_b32 m0, s31
	s_nop 0
	buffer_load_dwordx4 v144, s[4:7], s10 offen lds
	s_waitcnt lgkmcnt(8)
	s_barrier
	s_waitcnt lgkmcnt(0)
	v_mfma_f32_16x16x32_bf16 v[124:127], v[154:157], v[170:173], v[124:127]
	v_mfma_f32_16x16x32_bf16 v[124:127], v[158:161], v[174:177], v[124:127]
	v_mfma_f32_16x16x32_bf16 v[120:123], v[162:165], v[170:173], v[120:123]
	v_mfma_f32_16x16x32_bf16 v[120:123], v[166:169], v[174:177], v[120:123]
	v_mfma_f32_16x16x32_bf16 v[116:119], v[154:157], v[178:181], v[116:119]
	v_mfma_f32_16x16x32_bf16 v[116:119], v[158:161], v[182:185], v[116:119]
	v_mfma_f32_16x16x32_bf16 v[112:115], v[162:165], v[178:181], v[112:115]
	v_mfma_f32_16x16x32_bf16 v[112:115], v[166:169], v[182:185], v[112:115]
	v_mfma_f32_16x16x32_bf16 v[108:111], v[154:157], v[186:189], v[108:111]
	v_mfma_f32_16x16x32_bf16 v[108:111], v[158:161], v[190:193], v[108:111]
	v_mfma_f32_16x16x32_bf16 v[104:107], v[162:165], v[186:189], v[104:107]
	v_mfma_f32_16x16x32_bf16 v[104:107], v[166:169], v[190:193], v[104:107]
	v_mfma_f32_16x16x32_bf16 v[100:103], v[154:157], v[194:197], v[100:103]
	v_mfma_f32_16x16x32_bf16 v[100:103], v[158:161], v[198:201], v[100:103]
	v_mfma_f32_16x16x32_bf16 v[96:99], v[162:165], v[194:197], v[96:99]
	v_mfma_f32_16x16x32_bf16 v[96:99], v[166:169], v[198:201], v[96:99]
	s_barrier
	s_add_i32 s44, s39, s17
	s_add_i32 s45, s44, 0x100
	s_mov_b32 s10, s6
	s_mov_b32 s11, s7
	s_mov_b32 m0, s1
	ds_read_b128 v[202:205], v145
	ds_read_b128 v[206:209], v146
	ds_read_b128 v[210:213], v147
	ds_read_b128 v[214:217], v148
	buffer_load_dwordx4 v143, s[8:11], s45 offen lds
	s_mov_b32 m0, s3
	s_nop 0
	buffer_load_dwordx4 v144, s[8:11], s45 offen lds
	s_barrier
	s_waitcnt lgkmcnt(0)
	v_mfma_f32_16x16x32_bf16 v[92:95], v[202:205], v[170:173], v[92:95]
	v_mfma_f32_16x16x32_bf16 v[92:95], v[206:209], v[174:177], v[92:95]
	v_mfma_f32_16x16x32_bf16 v[88:91], v[210:213], v[170:173], v[88:91]
	v_mfma_f32_16x16x32_bf16 v[88:91], v[214:217], v[174:177], v[88:91]
	v_mfma_f32_16x16x32_bf16 v[84:87], v[202:205], v[178:181], v[84:87]
	v_mfma_f32_16x16x32_bf16 v[84:87], v[206:209], v[182:185], v[84:87]
	v_mfma_f32_16x16x32_bf16 v[80:83], v[210:213], v[178:181], v[80:83]
	v_mfma_f32_16x16x32_bf16 v[80:83], v[214:217], v[182:185], v[80:83]
	v_mfma_f32_16x16x32_bf16 v[76:79], v[202:205], v[186:189], v[76:79]
	v_mfma_f32_16x16x32_bf16 v[76:79], v[206:209], v[190:193], v[76:79]
	v_mfma_f32_16x16x32_bf16 v[72:75], v[210:213], v[186:189], v[72:75]
	v_mfma_f32_16x16x32_bf16 v[72:75], v[214:217], v[190:193], v[72:75]
	v_mfma_f32_16x16x32_bf16 v[68:71], v[202:205], v[194:197], v[68:71]
	v_mfma_f32_16x16x32_bf16 v[68:71], v[206:209], v[198:201], v[68:71]
	v_mfma_f32_16x16x32_bf16 v[64:67], v[210:213], v[194:197], v[64:67]
	v_mfma_f32_16x16x32_bf16 v[64:67], v[214:217], v[198:201], v[64:67]
	s_barrier
	s_add_i32 s45, s38, s17
	s_add_i32 s46, s45, 0x100
	s_mov_b32 m0, s0
	ds_read_b128 v[170:173], v131 offset:16384
	ds_read_b128 v[174:177], v131 offset:17408
	ds_read_b128 v[178:181], v134 offset:16384
	ds_read_b128 v[182:185], v134 offset:17408
	ds_read_b128 v[186:189], v133 offset:16384
	ds_read_b128 v[190:193], v133 offset:17408
	ds_read_b128 v[194:197], v132 offset:16384
	ds_read_b128 v[198:201], v132 offset:17408
	buffer_load_dwordx4 v143, s[4:7], s46 offen lds
	s_mov_b32 m0, s18
	s_nop 0
	buffer_load_dwordx4 v144, s[4:7], s46 offen lds
	s_barrier
	s_waitcnt lgkmcnt(0)
	v_mfma_f32_16x16x32_bf16 v[60:63], v[154:157], v[170:173], v[60:63]
	v_mfma_f32_16x16x32_bf16 v[60:63], v[158:161], v[174:177], v[60:63]
	v_mfma_f32_16x16x32_bf16 v[56:59], v[162:165], v[170:173], v[56:59]
	v_mfma_f32_16x16x32_bf16 v[56:59], v[166:169], v[174:177], v[56:59]
	v_mfma_f32_16x16x32_bf16 v[52:55], v[154:157], v[178:181], v[52:55]
	v_mfma_f32_16x16x32_bf16 v[52:55], v[158:161], v[182:185], v[52:55]
	v_mfma_f32_16x16x32_bf16 v[48:51], v[162:165], v[178:181], v[48:51]
	v_mfma_f32_16x16x32_bf16 v[48:51], v[166:169], v[182:185], v[48:51]
	v_mfma_f32_16x16x32_bf16 v[44:47], v[154:157], v[186:189], v[44:47]
	v_mfma_f32_16x16x32_bf16 v[44:47], v[158:161], v[190:193], v[44:47]
	v_mfma_f32_16x16x32_bf16 v[40:43], v[162:165], v[186:189], v[40:43]
	v_mfma_f32_16x16x32_bf16 v[40:43], v[166:169], v[190:193], v[40:43]
	v_mfma_f32_16x16x32_bf16 v[36:39], v[154:157], v[194:197], v[36:39]
	v_mfma_f32_16x16x32_bf16 v[36:39], v[158:161], v[198:201], v[36:39]
	v_mfma_f32_16x16x32_bf16 v[32:35], v[162:165], v[194:197], v[32:35]
	v_mfma_f32_16x16x32_bf16 v[32:35], v[166:169], v[198:201], v[32:35]
	s_barrier
	s_add_i32 s46, s40, s17
	s_add_i32 s47, s46, 0x100
	s_mov_b32 m0, s19
	s_nop 0
	buffer_load_dwordx4 v143, s[8:11], s47 offen lds
	s_mov_b32 m0, s20
	s_nop 0
	buffer_load_dwordx4 v144, s[8:11], s47 offen lds
	s_waitcnt vmcnt(6)
	s_barrier
; #define STAGE(P, RS, SOFF, OFF, kt) do { const int _so = (SOFF) + (kt) * (BK * 2); \
;     _Pragma("unroll") for (int _i = 0; _i < 2; ++_i) { \
;       __builtin_amdgcn_raw_ptr_buffer_load_lds(RS, (__attribute__((address_space(3))) void*)((P) + wave * 1024 + _i * 8192), 16, OFF[_i], _so, 0, 0); } } while (0)
; #define LDA(dst, b, h) _Pragma("unroll") for (int m = 0; m < 4; ++m) _Pragma("unroll") for (int k = 0; k < 2; ++k) \
;     dst[m][k] = *reinterpret_cast<const bf16x8*>(SA(b, h) + lds_byte(wr * 64 + m * 16 + fr, k * 32 + fq * 8))
; #define LDB(dst, b, h) _Pragma("unroll") for (int n = 0; n < 2; ++n) _Pragma("unroll") for (int k = 0; k < 2; ++k) \
;     dst[n][k] = *reinterpret_cast<const bf16x8*>(SB(b, h) + lds_byte(wc * 32 + n * 16 + fr, k * 32 + fq * 8))
; #define WAIT_V(n) asm volatile("s_waitcnt vmcnt(" #n ")" ::: "memory")
; #define WAIT_L(n) asm volatile("s_waitcnt lgkmcnt(" #n ")" ::: "memory")
; #define BAR __builtin_amdgcn_s_barrier()
; #define SCHED __builtin_amdgcn_sched_barrier(0)
;     ...
;       WAIT_V(6); BAR; MMA(1, 1, At, B1); BAR;
;       LDB(B0, 1, 0); SCHED; LDA(At, 1, 0); STAGE(SA(0, 1), rsA, sA1, offA, t + 2);
;       WAIT_L(8); BAR; WAIT_L(0); MMA(0, 0, At, B0); BAR; SCHED;
;       LDB(B1, 1, 1); STAGE(SB(1, 0), rsB, sB0, offB, t + 3);
;       BAR; WAIT_L(0); MMA(0, 1, At, B1); BAR;
;       LDA(At, 1, 1); STAGE(SA(1, 0), rsA, sA0, offA, t + 3);
;       BAR; WAIT_L(0); MMA(1, 0, At, B0); BAR; SCHED;
	v_mfma_f32_16x16x32_bf16 v[28:31], v[202:205], v[170:173], v[28:31]
	v_mfma_f32_16x16x32_bf16 v[28:31], v[206:209], v[174:177], v[28:31]
	v_mfma_f32_16x16x32_bf16 v[24:27], v[210:213], v[170:173], v[24:27]
	v_mfma_f32_16x16x32_bf16 v[24:27], v[214:217], v[174:177], v[24:27]
	v_mfma_f32_16x16x32_bf16 v[20:23], v[202:205], v[178:181], v[20:23]
	v_mfma_f32_16x16x32_bf16 v[20:23], v[206:209], v[182:185], v[20:23]
	v_mfma_f32_16x16x32_bf16 v[16:19], v[210:213], v[178:181], v[16:19]
	v_mfma_f32_16x16x32_bf16 v[16:19], v[214:217], v[182:185], v[16:19]
	v_mfma_f32_16x16x32_bf16 v[12:15], v[202:205], v[186:189], v[12:15]
	v_mfma_f32_16x16x32_bf16 v[12:15], v[206:209], v[190:193], v[12:15]
	v_mfma_f32_16x16x32_bf16 v[8:11], v[210:213], v[186:189], v[8:11]
	v_mfma_f32_16x16x32_bf16 v[8:11], v[214:217], v[190:193], v[8:11]
	v_mfma_f32_16x16x32_bf16 v[4:7], v[202:205], v[194:197], v[4:7]
	v_mfma_f32_16x16x32_bf16 v[4:7], v[206:209], v[198:201], v[4:7]
	v_mfma_f32_16x16x32_bf16 v[0:3], v[210:213], v[194:197], v[0:3]
	v_mfma_f32_16x16x32_bf16 v[0:3], v[214:217], v[198:201], v[0:3]
	s_barrier
	ds_read_b128 v[154:157], v139
	ds_read_b128 v[158:161], v140
	ds_read_b128 v[162:165], v141
	ds_read_b128 v[166:169], v142
	s_addk_i32 s43, 0x100
	s_mov_b32 m0, s21
	ds_read_b128 v[170:173], v131 offset:32768
	ds_read_b128 v[174:177], v131 offset:33792
	ds_read_b128 v[178:181], v134 offset:32768
	ds_read_b128 v[182:185], v134 offset:33792
	ds_read_b128 v[186:189], v133 offset:32768
	ds_read_b128 v[190:193], v133 offset:33792
	ds_read_b128 v[194:197], v132 offset:32768
	ds_read_b128 v[198:201], v132 offset:33792
	buffer_load_dwordx4 v143, s[4:7], s43 offen lds
	s_mov_b32 m0, s22
	s_nop 0
	buffer_load_dwordx4 v144, s[4:7], s43 offen lds
	s_waitcnt lgkmcnt(8)
	s_barrier
	s_waitcnt lgkmcnt(0)
	v_mfma_f32_16x16x32_bf16 v[124:127], v[154:157], v[170:173], v[124:127]
	v_mfma_f32_16x16x32_bf16 v[124:127], v[158:161], v[174:177], v[124:127]
	v_mfma_f32_16x16x32_bf16 v[120:123], v[162:165], v[170:173], v[120:123]
	v_mfma_f32_16x16x32_bf16 v[120:123], v[166:169], v[174:177], v[120:123]
	v_mfma_f32_16x16x32_bf16 v[116:119], v[154:157], v[178:181], v[116:119]
	v_mfma_f32_16x16x32_bf16 v[116:119], v[158:161], v[182:185], v[116:119]
	v_mfma_f32_16x16x32_bf16 v[112:115], v[162:165], v[178:181], v[112:115]
	v_mfma_f32_16x16x32_bf16 v[112:115], v[166:169], v[182:185], v[112:115]
	v_mfma_f32_16x16x32_bf16 v[108:111], v[154:157], v[186:189], v[108:111]
	v_mfma_f32_16x16x32_bf16 v[108:111], v[158:161], v[190:193], v[108:111]
	v_mfma_f32_16x16x32_bf16 v[104:107], v[162:165], v[186:189], v[104:107]
	v_mfma_f32_16x16x32_bf16 v[104:107], v[166:169], v[190:193], v[104:107]
	v_mfma_f32_16x16x32_bf16 v[100:103], v[154:157], v[194:197], v[100:103]
	v_mfma_f32_16x16x32_bf16 v[100:103], v[158:161], v[198:201], v[100:103]
	v_mfma_f32_16x16x32_bf16 v[96:99], v[162:165], v[194:197], v[96:99]
	v_mfma_f32_16x16x32_bf16 v[96:99], v[166:169], v[198:201], v[96:99]
	s_barrier
	s_addk_i32 s44, 0x180
	s_mov_b32 m0, s23
	ds_read_b128 v[202:205], v135
	ds_read_b128 v[206:209], v136
	ds_read_b128 v[210:213], v137
	ds_read_b128 v[214:217], v138
	buffer_load_dwordx4 v143, s[8:11], s44 offen lds
	s_mov_b32 m0, s24
	s_nop 0
	buffer_load_dwordx4 v144, s[8:11], s44 offen lds
	s_barrier
	s_waitcnt lgkmcnt(0)
	v_mfma_f32_16x16x32_bf16 v[92:95], v[202:205], v[170:173], v[92:95]
	v_mfma_f32_16x16x32_bf16 v[92:95], v[206:209], v[174:177], v[92:95]
	v_mfma_f32_16x16x32_bf16 v[88:91], v[210:213], v[170:173], v[88:91]
	v_mfma_f32_16x16x32_bf16 v[88:91], v[214:217], v[174:177], v[88:91]
	v_mfma_f32_16x16x32_bf16 v[84:87], v[202:205], v[178:181], v[84:87]
	v_mfma_f32_16x16x32_bf16 v[84:87], v[206:209], v[182:185], v[84:87]
	v_mfma_f32_16x16x32_bf16 v[80:83], v[210:213], v[178:181], v[80:83]
	v_mfma_f32_16x16x32_bf16 v[80:83], v[214:217], v[182:185], v[80:83]
	v_mfma_f32_16x16x32_bf16 v[76:79], v[202:205], v[186:189], v[76:79]
	v_mfma_f32_16x16x32_bf16 v[76:79], v[206:209], v[190:193], v[76:79]
	v_mfma_f32_16x16x32_bf16 v[72:75], v[210:213], v[186:189], v[72:75]
	v_mfma_f32_16x16x32_bf16 v[72:75], v[214:217], v[190:193], v[72:75]
	v_mfma_f32_16x16x32_bf16 v[68:71], v[202:205], v[194:197], v[68:71]
	v_mfma_f32_16x16x32_bf16 v[68:71], v[206:209], v[198:201], v[68:71]
	v_mfma_f32_16x16x32_bf16 v[64:67], v[210:213], v[194:197], v[64:67]
	v_mfma_f32_16x16x32_bf16 v[64:67], v[214:217], v[198:201], v[64:67]
	s_barrier
	s_addk_i32 s45, 0x180
	s_mov_b32 m0, s25
	ds_read_b128 v[170:173], v131 offset:49152
	ds_read_b128 v[174:177], v131 offset:50176
	ds_read_b128 v[178:181], v134 offset:49152
	ds_read_b128 v[182:185], v134 offset:50176
	ds_read_b128 v[186:189], v133 offset:49152
	ds_read_b128 v[190:193], v133 offset:50176
	ds_read_b128 v[194:197], v132 offset:49152
	ds_read_b128 v[198:201], v132 offset:50176
	buffer_load_dwordx4 v143, s[4:7], s45 offen lds
	s_mov_b32 m0, s26
	s_nop 0
	buffer_load_dwordx4 v144, s[4:7], s45 offen lds
	s_barrier
	s_waitcnt lgkmcnt(0)
	v_mfma_f32_16x16x32_bf16 v[60:63], v[154:157], v[170:173], v[60:63]
	v_mfma_f32_16x16x32_bf16 v[60:63], v[158:161], v[174:177], v[60:63]
	v_mfma_f32_16x16x32_bf16 v[56:59], v[162:165], v[170:173], v[56:59]
	v_mfma_f32_16x16x32_bf16 v[56:59], v[166:169], v[174:177], v[56:59]
	v_mfma_f32_16x16x32_bf16 v[52:55], v[154:157], v[178:181], v[52:55]
	v_mfma_f32_16x16x32_bf16 v[52:55], v[158:161], v[182:185], v[52:55]
	v_mfma_f32_16x16x32_bf16 v[48:51], v[162:165], v[178:181], v[48:51]
	v_mfma_f32_16x16x32_bf16 v[48:51], v[166:169], v[182:185], v[48:51]
	v_mfma_f32_16x16x32_bf16 v[44:47], v[154:157], v[186:189], v[44:47]
	v_mfma_f32_16x16x32_bf16 v[44:47], v[158:161], v[190:193], v[44:47]
	v_mfma_f32_16x16x32_bf16 v[40:43], v[162:165], v[186:189], v[40:43]
	v_mfma_f32_16x16x32_bf16 v[40:43], v[166:169], v[190:193], v[40:43]
	v_mfma_f32_16x16x32_bf16 v[36:39], v[154:157], v[194:197], v[36:39]
	v_mfma_f32_16x16x32_bf16 v[36:39], v[158:161], v[198:201], v[36:39]
	v_mfma_f32_16x16x32_bf16 v[32:35], v[162:165], v[194:197], v[32:35]
	v_mfma_f32_16x16x32_bf16 v[32:35], v[166:169], v[198:201], v[32:35]
	s_barrier
; #define STAGE(P, RS, SOFF, OFF, kt) do { const int _so = (SOFF) + (kt) * (BK * 2); \
;     _Pragma("unroll") for (int _i = 0; _i < 2; ++_i) { \
;       __builtin_amdgcn_raw_ptr_buffer_load_lds(RS, (__attribute__((address_space(3))) void*)((P) + wave * 1024 + _i * 8192), 16, OFF[_i], _so, 0, 0); } } while (0)
; #define LDA(dst, b, h) _Pragma("unroll") for (int m = 0; m < 4; ++m) _Pragma("unroll") for (int k = 0; k < 2; ++k) \
;     dst[m][k] = *reinterpret_cast<const bf16x8*>(SA(b, h) + lds_byte(wr * 64 + m * 16 + fr, k * 32 + fq * 8))
; #define LDB(dst, b, h) _Pragma("unroll") for (int n = 0; n < 2; ++n) _Pragma("unroll") for (int k = 0; k < 2; ++k) \
;     dst[n][k] = *reinterpret_cast<const bf16x8*>(SB(b, h) + lds_byte(wc * 32 + n * 16 + fr, k * 32 + fq * 8))
; #define WAIT_V(n) asm volatile("s_waitcnt vmcnt(" #n ")" ::: "memory")
; #define WAIT_L(n) asm volatile("s_waitcnt lgkmcnt(" #n ")" ::: "memory")
; #define BAR __builtin_amdgcn_s_barrier()
;     ...
;       STAGE(SB(1, 1), rsB, sB1, offB, t + 3);
;       WAIT_V(6); BAR; MMA(1, 1, At, B1); BAR;
;     }
;     { LDB(B0, 0, 0); LDA(At, 0, 0); STAGE(SA(1, 1), rsA, sA1, offA, nt - 1);
;       BAR; WAIT_L(0); MMA(0, 0, At, B0); BAR;
;       LDB(B1, 0, 1); BAR; WAIT_L(0); MMA(0, 1, At, B1); BAR;
;       LDA(At, 0, 1); WAIT_V(4); BAR; WAIT_L(0); MMA(1, 0, At, B0); MMA(1, 1, At, B1); BAR; }
	s_addk_i32 s46, 0x180
	s_mov_b32 m0, s27
	s_nop 0
	buffer_load_dwordx4 v143, s[8:11], s46 offen lds
	s_mov_b32 m0, s28
	s_nop 0
	buffer_load_dwordx4 v144, s[8:11], s46 offen lds
	s_add_i32 s16, s16, 2
	s_addk_i32 s17, 0x100
	s_cmp_gt_u32 s16, 27
	s_cbranch_scc0 .LBB0_354
	s_waitcnt vmcnt(6)
	s_barrier
	v_mfma_f32_16x16x32_bf16 v[28:31], v[202:205], v[170:173], v[28:31]
	v_mfma_f32_16x16x32_bf16 v[28:31], v[206:209], v[174:177], v[28:31]
	v_mfma_f32_16x16x32_bf16 v[24:27], v[210:213], v[170:173], v[24:27]
	v_mfma_f32_16x16x32_bf16 v[24:27], v[214:217], v[174:177], v[24:27]
	v_mfma_f32_16x16x32_bf16 v[20:23], v[202:205], v[178:181], v[20:23]
	v_mfma_f32_16x16x32_bf16 v[20:23], v[206:209], v[182:185], v[20:23]
	v_mfma_f32_16x16x32_bf16 v[16:19], v[210:213], v[178:181], v[16:19]
	v_mfma_f32_16x16x32_bf16 v[16:19], v[214:217], v[182:185], v[16:19]
	v_mfma_f32_16x16x32_bf16 v[12:15], v[202:205], v[186:189], v[12:15]
	v_mfma_f32_16x16x32_bf16 v[12:15], v[206:209], v[190:193], v[12:15]
	v_mfma_f32_16x16x32_bf16 v[8:11], v[210:213], v[186:189], v[8:11]
	v_mfma_f32_16x16x32_bf16 v[8:11], v[214:217], v[190:193], v[8:11]
	v_mfma_f32_16x16x32_bf16 v[4:7], v[202:205], v[194:197], v[4:7]
	v_mfma_f32_16x16x32_bf16 v[4:7], v[206:209], v[198:201], v[4:7]
	v_mfma_f32_16x16x32_bf16 v[0:3], v[210:213], v[194:197], v[0:3]
	v_mfma_f32_16x16x32_bf16 v[0:3], v[214:217], v[198:201], v[0:3]
	s_barrier
	s_add_i32 s10, s37, 0xf80
	s_mov_b32 m0, s30
	ds_read_b128 v[154:157], v149
	ds_read_b128 v[158:161], v150
	ds_read_b128 v[162:165], v151
	ds_read_b128 v[150:153], v152
	ds_read_b128 v[166:169], v131
	ds_read_b128 v[170:173], v131 offset:1024
	ds_read_b128 v[174:177], v134
	ds_read_b128 v[178:181], v134 offset:1024
	ds_read_b128 v[182:185], v133
	ds_read_b128 v[186:189], v133 offset:1024
	ds_read_b128 v[190:193], v132
	ds_read_b128 v[194:197], v132 offset:1024
	buffer_load_dwordx4 v143, s[4:7], s10 offen lds
	s_mov_b32 m0, s31
	s_nop 0
	buffer_load_dwordx4 v144, s[4:7], s10 offen lds
	s_barrier
	s_waitcnt lgkmcnt(0)
	v_mfma_f32_16x16x32_bf16 v[124:127], v[154:157], v[166:169], v[124:127]
	v_mfma_f32_16x16x32_bf16 v[124:127], v[158:161], v[170:173], v[124:127]
	v_mfma_f32_16x16x32_bf16 v[120:123], v[162:165], v[166:169], v[120:123]
	v_mfma_f32_16x16x32_bf16 v[120:123], v[150:153], v[170:173], v[120:123]
	v_mfma_f32_16x16x32_bf16 v[116:119], v[154:157], v[174:177], v[116:119]
	v_mfma_f32_16x16x32_bf16 v[116:119], v[158:161], v[178:181], v[116:119]
	v_mfma_f32_16x16x32_bf16 v[112:115], v[162:165], v[174:177], v[112:115]
	v_mfma_f32_16x16x32_bf16 v[112:115], v[150:153], v[178:181], v[112:115]
	v_mfma_f32_16x16x32_bf16 v[108:111], v[154:157], v[182:185], v[108:111]
	v_mfma_f32_16x16x32_bf16 v[108:111], v[158:161], v[186:189], v[108:111]
	v_mfma_f32_16x16x32_bf16 v[104:107], v[162:165], v[182:185], v[104:107]
	v_mfma_f32_16x16x32_bf16 v[104:107], v[150:153], v[186:189], v[104:107]
	v_mfma_f32_16x16x32_bf16 v[100:103], v[154:157], v[190:193], v[100:103]
	v_mfma_f32_16x16x32_bf16 v[100:103], v[158:161], v[194:197], v[100:103]
	v_mfma_f32_16x16x32_bf16 v[96:99], v[162:165], v[190:193], v[96:99]
	v_mfma_f32_16x16x32_bf16 v[96:99], v[150:153], v[194:197], v[96:99]
	s_barrier
	ds_read_b128 v[198:201], v145
	ds_read_b128 v[202:205], v146
	ds_read_b128 v[144:147], v147
	ds_read_b128 v[206:209], v148
	s_barrier
	s_waitcnt lgkmcnt(0)
	v_mfma_f32_16x16x32_bf16 v[92:95], v[198:201], v[166:169], v[92:95]
	v_mfma_f32_16x16x32_bf16 v[84:87], v[198:201], v[174:177], v[84:87]
	v_mfma_f32_16x16x32_bf16 v[76:79], v[198:201], v[182:185], v[76:79]
	v_mfma_f32_16x16x32_bf16 v[68:71], v[198:201], v[190:193], v[68:71]
	v_mfma_f32_16x16x32_bf16 v[88:91], v[144:147], v[166:169], v[88:91]
	v_mfma_f32_16x16x32_bf16 v[80:83], v[144:147], v[174:177], v[80:83]
	v_mfma_f32_16x16x32_bf16 v[72:75], v[144:147], v[182:185], v[72:75]
	v_mfma_f32_16x16x32_bf16 v[64:67], v[144:147], v[190:193], v[64:67]
	v_mfma_f32_16x16x32_bf16 v[92:95], v[202:205], v[170:173], v[92:95]
	v_mfma_f32_16x16x32_bf16 v[84:87], v[202:205], v[178:181], v[84:87]
	v_mfma_f32_16x16x32_bf16 v[76:79], v[202:205], v[186:189], v[76:79]
	v_mfma_f32_16x16x32_bf16 v[68:71], v[202:205], v[194:197], v[68:71]
	v_mfma_f32_16x16x32_bf16 v[166:169], v[206:209], v[170:173], v[88:91]
	v_mfma_f32_16x16x32_bf16 v[170:173], v[206:209], v[178:181], v[80:83]
	v_mfma_f32_16x16x32_bf16 v[174:177], v[206:209], v[186:189], v[72:75]
	v_mfma_f32_16x16x32_bf16 v[178:181], v[206:209], v[194:197], v[64:67]
	s_barrier
	s_nop 0
	ds_read_b128 v[64:67], v131 offset:16384
	ds_read_b128 v[72:75], v131 offset:17408
	ds_read_b128 v[80:83], v134 offset:16384
	ds_read_b128 v[88:91], v134 offset:17408
	ds_read_b128 v[182:185], v133 offset:16384
	ds_read_b128 v[186:189], v133 offset:17408
	ds_read_b128 v[190:193], v132 offset:16384
	ds_read_b128 v[194:197], v132 offset:17408
	s_waitcnt vmcnt(4)
	s_barrier
; #define LDA(dst, b, h) _Pragma("unroll") for (int m = 0; m < 4; ++m) _Pragma("unroll") for (int k = 0; k < 2; ++k) \
;     dst[m][k] = *reinterpret_cast<const bf16x8*>(SA(b, h) + lds_byte(wr * 64 + m * 16 + fr, k * 32 + fq * 8))
; #define LDB(dst, b, h) _Pragma("unroll") for (int n = 0; n < 2; ++n) _Pragma("unroll") for (int k = 0; k < 2; ++k) \
;     dst[n][k] = *reinterpret_cast<const bf16x8*>(SB(b, h) + lds_byte(wc * 32 + n * 16 + fr, k * 32 + fq * 8))
; #define WAIT_V(n) asm volatile("s_waitcnt vmcnt(" #n ")" ::: "memory")
; #define WAIT_L(n) asm volatile("s_waitcnt lgkmcnt(" #n ")" ::: "memory")
; #define BAR __builtin_amdgcn_s_barrier()
;     ...
;       LDA(At, 0, 1); WAIT_V(4); BAR; WAIT_L(0); MMA(1, 0, At, B0); MMA(1, 1, At, B1); BAR; }
;     { LDB(B0, 1, 0); LDA(At, 1, 0); WAIT_V(2); BAR; WAIT_L(0); MMA(0, 0, At, B0); BAR;
;       LDB(B1, 1, 1); WAIT_V(0); BAR; WAIT_L(0); MMA(0, 1, At, B1); BAR;
	s_waitcnt lgkmcnt(0)
	v_mfma_f32_16x16x32_bf16 v[60:63], v[154:157], v[64:67], v[60:63]
	v_mfma_f32_16x16x32_bf16 v[56:59], v[162:165], v[64:67], v[56:59]
	v_mfma_f32_16x16x32_bf16 v[52:55], v[154:157], v[80:83], v[52:55]
	v_mfma_f32_16x16x32_bf16 v[48:51], v[162:165], v[80:83], v[48:51]
	v_mfma_f32_16x16x32_bf16 v[44:47], v[154:157], v[182:185], v[44:47]
	v_mfma_f32_16x16x32_bf16 v[40:43], v[162:165], v[182:185], v[40:43]
	v_mfma_f32_16x16x32_bf16 v[36:39], v[154:157], v[190:193], v[36:39]
	v_mfma_f32_16x16x32_bf16 v[32:35], v[162:165], v[190:193], v[32:35]
	v_mfma_f32_16x16x32_bf16 v[60:63], v[158:161], v[72:75], v[60:63]
	v_mfma_f32_16x16x32_bf16 v[56:59], v[150:153], v[72:75], v[56:59]
	v_mfma_f32_16x16x32_bf16 v[52:55], v[158:161], v[88:91], v[52:55]
	v_mfma_f32_16x16x32_bf16 v[48:51], v[150:153], v[88:91], v[48:51]
	v_mfma_f32_16x16x32_bf16 v[44:47], v[158:161], v[186:189], v[44:47]
	v_mfma_f32_16x16x32_bf16 v[40:43], v[150:153], v[186:189], v[40:43]
	v_mfma_f32_16x16x32_bf16 v[36:39], v[158:161], v[194:197], v[36:39]
	v_mfma_f32_16x16x32_bf16 v[32:35], v[150:153], v[194:197], v[32:35]
	v_mfma_f32_16x16x32_bf16 v[28:31], v[198:201], v[64:67], v[28:31]
	v_mfma_f32_16x16x32_bf16 v[20:23], v[198:201], v[80:83], v[20:23]
	v_mfma_f32_16x16x32_bf16 v[12:15], v[198:201], v[182:185], v[12:15]
	v_mfma_f32_16x16x32_bf16 v[4:7], v[198:201], v[190:193], v[4:7]
	v_mfma_f32_16x16x32_bf16 v[24:27], v[144:147], v[64:67], v[24:27]
	v_mfma_f32_16x16x32_bf16 v[16:19], v[144:147], v[80:83], v[16:19]
	v_mfma_f32_16x16x32_bf16 v[8:11], v[144:147], v[182:185], v[8:11]
	v_mfma_f32_16x16x32_bf16 v[0:3], v[144:147], v[190:193], v[0:3]
	v_mfma_f32_16x16x32_bf16 v[28:31], v[202:205], v[72:75], v[28:31]
	v_mfma_f32_16x16x32_bf16 v[20:23], v[202:205], v[88:91], v[20:23]
	v_mfma_f32_16x16x32_bf16 v[12:15], v[202:205], v[186:189], v[12:15]
	v_mfma_f32_16x16x32_bf16 v[4:7], v[202:205], v[194:197], v[4:7]
	v_mfma_f32_16x16x32_bf16 v[144:147], v[206:209], v[72:75], v[24:27]
	v_mfma_f32_16x16x32_bf16 v[148:151], v[206:209], v[88:91], v[16:19]
	v_mfma_f32_16x16x32_bf16 v[152:155], v[206:209], v[186:189], v[8:11]
	v_mfma_f32_16x16x32_bf16 v[156:159], v[206:209], v[194:197], v[0:3]
	s_barrier
	s_nop 0
	ds_read_b128 v[0:3], v139
	ds_read_b128 v[8:11], v140
	ds_read_b128 v[16:19], v141
	ds_read_b128 v[140:143], v142
	ds_read_b128 v[24:27], v131 offset:32768
	ds_read_b128 v[160:163], v131 offset:33792
	ds_read_b128 v[182:185], v134 offset:32768
	ds_read_b128 v[186:189], v134 offset:33792
	ds_read_b128 v[190:193], v133 offset:32768
	ds_read_b128 v[194:197], v133 offset:33792
	ds_read_b128 v[198:201], v132 offset:32768
	ds_read_b128 v[202:205], v132 offset:33792
	s_waitcnt vmcnt(2)
	s_barrier
	s_waitcnt lgkmcnt(0)
	v_mfma_f32_16x16x32_bf16 v[64:67], v[0:3], v[24:27], v[124:127]
	v_mfma_f32_16x16x32_bf16 v[72:75], v[16:19], v[24:27], v[120:123]
	v_mfma_f32_16x16x32_bf16 v[80:83], v[0:3], v[182:185], v[116:119]
	v_mfma_f32_16x16x32_bf16 v[88:91], v[16:19], v[182:185], v[112:115]
	v_mfma_f32_16x16x32_bf16 v[108:111], v[0:3], v[190:193], v[108:111]
	v_mfma_f32_16x16x32_bf16 v[116:119], v[16:19], v[190:193], v[104:107]
	v_mfma_f32_16x16x32_bf16 v[100:103], v[0:3], v[198:201], v[100:103]
	v_mfma_f32_16x16x32_bf16 v[124:127], v[16:19], v[198:201], v[96:99]
	v_mfma_f32_16x16x32_bf16 v[120:123], v[8:11], v[160:163], v[64:67]
	v_mfma_f32_16x16x32_bf16 v[112:115], v[140:143], v[160:163], v[72:75]
	v_mfma_f32_16x16x32_bf16 v[104:107], v[8:11], v[186:189], v[80:83]
	v_mfma_f32_16x16x32_bf16 v[96:99], v[140:143], v[186:189], v[88:91]
	v_mfma_f32_16x16x32_bf16 v[88:91], v[8:11], v[194:197], v[108:111]
	v_mfma_f32_16x16x32_bf16 v[80:83], v[140:143], v[194:197], v[116:119]
	v_mfma_f32_16x16x32_bf16 v[72:75], v[8:11], v[202:205], v[100:103]
	v_mfma_f32_16x16x32_bf16 v[64:67], v[140:143], v[202:205], v[124:127]
	s_barrier
	ds_read_b128 v[206:209], v135
	ds_read_b128 v[210:213], v136
	ds_read_b128 v[214:217], v137
	ds_read_b128 v[136:139], v138
	s_waitcnt vmcnt(0)
	s_barrier
; #define LDA(dst, b, h) _Pragma("unroll") for (int m = 0; m < 4; ++m) _Pragma("unroll") for (int k = 0; k < 2; ++k) \
;     dst[m][k] = *reinterpret_cast<const bf16x8*>(SA(b, h) + lds_byte(wr * 64 + m * 16 + fr, k * 32 + fq * 8))
; #define LDB(dst, b, h) _Pragma("unroll") for (int n = 0; n < 2; ++n) _Pragma("unroll") for (int k = 0; k < 2; ++k) \
;     dst[n][k] = *reinterpret_cast<const bf16x8*>(SB(b, h) + lds_byte(wc * 32 + n * 16 + fr, k * 32 + fq * 8))
; #define WAIT_V(n) asm volatile("s_waitcnt vmcnt(" #n ")" ::: "memory")
; #define WAIT_L(n) asm volatile("s_waitcnt lgkmcnt(" #n ")" ::: "memory")
; #define BAR __builtin_amdgcn_s_barrier()
;     ...
;       LDB(B1, 1, 1); WAIT_V(0); BAR; WAIT_L(0); MMA(0, 1, At, B1); BAR;
;       LDA(At, 1, 1); BAR; WAIT_L(0); MMA(1, 0, At, B0); MMA(1, 1, At, B1); BAR; }
;     if (wr == 0) BAR;
	s_waitcnt lgkmcnt(0)
	v_mfma_f32_16x16x32_bf16 v[92:95], v[206:209], v[24:27], v[92:95]
	v_mfma_f32_16x16x32_bf16 v[24:27], v[214:217], v[24:27], v[166:169]
	v_mfma_f32_16x16x32_bf16 v[84:87], v[206:209], v[182:185], v[84:87]
	v_mfma_f32_16x16x32_bf16 v[100:103], v[214:217], v[182:185], v[170:173]
	v_mfma_f32_16x16x32_bf16 v[76:79], v[206:209], v[190:193], v[76:79]
	v_mfma_f32_16x16x32_bf16 v[164:167], v[214:217], v[190:193], v[174:177]
	v_mfma_f32_16x16x32_bf16 v[68:71], v[206:209], v[198:201], v[68:71]
	v_mfma_f32_16x16x32_bf16 v[168:171], v[214:217], v[198:201], v[178:181]
	v_mfma_f32_16x16x32_bf16 v[124:127], v[210:213], v[160:163], v[92:95]
	v_mfma_f32_16x16x32_bf16 v[116:119], v[136:139], v[160:163], v[24:27]
	v_mfma_f32_16x16x32_bf16 v[108:111], v[210:213], v[186:189], v[84:87]
	v_mfma_f32_16x16x32_bf16 v[100:103], v[136:139], v[186:189], v[100:103]
	v_mfma_f32_16x16x32_bf16 v[92:95], v[210:213], v[194:197], v[76:79]
	v_mfma_f32_16x16x32_bf16 v[84:87], v[136:139], v[194:197], v[164:167]
	v_mfma_f32_16x16x32_bf16 v[76:79], v[210:213], v[202:205], v[68:71]
	v_mfma_f32_16x16x32_bf16 v[68:71], v[136:139], v[202:205], v[168:171]
	s_barrier
	ds_read_b128 v[160:163], v131 offset:49152
	ds_read_b128 v[164:167], v131 offset:50176
	ds_read_b128 v[168:171], v134 offset:49152
	ds_read_b128 v[172:175], v134 offset:50176
	ds_read_b128 v[176:179], v133 offset:49152
	ds_read_b128 v[180:183], v133 offset:50176
	ds_read_b128 v[184:187], v132 offset:49152
	ds_read_b128 v[132:135], v132 offset:50176
	s_barrier
	s_waitcnt lgkmcnt(0)
	v_mfma_f32_16x16x32_bf16 v[24:27], v[0:3], v[160:163], v[60:63]
	v_mfma_f32_16x16x32_bf16 v[60:63], v[16:19], v[160:163], v[56:59]
	v_mfma_f32_16x16x32_bf16 v[52:55], v[0:3], v[168:171], v[52:55]
	v_mfma_f32_16x16x32_bf16 v[188:191], v[16:19], v[168:171], v[48:51]
	v_mfma_f32_16x16x32_bf16 v[44:47], v[0:3], v[176:179], v[44:47]
	v_mfma_f32_16x16x32_bf16 v[192:195], v[16:19], v[176:179], v[40:43]
	v_mfma_f32_16x16x32_bf16 v[0:3], v[0:3], v[184:187], v[36:39]
	v_mfma_f32_16x16x32_bf16 v[36:39], v[16:19], v[184:187], v[32:35]
	v_mfma_f32_16x16x32_bf16 v[56:59], v[8:11], v[164:167], v[24:27]
	v_mfma_f32_16x16x32_bf16 v[48:51], v[140:143], v[164:167], v[60:63]
	v_mfma_f32_16x16x32_bf16 v[40:43], v[8:11], v[172:175], v[52:55]
	v_mfma_f32_16x16x32_bf16 v[32:35], v[140:143], v[172:175], v[188:191]
	v_mfma_f32_16x16x32_bf16 v[24:27], v[8:11], v[180:183], v[44:47]
	v_mfma_f32_16x16x32_bf16 v[16:19], v[140:143], v[180:183], v[192:195]
	v_mfma_f32_16x16x32_bf16 v[8:11], v[8:11], v[132:135], v[0:3]
	v_mfma_f32_16x16x32_bf16 v[0:3], v[140:143], v[132:135], v[36:39]
	v_mfma_f32_16x16x32_bf16 v[28:31], v[206:209], v[160:163], v[28:31]
	v_mfma_f32_16x16x32_bf16 v[36:39], v[214:217], v[160:163], v[144:147]
	v_mfma_f32_16x16x32_bf16 v[20:23], v[206:209], v[168:171], v[20:23]
	v_mfma_f32_16x16x32_bf16 v[140:143], v[214:217], v[168:171], v[148:151]
	v_mfma_f32_16x16x32_bf16 v[12:15], v[206:209], v[176:179], v[12:15]
	v_mfma_f32_16x16x32_bf16 v[144:147], v[214:217], v[176:179], v[152:155]
	v_mfma_f32_16x16x32_bf16 v[4:7], v[206:209], v[184:187], v[4:7]
	v_mfma_f32_16x16x32_bf16 v[148:151], v[214:217], v[184:187], v[156:159]
	v_mfma_f32_16x16x32_bf16 v[60:63], v[210:213], v[164:167], v[28:31]
	v_mfma_f32_16x16x32_bf16 v[52:55], v[136:139], v[164:167], v[36:39]
	v_mfma_f32_16x16x32_bf16 v[44:47], v[210:213], v[172:175], v[20:23]
	v_mfma_f32_16x16x32_bf16 v[36:39], v[136:139], v[172:175], v[140:143]
	v_mfma_f32_16x16x32_bf16 v[28:31], v[210:213], v[180:183], v[12:15]
	v_mfma_f32_16x16x32_bf16 v[20:23], v[136:139], v[180:183], v[144:147]
	v_mfma_f32_16x16x32_bf16 v[12:15], v[210:213], v[132:135], v[4:7]
	v_mfma_f32_16x16x32_bf16 v[4:7], v[136:139], v[132:135], v[148:151]
	v_cmp_gt_u32_e32 vcc, s35, v130
	s_barrier
	s_and_saveexec_b64 s[10:11], vcc
	s_cbranch_execz .LBB0_357
	s_barrier

; #define WAIT_V(n) asm volatile("s_waitcnt vmcnt(" #n ")" ::: "memory")
; #define BAR __builtin_amdgcn_s_barrier()
;     ...
;     const int tid = opaque_tid(wave);
;     const int wid = tid >> 6, lane = tid & 63, wr = wid >> 2, wc = wid & 3, fr = lane & 15, fq = lane >> 4;
;     int offA[2], offB[2];
;     _Pragma("unroll") for (int i = 0; i < 2; ++i) {
;       int r, c; stage_rc(tid * 16 + i * 8192, r, c);
;       offA[i] = (r * lda + c) * 2; offB[i] = (r * ldb + c) * 2;
;     }
;     const int brow = pm * BM;
;     f32x4 acc[2][2][4][2];
;     _Pragma("unroll") for (int a = 0; a < 2; ++a) _Pragma("unroll") for (int b = 0; b < 2; ++b) _Pragma("unroll") for (int m = 0; m < 4; ++m) _Pragma("unroll") for (int n = 0; n < 2; ++n)
;       acc[a][b][m][n] = f32x4{0.f, 0.f, 0.f, 0.f};
;     bf16x8 At[4][2], B0[2][2], B1[2][2];
;     if (wr == 1) BAR;
;     if (first_tile) { WAIT_V(0); }
;     else if constexpr (mode == MODE_RESID_LN) { WAIT_V(0); }
;     else if constexpr (mode == MODE_SWIGLU) { WAIT_V(6); }
;     else if constexpr (mode == MODE_V) { WAIT_V(24); }
;     else { WAIT_V(12); }
;     first_tile = false;
;     BAR;
;     BAR;
.LBB0_391:
	v_bfe_i32 v4, v128, 27, 1
	v_lshlrev_b32_e32 v2, 4, v128
	v_lshrrev_b32_e32 v4, 22, v4
	v_add_u32_e32 v4, v2, v4
	v_and_b32_e32 v4, 0xfffffc00, v4
	v_sub_u32_e32 v4, v2, v4
	v_lshrrev_b32_e32 v5, 4, v4
	v_bitop3_b32 v4, v5, v4, 32 bitop3:0x6c
	v_ashrrev_i32_e32 v3, 31, v128
	v_ashrrev_i32_e32 v6, 31, v4
	v_lshrrev_b32_e32 v3, 26, v3
	v_lshrrev_b32_e32 v6, 26, v6
	v_add_u32_e32 v3, v128, v3
	v_add_u32_e32 v6, v4, v6
	v_ashrrev_i32_e32 v3, 6, v3
	v_lshrrev_b32_e32 v7, 6, v6
	v_and_b32_e32 v6, 0xc0, v6
	v_lshlrev_b32_e32 v5, 3, v3
	v_lshlrev_b32_e32 v3, 5, v3
	v_sub_u32_e32 v4, v4, v6
	v_and_b32_e32 v5, 0x7fff0, v5
	v_and_b32_e32 v3, 32, v3
	v_ashrrev_i16_sdwa v4, v216, sext(v4) dst_sel:DWORD dst_unused:UNUSED_PAD src0_sel:DWORD src1_sel:BYTE_0
	v_add_u32_sdwa v3, v3, sext(v4) dst_sel:DWORD dst_unused:UNUSED_PAD src0_sel:DWORD src1_sel:WORD_0
	v_add_lshl_u32 v4, v7, v5, 13
	v_add_u32_e32 v2, 0x2000, v2
	v_lshl_add_u32 v141, v3, 1, v4
	v_ashrrev_i32_e32 v3, 31, v2
	v_lshrrev_b32_e32 v3, 22, v3
	v_add_u32_e32 v3, v2, v3
	v_ashrrev_i32_e32 v3, 10, v3
	v_mul_i32_i24_e32 v4, 0x400, v3
	v_sub_u32_e32 v2, v2, v4
	v_lshrrev_b32_e32 v4, 4, v2
	v_bitop3_b32 v2, v4, v2, 32 bitop3:0x6c
	v_ashrrev_i32_e32 v5, 31, v2
	v_lshrrev_b32_e32 v5, 26, v5
	v_add_u32_e32 v5, v2, v5
	v_lshrrev_b32_e32 v6, 6, v5
	v_and_b32_e32 v5, 0xc0, v5
	v_lshlrev_b32_e32 v4, 3, v3
	v_lshlrev_b32_e32 v3, 5, v3
	v_sub_u32_e32 v2, v2, v5
	v_and_b32_e32 v4, 0x7fff0, v4
	v_and_b32_e32 v3, 32, v3
	v_ashrrev_i16_sdwa v2, v216, sext(v2) dst_sel:DWORD dst_unused:UNUSED_PAD src0_sel:DWORD src1_sel:BYTE_0
	v_add_u32_sdwa v2, v3, sext(v2) dst_sel:DWORD dst_unused:UNUSED_PAD src0_sel:DWORD src1_sel:WORD_0
	v_add_lshl_u32 v3, v6, v4, 13
	v_lshl_add_u32 v142, v2, 1, v3
	v_and_b32_e32 v3, 15, v0
	v_lshlrev_b32_e32 v5, 2, v0
	v_and_b32_e32 v2, 48, v0
	v_lshlrev_b32_e32 v3, 6, v3
	v_and_b32_e32 v5, 32, v5
	v_or_b32_e32 v4, v3, v2
	v_bitop3_b32 v3, v3, v5, v2 bitop3:0x36
	v_lshlrev_b32_e32 v6, 6, v128
	s_movk_i32 s1, 0x3000
	v_and_or_b32 v3, v6, s1, v3
	v_lshlrev_b32_e32 v0, 6, v0
	s_movk_i32 s1, 0x3c0
	v_lshlrev_b32_e32 v1, 13, v1
	v_and_or_b32 v0, v0, s1, v2
	v_bitop3_b32 v0, v1, v0, v5 bitop3:0xf6
	v_or_b32_e32 v6, 0x400, v3
	v_or_b32_e32 v7, 0x800, v3
	v_or_b32_e32 v8, 0xc00, v3
	v_or_b32_e32 v132, 0x800, v0
	v_or_b32_e32 v131, 0x1000, v0
	v_or_b32_e32 v130, 0x1800, v0
	v_mov_b32_e32 v0, 0
	v_bitop3_b32 v129, v4, v1, v5 bitop3:0xde
	s_mov_b32 s1, -2
	s_mov_b32 s3, 0
	v_or_b32_e32 v147, 0x10000, v3
	v_or_b32_e32 v148, 0x10000, v6
	v_or_b32_e32 v149, 0x10000, v7
	v_or_b32_e32 v150, 0x10000, v8
	v_or_b32_e32 v143, 0x14000, v3
	v_or_b32_e32 v144, 0x14000, v6
	v_or_b32_e32 v145, 0x14000, v7
	v_or_b32_e32 v146, 0x14000, v8
	v_or_b32_e32 v137, 0x18000, v3
	v_or_b32_e32 v138, 0x18000, v6
	v_or_b32_e32 v139, 0x18000, v7
	v_or_b32_e32 v140, 0x18000, v8
	v_or_b32_e32 v133, 0x1c000, v3
	v_or_b32_e32 v134, 0x1c000, v6
	v_or_b32_e32 v135, 0x1c000, v7
	v_or_b32_e32 v136, 0x1c000, v8
	v_mov_b32_e32 v1, v0
	v_mov_b32_e32 v2, v0
	v_mov_b32_e32 v3, v0
	v_mov_b32_e32 v4, v0
	v_mov_b32_e32 v5, v0
	v_mov_b32_e32 v6, v0
	v_mov_b32_e32 v7, v0
	v_mov_b32_e32 v8, v0
	v_mov_b32_e32 v9, v0
	v_mov_b32_e32 v10, v0
	v_mov_b32_e32 v11, v0
	v_mov_b32_e32 v12, v0
	v_mov_b32_e32 v13, v0
	v_mov_b32_e32 v14, v0
	v_mov_b32_e32 v15, v0
	v_mov_b32_e32 v16, v0
	v_mov_b32_e32 v17, v0
	v_mov_b32_e32 v18, v0
	v_mov_b32_e32 v19, v0
	v_mov_b32_e32 v20, v0
	v_mov_b32_e32 v21, v0
	v_mov_b32_e32 v22, v0
	v_mov_b32_e32 v23, v0
	v_mov_b32_e32 v24, v0
	v_mov_b32_e32 v25, v0
	v_mov_b32_e32 v26, v0
	v_mov_b32_e32 v27, v0
	v_mov_b32_e32 v28, v0
	v_mov_b32_e32 v29, v0
	v_mov_b32_e32 v30, v0
	v_mov_b32_e32 v31, v0
	v_mov_b32_e32 v32, v0
	v_mov_b32_e32 v33, v0
	v_mov_b32_e32 v34, v0
	v_mov_b32_e32 v35, v0
	v_mov_b32_e32 v36, v0
	v_mov_b32_e32 v37, v0
	v_mov_b32_e32 v38, v0
	v_mov_b32_e32 v39, v0
	v_mov_b32_e32 v40, v0
	v_mov_b32_e32 v41, v0
	v_mov_b32_e32 v42, v0
	v_mov_b32_e32 v43, v0
	v_mov_b32_e32 v44, v0
	v_mov_b32_e32 v45, v0
	v_mov_b32_e32 v46, v0
	v_mov_b32_e32 v47, v0
	v_mov_b32_e32 v48, v0
	v_mov_b32_e32 v49, v0
	v_mov_b32_e32 v50, v0
	v_mov_b32_e32 v51, v0
	v_mov_b32_e32 v52, v0
	v_mov_b32_e32 v53, v0
	v_mov_b32_e32 v54, v0
	v_mov_b32_e32 v55, v0
	v_mov_b32_e32 v56, v0
	v_mov_b32_e32 v57, v0
	v_mov_b32_e32 v58, v0
	v_mov_b32_e32 v59, v0
	v_mov_b32_e32 v60, v0
	v_mov_b32_e32 v61, v0
	v_mov_b32_e32 v62, v0
	v_mov_b32_e32 v63, v0
	v_mov_b32_e32 v68, v0
	v_mov_b32_e32 v69, v0
	v_mov_b32_e32 v70, v0
	v_mov_b32_e32 v71, v0
	v_mov_b32_e32 v80, v0
	v_mov_b32_e32 v81, v0
	v_mov_b32_e32 v82, v0
	v_mov_b32_e32 v83, v0
	v_mov_b32_e32 v88, v0
	v_mov_b32_e32 v89, v0
	v_mov_b32_e32 v90, v0
	v_mov_b32_e32 v91, v0
	v_mov_b32_e32 v92, v0
	v_mov_b32_e32 v93, v0
	v_mov_b32_e32 v94, v0
	v_mov_b32_e32 v95, v0
	v_mov_b32_e32 v96, v0
	v_mov_b32_e32 v97, v0
	v_mov_b32_e32 v98, v0
	v_mov_b32_e32 v99, v0
	v_mov_b32_e32 v100, v0
	v_mov_b32_e32 v101, v0
	v_mov_b32_e32 v102, v0
	v_mov_b32_e32 v103, v0
	v_mov_b32_e32 v104, v0
	v_mov_b32_e32 v105, v0
	v_mov_b32_e32 v106, v0
	v_mov_b32_e32 v107, v0
	v_mov_b32_e32 v108, v0
	v_mov_b32_e32 v109, v0
	v_mov_b32_e32 v110, v0
	v_mov_b32_e32 v111, v0
	v_mov_b32_e32 v112, v0
	v_mov_b32_e32 v113, v0
	v_mov_b32_e32 v114, v0
	v_mov_b32_e32 v115, v0
	v_mov_b32_e32 v116, v0
	v_mov_b32_e32 v117, v0
	v_mov_b32_e32 v118, v0
	v_mov_b32_e32 v119, v0
	v_mov_b32_e32 v120, v0
	v_mov_b32_e32 v121, v0
	v_mov_b32_e32 v122, v0
	v_mov_b32_e32 v123, v0
	v_mov_b32_e32 v124, v0
	v_mov_b32_e32 v125, v0
	v_mov_b32_e32 v126, v0
	v_mov_b32_e32 v127, v0
	v_mov_b32_e32 v64, v0
	v_mov_b32_e32 v65, v0
	v_mov_b32_e32 v66, v0
	v_mov_b32_e32 v67, v0
	v_mov_b32_e32 v72, v0
	v_mov_b32_e32 v73, v0
	v_mov_b32_e32 v74, v0
	v_mov_b32_e32 v75, v0
	v_mov_b32_e32 v76, v0
	v_mov_b32_e32 v77, v0
	v_mov_b32_e32 v78, v0
	v_mov_b32_e32 v79, v0
	v_mov_b32_e32 v84, v0
	v_mov_b32_e32 v85, v0
	v_mov_b32_e32 v86, v0
	v_mov_b32_e32 v87, v0
	s_barrier
	s_barrier
	s_branch .Lmy_rot_392

; #define STAGE(P, RS, SOFF, OFF, kt) do { const int _so = (SOFF) + (kt) * (BK * 2); \
;     _Pragma("unroll") for (int _i = 0; _i < 2; ++_i) { \
;       __builtin_amdgcn_raw_ptr_buffer_load_lds(RS, (__attribute__((address_space(3))) void*)((P) + wave * 1024 + _i * 8192), 16, OFF[_i], _so, 0, 0); } } while (0)
; #define LDA(dst, b, h) _Pragma("unroll") for (int m = 0; m < 4; ++m) _Pragma("unroll") for (int k = 0; k < 2; ++k) \
;     dst[m][k] = *reinterpret_cast<const bf16x8*>(SA(b, h) + lds_byte(wr * 64 + m * 16 + fr, k * 32 + fq * 8))
; #define LDB(dst, b, h) _Pragma("unroll") for (int n = 0; n < 2; ++n) _Pragma("unroll") for (int k = 0; k < 2; ++k) \
;     dst[n][k] = *reinterpret_cast<const bf16x8*>(SB(b, h) + lds_byte(wc * 32 + n * 16 + fr, k * 32 + fq * 8))
; #define WAIT_V(n) asm volatile("s_waitcnt vmcnt(" #n ")" ::: "memory")
; #define WAIT_L(n) asm volatile("s_waitcnt lgkmcnt(" #n ")" ::: "memory")
; #define BAR __builtin_amdgcn_s_barrier()
; #define SCHED __builtin_amdgcn_sched_barrier(0)
;     ...
;       LDB(B0, 0, 0); SCHED; LDA(At, 0, 0); STAGE(SA(1, 1), rsA, sA1, offA, t + 1);
;       WAIT_L(8); BAR; WAIT_L(0); MMA(0, 0, At, B0); BAR; SCHED;
;       LDB(B1, 0, 1); STAGE(SB(0, 0), rsB, sB0, offB, t + 2);
;       BAR; WAIT_L(0); MMA(0, 1, At, B1); BAR;
;       LDA(At, 0, 1); STAGE(SA(0, 0), rsA, sA0, offA, t + 2);
;       BAR; WAIT_L(0); MMA(1, 0, At, B0); BAR; SCHED;
;       STAGE(SB(0, 1), rsB, sB1, offB, t + 2);
;       WAIT_V(6); BAR; MMA(1, 1, At, B1); BAR;
.Lmy_rot_392:
	ds_read_b128 v[152:155], v147
	ds_read_b128 v[156:159], v148
	ds_read_b128 v[160:163], v149
	ds_read_b128 v[164:167], v150
	s_add_i32 s5, s86, s3
	s_add_i32 s6, s5, 0x80
	s_mov_b32 m0, s36
	ds_read_b128 v[168:171], v129
	ds_read_b128 v[172:175], v129 offset:1024
	ds_read_b128 v[176:179], v132
	ds_read_b128 v[180:183], v132 offset:1024
	ds_read_b128 v[184:187], v131
	ds_read_b128 v[188:191], v131 offset:1024
	ds_read_b128 v[192:195], v130
	ds_read_b128 v[196:199], v130 offset:1024
	buffer_load_dwordx4 v141, s[8:11], s6 offen lds
	s_mov_b32 m0, s59
	s_nop 0
	buffer_load_dwordx4 v142, s[8:11], s6 offen lds
	s_waitcnt lgkmcnt(8)
	s_barrier
	s_waitcnt lgkmcnt(0)
	v_mfma_f32_16x16x32_bf16 v[124:127], v[152:155], v[168:171], v[124:127]
	v_mfma_f32_16x16x32_bf16 v[124:127], v[156:159], v[172:175], v[124:127]
	v_mfma_f32_16x16x32_bf16 v[120:123], v[160:163], v[168:171], v[120:123]
	v_mfma_f32_16x16x32_bf16 v[120:123], v[164:167], v[172:175], v[120:123]
	v_mfma_f32_16x16x32_bf16 v[116:119], v[152:155], v[176:179], v[116:119]
	v_mfma_f32_16x16x32_bf16 v[116:119], v[156:159], v[180:183], v[116:119]
	v_mfma_f32_16x16x32_bf16 v[112:115], v[160:163], v[176:179], v[112:115]
	v_mfma_f32_16x16x32_bf16 v[112:115], v[164:167], v[180:183], v[112:115]
	v_mfma_f32_16x16x32_bf16 v[108:111], v[152:155], v[184:187], v[108:111]
	v_mfma_f32_16x16x32_bf16 v[108:111], v[156:159], v[188:191], v[108:111]
	v_mfma_f32_16x16x32_bf16 v[104:107], v[160:163], v[184:187], v[104:107]
	v_mfma_f32_16x16x32_bf16 v[104:107], v[164:167], v[188:191], v[104:107]
	v_mfma_f32_16x16x32_bf16 v[100:103], v[152:155], v[192:195], v[100:103]
	v_mfma_f32_16x16x32_bf16 v[100:103], v[156:159], v[196:199], v[100:103]
	v_mfma_f32_16x16x32_bf16 v[96:99], v[160:163], v[192:195], v[96:99]
	v_mfma_f32_16x16x32_bf16 v[96:99], v[164:167], v[196:199], v[96:99]
	s_barrier
	s_add_i32 s6, s92, s3
	s_add_i32 s7, s6, 0x100
	s_mov_b32 s14, s10
	s_mov_b32 s15, s11
	s_mov_b32 m0, s37
	ds_read_b128 v[200:203], v143
	ds_read_b128 v[204:207], v144
	ds_read_b128 v[208:211], v145
	ds_read_b128 v[212:215], v146
	buffer_load_dwordx4 v141, s[12:15], s7 offen lds
	s_mov_b32 m0, s48
	s_nop 0
	buffer_load_dwordx4 v142, s[12:15], s7 offen lds
	s_barrier
	s_waitcnt lgkmcnt(0)
	v_mfma_f32_16x16x32_bf16 v[92:95], v[200:203], v[168:171], v[92:95]
	v_mfma_f32_16x16x32_bf16 v[92:95], v[204:207], v[172:175], v[92:95]
	v_mfma_f32_16x16x32_bf16 v[88:91], v[208:211], v[168:171], v[88:91]
	v_mfma_f32_16x16x32_bf16 v[88:91], v[212:215], v[172:175], v[88:91]
	v_mfma_f32_16x16x32_bf16 v[80:83], v[200:203], v[176:179], v[80:83]
	v_mfma_f32_16x16x32_bf16 v[80:83], v[204:207], v[180:183], v[80:83]
	v_mfma_f32_16x16x32_bf16 v[68:71], v[208:211], v[176:179], v[68:71]
	v_mfma_f32_16x16x32_bf16 v[68:71], v[212:215], v[180:183], v[68:71]
	v_mfma_f32_16x16x32_bf16 v[60:63], v[200:203], v[184:187], v[60:63]
	v_mfma_f32_16x16x32_bf16 v[60:63], v[204:207], v[188:191], v[60:63]
	v_mfma_f32_16x16x32_bf16 v[56:59], v[208:211], v[184:187], v[56:59]
	v_mfma_f32_16x16x32_bf16 v[56:59], v[212:215], v[188:191], v[56:59]
	v_mfma_f32_16x16x32_bf16 v[52:55], v[200:203], v[192:195], v[52:55]
	v_mfma_f32_16x16x32_bf16 v[52:55], v[204:207], v[196:199], v[52:55]
	v_mfma_f32_16x16x32_bf16 v[48:51], v[208:211], v[192:195], v[48:51]
	v_mfma_f32_16x16x32_bf16 v[48:51], v[212:215], v[196:199], v[48:51]
	s_barrier
	s_add_i32 s7, s87, s3
	s_add_i32 s22, s7, 0x100
	s_mov_b32 m0, s35
	ds_read_b128 v[168:171], v129 offset:16384
	ds_read_b128 v[172:175], v129 offset:17408
	ds_read_b128 v[176:179], v132 offset:16384
	ds_read_b128 v[180:183], v132 offset:17408
	ds_read_b128 v[184:187], v131 offset:16384
	ds_read_b128 v[188:191], v131 offset:17408
	ds_read_b128 v[192:195], v130 offset:16384
	ds_read_b128 v[196:199], v130 offset:17408
	buffer_load_dwordx4 v141, s[8:11], s22 offen lds
	s_mov_b32 m0, s49
	s_nop 0
	buffer_load_dwordx4 v142, s[8:11], s22 offen lds
	s_barrier
	s_waitcnt lgkmcnt(0)
	v_mfma_f32_16x16x32_bf16 v[44:47], v[152:155], v[168:171], v[44:47]
	v_mfma_f32_16x16x32_bf16 v[44:47], v[156:159], v[172:175], v[44:47]
	v_mfma_f32_16x16x32_bf16 v[40:43], v[160:163], v[168:171], v[40:43]
	v_mfma_f32_16x16x32_bf16 v[40:43], v[164:167], v[172:175], v[40:43]
	v_mfma_f32_16x16x32_bf16 v[36:39], v[152:155], v[176:179], v[36:39]
	v_mfma_f32_16x16x32_bf16 v[36:39], v[156:159], v[180:183], v[36:39]
	v_mfma_f32_16x16x32_bf16 v[32:35], v[160:163], v[176:179], v[32:35]
	v_mfma_f32_16x16x32_bf16 v[32:35], v[164:167], v[180:183], v[32:35]
	v_mfma_f32_16x16x32_bf16 v[28:31], v[152:155], v[184:187], v[28:31]
	v_mfma_f32_16x16x32_bf16 v[28:31], v[156:159], v[188:191], v[28:31]
	v_mfma_f32_16x16x32_bf16 v[24:27], v[160:163], v[184:187], v[24:27]
	v_mfma_f32_16x16x32_bf16 v[24:27], v[164:167], v[188:191], v[24:27]
	v_mfma_f32_16x16x32_bf16 v[20:23], v[152:155], v[192:195], v[20:23]
	v_mfma_f32_16x16x32_bf16 v[20:23], v[156:159], v[196:199], v[20:23]
	v_mfma_f32_16x16x32_bf16 v[16:19], v[160:163], v[192:195], v[16:19]
	v_mfma_f32_16x16x32_bf16 v[16:19], v[164:167], v[196:199], v[16:19]
	s_barrier
	s_add_i32 s22, s93, s3
	s_add_i32 s23, s22, 0x100
	s_mov_b32 m0, s38
	s_nop 0
	buffer_load_dwordx4 v141, s[12:15], s23 offen lds
	s_mov_b32 m0, s54
	s_nop 0
	buffer_load_dwordx4 v142, s[12:15], s23 offen lds
	s_waitcnt vmcnt(6)
	s_barrier
; #define STAGE(P, RS, SOFF, OFF, kt) do { const int _so = (SOFF) + (kt) * (BK * 2); \
;     _Pragma("unroll") for (int _i = 0; _i < 2; ++_i) { \
;       __builtin_amdgcn_raw_ptr_buffer_load_lds(RS, (__attribute__((address_space(3))) void*)((P) + wave * 1024 + _i * 8192), 16, OFF[_i], _so, 0, 0); } } while (0)
; #define LDA(dst, b, h) _Pragma("unroll") for (int m = 0; m < 4; ++m) _Pragma("unroll") for (int k = 0; k < 2; ++k) \
;     dst[m][k] = *reinterpret_cast<const bf16x8*>(SA(b, h) + lds_byte(wr * 64 + m * 16 + fr, k * 32 + fq * 8))
; #define LDB(dst, b, h) _Pragma("unroll") for (int n = 0; n < 2; ++n) _Pragma("unroll") for (int k = 0; k < 2; ++k) \
;     dst[n][k] = *reinterpret_cast<const bf16x8*>(SB(b, h) + lds_byte(wc * 32 + n * 16 + fr, k * 32 + fq * 8))
; #define WAIT_V(n) asm volatile("s_waitcnt vmcnt(" #n ")" ::: "memory")
; #define WAIT_L(n) asm volatile("s_waitcnt lgkmcnt(" #n ")" ::: "memory")
; #define BAR __builtin_amdgcn_s_barrier()
; #define SCHED __builtin_amdgcn_sched_barrier(0)
;     ...
;       WAIT_V(6); BAR; MMA(1, 1, At, B1); BAR;
;       LDB(B0, 1, 0); SCHED; LDA(At, 1, 0); STAGE(SA(0, 1), rsA, sA1, offA, t + 2);
;       WAIT_L(8); BAR; WAIT_L(0); MMA(0, 0, At, B0); BAR; SCHED;
;       LDB(B1, 1, 1); STAGE(SB(1, 0), rsB, sB0, offB, t + 3);
;       BAR; WAIT_L(0); MMA(0, 1, At, B1); BAR;
;       LDA(At, 1, 1); STAGE(SA(1, 0), rsA, sA0, offA, t + 3);
;       BAR; WAIT_L(0); MMA(1, 0, At, B0); BAR; SCHED;
	v_mfma_f32_16x16x32_bf16 v[12:15], v[200:203], v[168:171], v[12:15]
	v_mfma_f32_16x16x32_bf16 v[12:15], v[204:207], v[172:175], v[12:15]
	v_mfma_f32_16x16x32_bf16 v[8:11], v[208:211], v[168:171], v[8:11]
	v_mfma_f32_16x16x32_bf16 v[8:11], v[212:215], v[172:175], v[8:11]
	v_mfma_f32_16x16x32_bf16 v[4:7], v[200:203], v[176:179], v[4:7]
	v_mfma_f32_16x16x32_bf16 v[4:7], v[204:207], v[180:183], v[4:7]
	v_mfma_f32_16x16x32_bf16 v[0:3], v[208:211], v[176:179], v[0:3]
	v_mfma_f32_16x16x32_bf16 v[0:3], v[212:215], v[180:183], v[0:3]
	v_mfma_f32_16x16x32_bf16 v[64:67], v[200:203], v[184:187], v[64:67]
	v_mfma_f32_16x16x32_bf16 v[64:67], v[204:207], v[188:191], v[64:67]
	v_mfma_f32_16x16x32_bf16 v[72:75], v[208:211], v[184:187], v[72:75]
	v_mfma_f32_16x16x32_bf16 v[72:75], v[212:215], v[188:191], v[72:75]
	v_mfma_f32_16x16x32_bf16 v[76:79], v[200:203], v[192:195], v[76:79]
	v_mfma_f32_16x16x32_bf16 v[76:79], v[204:207], v[196:199], v[76:79]
	v_mfma_f32_16x16x32_bf16 v[84:87], v[208:211], v[192:195], v[84:87]
	v_mfma_f32_16x16x32_bf16 v[84:87], v[212:215], v[196:199], v[84:87]
	s_barrier
	ds_read_b128 v[152:155], v137
	ds_read_b128 v[156:159], v138
	ds_read_b128 v[160:163], v139
	ds_read_b128 v[164:167], v140
	s_addk_i32 s5, 0x100
	s_mov_b32 m0, s39
	ds_read_b128 v[168:171], v129 offset:32768
	ds_read_b128 v[172:175], v129 offset:33792
	ds_read_b128 v[176:179], v132 offset:32768
	ds_read_b128 v[180:183], v132 offset:33792
	ds_read_b128 v[184:187], v131 offset:32768
	ds_read_b128 v[188:191], v131 offset:33792
	ds_read_b128 v[192:195], v130 offset:32768
	ds_read_b128 v[196:199], v130 offset:33792
	buffer_load_dwordx4 v141, s[8:11], s5 offen lds
	s_mov_b32 m0, s55
	s_nop 0
	buffer_load_dwordx4 v142, s[8:11], s5 offen lds
	s_waitcnt lgkmcnt(8)
	s_barrier
	s_waitcnt lgkmcnt(0)
	v_mfma_f32_16x16x32_bf16 v[124:127], v[152:155], v[168:171], v[124:127]
	v_mfma_f32_16x16x32_bf16 v[124:127], v[156:159], v[172:175], v[124:127]
	v_mfma_f32_16x16x32_bf16 v[120:123], v[160:163], v[168:171], v[120:123]
	v_mfma_f32_16x16x32_bf16 v[120:123], v[164:167], v[172:175], v[120:123]
	v_mfma_f32_16x16x32_bf16 v[116:119], v[152:155], v[176:179], v[116:119]
	v_mfma_f32_16x16x32_bf16 v[116:119], v[156:159], v[180:183], v[116:119]
	v_mfma_f32_16x16x32_bf16 v[112:115], v[160:163], v[176:179], v[112:115]
	v_mfma_f32_16x16x32_bf16 v[112:115], v[164:167], v[180:183], v[112:115]
	v_mfma_f32_16x16x32_bf16 v[108:111], v[152:155], v[184:187], v[108:111]
	v_mfma_f32_16x16x32_bf16 v[108:111], v[156:159], v[188:191], v[108:111]
	v_mfma_f32_16x16x32_bf16 v[104:107], v[160:163], v[184:187], v[104:107]
	v_mfma_f32_16x16x32_bf16 v[104:107], v[164:167], v[188:191], v[104:107]
	v_mfma_f32_16x16x32_bf16 v[100:103], v[152:155], v[192:195], v[100:103]
	v_mfma_f32_16x16x32_bf16 v[100:103], v[156:159], v[196:199], v[100:103]
	v_mfma_f32_16x16x32_bf16 v[96:99], v[160:163], v[192:195], v[96:99]
	v_mfma_f32_16x16x32_bf16 v[96:99], v[164:167], v[196:199], v[96:99]
	s_barrier
	s_addk_i32 s6, 0x180
	s_mov_b32 m0, s42
	ds_read_b128 v[200:203], v133
	ds_read_b128 v[204:207], v134
	ds_read_b128 v[208:211], v135
	ds_read_b128 v[212:215], v136
	buffer_load_dwordx4 v141, s[12:15], s6 offen lds
	s_mov_b32 m0, s56
	s_nop 0
	buffer_load_dwordx4 v142, s[12:15], s6 offen lds
	s_barrier
	s_waitcnt lgkmcnt(0)
	v_mfma_f32_16x16x32_bf16 v[92:95], v[200:203], v[168:171], v[92:95]
	v_mfma_f32_16x16x32_bf16 v[92:95], v[204:207], v[172:175], v[92:95]
	v_mfma_f32_16x16x32_bf16 v[88:91], v[208:211], v[168:171], v[88:91]
	v_mfma_f32_16x16x32_bf16 v[88:91], v[212:215], v[172:175], v[88:91]
	v_mfma_f32_16x16x32_bf16 v[80:83], v[200:203], v[176:179], v[80:83]
	v_mfma_f32_16x16x32_bf16 v[80:83], v[204:207], v[180:183], v[80:83]
	v_mfma_f32_16x16x32_bf16 v[68:71], v[208:211], v[176:179], v[68:71]
	v_mfma_f32_16x16x32_bf16 v[68:71], v[212:215], v[180:183], v[68:71]
	v_mfma_f32_16x16x32_bf16 v[60:63], v[200:203], v[184:187], v[60:63]
	v_mfma_f32_16x16x32_bf16 v[60:63], v[204:207], v[188:191], v[60:63]
	v_mfma_f32_16x16x32_bf16 v[56:59], v[208:211], v[184:187], v[56:59]
	v_mfma_f32_16x16x32_bf16 v[56:59], v[212:215], v[188:191], v[56:59]
	v_mfma_f32_16x16x32_bf16 v[52:55], v[200:203], v[192:195], v[52:55]
	v_mfma_f32_16x16x32_bf16 v[52:55], v[204:207], v[196:199], v[52:55]
	v_mfma_f32_16x16x32_bf16 v[48:51], v[208:211], v[192:195], v[48:51]
	v_mfma_f32_16x16x32_bf16 v[48:51], v[212:215], v[196:199], v[48:51]
	s_barrier
	s_addk_i32 s7, 0x180
	s_mov_b32 m0, s43
	ds_read_b128 v[168:171], v129 offset:49152
	ds_read_b128 v[172:175], v129 offset:50176
	ds_read_b128 v[176:179], v132 offset:49152
	ds_read_b128 v[180:183], v132 offset:50176
	ds_read_b128 v[184:187], v131 offset:49152
	ds_read_b128 v[188:191], v131 offset:50176
	ds_read_b128 v[192:195], v130 offset:49152
	ds_read_b128 v[196:199], v130 offset:50176
	buffer_load_dwordx4 v141, s[8:11], s7 offen lds
	s_mov_b32 m0, s57
	s_nop 0
	buffer_load_dwordx4 v142, s[8:11], s7 offen lds
	s_barrier
	s_waitcnt lgkmcnt(0)
	v_mfma_f32_16x16x32_bf16 v[44:47], v[152:155], v[168:171], v[44:47]
	v_mfma_f32_16x16x32_bf16 v[44:47], v[156:159], v[172:175], v[44:47]
	v_mfma_f32_16x16x32_bf16 v[40:43], v[160:163], v[168:171], v[40:43]
	v_mfma_f32_16x16x32_bf16 v[40:43], v[164:167], v[172:175], v[40:43]
	v_mfma_f32_16x16x32_bf16 v[36:39], v[152:155], v[176:179], v[36:39]
	v_mfma_f32_16x16x32_bf16 v[36:39], v[156:159], v[180:183], v[36:39]
	v_mfma_f32_16x16x32_bf16 v[32:35], v[160:163], v[176:179], v[32:35]
	v_mfma_f32_16x16x32_bf16 v[32:35], v[164:167], v[180:183], v[32:35]
	v_mfma_f32_16x16x32_bf16 v[28:31], v[152:155], v[184:187], v[28:31]
	v_mfma_f32_16x16x32_bf16 v[28:31], v[156:159], v[188:191], v[28:31]
	v_mfma_f32_16x16x32_bf16 v[24:27], v[160:163], v[184:187], v[24:27]
	v_mfma_f32_16x16x32_bf16 v[24:27], v[164:167], v[188:191], v[24:27]
	v_mfma_f32_16x16x32_bf16 v[20:23], v[152:155], v[192:195], v[20:23]
	v_mfma_f32_16x16x32_bf16 v[20:23], v[156:159], v[196:199], v[20:23]
	v_mfma_f32_16x16x32_bf16 v[16:19], v[160:163], v[192:195], v[16:19]
	v_mfma_f32_16x16x32_bf16 v[16:19], v[164:167], v[196:199], v[16:19]
	s_barrier
; #define STAGE(P, RS, SOFF, OFF, kt) do { const int _so = (SOFF) + (kt) * (BK * 2); \
;     _Pragma("unroll") for (int _i = 0; _i < 2; ++_i) { \
;       __builtin_amdgcn_raw_ptr_buffer_load_lds(RS, (__attribute__((address_space(3))) void*)((P) + wave * 1024 + _i * 8192), 16, OFF[_i], _so, 0, 0); } } while (0)
; #define LDA(dst, b, h) _Pragma("unroll") for (int m = 0; m < 4; ++m) _Pragma("unroll") for (int k = 0; k < 2; ++k) \
;     dst[m][k] = *reinterpret_cast<const bf16x8*>(SA(b, h) + lds_byte(wr * 64 + m * 16 + fr, k * 32 + fq * 8))
; #define LDB(dst, b, h) _Pragma("unroll") for (int n = 0; n < 2; ++n) _Pragma("unroll") for (int k = 0; k < 2; ++k) \
;     dst[n][k] = *reinterpret_cast<const bf16x8*>(SB(b, h) + lds_byte(wc * 32 + n * 16 + fr, k * 32 + fq * 8))
; #define WAIT_V(n) asm volatile("s_waitcnt vmcnt(" #n ")" ::: "memory")
; #define WAIT_L(n) asm volatile("s_waitcnt lgkmcnt(" #n ")" ::: "memory")
; #define BAR __builtin_amdgcn_s_barrier()
;     ...
;       STAGE(SB(1, 1), rsB, sB1, offB, t + 3);
;       WAIT_V(6); BAR; MMA(1, 1, At, B1); BAR;
;     }
;     { LDB(B0, 0, 0); LDA(At, 0, 0); STAGE(SA(1, 1), rsA, sA1, offA, nt - 1);
;       BAR; WAIT_L(0); MMA(0, 0, At, B0); BAR;
;       LDB(B1, 0, 1); BAR; WAIT_L(0); MMA(0, 1, At, B1); BAR;
;       LDA(At, 0, 1); WAIT_V(4); BAR; WAIT_L(0); MMA(1, 0, At, B0); MMA(1, 1, At, B1); BAR; }
	s_addk_i32 s22, 0x180
	s_mov_b32 m0, s44
	s_nop 0
	buffer_load_dwordx4 v141, s[12:15], s22 offen lds
	s_mov_b32 m0, s58
	s_nop 0
	buffer_load_dwordx4 v142, s[12:15], s22 offen lds
	s_add_i32 s1, s1, 2
	s_addk_i32 s3, 0x100
	s_cmp_gt_u32 s1, 59
	s_cbranch_scc0 .LBB0_392
	s_waitcnt vmcnt(6)
	s_barrier
	v_mfma_f32_16x16x32_bf16 v[12:15], v[200:203], v[168:171], v[12:15]
	v_mfma_f32_16x16x32_bf16 v[12:15], v[204:207], v[172:175], v[12:15]
	v_mfma_f32_16x16x32_bf16 v[8:11], v[208:211], v[168:171], v[8:11]
	v_mfma_f32_16x16x32_bf16 v[8:11], v[212:215], v[172:175], v[8:11]
	v_mfma_f32_16x16x32_bf16 v[4:7], v[200:203], v[176:179], v[4:7]
	v_mfma_f32_16x16x32_bf16 v[4:7], v[204:207], v[180:183], v[4:7]
	v_mfma_f32_16x16x32_bf16 v[0:3], v[208:211], v[176:179], v[0:3]
	v_mfma_f32_16x16x32_bf16 v[0:3], v[212:215], v[180:183], v[0:3]
	v_mfma_f32_16x16x32_bf16 v[64:67], v[200:203], v[184:187], v[64:67]
	v_mfma_f32_16x16x32_bf16 v[64:67], v[204:207], v[188:191], v[64:67]
	v_mfma_f32_16x16x32_bf16 v[72:75], v[208:211], v[184:187], v[72:75]
	v_mfma_f32_16x16x32_bf16 v[72:75], v[212:215], v[188:191], v[72:75]
	v_mfma_f32_16x16x32_bf16 v[76:79], v[200:203], v[192:195], v[76:79]
	v_mfma_f32_16x16x32_bf16 v[76:79], v[204:207], v[196:199], v[76:79]
	v_mfma_f32_16x16x32_bf16 v[84:87], v[208:211], v[192:195], v[84:87]
	v_mfma_f32_16x16x32_bf16 v[84:87], v[212:215], v[196:199], v[84:87]
	s_barrier
	s_add_i32 s1, s86, 0x1f80
	s_mov_b32 m0, s36
	ds_read_b128 v[152:155], v147
	ds_read_b128 v[156:159], v148
	ds_read_b128 v[160:163], v149
	ds_read_b128 v[148:151], v150
	ds_read_b128 v[164:167], v129
	ds_read_b128 v[168:171], v129 offset:1024
	ds_read_b128 v[172:175], v132
	ds_read_b128 v[176:179], v132 offset:1024
	ds_read_b128 v[180:183], v131
	ds_read_b128 v[184:187], v131 offset:1024
	ds_read_b128 v[188:191], v130
	ds_read_b128 v[192:195], v130 offset:1024
	buffer_load_dwordx4 v141, s[8:11], s1 offen lds
	s_mov_b32 m0, s59
	s_nop 0
	buffer_load_dwordx4 v142, s[8:11], s1 offen lds
	s_barrier
	s_waitcnt lgkmcnt(0)
	v_mfma_f32_16x16x32_bf16 v[124:127], v[152:155], v[164:167], v[124:127]
	v_mfma_f32_16x16x32_bf16 v[124:127], v[156:159], v[168:171], v[124:127]
	v_mfma_f32_16x16x32_bf16 v[120:123], v[160:163], v[164:167], v[120:123]
	v_mfma_f32_16x16x32_bf16 v[120:123], v[148:151], v[168:171], v[120:123]
	v_mfma_f32_16x16x32_bf16 v[116:119], v[152:155], v[172:175], v[116:119]
	v_mfma_f32_16x16x32_bf16 v[116:119], v[156:159], v[176:179], v[116:119]
	v_mfma_f32_16x16x32_bf16 v[112:115], v[160:163], v[172:175], v[112:115]
	v_mfma_f32_16x16x32_bf16 v[112:115], v[148:151], v[176:179], v[112:115]
	v_mfma_f32_16x16x32_bf16 v[108:111], v[152:155], v[180:183], v[108:111]
	v_mfma_f32_16x16x32_bf16 v[108:111], v[156:159], v[184:187], v[108:111]
	v_mfma_f32_16x16x32_bf16 v[104:107], v[160:163], v[180:183], v[104:107]
	v_mfma_f32_16x16x32_bf16 v[104:107], v[148:151], v[184:187], v[104:107]
	v_mfma_f32_16x16x32_bf16 v[100:103], v[152:155], v[188:191], v[100:103]
	v_mfma_f32_16x16x32_bf16 v[100:103], v[156:159], v[192:195], v[100:103]
	v_mfma_f32_16x16x32_bf16 v[96:99], v[160:163], v[188:191], v[96:99]
	v_mfma_f32_16x16x32_bf16 v[96:99], v[148:151], v[192:195], v[96:99]
	s_barrier
	ds_read_b128 v[196:199], v143
	ds_read_b128 v[200:203], v144
	ds_read_b128 v[142:145], v145
	ds_read_b128 v[204:207], v146
	s_barrier
	s_waitcnt lgkmcnt(0)
	v_mfma_f32_16x16x32_bf16 v[80:83], v[196:199], v[172:175], v[80:83]
	v_mfma_f32_16x16x32_bf16 v[68:71], v[142:145], v[172:175], v[68:71]
	v_mfma_f32_16x16x32_bf16 v[60:63], v[196:199], v[180:183], v[60:63]
	v_mfma_f32_16x16x32_bf16 v[56:59], v[142:145], v[180:183], v[56:59]
	v_mfma_f32_16x16x32_bf16 v[52:55], v[196:199], v[188:191], v[52:55]
	v_mfma_f32_16x16x32_bf16 v[48:51], v[142:145], v[188:191], v[48:51]
	v_mfma_f32_16x16x32_bf16 v[92:95], v[196:199], v[164:167], v[92:95]
	v_mfma_f32_16x16x32_bf16 v[88:91], v[142:145], v[164:167], v[88:91]
	v_mfma_f32_16x16x32_bf16 v[80:83], v[200:203], v[176:179], v[80:83]
	v_mfma_f32_16x16x32_bf16 v[68:71], v[204:207], v[176:179], v[68:71]
	v_mfma_f32_16x16x32_bf16 v[60:63], v[200:203], v[184:187], v[60:63]
	v_mfma_f32_16x16x32_bf16 v[56:59], v[204:207], v[184:187], v[56:59]
	v_mfma_f32_16x16x32_bf16 v[52:55], v[200:203], v[192:195], v[52:55]
	v_mfma_f32_16x16x32_bf16 v[48:51], v[204:207], v[192:195], v[48:51]
	v_mfma_f32_16x16x32_bf16 v[164:167], v[200:203], v[168:171], v[92:95]
	v_mfma_f32_16x16x32_bf16 v[168:171], v[204:207], v[168:171], v[88:91]
	s_barrier
	s_nop 0
	ds_read_b128 v[88:91], v129 offset:16384
	ds_read_b128 v[92:95], v129 offset:17408
	ds_read_b128 v[172:175], v132 offset:16384
	ds_read_b128 v[176:179], v132 offset:17408
	ds_read_b128 v[180:183], v131 offset:16384
	ds_read_b128 v[184:187], v131 offset:17408
	ds_read_b128 v[188:191], v130 offset:16384
	ds_read_b128 v[192:195], v130 offset:17408
	s_waitcnt vmcnt(4)
	s_barrier
; #define LDA(dst, b, h) _Pragma("unroll") for (int m = 0; m < 4; ++m) _Pragma("unroll") for (int k = 0; k < 2; ++k) \
;     dst[m][k] = *reinterpret_cast<const bf16x8*>(SA(b, h) + lds_byte(wr * 64 + m * 16 + fr, k * 32 + fq * 8))
; #define LDB(dst, b, h) _Pragma("unroll") for (int n = 0; n < 2; ++n) _Pragma("unroll") for (int k = 0; k < 2; ++k) \
;     dst[n][k] = *reinterpret_cast<const bf16x8*>(SB(b, h) + lds_byte(wc * 32 + n * 16 + fr, k * 32 + fq * 8))
; #define WAIT_V(n) asm volatile("s_waitcnt vmcnt(" #n ")" ::: "memory")
; #define WAIT_L(n) asm volatile("s_waitcnt lgkmcnt(" #n ")" ::: "memory")
; #define BAR __builtin_amdgcn_s_barrier()
;     ...
;       LDA(At, 0, 1); WAIT_V(4); BAR; WAIT_L(0); MMA(1, 0, At, B0); MMA(1, 1, At, B1); BAR; }
;     { LDB(B0, 1, 0); LDA(At, 1, 0); WAIT_V(2); BAR; WAIT_L(0); MMA(0, 0, At, B0); BAR;
	s_waitcnt lgkmcnt(0)
	v_mfma_f32_16x16x32_bf16 v[44:47], v[152:155], v[88:91], v[44:47]
	v_mfma_f32_16x16x32_bf16 v[40:43], v[160:163], v[88:91], v[40:43]
	v_mfma_f32_16x16x32_bf16 v[36:39], v[152:155], v[172:175], v[36:39]
	v_mfma_f32_16x16x32_bf16 v[32:35], v[160:163], v[172:175], v[32:35]
	v_mfma_f32_16x16x32_bf16 v[28:31], v[152:155], v[180:183], v[28:31]
	v_mfma_f32_16x16x32_bf16 v[24:27], v[160:163], v[180:183], v[24:27]
	v_mfma_f32_16x16x32_bf16 v[20:23], v[152:155], v[188:191], v[20:23]
	v_mfma_f32_16x16x32_bf16 v[16:19], v[160:163], v[188:191], v[16:19]
	v_mfma_f32_16x16x32_bf16 v[44:47], v[156:159], v[92:95], v[44:47]
	v_mfma_f32_16x16x32_bf16 v[40:43], v[148:151], v[92:95], v[40:43]
	v_mfma_f32_16x16x32_bf16 v[36:39], v[156:159], v[176:179], v[36:39]
	v_mfma_f32_16x16x32_bf16 v[32:35], v[148:151], v[176:179], v[32:35]
	v_mfma_f32_16x16x32_bf16 v[28:31], v[156:159], v[184:187], v[28:31]
	v_mfma_f32_16x16x32_bf16 v[24:27], v[148:151], v[184:187], v[24:27]
	v_mfma_f32_16x16x32_bf16 v[20:23], v[156:159], v[192:195], v[20:23]
	v_mfma_f32_16x16x32_bf16 v[16:19], v[148:151], v[192:195], v[16:19]
	v_mfma_f32_16x16x32_bf16 v[4:7], v[196:199], v[172:175], v[4:7]
	v_mfma_f32_16x16x32_bf16 v[0:3], v[142:145], v[172:175], v[0:3]
	v_mfma_f32_16x16x32_bf16 v[12:15], v[196:199], v[88:91], v[12:15]
	v_mfma_f32_16x16x32_bf16 v[8:11], v[142:145], v[88:91], v[8:11]
	v_mfma_f32_16x16x32_bf16 v[64:67], v[196:199], v[180:183], v[64:67]
	v_mfma_f32_16x16x32_bf16 v[72:75], v[142:145], v[180:183], v[72:75]
	v_mfma_f32_16x16x32_bf16 v[76:79], v[196:199], v[188:191], v[76:79]
	v_mfma_f32_16x16x32_bf16 v[84:87], v[142:145], v[188:191], v[84:87]
	v_mfma_f32_16x16x32_bf16 v[4:7], v[200:203], v[176:179], v[4:7]
	v_mfma_f32_16x16x32_bf16 v[0:3], v[204:207], v[176:179], v[0:3]
	v_mfma_f32_16x16x32_bf16 v[142:145], v[200:203], v[92:95], v[12:15]
	v_mfma_f32_16x16x32_bf16 v[146:149], v[204:207], v[92:95], v[8:11]
	v_mfma_f32_16x16x32_bf16 v[150:153], v[200:203], v[184:187], v[64:67]
	v_mfma_f32_16x16x32_bf16 v[154:157], v[204:207], v[184:187], v[72:75]
	v_mfma_f32_16x16x32_bf16 v[158:161], v[200:203], v[192:195], v[76:79]
	v_mfma_f32_16x16x32_bf16 v[172:175], v[204:207], v[192:195], v[84:87]
	s_barrier
	ds_read_b128 v[8:11], v137
	ds_read_b128 v[12:15], v138
	ds_read_b128 v[176:179], v139
	ds_read_b128 v[138:141], v140
	ds_read_b128 v[64:67], v129 offset:32768
	ds_read_b128 v[84:87], v129 offset:33792
	ds_read_b128 v[180:183], v132 offset:32768
	ds_read_b128 v[184:187], v132 offset:33792
	ds_read_b128 v[188:191], v131 offset:32768
	ds_read_b128 v[192:195], v131 offset:33792
	ds_read_b128 v[196:199], v130 offset:32768
	ds_read_b128 v[200:203], v130 offset:33792
	s_waitcnt vmcnt(2)
	s_barrier
	s_waitcnt lgkmcnt(0)
	v_mfma_f32_16x16x32_bf16 v[72:75], v[8:11], v[64:67], v[124:127]
	v_mfma_f32_16x16x32_bf16 v[76:79], v[176:179], v[64:67], v[120:123]
	v_mfma_f32_16x16x32_bf16 v[88:91], v[8:11], v[180:183], v[116:119]
	v_mfma_f32_16x16x32_bf16 v[92:95], v[176:179], v[180:183], v[112:115]
	v_mfma_f32_16x16x32_bf16 v[112:115], v[8:11], v[188:191], v[108:111]
	v_mfma_f32_16x16x32_bf16 v[120:123], v[176:179], v[188:191], v[104:107]
	v_mfma_f32_16x16x32_bf16 v[100:103], v[8:11], v[196:199], v[100:103]
	v_mfma_f32_16x16x32_bf16 v[96:99], v[176:179], v[196:199], v[96:99]
	v_mfma_f32_16x16x32_bf16 v[124:127], v[12:15], v[84:87], v[72:75]
	v_mfma_f32_16x16x32_bf16 v[116:119], v[138:141], v[84:87], v[76:79]
	v_mfma_f32_16x16x32_bf16 v[108:111], v[12:15], v[184:187], v[88:91]
	v_mfma_f32_16x16x32_bf16 v[104:107], v[138:141], v[184:187], v[92:95]
	v_mfma_f32_16x16x32_bf16 v[92:95], v[12:15], v[192:195], v[112:115]
	v_mfma_f32_16x16x32_bf16 v[88:91], v[138:141], v[192:195], v[120:123]
	v_mfma_f32_16x16x32_bf16 v[76:79], v[12:15], v[200:203], v[100:103]
	v_mfma_f32_16x16x32_bf16 v[72:75], v[138:141], v[200:203], v[96:99]
	s_barrier
; #define LDA(dst, b, h) _Pragma("unroll") for (int m = 0; m < 4; ++m) _Pragma("unroll") for (int k = 0; k < 2; ++k) \
;     dst[m][k] = *reinterpret_cast<const bf16x8*>(SA(b, h) + lds_byte(wr * 64 + m * 16 + fr, k * 32 + fq * 8))
; #define LDB(dst, b, h) _Pragma("unroll") for (int n = 0; n < 2; ++n) _Pragma("unroll") for (int k = 0; k < 2; ++k) \
;     dst[n][k] = *reinterpret_cast<const bf16x8*>(SB(b, h) + lds_byte(wc * 32 + n * 16 + fr, k * 32 + fq * 8))
; #define WAIT_V(n) asm volatile("s_waitcnt vmcnt(" #n ")" ::: "memory")
; #define WAIT_L(n) asm volatile("s_waitcnt lgkmcnt(" #n ")" ::: "memory")
; #define BAR __builtin_amdgcn_s_barrier()
;     ...
;       LDB(B1, 1, 1); WAIT_V(0); BAR; WAIT_L(0); MMA(0, 1, At, B1); BAR;
;       LDA(At, 1, 1); BAR; WAIT_L(0); MMA(1, 0, At, B0); MMA(1, 1, At, B1); BAR; }
;     if (wr == 0) BAR;
	ds_read_b128 v[204:207], v133
	ds_read_b128 v[208:211], v134
	ds_read_b128 v[212:215], v135
	ds_read_b128 v[134:137], v136
	s_waitcnt vmcnt(0)
	s_barrier
	s_waitcnt lgkmcnt(0)
	v_mfma_f32_16x16x32_bf16 v[96:99], v[204:207], v[64:67], v[164:167]
	v_mfma_f32_16x16x32_bf16 v[64:67], v[212:215], v[64:67], v[168:171]
	v_mfma_f32_16x16x32_bf16 v[80:83], v[204:207], v[180:183], v[80:83]
	v_mfma_f32_16x16x32_bf16 v[68:71], v[212:215], v[180:183], v[68:71]
	v_mfma_f32_16x16x32_bf16 v[60:63], v[204:207], v[188:191], v[60:63]
	v_mfma_f32_16x16x32_bf16 v[56:59], v[212:215], v[188:191], v[56:59]
	v_mfma_f32_16x16x32_bf16 v[52:55], v[204:207], v[196:199], v[52:55]
	v_mfma_f32_16x16x32_bf16 v[48:51], v[212:215], v[196:199], v[48:51]
	v_mfma_f32_16x16x32_bf16 v[120:123], v[208:211], v[84:87], v[96:99]
	v_mfma_f32_16x16x32_bf16 v[112:115], v[134:137], v[84:87], v[64:67]
	v_mfma_f32_16x16x32_bf16 v[100:103], v[208:211], v[184:187], v[80:83]
	v_mfma_f32_16x16x32_bf16 v[96:99], v[134:137], v[184:187], v[68:71]
	v_mfma_f32_16x16x32_bf16 v[84:87], v[208:211], v[192:195], v[60:63]
	v_mfma_f32_16x16x32_bf16 v[80:83], v[134:137], v[192:195], v[56:59]
	v_mfma_f32_16x16x32_bf16 v[68:71], v[208:211], v[200:203], v[52:55]
	v_mfma_f32_16x16x32_bf16 v[64:67], v[134:137], v[200:203], v[48:51]
	s_barrier
	s_nop 0
	ds_read_b128 v[48:51], v129 offset:49152
	ds_read_b128 v[162:165], v129 offset:50176
	ds_read_b128 v[52:55], v132 offset:49152
	ds_read_b128 v[166:169], v132 offset:50176
	ds_read_b128 v[180:183], v131 offset:49152
	ds_read_b128 v[184:187], v131 offset:50176
	ds_read_b128 v[188:191], v130 offset:49152
	ds_read_b128 v[130:133], v130 offset:50176
	s_barrier
	s_waitcnt lgkmcnt(0)
	v_mfma_f32_16x16x32_bf16 v[44:47], v[8:11], v[48:51], v[44:47]
	v_mfma_f32_16x16x32_bf16 v[40:43], v[176:179], v[48:51], v[40:43]
	v_mfma_f32_16x16x32_bf16 v[36:39], v[8:11], v[52:55], v[36:39]
	v_mfma_f32_16x16x32_bf16 v[32:35], v[176:179], v[52:55], v[32:35]
	v_mfma_f32_16x16x32_bf16 v[28:31], v[8:11], v[180:183], v[28:31]
	v_mfma_f32_16x16x32_bf16 v[24:27], v[176:179], v[180:183], v[24:27]
	v_mfma_f32_16x16x32_bf16 v[8:11], v[8:11], v[188:191], v[20:23]
	v_mfma_f32_16x16x32_bf16 v[16:19], v[176:179], v[188:191], v[16:19]
	v_mfma_f32_16x16x32_bf16 v[60:63], v[12:15], v[162:165], v[44:47]
	v_mfma_f32_16x16x32_bf16 v[56:59], v[138:141], v[162:165], v[40:43]
	v_mfma_f32_16x16x32_bf16 v[44:47], v[12:15], v[166:169], v[36:39]
	v_mfma_f32_16x16x32_bf16 v[40:43], v[138:141], v[166:169], v[32:35]
	v_mfma_f32_16x16x32_bf16 v[28:31], v[12:15], v[184:187], v[28:31]
	v_mfma_f32_16x16x32_bf16 v[24:27], v[138:141], v[184:187], v[24:27]
	v_mfma_f32_16x16x32_bf16 v[12:15], v[12:15], v[130:133], v[8:11]
	v_mfma_f32_16x16x32_bf16 v[8:11], v[138:141], v[130:133], v[16:19]
	v_mfma_f32_16x16x32_bf16 v[16:19], v[204:207], v[48:51], v[142:145]
	v_mfma_f32_16x16x32_bf16 v[20:23], v[212:215], v[48:51], v[146:149]
	v_mfma_f32_16x16x32_bf16 v[4:7], v[204:207], v[52:55], v[4:7]
	v_mfma_f32_16x16x32_bf16 v[0:3], v[212:215], v[52:55], v[0:3]
	v_mfma_f32_16x16x32_bf16 v[138:141], v[204:207], v[180:183], v[150:153]
	v_mfma_f32_16x16x32_bf16 v[142:145], v[212:215], v[180:183], v[154:157]
	v_mfma_f32_16x16x32_bf16 v[146:149], v[204:207], v[188:191], v[158:161]
	v_mfma_f32_16x16x32_bf16 v[150:153], v[212:215], v[188:191], v[172:175]
	v_mfma_f32_16x16x32_bf16 v[52:55], v[208:211], v[162:165], v[16:19]
	v_mfma_f32_16x16x32_bf16 v[48:51], v[134:137], v[162:165], v[20:23]
	v_mfma_f32_16x16x32_bf16 v[36:39], v[208:211], v[166:169], v[4:7]
	v_mfma_f32_16x16x32_bf16 v[32:35], v[134:137], v[166:169], v[0:3]
	v_mfma_f32_16x16x32_bf16 v[20:23], v[208:211], v[184:187], v[138:141]
	v_mfma_f32_16x16x32_bf16 v[16:19], v[134:137], v[184:187], v[142:145]
	v_mfma_f32_16x16x32_bf16 v[4:7], v[208:211], v[130:133], v[146:149]
	v_mfma_f32_16x16x32_bf16 v[0:3], v[134:137], v[130:133], v[150:153]
	v_cmp_gt_u32_e32 vcc, s40, v128
	s_barrier
	s_and_saveexec_b64 s[6:7], vcc
	s_cbranch_execz .LBB0_395
	s_barrier

; #define STAGE(P, RS, SOFF, OFF, kt) do { const int _so = (SOFF) + (kt) * (BK * 2); \
;     _Pragma("unroll") for (int _i = 0; _i < 2; ++_i) { \
;       __builtin_amdgcn_raw_ptr_buffer_load_lds(RS, (__attribute__((address_space(3))) void*)((P) + wave * 1024 + _i * 8192), 16, OFF[_i], _so, 0, 0); } } while (0)
; #define LDA(dst, b, h) _Pragma("unroll") for (int m = 0; m < 4; ++m) _Pragma("unroll") for (int k = 0; k < 2; ++k) \
;     dst[m][k] = *reinterpret_cast<const bf16x8*>(SA(b, h) + lds_byte(wr * 64 + m * 16 + fr, k * 32 + fq * 8))
; #define LDB(dst, b, h) _Pragma("unroll") for (int n = 0; n < 2; ++n) _Pragma("unroll") for (int k = 0; k < 2; ++k) \
;     dst[n][k] = *reinterpret_cast<const bf16x8*>(SB(b, h) + lds_byte(wc * 32 + n * 16 + fr, k * 32 + fq * 8))
; #define WAIT_V(n) asm volatile("s_waitcnt vmcnt(" #n ")" ::: "memory")
; #define WAIT_L(n) asm volatile("s_waitcnt lgkmcnt(" #n ")" ::: "memory")
; #define BAR __builtin_amdgcn_s_barrier()
; #define SCHED __builtin_amdgcn_sched_barrier(0)
;     ...
;       LDB(B0, 0, 0); SCHED; LDA(At, 0, 0); STAGE(SA(1, 1), rsA, sA1, offA, t + 1);
;       WAIT_L(8); BAR; WAIT_L(0); MMA(0, 0, At, B0); BAR; SCHED;
;       LDB(B1, 0, 1); STAGE(SB(0, 0), rsB, sB0, offB, t + 2);
;       BAR; WAIT_L(0); MMA(0, 1, At, B1); BAR;
;       LDA(At, 0, 1); STAGE(SA(0, 0), rsA, sA0, offA, t + 2);
;       BAR; WAIT_L(0); MMA(1, 0, At, B0); BAR; SCHED;
;       STAGE(SB(0, 1), rsB, sB1, offB, t + 2);
;       WAIT_V(6); BAR; MMA(1, 1, At, B1); BAR;
.Lmy_rot_494:
	ds_read_b128 v[152:155], v147
	ds_read_b128 v[156:159], v148
	ds_read_b128 v[160:163], v149
	ds_read_b128 v[164:167], v150
	s_add_i32 s5, s82, s3
	s_add_i32 s6, s5, 0x80
	s_mov_b32 m0, s36
	ds_read_b128 v[168:171], v129
	ds_read_b128 v[172:175], v129 offset:1024
	ds_read_b128 v[176:179], v132
	ds_read_b128 v[180:183], v132 offset:1024
	ds_read_b128 v[184:187], v131
	ds_read_b128 v[188:191], v131 offset:1024
	ds_read_b128 v[192:195], v130
	ds_read_b128 v[196:199], v130 offset:1024
	buffer_load_dwordx4 v141, s[8:11], s6 offen lds
	s_mov_b32 m0, s59
	s_nop 0
	buffer_load_dwordx4 v142, s[8:11], s6 offen lds
	s_waitcnt lgkmcnt(8)
	s_barrier
	s_waitcnt lgkmcnt(0)
	v_mfma_f32_16x16x32_bf16 v[124:127], v[152:155], v[168:171], v[124:127]
	v_mfma_f32_16x16x32_bf16 v[124:127], v[156:159], v[172:175], v[124:127]
	v_mfma_f32_16x16x32_bf16 v[120:123], v[160:163], v[168:171], v[120:123]
	v_mfma_f32_16x16x32_bf16 v[120:123], v[164:167], v[172:175], v[120:123]
	v_mfma_f32_16x16x32_bf16 v[116:119], v[152:155], v[176:179], v[116:119]
	v_mfma_f32_16x16x32_bf16 v[116:119], v[156:159], v[180:183], v[116:119]
	v_mfma_f32_16x16x32_bf16 v[112:115], v[160:163], v[176:179], v[112:115]
	v_mfma_f32_16x16x32_bf16 v[112:115], v[164:167], v[180:183], v[112:115]
	v_mfma_f32_16x16x32_bf16 v[108:111], v[152:155], v[184:187], v[108:111]
	v_mfma_f32_16x16x32_bf16 v[108:111], v[156:159], v[188:191], v[108:111]
	v_mfma_f32_16x16x32_bf16 v[104:107], v[160:163], v[184:187], v[104:107]
	v_mfma_f32_16x16x32_bf16 v[104:107], v[164:167], v[188:191], v[104:107]
	v_mfma_f32_16x16x32_bf16 v[100:103], v[152:155], v[192:195], v[100:103]
	v_mfma_f32_16x16x32_bf16 v[100:103], v[156:159], v[196:199], v[100:103]
	v_mfma_f32_16x16x32_bf16 v[96:99], v[160:163], v[192:195], v[96:99]
	v_mfma_f32_16x16x32_bf16 v[96:99], v[164:167], v[196:199], v[96:99]
	s_barrier
	s_add_i32 s6, s84, s3
	s_add_i32 s7, s6, 0x100
	s_mov_b32 s14, s10
	s_mov_b32 s15, s11
	s_mov_b32 m0, s37
	ds_read_b128 v[200:203], v143
	ds_read_b128 v[204:207], v144
	ds_read_b128 v[208:211], v145
	ds_read_b128 v[212:215], v146
	buffer_load_dwordx4 v141, s[12:15], s7 offen lds
	s_mov_b32 m0, s70
	s_nop 0
	buffer_load_dwordx4 v142, s[12:15], s7 offen lds
	s_barrier
	s_waitcnt lgkmcnt(0)
	v_mfma_f32_16x16x32_bf16 v[92:95], v[200:203], v[168:171], v[92:95]
	v_mfma_f32_16x16x32_bf16 v[92:95], v[204:207], v[172:175], v[92:95]
	v_mfma_f32_16x16x32_bf16 v[88:91], v[208:211], v[168:171], v[88:91]
	v_mfma_f32_16x16x32_bf16 v[88:91], v[212:215], v[172:175], v[88:91]
	v_mfma_f32_16x16x32_bf16 v[80:83], v[200:203], v[176:179], v[80:83]
	v_mfma_f32_16x16x32_bf16 v[80:83], v[204:207], v[180:183], v[80:83]
	v_mfma_f32_16x16x32_bf16 v[68:71], v[208:211], v[176:179], v[68:71]
	v_mfma_f32_16x16x32_bf16 v[68:71], v[212:215], v[180:183], v[68:71]
	v_mfma_f32_16x16x32_bf16 v[60:63], v[200:203], v[184:187], v[60:63]
	v_mfma_f32_16x16x32_bf16 v[60:63], v[204:207], v[188:191], v[60:63]
	v_mfma_f32_16x16x32_bf16 v[56:59], v[208:211], v[184:187], v[56:59]
	v_mfma_f32_16x16x32_bf16 v[56:59], v[212:215], v[188:191], v[56:59]
	v_mfma_f32_16x16x32_bf16 v[52:55], v[200:203], v[192:195], v[52:55]
	v_mfma_f32_16x16x32_bf16 v[52:55], v[204:207], v[196:199], v[52:55]
	v_mfma_f32_16x16x32_bf16 v[48:51], v[208:211], v[192:195], v[48:51]
	v_mfma_f32_16x16x32_bf16 v[48:51], v[212:215], v[196:199], v[48:51]
	s_barrier
	s_add_i32 s7, s83, s3
	s_add_i32 s22, s7, 0x100
	s_mov_b32 m0, s35
	ds_read_b128 v[168:171], v129 offset:16384
	ds_read_b128 v[172:175], v129 offset:17408
	ds_read_b128 v[176:179], v132 offset:16384
	ds_read_b128 v[180:183], v132 offset:17408
	ds_read_b128 v[184:187], v131 offset:16384
	ds_read_b128 v[188:191], v131 offset:17408
	ds_read_b128 v[192:195], v130 offset:16384
	ds_read_b128 v[196:199], v130 offset:17408
	buffer_load_dwordx4 v141, s[8:11], s22 offen lds
	s_mov_b32 m0, s95
	s_nop 0
	buffer_load_dwordx4 v142, s[8:11], s22 offen lds
	s_barrier
	s_waitcnt lgkmcnt(0)
	v_mfma_f32_16x16x32_bf16 v[44:47], v[152:155], v[168:171], v[44:47]
	v_mfma_f32_16x16x32_bf16 v[44:47], v[156:159], v[172:175], v[44:47]
	v_mfma_f32_16x16x32_bf16 v[40:43], v[160:163], v[168:171], v[40:43]
	v_mfma_f32_16x16x32_bf16 v[40:43], v[164:167], v[172:175], v[40:43]
	v_mfma_f32_16x16x32_bf16 v[36:39], v[152:155], v[176:179], v[36:39]
	v_mfma_f32_16x16x32_bf16 v[36:39], v[156:159], v[180:183], v[36:39]
	v_mfma_f32_16x16x32_bf16 v[32:35], v[160:163], v[176:179], v[32:35]
	v_mfma_f32_16x16x32_bf16 v[32:35], v[164:167], v[180:183], v[32:35]
	v_mfma_f32_16x16x32_bf16 v[28:31], v[152:155], v[184:187], v[28:31]
	v_mfma_f32_16x16x32_bf16 v[28:31], v[156:159], v[188:191], v[28:31]
	v_mfma_f32_16x16x32_bf16 v[24:27], v[160:163], v[184:187], v[24:27]
	v_mfma_f32_16x16x32_bf16 v[24:27], v[164:167], v[188:191], v[24:27]
	v_mfma_f32_16x16x32_bf16 v[20:23], v[152:155], v[192:195], v[20:23]
	v_mfma_f32_16x16x32_bf16 v[20:23], v[156:159], v[196:199], v[20:23]
	v_mfma_f32_16x16x32_bf16 v[16:19], v[160:163], v[192:195], v[16:19]
	v_mfma_f32_16x16x32_bf16 v[16:19], v[164:167], v[196:199], v[16:19]
	s_barrier
	s_add_i32 s22, s85, s3
	s_add_i32 s23, s22, 0x100
	s_mov_b32 m0, s38
	s_nop 0
	buffer_load_dwordx4 v141, s[12:15], s23 offen lds
	s_mov_b32 m0, s71
	s_nop 0
	buffer_load_dwordx4 v142, s[12:15], s23 offen lds
	s_waitcnt vmcnt(6)
	s_barrier
; #define STAGE(P, RS, SOFF, OFF, kt) do { const int _so = (SOFF) + (kt) * (BK * 2); \
;     _Pragma("unroll") for (int _i = 0; _i < 2; ++_i) { \
;       __builtin_amdgcn_raw_ptr_buffer_load_lds(RS, (__attribute__((address_space(3))) void*)((P) + wave * 1024 + _i * 8192), 16, OFF[_i], _so, 0, 0); } } while (0)
; #define LDA(dst, b, h) _Pragma("unroll") for (int m = 0; m < 4; ++m) _Pragma("unroll") for (int k = 0; k < 2; ++k) \
;     dst[m][k] = *reinterpret_cast<const bf16x8*>(SA(b, h) + lds_byte(wr * 64 + m * 16 + fr, k * 32 + fq * 8))
; #define LDB(dst, b, h) _Pragma("unroll") for (int n = 0; n < 2; ++n) _Pragma("unroll") for (int k = 0; k < 2; ++k) \
;     dst[n][k] = *reinterpret_cast<const bf16x8*>(SB(b, h) + lds_byte(wc * 32 + n * 16 + fr, k * 32 + fq * 8))
; #define WAIT_V(n) asm volatile("s_waitcnt vmcnt(" #n ")" ::: "memory")
; #define WAIT_L(n) asm volatile("s_waitcnt lgkmcnt(" #n ")" ::: "memory")
; #define BAR __builtin_amdgcn_s_barrier()
; #define SCHED __builtin_amdgcn_sched_barrier(0)
;     ...
;       WAIT_V(6); BAR; MMA(1, 1, At, B1); BAR;
;       LDB(B0, 1, 0); SCHED; LDA(At, 1, 0); STAGE(SA(0, 1), rsA, sA1, offA, t + 2);
;       WAIT_L(8); BAR; WAIT_L(0); MMA(0, 0, At, B0); BAR; SCHED;
;       LDB(B1, 1, 1); STAGE(SB(1, 0), rsB, sB0, offB, t + 3);
;       BAR; WAIT_L(0); MMA(0, 1, At, B1); BAR;
;       LDA(At, 1, 1); STAGE(SA(1, 0), rsA, sA0, offA, t + 3);
;       BAR; WAIT_L(0); MMA(1, 0, At, B0); BAR; SCHED;
	v_mfma_f32_16x16x32_bf16 v[12:15], v[200:203], v[168:171], v[12:15]
	v_mfma_f32_16x16x32_bf16 v[12:15], v[204:207], v[172:175], v[12:15]
	v_mfma_f32_16x16x32_bf16 v[8:11], v[208:211], v[168:171], v[8:11]
	v_mfma_f32_16x16x32_bf16 v[8:11], v[212:215], v[172:175], v[8:11]
	v_mfma_f32_16x16x32_bf16 v[4:7], v[200:203], v[176:179], v[4:7]
	v_mfma_f32_16x16x32_bf16 v[4:7], v[204:207], v[180:183], v[4:7]
	v_mfma_f32_16x16x32_bf16 v[0:3], v[208:211], v[176:179], v[0:3]
	v_mfma_f32_16x16x32_bf16 v[0:3], v[212:215], v[180:183], v[0:3]
	v_mfma_f32_16x16x32_bf16 v[64:67], v[200:203], v[184:187], v[64:67]
	v_mfma_f32_16x16x32_bf16 v[64:67], v[204:207], v[188:191], v[64:67]
	v_mfma_f32_16x16x32_bf16 v[72:75], v[208:211], v[184:187], v[72:75]
	v_mfma_f32_16x16x32_bf16 v[72:75], v[212:215], v[188:191], v[72:75]
	v_mfma_f32_16x16x32_bf16 v[76:79], v[200:203], v[192:195], v[76:79]
	v_mfma_f32_16x16x32_bf16 v[76:79], v[204:207], v[196:199], v[76:79]
	v_mfma_f32_16x16x32_bf16 v[84:87], v[208:211], v[192:195], v[84:87]
	v_mfma_f32_16x16x32_bf16 v[84:87], v[212:215], v[196:199], v[84:87]
	s_barrier
	ds_read_b128 v[152:155], v137
	ds_read_b128 v[156:159], v138
	ds_read_b128 v[160:163], v139
	ds_read_b128 v[164:167], v140
	s_addk_i32 s5, 0x100
	s_mov_b32 m0, s39
	ds_read_b128 v[168:171], v129 offset:32768
	ds_read_b128 v[172:175], v129 offset:33792
	ds_read_b128 v[176:179], v132 offset:32768
	ds_read_b128 v[180:183], v132 offset:33792
	ds_read_b128 v[184:187], v131 offset:32768
	ds_read_b128 v[188:191], v131 offset:33792
	ds_read_b128 v[192:195], v130 offset:32768
	ds_read_b128 v[196:199], v130 offset:33792
	buffer_load_dwordx4 v141, s[8:11], s5 offen lds
	s_mov_b32 m0, s97
	s_nop 0
	buffer_load_dwordx4 v142, s[8:11], s5 offen lds
	s_waitcnt lgkmcnt(8)
	s_barrier
	s_waitcnt lgkmcnt(0)
	v_mfma_f32_16x16x32_bf16 v[124:127], v[152:155], v[168:171], v[124:127]
	v_mfma_f32_16x16x32_bf16 v[124:127], v[156:159], v[172:175], v[124:127]
	v_mfma_f32_16x16x32_bf16 v[120:123], v[160:163], v[168:171], v[120:123]
	v_mfma_f32_16x16x32_bf16 v[120:123], v[164:167], v[172:175], v[120:123]
	v_mfma_f32_16x16x32_bf16 v[116:119], v[152:155], v[176:179], v[116:119]
	v_mfma_f32_16x16x32_bf16 v[116:119], v[156:159], v[180:183], v[116:119]
	v_mfma_f32_16x16x32_bf16 v[112:115], v[160:163], v[176:179], v[112:115]
	v_mfma_f32_16x16x32_bf16 v[112:115], v[164:167], v[180:183], v[112:115]
	v_mfma_f32_16x16x32_bf16 v[108:111], v[152:155], v[184:187], v[108:111]
	v_mfma_f32_16x16x32_bf16 v[108:111], v[156:159], v[188:191], v[108:111]
	v_mfma_f32_16x16x32_bf16 v[104:107], v[160:163], v[184:187], v[104:107]
	v_mfma_f32_16x16x32_bf16 v[104:107], v[164:167], v[188:191], v[104:107]
	v_mfma_f32_16x16x32_bf16 v[100:103], v[152:155], v[192:195], v[100:103]
	v_mfma_f32_16x16x32_bf16 v[100:103], v[156:159], v[196:199], v[100:103]
	v_mfma_f32_16x16x32_bf16 v[96:99], v[160:163], v[192:195], v[96:99]
	v_mfma_f32_16x16x32_bf16 v[96:99], v[164:167], v[196:199], v[96:99]
	s_barrier
	s_addk_i32 s6, 0x180
	s_mov_b32 m0, s92
	ds_read_b128 v[200:203], v133
	ds_read_b128 v[204:207], v134
	ds_read_b128 v[208:211], v135
	ds_read_b128 v[212:215], v136
	buffer_load_dwordx4 v141, s[12:15], s6 offen lds
	s_mov_b32 m0, s56
	s_nop 0
	buffer_load_dwordx4 v142, s[12:15], s6 offen lds
	s_barrier
	s_waitcnt lgkmcnt(0)
	v_mfma_f32_16x16x32_bf16 v[92:95], v[200:203], v[168:171], v[92:95]
	v_mfma_f32_16x16x32_bf16 v[92:95], v[204:207], v[172:175], v[92:95]
	v_mfma_f32_16x16x32_bf16 v[88:91], v[208:211], v[168:171], v[88:91]
	v_mfma_f32_16x16x32_bf16 v[88:91], v[212:215], v[172:175], v[88:91]
	v_mfma_f32_16x16x32_bf16 v[80:83], v[200:203], v[176:179], v[80:83]
	v_mfma_f32_16x16x32_bf16 v[80:83], v[204:207], v[180:183], v[80:83]
	v_mfma_f32_16x16x32_bf16 v[68:71], v[208:211], v[176:179], v[68:71]
	v_mfma_f32_16x16x32_bf16 v[68:71], v[212:215], v[180:183], v[68:71]
	v_mfma_f32_16x16x32_bf16 v[60:63], v[200:203], v[184:187], v[60:63]
	v_mfma_f32_16x16x32_bf16 v[60:63], v[204:207], v[188:191], v[60:63]
	v_mfma_f32_16x16x32_bf16 v[56:59], v[208:211], v[184:187], v[56:59]
	v_mfma_f32_16x16x32_bf16 v[56:59], v[212:215], v[188:191], v[56:59]
	v_mfma_f32_16x16x32_bf16 v[52:55], v[200:203], v[192:195], v[52:55]
	v_mfma_f32_16x16x32_bf16 v[52:55], v[204:207], v[196:199], v[52:55]
	v_mfma_f32_16x16x32_bf16 v[48:51], v[208:211], v[192:195], v[48:51]
	v_mfma_f32_16x16x32_bf16 v[48:51], v[212:215], v[196:199], v[48:51]
	s_barrier
	s_addk_i32 s7, 0x180
	s_mov_b32 m0, s93
	ds_read_b128 v[168:171], v129 offset:49152
	ds_read_b128 v[172:175], v129 offset:50176
	ds_read_b128 v[176:179], v132 offset:49152
	ds_read_b128 v[180:183], v132 offset:50176
	ds_read_b128 v[184:187], v131 offset:49152
	ds_read_b128 v[188:191], v131 offset:50176
	ds_read_b128 v[192:195], v130 offset:49152
	ds_read_b128 v[196:199], v130 offset:50176
	buffer_load_dwordx4 v141, s[8:11], s7 offen lds
	s_mov_b32 m0, s57
	s_nop 0
	buffer_load_dwordx4 v142, s[8:11], s7 offen lds
	s_barrier
	s_waitcnt lgkmcnt(0)
	v_mfma_f32_16x16x32_bf16 v[44:47], v[152:155], v[168:171], v[44:47]
	v_mfma_f32_16x16x32_bf16 v[44:47], v[156:159], v[172:175], v[44:47]
	v_mfma_f32_16x16x32_bf16 v[40:43], v[160:163], v[168:171], v[40:43]
	v_mfma_f32_16x16x32_bf16 v[40:43], v[164:167], v[172:175], v[40:43]
	v_mfma_f32_16x16x32_bf16 v[36:39], v[152:155], v[176:179], v[36:39]
	v_mfma_f32_16x16x32_bf16 v[36:39], v[156:159], v[180:183], v[36:39]
	v_mfma_f32_16x16x32_bf16 v[32:35], v[160:163], v[176:179], v[32:35]
	v_mfma_f32_16x16x32_bf16 v[32:35], v[164:167], v[180:183], v[32:35]
	v_mfma_f32_16x16x32_bf16 v[28:31], v[152:155], v[184:187], v[28:31]
	v_mfma_f32_16x16x32_bf16 v[28:31], v[156:159], v[188:191], v[28:31]
	v_mfma_f32_16x16x32_bf16 v[24:27], v[160:163], v[184:187], v[24:27]
	v_mfma_f32_16x16x32_bf16 v[24:27], v[164:167], v[188:191], v[24:27]
	v_mfma_f32_16x16x32_bf16 v[20:23], v[152:155], v[192:195], v[20:23]
	v_mfma_f32_16x16x32_bf16 v[20:23], v[156:159], v[196:199], v[20:23]
	v_mfma_f32_16x16x32_bf16 v[16:19], v[160:163], v[192:195], v[16:19]
	v_mfma_f32_16x16x32_bf16 v[16:19], v[164:167], v[196:199], v[16:19]
	s_barrier
; #define STAGE(P, RS, SOFF, OFF, kt) do { const int _so = (SOFF) + (kt) * (BK * 2); \
;     _Pragma("unroll") for (int _i = 0; _i < 2; ++_i) { \
;       __builtin_amdgcn_raw_ptr_buffer_load_lds(RS, (__attribute__((address_space(3))) void*)((P) + wave * 1024 + _i * 8192), 16, OFF[_i], _so, 0, 0); } } while (0)
; #define LDA(dst, b, h) _Pragma("unroll") for (int m = 0; m < 4; ++m) _Pragma("unroll") for (int k = 0; k < 2; ++k) \
;     dst[m][k] = *reinterpret_cast<const bf16x8*>(SA(b, h) + lds_byte(wr * 64 + m * 16 + fr, k * 32 + fq * 8))
; #define LDB(dst, b, h) _Pragma("unroll") for (int n = 0; n < 2; ++n) _Pragma("unroll") for (int k = 0; k < 2; ++k) \
;     dst[n][k] = *reinterpret_cast<const bf16x8*>(SB(b, h) + lds_byte(wc * 32 + n * 16 + fr, k * 32 + fq * 8))
; #define WAIT_V(n) asm volatile("s_waitcnt vmcnt(" #n ")" ::: "memory")
; #define WAIT_L(n) asm volatile("s_waitcnt lgkmcnt(" #n ")" ::: "memory")
; #define BAR __builtin_amdgcn_s_barrier()
;     ...
;       STAGE(SB(1, 1), rsB, sB1, offB, t + 3);
;       WAIT_V(6); BAR; MMA(1, 1, At, B1); BAR;
;     }
;     { LDB(B0, 0, 0); LDA(At, 0, 0); STAGE(SA(1, 1), rsA, sA1, offA, nt - 1);
;       BAR; WAIT_L(0); MMA(0, 0, At, B0); BAR;
;       LDB(B1, 0, 1); BAR; WAIT_L(0); MMA(0, 1, At, B1); BAR;
;       LDA(At, 0, 1); WAIT_V(4); BAR; WAIT_L(0); MMA(1, 0, At, B0); MMA(1, 1, At, B1); BAR; }
	s_addk_i32 s22, 0x180
	s_mov_b32 m0, s94
	s_nop 0
	buffer_load_dwordx4 v141, s[12:15], s22 offen lds
	s_mov_b32 m0, s58
	s_nop 0
	buffer_load_dwordx4 v142, s[12:15], s22 offen lds
	s_add_i32 s1, s1, 2
	s_addk_i32 s3, 0x100
	s_cmp_gt_u32 s1, 59
	s_cbranch_scc0 .LBB0_494
	s_waitcnt vmcnt(6)
	s_barrier
	v_mfma_f32_16x16x32_bf16 v[12:15], v[200:203], v[168:171], v[12:15]
	v_mfma_f32_16x16x32_bf16 v[12:15], v[204:207], v[172:175], v[12:15]
	v_mfma_f32_16x16x32_bf16 v[8:11], v[208:211], v[168:171], v[8:11]
	v_mfma_f32_16x16x32_bf16 v[8:11], v[212:215], v[172:175], v[8:11]
	v_mfma_f32_16x16x32_bf16 v[4:7], v[200:203], v[176:179], v[4:7]
	v_mfma_f32_16x16x32_bf16 v[4:7], v[204:207], v[180:183], v[4:7]
	v_mfma_f32_16x16x32_bf16 v[0:3], v[208:211], v[176:179], v[0:3]
	v_mfma_f32_16x16x32_bf16 v[0:3], v[212:215], v[180:183], v[0:3]
	v_mfma_f32_16x16x32_bf16 v[64:67], v[200:203], v[184:187], v[64:67]
	v_mfma_f32_16x16x32_bf16 v[64:67], v[204:207], v[188:191], v[64:67]
	v_mfma_f32_16x16x32_bf16 v[72:75], v[208:211], v[184:187], v[72:75]
	v_mfma_f32_16x16x32_bf16 v[72:75], v[212:215], v[188:191], v[72:75]
	v_mfma_f32_16x16x32_bf16 v[76:79], v[200:203], v[192:195], v[76:79]
	v_mfma_f32_16x16x32_bf16 v[76:79], v[204:207], v[196:199], v[76:79]
	v_mfma_f32_16x16x32_bf16 v[84:87], v[208:211], v[192:195], v[84:87]
	v_mfma_f32_16x16x32_bf16 v[84:87], v[212:215], v[196:199], v[84:87]
	s_barrier
	s_add_i32 s1, s82, 0x1f80
	s_mov_b32 m0, s36
	ds_read_b128 v[152:155], v147
	ds_read_b128 v[156:159], v148
	ds_read_b128 v[160:163], v149
	ds_read_b128 v[148:151], v150
	ds_read_b128 v[164:167], v129
	ds_read_b128 v[168:171], v129 offset:1024
	ds_read_b128 v[172:175], v132
	ds_read_b128 v[176:179], v132 offset:1024
	ds_read_b128 v[180:183], v131
	ds_read_b128 v[184:187], v131 offset:1024
	ds_read_b128 v[188:191], v130
	ds_read_b128 v[192:195], v130 offset:1024
	buffer_load_dwordx4 v141, s[8:11], s1 offen lds
	s_mov_b32 m0, s59
	s_nop 0
	buffer_load_dwordx4 v142, s[8:11], s1 offen lds
	s_barrier
	s_waitcnt lgkmcnt(0)
	v_mfma_f32_16x16x32_bf16 v[124:127], v[152:155], v[164:167], v[124:127]
	v_mfma_f32_16x16x32_bf16 v[124:127], v[156:159], v[168:171], v[124:127]
	v_mfma_f32_16x16x32_bf16 v[120:123], v[160:163], v[164:167], v[120:123]
	v_mfma_f32_16x16x32_bf16 v[120:123], v[148:151], v[168:171], v[120:123]
	v_mfma_f32_16x16x32_bf16 v[116:119], v[152:155], v[172:175], v[116:119]
	v_mfma_f32_16x16x32_bf16 v[116:119], v[156:159], v[176:179], v[116:119]
	v_mfma_f32_16x16x32_bf16 v[112:115], v[160:163], v[172:175], v[112:115]
	v_mfma_f32_16x16x32_bf16 v[112:115], v[148:151], v[176:179], v[112:115]
	v_mfma_f32_16x16x32_bf16 v[108:111], v[152:155], v[180:183], v[108:111]
	v_mfma_f32_16x16x32_bf16 v[108:111], v[156:159], v[184:187], v[108:111]
	v_mfma_f32_16x16x32_bf16 v[104:107], v[160:163], v[180:183], v[104:107]
	v_mfma_f32_16x16x32_bf16 v[104:107], v[148:151], v[184:187], v[104:107]
	v_mfma_f32_16x16x32_bf16 v[100:103], v[152:155], v[188:191], v[100:103]
	v_mfma_f32_16x16x32_bf16 v[100:103], v[156:159], v[192:195], v[100:103]
	v_mfma_f32_16x16x32_bf16 v[96:99], v[160:163], v[188:191], v[96:99]
	v_mfma_f32_16x16x32_bf16 v[96:99], v[148:151], v[192:195], v[96:99]
	s_barrier
	ds_read_b128 v[196:199], v143
	ds_read_b128 v[200:203], v144
	ds_read_b128 v[142:145], v145
	ds_read_b128 v[204:207], v146
	s_barrier
	s_waitcnt lgkmcnt(0)
	v_mfma_f32_16x16x32_bf16 v[80:83], v[196:199], v[172:175], v[80:83]
	v_mfma_f32_16x16x32_bf16 v[68:71], v[142:145], v[172:175], v[68:71]
	v_mfma_f32_16x16x32_bf16 v[60:63], v[196:199], v[180:183], v[60:63]
	v_mfma_f32_16x16x32_bf16 v[56:59], v[142:145], v[180:183], v[56:59]
	v_mfma_f32_16x16x32_bf16 v[52:55], v[196:199], v[188:191], v[52:55]
	v_mfma_f32_16x16x32_bf16 v[48:51], v[142:145], v[188:191], v[48:51]
	v_mfma_f32_16x16x32_bf16 v[92:95], v[196:199], v[164:167], v[92:95]
	v_mfma_f32_16x16x32_bf16 v[88:91], v[142:145], v[164:167], v[88:91]
	v_mfma_f32_16x16x32_bf16 v[80:83], v[200:203], v[176:179], v[80:83]
	v_mfma_f32_16x16x32_bf16 v[68:71], v[204:207], v[176:179], v[68:71]
	v_mfma_f32_16x16x32_bf16 v[60:63], v[200:203], v[184:187], v[60:63]
	v_mfma_f32_16x16x32_bf16 v[56:59], v[204:207], v[184:187], v[56:59]
	v_mfma_f32_16x16x32_bf16 v[52:55], v[200:203], v[192:195], v[52:55]
	v_mfma_f32_16x16x32_bf16 v[48:51], v[204:207], v[192:195], v[48:51]
	v_mfma_f32_16x16x32_bf16 v[164:167], v[200:203], v[168:171], v[92:95]
	v_mfma_f32_16x16x32_bf16 v[168:171], v[204:207], v[168:171], v[88:91]
	s_barrier
	s_nop 0
	ds_read_b128 v[88:91], v129 offset:16384
	ds_read_b128 v[92:95], v129 offset:17408
	ds_read_b128 v[172:175], v132 offset:16384
	ds_read_b128 v[176:179], v132 offset:17408
	ds_read_b128 v[180:183], v131 offset:16384
	ds_read_b128 v[184:187], v131 offset:17408
	ds_read_b128 v[188:191], v130 offset:16384
	ds_read_b128 v[192:195], v130 offset:17408
	s_waitcnt vmcnt(4)
	s_barrier
; #define LDA(dst, b, h) _Pragma("unroll") for (int m = 0; m < 4; ++m) _Pragma("unroll") for (int k = 0; k < 2; ++k) \
;     dst[m][k] = *reinterpret_cast<const bf16x8*>(SA(b, h) + lds_byte(wr * 64 + m * 16 + fr, k * 32 + fq * 8))
; #define LDB(dst, b, h) _Pragma("unroll") for (int n = 0; n < 2; ++n) _Pragma("unroll") for (int k = 0; k < 2; ++k) \
;     dst[n][k] = *reinterpret_cast<const bf16x8*>(SB(b, h) + lds_byte(wc * 32 + n * 16 + fr, k * 32 + fq * 8))
; #define WAIT_V(n) asm volatile("s_waitcnt vmcnt(" #n ")" ::: "memory")
; #define WAIT_L(n) asm volatile("s_waitcnt lgkmcnt(" #n ")" ::: "memory")
; #define BAR __builtin_amdgcn_s_barrier()
;     ...
;       LDA(At, 0, 1); WAIT_V(4); BAR; WAIT_L(0); MMA(1, 0, At, B0); MMA(1, 1, At, B1); BAR; }
;     { LDB(B0, 1, 0); LDA(At, 1, 0); WAIT_V(2); BAR; WAIT_L(0); MMA(0, 0, At, B0); BAR;
	s_waitcnt lgkmcnt(0)
	v_mfma_f32_16x16x32_bf16 v[44:47], v[152:155], v[88:91], v[44:47]
	v_mfma_f32_16x16x32_bf16 v[40:43], v[160:163], v[88:91], v[40:43]
	v_mfma_f32_16x16x32_bf16 v[36:39], v[152:155], v[172:175], v[36:39]
	v_mfma_f32_16x16x32_bf16 v[32:35], v[160:163], v[172:175], v[32:35]
	v_mfma_f32_16x16x32_bf16 v[28:31], v[152:155], v[180:183], v[28:31]
	v_mfma_f32_16x16x32_bf16 v[24:27], v[160:163], v[180:183], v[24:27]
	v_mfma_f32_16x16x32_bf16 v[20:23], v[152:155], v[188:191], v[20:23]
	v_mfma_f32_16x16x32_bf16 v[16:19], v[160:163], v[188:191], v[16:19]
	v_mfma_f32_16x16x32_bf16 v[44:47], v[156:159], v[92:95], v[44:47]
	v_mfma_f32_16x16x32_bf16 v[40:43], v[148:151], v[92:95], v[40:43]
	v_mfma_f32_16x16x32_bf16 v[36:39], v[156:159], v[176:179], v[36:39]
	v_mfma_f32_16x16x32_bf16 v[32:35], v[148:151], v[176:179], v[32:35]
	v_mfma_f32_16x16x32_bf16 v[28:31], v[156:159], v[184:187], v[28:31]
	v_mfma_f32_16x16x32_bf16 v[24:27], v[148:151], v[184:187], v[24:27]
	v_mfma_f32_16x16x32_bf16 v[20:23], v[156:159], v[192:195], v[20:23]
	v_mfma_f32_16x16x32_bf16 v[16:19], v[148:151], v[192:195], v[16:19]
	v_mfma_f32_16x16x32_bf16 v[4:7], v[196:199], v[172:175], v[4:7]
	v_mfma_f32_16x16x32_bf16 v[0:3], v[142:145], v[172:175], v[0:3]
	v_mfma_f32_16x16x32_bf16 v[12:15], v[196:199], v[88:91], v[12:15]
	v_mfma_f32_16x16x32_bf16 v[8:11], v[142:145], v[88:91], v[8:11]
	v_mfma_f32_16x16x32_bf16 v[64:67], v[196:199], v[180:183], v[64:67]
	v_mfma_f32_16x16x32_bf16 v[72:75], v[142:145], v[180:183], v[72:75]
	v_mfma_f32_16x16x32_bf16 v[76:79], v[196:199], v[188:191], v[76:79]
	v_mfma_f32_16x16x32_bf16 v[84:87], v[142:145], v[188:191], v[84:87]
	v_mfma_f32_16x16x32_bf16 v[4:7], v[200:203], v[176:179], v[4:7]
	v_mfma_f32_16x16x32_bf16 v[0:3], v[204:207], v[176:179], v[0:3]
	v_mfma_f32_16x16x32_bf16 v[142:145], v[200:203], v[92:95], v[12:15]
	v_mfma_f32_16x16x32_bf16 v[146:149], v[204:207], v[92:95], v[8:11]
	v_mfma_f32_16x16x32_bf16 v[150:153], v[200:203], v[184:187], v[64:67]
	v_mfma_f32_16x16x32_bf16 v[154:157], v[204:207], v[184:187], v[72:75]
	v_mfma_f32_16x16x32_bf16 v[158:161], v[200:203], v[192:195], v[76:79]
	v_mfma_f32_16x16x32_bf16 v[172:175], v[204:207], v[192:195], v[84:87]
	s_barrier
	ds_read_b128 v[8:11], v137
	ds_read_b128 v[12:15], v138
	ds_read_b128 v[176:179], v139
	ds_read_b128 v[138:141], v140
	ds_read_b128 v[64:67], v129 offset:32768
	ds_read_b128 v[84:87], v129 offset:33792
	ds_read_b128 v[180:183], v132 offset:32768
	ds_read_b128 v[184:187], v132 offset:33792
	ds_read_b128 v[188:191], v131 offset:32768
	ds_read_b128 v[192:195], v131 offset:33792
	ds_read_b128 v[196:199], v130 offset:32768
	ds_read_b128 v[200:203], v130 offset:33792
	s_waitcnt vmcnt(2)
	s_barrier
	s_waitcnt lgkmcnt(0)
	v_mfma_f32_16x16x32_bf16 v[72:75], v[8:11], v[64:67], v[124:127]
	v_mfma_f32_16x16x32_bf16 v[76:79], v[176:179], v[64:67], v[120:123]
	v_mfma_f32_16x16x32_bf16 v[88:91], v[8:11], v[180:183], v[116:119]
	v_mfma_f32_16x16x32_bf16 v[92:95], v[176:179], v[180:183], v[112:115]
	v_mfma_f32_16x16x32_bf16 v[112:115], v[8:11], v[188:191], v[108:111]
	v_mfma_f32_16x16x32_bf16 v[120:123], v[176:179], v[188:191], v[104:107]
	v_mfma_f32_16x16x32_bf16 v[100:103], v[8:11], v[196:199], v[100:103]
	v_mfma_f32_16x16x32_bf16 v[96:99], v[176:179], v[196:199], v[96:99]
	v_mfma_f32_16x16x32_bf16 v[124:127], v[12:15], v[84:87], v[72:75]
	v_mfma_f32_16x16x32_bf16 v[116:119], v[138:141], v[84:87], v[76:79]
	v_mfma_f32_16x16x32_bf16 v[108:111], v[12:15], v[184:187], v[88:91]
	v_mfma_f32_16x16x32_bf16 v[104:107], v[138:141], v[184:187], v[92:95]
	v_mfma_f32_16x16x32_bf16 v[92:95], v[12:15], v[192:195], v[112:115]
	v_mfma_f32_16x16x32_bf16 v[88:91], v[138:141], v[192:195], v[120:123]
	v_mfma_f32_16x16x32_bf16 v[76:79], v[12:15], v[200:203], v[100:103]
	v_mfma_f32_16x16x32_bf16 v[72:75], v[138:141], v[200:203], v[96:99]
	s_barrier
; #define LDA(dst, b, h) _Pragma("unroll") for (int m = 0; m < 4; ++m) _Pragma("unroll") for (int k = 0; k < 2; ++k) \
;     dst[m][k] = *reinterpret_cast<const bf16x8*>(SA(b, h) + lds_byte(wr * 64 + m * 16 + fr, k * 32 + fq * 8))
; #define LDB(dst, b, h) _Pragma("unroll") for (int n = 0; n < 2; ++n) _Pragma("unroll") for (int k = 0; k < 2; ++k) \
;     dst[n][k] = *reinterpret_cast<const bf16x8*>(SB(b, h) + lds_byte(wc * 32 + n * 16 + fr, k * 32 + fq * 8))
; #define WAIT_V(n) asm volatile("s_waitcnt vmcnt(" #n ")" ::: "memory")
; #define WAIT_L(n) asm volatile("s_waitcnt lgkmcnt(" #n ")" ::: "memory")
; #define BAR __builtin_amdgcn_s_barrier()
;     ...
;       LDB(B1, 1, 1); WAIT_V(0); BAR; WAIT_L(0); MMA(0, 1, At, B1); BAR;
;       LDA(At, 1, 1); BAR; WAIT_L(0); MMA(1, 0, At, B0); MMA(1, 1, At, B1); BAR; }
;     if (wr == 0) BAR;
	ds_read_b128 v[204:207], v133
	ds_read_b128 v[208:211], v134
	ds_read_b128 v[212:215], v135
	ds_read_b128 v[134:137], v136
	s_waitcnt vmcnt(0)
	s_barrier
	s_waitcnt lgkmcnt(0)
	v_mfma_f32_16x16x32_bf16 v[96:99], v[204:207], v[64:67], v[164:167]
	v_mfma_f32_16x16x32_bf16 v[64:67], v[212:215], v[64:67], v[168:171]
	v_mfma_f32_16x16x32_bf16 v[80:83], v[204:207], v[180:183], v[80:83]
	v_mfma_f32_16x16x32_bf16 v[68:71], v[212:215], v[180:183], v[68:71]
	v_mfma_f32_16x16x32_bf16 v[60:63], v[204:207], v[188:191], v[60:63]
	v_mfma_f32_16x16x32_bf16 v[56:59], v[212:215], v[188:191], v[56:59]
	v_mfma_f32_16x16x32_bf16 v[52:55], v[204:207], v[196:199], v[52:55]
	v_mfma_f32_16x16x32_bf16 v[48:51], v[212:215], v[196:199], v[48:51]
	v_mfma_f32_16x16x32_bf16 v[120:123], v[208:211], v[84:87], v[96:99]
	v_mfma_f32_16x16x32_bf16 v[112:115], v[134:137], v[84:87], v[64:67]
	v_mfma_f32_16x16x32_bf16 v[100:103], v[208:211], v[184:187], v[80:83]
	v_mfma_f32_16x16x32_bf16 v[96:99], v[134:137], v[184:187], v[68:71]
	v_mfma_f32_16x16x32_bf16 v[84:87], v[208:211], v[192:195], v[60:63]
	v_mfma_f32_16x16x32_bf16 v[80:83], v[134:137], v[192:195], v[56:59]
	v_mfma_f32_16x16x32_bf16 v[68:71], v[208:211], v[200:203], v[52:55]
	v_mfma_f32_16x16x32_bf16 v[64:67], v[134:137], v[200:203], v[48:51]
	s_barrier
	s_nop 0
	ds_read_b128 v[48:51], v129 offset:49152
	ds_read_b128 v[162:165], v129 offset:50176
	ds_read_b128 v[52:55], v132 offset:49152
	ds_read_b128 v[166:169], v132 offset:50176
	ds_read_b128 v[180:183], v131 offset:49152
	ds_read_b128 v[184:187], v131 offset:50176
	ds_read_b128 v[188:191], v130 offset:49152
	ds_read_b128 v[130:133], v130 offset:50176
	s_barrier
	s_waitcnt lgkmcnt(0)
	v_mfma_f32_16x16x32_bf16 v[44:47], v[8:11], v[48:51], v[44:47]
	v_mfma_f32_16x16x32_bf16 v[40:43], v[176:179], v[48:51], v[40:43]
	v_mfma_f32_16x16x32_bf16 v[36:39], v[8:11], v[52:55], v[36:39]
	v_mfma_f32_16x16x32_bf16 v[32:35], v[176:179], v[52:55], v[32:35]
	v_mfma_f32_16x16x32_bf16 v[28:31], v[8:11], v[180:183], v[28:31]
	v_mfma_f32_16x16x32_bf16 v[24:27], v[176:179], v[180:183], v[24:27]
	v_mfma_f32_16x16x32_bf16 v[8:11], v[8:11], v[188:191], v[20:23]
	v_mfma_f32_16x16x32_bf16 v[16:19], v[176:179], v[188:191], v[16:19]
	v_mfma_f32_16x16x32_bf16 v[60:63], v[12:15], v[162:165], v[44:47]
	v_mfma_f32_16x16x32_bf16 v[56:59], v[138:141], v[162:165], v[40:43]
	v_mfma_f32_16x16x32_bf16 v[44:47], v[12:15], v[166:169], v[36:39]
	v_mfma_f32_16x16x32_bf16 v[40:43], v[138:141], v[166:169], v[32:35]
	v_mfma_f32_16x16x32_bf16 v[28:31], v[12:15], v[184:187], v[28:31]
	v_mfma_f32_16x16x32_bf16 v[24:27], v[138:141], v[184:187], v[24:27]
	v_mfma_f32_16x16x32_bf16 v[12:15], v[12:15], v[130:133], v[8:11]
	v_mfma_f32_16x16x32_bf16 v[8:11], v[138:141], v[130:133], v[16:19]
	v_mfma_f32_16x16x32_bf16 v[16:19], v[204:207], v[48:51], v[142:145]
	v_mfma_f32_16x16x32_bf16 v[20:23], v[212:215], v[48:51], v[146:149]
	v_mfma_f32_16x16x32_bf16 v[4:7], v[204:207], v[52:55], v[4:7]
	v_mfma_f32_16x16x32_bf16 v[0:3], v[212:215], v[52:55], v[0:3]
	v_mfma_f32_16x16x32_bf16 v[138:141], v[204:207], v[180:183], v[150:153]
	v_mfma_f32_16x16x32_bf16 v[142:145], v[212:215], v[180:183], v[154:157]
	v_mfma_f32_16x16x32_bf16 v[146:149], v[204:207], v[188:191], v[158:161]
	v_mfma_f32_16x16x32_bf16 v[150:153], v[212:215], v[188:191], v[172:175]
	v_mfma_f32_16x16x32_bf16 v[52:55], v[208:211], v[162:165], v[16:19]
	v_mfma_f32_16x16x32_bf16 v[48:51], v[134:137], v[162:165], v[20:23]
	v_mfma_f32_16x16x32_bf16 v[36:39], v[208:211], v[166:169], v[4:7]
	v_mfma_f32_16x16x32_bf16 v[32:35], v[134:137], v[166:169], v[0:3]
	v_mfma_f32_16x16x32_bf16 v[20:23], v[208:211], v[184:187], v[138:141]
	v_mfma_f32_16x16x32_bf16 v[16:19], v[134:137], v[184:187], v[142:145]
	v_mfma_f32_16x16x32_bf16 v[4:7], v[208:211], v[130:133], v[146:149]
	v_mfma_f32_16x16x32_bf16 v[0:3], v[134:137], v[130:133], v[150:153]
	v_cmp_gt_u32_e32 vcc, s76, v128
	s_barrier
	s_and_saveexec_b64 s[6:7], vcc
	s_cbranch_execz .LBB0_497
	s_barrier

; #define STAGE(P, RS, SOFF, OFF, kt) do { const int _so = (SOFF) + (kt) * (BK * 2); \
;     _Pragma("unroll") for (int _i = 0; _i < 2; ++_i) { \
;       __builtin_amdgcn_raw_ptr_buffer_load_lds(RS, (__attribute__((address_space(3))) void*)((P) + wave * 1024 + _i * 8192), 16, OFF[_i], _so, 0, 0); } } while (0)
; #define LDA(dst, b, h) _Pragma("unroll") for (int m = 0; m < 4; ++m) _Pragma("unroll") for (int k = 0; k < 2; ++k) \
;     dst[m][k] = *reinterpret_cast<const bf16x8*>(SA(b, h) + lds_byte(wr * 64 + m * 16 + fr, k * 32 + fq * 8))
; #define LDB(dst, b, h) _Pragma("unroll") for (int n = 0; n < 2; ++n) _Pragma("unroll") for (int k = 0; k < 2; ++k) \
;     dst[n][k] = *reinterpret_cast<const bf16x8*>(SB(b, h) + lds_byte(wc * 32 + n * 16 + fr, k * 32 + fq * 8))
; #define WAIT_V(n) asm volatile("s_waitcnt vmcnt(" #n ")" ::: "memory")
; #define WAIT_L(n) asm volatile("s_waitcnt lgkmcnt(" #n ")" ::: "memory")
; #define BAR __builtin_amdgcn_s_barrier()
; #define SCHED __builtin_amdgcn_sched_barrier(0)
;     ...
;       LDB(B0, 0, 0); SCHED; LDA(At, 0, 0); STAGE(SA(1, 1), rsA, sA1, offA, t + 1);
;       WAIT_L(8); BAR; WAIT_L(0); MMA(0, 0, At, B0); BAR; SCHED;
;       LDB(B1, 0, 1); STAGE(SB(0, 0), rsB, sB0, offB, t + 2);
;       BAR; WAIT_L(0); MMA(0, 1, At, B1); BAR;
;       LDA(At, 0, 1); STAGE(SA(0, 0), rsA, sA0, offA, t + 2);
;       BAR; WAIT_L(0); MMA(1, 0, At, B0); BAR; SCHED;
;       STAGE(SB(0, 1), rsB, sB1, offB, t + 2);
;       WAIT_V(6); BAR; MMA(1, 1, At, B1); BAR;
.Lmy_rot_556:
	ds_read_b128 v[154:157], v149
	ds_read_b128 v[158:161], v150
	ds_read_b128 v[162:165], v151
	ds_read_b128 v[166:169], v152
	s_add_i32 s43, s37, s17
	s_add_i32 s10, s43, 0x80
	s_mov_b32 m0, s30
	ds_read_b128 v[170:173], v131
	ds_read_b128 v[174:177], v131 offset:1024
	ds_read_b128 v[178:181], v134
	ds_read_b128 v[182:185], v134 offset:1024
	ds_read_b128 v[186:189], v133
	ds_read_b128 v[190:193], v133 offset:1024
	ds_read_b128 v[194:197], v132
	ds_read_b128 v[198:201], v132 offset:1024
	buffer_load_dwordx4 v143, s[4:7], s10 offen lds
	s_mov_b32 m0, s31
	s_nop 0
	buffer_load_dwordx4 v144, s[4:7], s10 offen lds
	s_waitcnt lgkmcnt(8)
	s_barrier
	s_waitcnt lgkmcnt(0)
	v_mfma_f32_16x16x32_bf16 v[124:127], v[154:157], v[170:173], v[124:127]
	v_mfma_f32_16x16x32_bf16 v[124:127], v[158:161], v[174:177], v[124:127]
	v_mfma_f32_16x16x32_bf16 v[120:123], v[162:165], v[170:173], v[120:123]
	v_mfma_f32_16x16x32_bf16 v[120:123], v[166:169], v[174:177], v[120:123]
	v_mfma_f32_16x16x32_bf16 v[116:119], v[154:157], v[178:181], v[116:119]
	v_mfma_f32_16x16x32_bf16 v[116:119], v[158:161], v[182:185], v[116:119]
	v_mfma_f32_16x16x32_bf16 v[112:115], v[162:165], v[178:181], v[112:115]
	v_mfma_f32_16x16x32_bf16 v[112:115], v[166:169], v[182:185], v[112:115]
	v_mfma_f32_16x16x32_bf16 v[108:111], v[154:157], v[186:189], v[108:111]
	v_mfma_f32_16x16x32_bf16 v[108:111], v[158:161], v[190:193], v[108:111]
	v_mfma_f32_16x16x32_bf16 v[104:107], v[162:165], v[186:189], v[104:107]
	v_mfma_f32_16x16x32_bf16 v[104:107], v[166:169], v[190:193], v[104:107]
	v_mfma_f32_16x16x32_bf16 v[100:103], v[154:157], v[194:197], v[100:103]
	v_mfma_f32_16x16x32_bf16 v[100:103], v[158:161], v[198:201], v[100:103]
	v_mfma_f32_16x16x32_bf16 v[96:99], v[162:165], v[194:197], v[96:99]
	v_mfma_f32_16x16x32_bf16 v[96:99], v[166:169], v[198:201], v[96:99]
	s_barrier
	s_add_i32 s44, s39, s17
	s_add_i32 s45, s44, 0x100
	s_mov_b32 s10, s6
	s_mov_b32 s11, s7
	s_mov_b32 m0, s1
	ds_read_b128 v[202:205], v145
	ds_read_b128 v[206:209], v146
	ds_read_b128 v[210:213], v147
	ds_read_b128 v[214:217], v148
	buffer_load_dwordx4 v143, s[8:11], s45 offen lds
	s_mov_b32 m0, s3
	s_nop 0
	buffer_load_dwordx4 v144, s[8:11], s45 offen lds
	s_barrier
	s_waitcnt lgkmcnt(0)
	v_mfma_f32_16x16x32_bf16 v[92:95], v[202:205], v[170:173], v[92:95]
	v_mfma_f32_16x16x32_bf16 v[92:95], v[206:209], v[174:177], v[92:95]
	v_mfma_f32_16x16x32_bf16 v[88:91], v[210:213], v[170:173], v[88:91]
	v_mfma_f32_16x16x32_bf16 v[88:91], v[214:217], v[174:177], v[88:91]
	v_mfma_f32_16x16x32_bf16 v[84:87], v[202:205], v[178:181], v[84:87]
	v_mfma_f32_16x16x32_bf16 v[84:87], v[206:209], v[182:185], v[84:87]
	v_mfma_f32_16x16x32_bf16 v[80:83], v[210:213], v[178:181], v[80:83]
	v_mfma_f32_16x16x32_bf16 v[80:83], v[214:217], v[182:185], v[80:83]
	v_mfma_f32_16x16x32_bf16 v[76:79], v[202:205], v[186:189], v[76:79]
	v_mfma_f32_16x16x32_bf16 v[76:79], v[206:209], v[190:193], v[76:79]
	v_mfma_f32_16x16x32_bf16 v[72:75], v[210:213], v[186:189], v[72:75]
	v_mfma_f32_16x16x32_bf16 v[72:75], v[214:217], v[190:193], v[72:75]
	v_mfma_f32_16x16x32_bf16 v[68:71], v[202:205], v[194:197], v[68:71]
	v_mfma_f32_16x16x32_bf16 v[68:71], v[206:209], v[198:201], v[68:71]
	v_mfma_f32_16x16x32_bf16 v[64:67], v[210:213], v[194:197], v[64:67]
	v_mfma_f32_16x16x32_bf16 v[64:67], v[214:217], v[198:201], v[64:67]
	s_barrier
	s_add_i32 s45, s38, s17
	s_add_i32 s46, s45, 0x100
	s_mov_b32 m0, s0
	ds_read_b128 v[170:173], v131 offset:16384
	ds_read_b128 v[174:177], v131 offset:17408
	ds_read_b128 v[178:181], v134 offset:16384
	ds_read_b128 v[182:185], v134 offset:17408
	ds_read_b128 v[186:189], v133 offset:16384
	ds_read_b128 v[190:193], v133 offset:17408
	ds_read_b128 v[194:197], v132 offset:16384
	ds_read_b128 v[198:201], v132 offset:17408
	buffer_load_dwordx4 v143, s[4:7], s46 offen lds
	s_mov_b32 m0, s18
	s_nop 0
	buffer_load_dwordx4 v144, s[4:7], s46 offen lds
	s_barrier
	s_waitcnt lgkmcnt(0)
	v_mfma_f32_16x16x32_bf16 v[60:63], v[154:157], v[170:173], v[60:63]
	v_mfma_f32_16x16x32_bf16 v[60:63], v[158:161], v[174:177], v[60:63]
	v_mfma_f32_16x16x32_bf16 v[56:59], v[162:165], v[170:173], v[56:59]
	v_mfma_f32_16x16x32_bf16 v[56:59], v[166:169], v[174:177], v[56:59]
	v_mfma_f32_16x16x32_bf16 v[52:55], v[154:157], v[178:181], v[52:55]
	v_mfma_f32_16x16x32_bf16 v[52:55], v[158:161], v[182:185], v[52:55]
	v_mfma_f32_16x16x32_bf16 v[48:51], v[162:165], v[178:181], v[48:51]
	v_mfma_f32_16x16x32_bf16 v[48:51], v[166:169], v[182:185], v[48:51]
	v_mfma_f32_16x16x32_bf16 v[44:47], v[154:157], v[186:189], v[44:47]
	v_mfma_f32_16x16x32_bf16 v[44:47], v[158:161], v[190:193], v[44:47]
	v_mfma_f32_16x16x32_bf16 v[40:43], v[162:165], v[186:189], v[40:43]
	v_mfma_f32_16x16x32_bf16 v[40:43], v[166:169], v[190:193], v[40:43]
	v_mfma_f32_16x16x32_bf16 v[36:39], v[154:157], v[194:197], v[36:39]
	v_mfma_f32_16x16x32_bf16 v[36:39], v[158:161], v[198:201], v[36:39]
	v_mfma_f32_16x16x32_bf16 v[32:35], v[162:165], v[194:197], v[32:35]
	v_mfma_f32_16x16x32_bf16 v[32:35], v[166:169], v[198:201], v[32:35]
	s_barrier
	s_add_i32 s46, s40, s17
	s_add_i32 s47, s46, 0x100
	s_mov_b32 m0, s19
	s_nop 0
	buffer_load_dwordx4 v143, s[8:11], s47 offen lds
	s_mov_b32 m0, s20
	s_nop 0
	buffer_load_dwordx4 v144, s[8:11], s47 offen lds
	s_waitcnt vmcnt(6)
	s_barrier
; #define STAGE(P, RS, SOFF, OFF, kt) do { const int _so = (SOFF) + (kt) * (BK * 2); \
;     _Pragma("unroll") for (int _i = 0; _i < 2; ++_i) { \
;       __builtin_amdgcn_raw_ptr_buffer_load_lds(RS, (__attribute__((address_space(3))) void*)((P) + wave * 1024 + _i * 8192), 16, OFF[_i], _so, 0, 0); } } while (0)
; #define LDA(dst, b, h) _Pragma("unroll") for (int m = 0; m < 4; ++m) _Pragma("unroll") for (int k = 0; k < 2; ++k) \
;     dst[m][k] = *reinterpret_cast<const bf16x8*>(SA(b, h) + lds_byte(wr * 64 + m * 16 + fr, k * 32 + fq * 8))
; #define LDB(dst, b, h) _Pragma("unroll") for (int n = 0; n < 2; ++n) _Pragma("unroll") for (int k = 0; k < 2; ++k) \
;     dst[n][k] = *reinterpret_cast<const bf16x8*>(SB(b, h) + lds_byte(wc * 32 + n * 16 + fr, k * 32 + fq * 8))
; #define WAIT_V(n) asm volatile("s_waitcnt vmcnt(" #n ")" ::: "memory")
; #define WAIT_L(n) asm volatile("s_waitcnt lgkmcnt(" #n ")" ::: "memory")
; #define BAR __builtin_amdgcn_s_barrier()
; #define SCHED __builtin_amdgcn_sched_barrier(0)
;     ...
;       WAIT_V(6); BAR; MMA(1, 1, At, B1); BAR;
;       LDB(B0, 1, 0); SCHED; LDA(At, 1, 0); STAGE(SA(0, 1), rsA, sA1, offA, t + 2);
;       WAIT_L(8); BAR; WAIT_L(0); MMA(0, 0, At, B0); BAR; SCHED;
;       LDB(B1, 1, 1); STAGE(SB(1, 0), rsB, sB0, offB, t + 3);
;       BAR; WAIT_L(0); MMA(0, 1, At, B1); BAR;
;       LDA(At, 1, 1); STAGE(SA(1, 0), rsA, sA0, offA, t + 3);
;       BAR; WAIT_L(0); MMA(1, 0, At, B0); BAR; SCHED;
	v_mfma_f32_16x16x32_bf16 v[28:31], v[202:205], v[170:173], v[28:31]
	v_mfma_f32_16x16x32_bf16 v[28:31], v[206:209], v[174:177], v[28:31]
	v_mfma_f32_16x16x32_bf16 v[24:27], v[210:213], v[170:173], v[24:27]
	v_mfma_f32_16x16x32_bf16 v[24:27], v[214:217], v[174:177], v[24:27]
	v_mfma_f32_16x16x32_bf16 v[20:23], v[202:205], v[178:181], v[20:23]
	v_mfma_f32_16x16x32_bf16 v[20:23], v[206:209], v[182:185], v[20:23]
	v_mfma_f32_16x16x32_bf16 v[16:19], v[210:213], v[178:181], v[16:19]
	v_mfma_f32_16x16x32_bf16 v[16:19], v[214:217], v[182:185], v[16:19]
	v_mfma_f32_16x16x32_bf16 v[12:15], v[202:205], v[186:189], v[12:15]
	v_mfma_f32_16x16x32_bf16 v[12:15], v[206:209], v[190:193], v[12:15]
	v_mfma_f32_16x16x32_bf16 v[8:11], v[210:213], v[186:189], v[8:11]
	v_mfma_f32_16x16x32_bf16 v[8:11], v[214:217], v[190:193], v[8:11]
	v_mfma_f32_16x16x32_bf16 v[4:7], v[202:205], v[194:197], v[4:7]
	v_mfma_f32_16x16x32_bf16 v[4:7], v[206:209], v[198:201], v[4:7]
	v_mfma_f32_16x16x32_bf16 v[0:3], v[210:213], v[194:197], v[0:3]
	v_mfma_f32_16x16x32_bf16 v[0:3], v[214:217], v[198:201], v[0:3]
	s_barrier
	ds_read_b128 v[154:157], v139
	ds_read_b128 v[158:161], v140
	ds_read_b128 v[162:165], v141
	ds_read_b128 v[166:169], v142
	s_addk_i32 s43, 0x100
	s_mov_b32 m0, s21
	ds_read_b128 v[170:173], v131 offset:32768
	ds_read_b128 v[174:177], v131 offset:33792
	ds_read_b128 v[178:181], v134 offset:32768
	ds_read_b128 v[182:185], v134 offset:33792
	ds_read_b128 v[186:189], v133 offset:32768
	ds_read_b128 v[190:193], v133 offset:33792
	ds_read_b128 v[194:197], v132 offset:32768
	ds_read_b128 v[198:201], v132 offset:33792
	buffer_load_dwordx4 v143, s[4:7], s43 offen lds
	s_mov_b32 m0, s22
	s_nop 0
	buffer_load_dwordx4 v144, s[4:7], s43 offen lds
	s_waitcnt lgkmcnt(8)
	s_barrier
	s_waitcnt lgkmcnt(0)
	v_mfma_f32_16x16x32_bf16 v[124:127], v[154:157], v[170:173], v[124:127]
	v_mfma_f32_16x16x32_bf16 v[124:127], v[158:161], v[174:177], v[124:127]
	v_mfma_f32_16x16x32_bf16 v[120:123], v[162:165], v[170:173], v[120:123]
	v_mfma_f32_16x16x32_bf16 v[120:123], v[166:169], v[174:177], v[120:123]
	v_mfma_f32_16x16x32_bf16 v[116:119], v[154:157], v[178:181], v[116:119]
	v_mfma_f32_16x16x32_bf16 v[116:119], v[158:161], v[182:185], v[116:119]
	v_mfma_f32_16x16x32_bf16 v[112:115], v[162:165], v[178:181], v[112:115]
	v_mfma_f32_16x16x32_bf16 v[112:115], v[166:169], v[182:185], v[112:115]
	v_mfma_f32_16x16x32_bf16 v[108:111], v[154:157], v[186:189], v[108:111]
	v_mfma_f32_16x16x32_bf16 v[108:111], v[158:161], v[190:193], v[108:111]
	v_mfma_f32_16x16x32_bf16 v[104:107], v[162:165], v[186:189], v[104:107]
	v_mfma_f32_16x16x32_bf16 v[104:107], v[166:169], v[190:193], v[104:107]
	v_mfma_f32_16x16x32_bf16 v[100:103], v[154:157], v[194:197], v[100:103]
	v_mfma_f32_16x16x32_bf16 v[100:103], v[158:161], v[198:201], v[100:103]
	v_mfma_f32_16x16x32_bf16 v[96:99], v[162:165], v[194:197], v[96:99]
	v_mfma_f32_16x16x32_bf16 v[96:99], v[166:169], v[198:201], v[96:99]
	s_barrier
	s_addk_i32 s44, 0x180
	s_mov_b32 m0, s23
	ds_read_b128 v[202:205], v135
	ds_read_b128 v[206:209], v136
	ds_read_b128 v[210:213], v137
	ds_read_b128 v[214:217], v138
	buffer_load_dwordx4 v143, s[8:11], s44 offen lds
	s_mov_b32 m0, s24
	s_nop 0
	buffer_load_dwordx4 v144, s[8:11], s44 offen lds
	s_barrier
	s_waitcnt lgkmcnt(0)
	v_mfma_f32_16x16x32_bf16 v[92:95], v[202:205], v[170:173], v[92:95]
	v_mfma_f32_16x16x32_bf16 v[92:95], v[206:209], v[174:177], v[92:95]
	v_mfma_f32_16x16x32_bf16 v[88:91], v[210:213], v[170:173], v[88:91]
	v_mfma_f32_16x16x32_bf16 v[88:91], v[214:217], v[174:177], v[88:91]
	v_mfma_f32_16x16x32_bf16 v[84:87], v[202:205], v[178:181], v[84:87]
	v_mfma_f32_16x16x32_bf16 v[84:87], v[206:209], v[182:185], v[84:87]
	v_mfma_f32_16x16x32_bf16 v[80:83], v[210:213], v[178:181], v[80:83]
	v_mfma_f32_16x16x32_bf16 v[80:83], v[214:217], v[182:185], v[80:83]
	v_mfma_f32_16x16x32_bf16 v[76:79], v[202:205], v[186:189], v[76:79]
	v_mfma_f32_16x16x32_bf16 v[76:79], v[206:209], v[190:193], v[76:79]
	v_mfma_f32_16x16x32_bf16 v[72:75], v[210:213], v[186:189], v[72:75]
	v_mfma_f32_16x16x32_bf16 v[72:75], v[214:217], v[190:193], v[72:75]
	v_mfma_f32_16x16x32_bf16 v[68:71], v[202:205], v[194:197], v[68:71]
	v_mfma_f32_16x16x32_bf16 v[68:71], v[206:209], v[198:201], v[68:71]
	v_mfma_f32_16x16x32_bf16 v[64:67], v[210:213], v[194:197], v[64:67]
	v_mfma_f32_16x16x32_bf16 v[64:67], v[214:217], v[198:201], v[64:67]
	s_barrier
	s_addk_i32 s45, 0x180
	s_mov_b32 m0, s25
	ds_read_b128 v[170:173], v131 offset:49152
	ds_read_b128 v[174:177], v131 offset:50176
	ds_read_b128 v[178:181], v134 offset:49152
	ds_read_b128 v[182:185], v134 offset:50176
	ds_read_b128 v[186:189], v133 offset:49152
	ds_read_b128 v[190:193], v133 offset:50176
	ds_read_b128 v[194:197], v132 offset:49152
	ds_read_b128 v[198:201], v132 offset:50176
	buffer_load_dwordx4 v143, s[4:7], s45 offen lds
	s_mov_b32 m0, s26
	s_nop 0
	buffer_load_dwordx4 v144, s[4:7], s45 offen lds
	s_barrier
	s_waitcnt lgkmcnt(0)
	v_mfma_f32_16x16x32_bf16 v[60:63], v[154:157], v[170:173], v[60:63]
	v_mfma_f32_16x16x32_bf16 v[60:63], v[158:161], v[174:177], v[60:63]
	v_mfma_f32_16x16x32_bf16 v[56:59], v[162:165], v[170:173], v[56:59]
	v_mfma_f32_16x16x32_bf16 v[56:59], v[166:169], v[174:177], v[56:59]
	v_mfma_f32_16x16x32_bf16 v[52:55], v[154:157], v[178:181], v[52:55]
	v_mfma_f32_16x16x32_bf16 v[52:55], v[158:161], v[182:185], v[52:55]
	v_mfma_f32_16x16x32_bf16 v[48:51], v[162:165], v[178:181], v[48:51]
	v_mfma_f32_16x16x32_bf16 v[48:51], v[166:169], v[182:185], v[48:51]
	v_mfma_f32_16x16x32_bf16 v[44:47], v[154:157], v[186:189], v[44:47]
	v_mfma_f32_16x16x32_bf16 v[44:47], v[158:161], v[190:193], v[44:47]
	v_mfma_f32_16x16x32_bf16 v[40:43], v[162:165], v[186:189], v[40:43]
	v_mfma_f32_16x16x32_bf16 v[40:43], v[166:169], v[190:193], v[40:43]
	v_mfma_f32_16x16x32_bf16 v[36:39], v[154:157], v[194:197], v[36:39]
	v_mfma_f32_16x16x32_bf16 v[36:39], v[158:161], v[198:201], v[36:39]
	v_mfma_f32_16x16x32_bf16 v[32:35], v[162:165], v[194:197], v[32:35]
	v_mfma_f32_16x16x32_bf16 v[32:35], v[166:169], v[198:201], v[32:35]
	s_barrier
; #define STAGE(P, RS, SOFF, OFF, kt) do { const int _so = (SOFF) + (kt) * (BK * 2); \
;     _Pragma("unroll") for (int _i = 0; _i < 2; ++_i) { \
;       __builtin_amdgcn_raw_ptr_buffer_load_lds(RS, (__attribute__((address_space(3))) void*)((P) + wave * 1024 + _i * 8192), 16, OFF[_i], _so, 0, 0); } } while (0)
; #define LDA(dst, b, h) _Pragma("unroll") for (int m = 0; m < 4; ++m) _Pragma("unroll") for (int k = 0; k < 2; ++k) \
;     dst[m][k] = *reinterpret_cast<const bf16x8*>(SA(b, h) + lds_byte(wr * 64 + m * 16 + fr, k * 32 + fq * 8))
; #define LDB(dst, b, h) _Pragma("unroll") for (int n = 0; n < 2; ++n) _Pragma("unroll") for (int k = 0; k < 2; ++k) \
;     dst[n][k] = *reinterpret_cast<const bf16x8*>(SB(b, h) + lds_byte(wc * 32 + n * 16 + fr, k * 32 + fq * 8))
; #define WAIT_V(n) asm volatile("s_waitcnt vmcnt(" #n ")" ::: "memory")
; #define WAIT_L(n) asm volatile("s_waitcnt lgkmcnt(" #n ")" ::: "memory")
; #define BAR __builtin_amdgcn_s_barrier()
;     ...
;       STAGE(SB(1, 1), rsB, sB1, offB, t + 3);
;       WAIT_V(6); BAR; MMA(1, 1, At, B1); BAR;
;     }
;     { LDB(B0, 0, 0); LDA(At, 0, 0); STAGE(SA(1, 1), rsA, sA1, offA, nt - 1);
;       BAR; WAIT_L(0); MMA(0, 0, At, B0); BAR;
;       LDB(B1, 0, 1); BAR; WAIT_L(0); MMA(0, 1, At, B1); BAR;
;       LDA(At, 0, 1); WAIT_V(4); BAR; WAIT_L(0); MMA(1, 0, At, B0); MMA(1, 1, At, B1); BAR; }
	s_addk_i32 s46, 0x180
	s_mov_b32 m0, s27
	s_nop 0
	buffer_load_dwordx4 v143, s[8:11], s46 offen lds
	s_mov_b32 m0, s28
	s_nop 0
	buffer_load_dwordx4 v144, s[8:11], s46 offen lds
	s_add_i32 s16, s16, 2
	s_addk_i32 s17, 0x100
	s_cmp_gt_u32 s16, 27
	s_cbranch_scc0 .LBB0_556
	s_waitcnt vmcnt(6)
	s_barrier
	v_mfma_f32_16x16x32_bf16 v[28:31], v[202:205], v[170:173], v[28:31]
	v_mfma_f32_16x16x32_bf16 v[28:31], v[206:209], v[174:177], v[28:31]
	v_mfma_f32_16x16x32_bf16 v[24:27], v[210:213], v[170:173], v[24:27]
	v_mfma_f32_16x16x32_bf16 v[24:27], v[214:217], v[174:177], v[24:27]
	v_mfma_f32_16x16x32_bf16 v[20:23], v[202:205], v[178:181], v[20:23]
	v_mfma_f32_16x16x32_bf16 v[20:23], v[206:209], v[182:185], v[20:23]
	v_mfma_f32_16x16x32_bf16 v[16:19], v[210:213], v[178:181], v[16:19]
	v_mfma_f32_16x16x32_bf16 v[16:19], v[214:217], v[182:185], v[16:19]
	v_mfma_f32_16x16x32_bf16 v[12:15], v[202:205], v[186:189], v[12:15]
	v_mfma_f32_16x16x32_bf16 v[12:15], v[206:209], v[190:193], v[12:15]
	v_mfma_f32_16x16x32_bf16 v[8:11], v[210:213], v[186:189], v[8:11]
	v_mfma_f32_16x16x32_bf16 v[8:11], v[214:217], v[190:193], v[8:11]
	v_mfma_f32_16x16x32_bf16 v[4:7], v[202:205], v[194:197], v[4:7]
	v_mfma_f32_16x16x32_bf16 v[4:7], v[206:209], v[198:201], v[4:7]
	v_mfma_f32_16x16x32_bf16 v[0:3], v[210:213], v[194:197], v[0:3]
	v_mfma_f32_16x16x32_bf16 v[0:3], v[214:217], v[198:201], v[0:3]
	s_barrier
	s_add_i32 s10, s37, 0xf80
	s_mov_b32 m0, s30
	ds_read_b128 v[154:157], v149
	ds_read_b128 v[158:161], v150
	ds_read_b128 v[162:165], v151
	ds_read_b128 v[150:153], v152
	ds_read_b128 v[166:169], v131
	ds_read_b128 v[170:173], v131 offset:1024
	ds_read_b128 v[174:177], v134
	ds_read_b128 v[178:181], v134 offset:1024
	ds_read_b128 v[182:185], v133
	ds_read_b128 v[186:189], v133 offset:1024
	ds_read_b128 v[190:193], v132
	ds_read_b128 v[194:197], v132 offset:1024
	buffer_load_dwordx4 v143, s[4:7], s10 offen lds
	s_mov_b32 m0, s31
	s_nop 0
	buffer_load_dwordx4 v144, s[4:7], s10 offen lds
	s_barrier
	s_waitcnt lgkmcnt(0)
	v_mfma_f32_16x16x32_bf16 v[124:127], v[154:157], v[166:169], v[124:127]
	v_mfma_f32_16x16x32_bf16 v[124:127], v[158:161], v[170:173], v[124:127]
	v_mfma_f32_16x16x32_bf16 v[120:123], v[162:165], v[166:169], v[120:123]
	v_mfma_f32_16x16x32_bf16 v[120:123], v[150:153], v[170:173], v[120:123]
	v_mfma_f32_16x16x32_bf16 v[116:119], v[154:157], v[174:177], v[116:119]
	v_mfma_f32_16x16x32_bf16 v[116:119], v[158:161], v[178:181], v[116:119]
	v_mfma_f32_16x16x32_bf16 v[112:115], v[162:165], v[174:177], v[112:115]
	v_mfma_f32_16x16x32_bf16 v[112:115], v[150:153], v[178:181], v[112:115]
	v_mfma_f32_16x16x32_bf16 v[108:111], v[154:157], v[182:185], v[108:111]
	v_mfma_f32_16x16x32_bf16 v[108:111], v[158:161], v[186:189], v[108:111]
	v_mfma_f32_16x16x32_bf16 v[104:107], v[162:165], v[182:185], v[104:107]
	v_mfma_f32_16x16x32_bf16 v[104:107], v[150:153], v[186:189], v[104:107]
	v_mfma_f32_16x16x32_bf16 v[100:103], v[154:157], v[190:193], v[100:103]
	v_mfma_f32_16x16x32_bf16 v[100:103], v[158:161], v[194:197], v[100:103]
	v_mfma_f32_16x16x32_bf16 v[96:99], v[162:165], v[190:193], v[96:99]
	v_mfma_f32_16x16x32_bf16 v[96:99], v[150:153], v[194:197], v[96:99]
	s_barrier
	ds_read_b128 v[198:201], v145
	ds_read_b128 v[202:205], v146
	ds_read_b128 v[144:147], v147
	ds_read_b128 v[206:209], v148
	s_barrier
	s_waitcnt lgkmcnt(0)
	v_mfma_f32_16x16x32_bf16 v[92:95], v[198:201], v[166:169], v[92:95]
	v_mfma_f32_16x16x32_bf16 v[92:95], v[202:205], v[170:173], v[92:95]
	v_mfma_f32_16x16x32_bf16 v[88:91], v[144:147], v[166:169], v[88:91]
	v_mfma_f32_16x16x32_bf16 v[88:91], v[206:209], v[170:173], v[88:91]
	v_mfma_f32_16x16x32_bf16 v[84:87], v[198:201], v[174:177], v[84:87]
	v_mfma_f32_16x16x32_bf16 v[84:87], v[202:205], v[178:181], v[84:87]
	v_mfma_f32_16x16x32_bf16 v[80:83], v[144:147], v[174:177], v[80:83]
	v_mfma_f32_16x16x32_bf16 v[80:83], v[206:209], v[178:181], v[80:83]
	v_mfma_f32_16x16x32_bf16 v[76:79], v[198:201], v[182:185], v[76:79]
	v_mfma_f32_16x16x32_bf16 v[76:79], v[202:205], v[186:189], v[76:79]
	v_mfma_f32_16x16x32_bf16 v[72:75], v[144:147], v[182:185], v[72:75]
	v_mfma_f32_16x16x32_bf16 v[72:75], v[206:209], v[186:189], v[72:75]
	v_mfma_f32_16x16x32_bf16 v[68:71], v[198:201], v[190:193], v[68:71]
	v_mfma_f32_16x16x32_bf16 v[68:71], v[202:205], v[194:197], v[68:71]
	v_mfma_f32_16x16x32_bf16 v[64:67], v[144:147], v[190:193], v[64:67]
	v_mfma_f32_16x16x32_bf16 v[64:67], v[206:209], v[194:197], v[64:67]
	s_barrier
	ds_read_b128 v[166:169], v131 offset:16384
	ds_read_b128 v[170:173], v131 offset:17408
	ds_read_b128 v[174:177], v134 offset:16384
	ds_read_b128 v[178:181], v134 offset:17408
	ds_read_b128 v[182:185], v133 offset:16384
	ds_read_b128 v[186:189], v133 offset:17408
	ds_read_b128 v[190:193], v132 offset:16384
	ds_read_b128 v[194:197], v132 offset:17408
	s_waitcnt vmcnt(4)
	s_barrier
; #define LDA(dst, b, h) _Pragma("unroll") for (int m = 0; m < 4; ++m) _Pragma("unroll") for (int k = 0; k < 2; ++k) \
;     dst[m][k] = *reinterpret_cast<const bf16x8*>(SA(b, h) + lds_byte(wr * 64 + m * 16 + fr, k * 32 + fq * 8))
; #define LDB(dst, b, h) _Pragma("unroll") for (int n = 0; n < 2; ++n) _Pragma("unroll") for (int k = 0; k < 2; ++k) \
;     dst[n][k] = *reinterpret_cast<const bf16x8*>(SB(b, h) + lds_byte(wc * 32 + n * 16 + fr, k * 32 + fq * 8))
; #define WAIT_V(n) asm volatile("s_waitcnt vmcnt(" #n ")" ::: "memory")
; #define WAIT_L(n) asm volatile("s_waitcnt lgkmcnt(" #n ")" ::: "memory")
; #define BAR __builtin_amdgcn_s_barrier()
;     ...
;       LDA(At, 0, 1); WAIT_V(4); BAR; WAIT_L(0); MMA(1, 0, At, B0); MMA(1, 1, At, B1); BAR; }
;     { LDB(B0, 1, 0); LDA(At, 1, 0); WAIT_V(2); BAR; WAIT_L(0); MMA(0, 0, At, B0); BAR;
	s_waitcnt lgkmcnt(0)
	v_mfma_f32_16x16x32_bf16 v[60:63], v[154:157], v[166:169], v[60:63]
	v_mfma_f32_16x16x32_bf16 v[60:63], v[158:161], v[170:173], v[60:63]
	v_mfma_f32_16x16x32_bf16 v[56:59], v[162:165], v[166:169], v[56:59]
	v_mfma_f32_16x16x32_bf16 v[56:59], v[150:153], v[170:173], v[56:59]
	v_mfma_f32_16x16x32_bf16 v[52:55], v[154:157], v[174:177], v[52:55]
	v_mfma_f32_16x16x32_bf16 v[52:55], v[158:161], v[178:181], v[52:55]
	v_mfma_f32_16x16x32_bf16 v[48:51], v[162:165], v[174:177], v[48:51]
	v_mfma_f32_16x16x32_bf16 v[48:51], v[150:153], v[178:181], v[48:51]
	v_mfma_f32_16x16x32_bf16 v[44:47], v[154:157], v[182:185], v[44:47]
	v_mfma_f32_16x16x32_bf16 v[44:47], v[158:161], v[186:189], v[44:47]
	v_mfma_f32_16x16x32_bf16 v[40:43], v[162:165], v[182:185], v[40:43]
	v_mfma_f32_16x16x32_bf16 v[40:43], v[150:153], v[186:189], v[40:43]
	v_mfma_f32_16x16x32_bf16 v[36:39], v[154:157], v[190:193], v[36:39]
	v_mfma_f32_16x16x32_bf16 v[36:39], v[158:161], v[194:197], v[36:39]
	v_mfma_f32_16x16x32_bf16 v[32:35], v[162:165], v[190:193], v[32:35]
	v_mfma_f32_16x16x32_bf16 v[32:35], v[150:153], v[194:197], v[32:35]
	v_mfma_f32_16x16x32_bf16 v[28:31], v[198:201], v[166:169], v[28:31]
	v_mfma_f32_16x16x32_bf16 v[28:31], v[202:205], v[170:173], v[28:31]
	v_mfma_f32_16x16x32_bf16 v[24:27], v[144:147], v[166:169], v[24:27]
	v_mfma_f32_16x16x32_bf16 v[24:27], v[206:209], v[170:173], v[24:27]
	v_mfma_f32_16x16x32_bf16 v[20:23], v[198:201], v[174:177], v[20:23]
	v_mfma_f32_16x16x32_bf16 v[20:23], v[202:205], v[178:181], v[20:23]
	v_mfma_f32_16x16x32_bf16 v[16:19], v[144:147], v[174:177], v[16:19]
	v_mfma_f32_16x16x32_bf16 v[16:19], v[206:209], v[178:181], v[16:19]
	v_mfma_f32_16x16x32_bf16 v[12:15], v[198:201], v[182:185], v[12:15]
	v_mfma_f32_16x16x32_bf16 v[12:15], v[202:205], v[186:189], v[12:15]
	v_mfma_f32_16x16x32_bf16 v[8:11], v[144:147], v[182:185], v[8:11]
	v_mfma_f32_16x16x32_bf16 v[8:11], v[206:209], v[186:189], v[8:11]
	v_mfma_f32_16x16x32_bf16 v[4:7], v[198:201], v[190:193], v[4:7]
	v_mfma_f32_16x16x32_bf16 v[4:7], v[202:205], v[194:197], v[4:7]
	v_mfma_f32_16x16x32_bf16 v[0:3], v[144:147], v[190:193], v[0:3]
	v_mfma_f32_16x16x32_bf16 v[0:3], v[206:209], v[194:197], v[0:3]
	s_barrier
	ds_read_b128 v[144:147], v139
	ds_read_b128 v[148:151], v140
	ds_read_b128 v[152:155], v141
	ds_read_b128 v[140:143], v142
	ds_read_b128 v[156:159], v131 offset:32768
	ds_read_b128 v[160:163], v131 offset:33792
	ds_read_b128 v[164:167], v134 offset:32768
	ds_read_b128 v[168:171], v134 offset:33792
	ds_read_b128 v[172:175], v133 offset:32768
	ds_read_b128 v[176:179], v133 offset:33792
	ds_read_b128 v[180:183], v132 offset:32768
	ds_read_b128 v[184:187], v132 offset:33792
	s_waitcnt vmcnt(2)
	s_barrier
	s_waitcnt lgkmcnt(0)
	v_mfma_f32_16x16x32_bf16 v[124:127], v[144:147], v[156:159], v[124:127]
	v_mfma_f32_16x16x32_bf16 v[124:127], v[148:151], v[160:163], v[124:127]
	v_mfma_f32_16x16x32_bf16 v[120:123], v[152:155], v[156:159], v[120:123]
	v_mfma_f32_16x16x32_bf16 v[120:123], v[140:143], v[160:163], v[120:123]
	v_mfma_f32_16x16x32_bf16 v[116:119], v[144:147], v[164:167], v[116:119]
	v_mfma_f32_16x16x32_bf16 v[116:119], v[148:151], v[168:171], v[116:119]
	v_mfma_f32_16x16x32_bf16 v[112:115], v[152:155], v[164:167], v[112:115]
	v_mfma_f32_16x16x32_bf16 v[112:115], v[140:143], v[168:171], v[112:115]
	v_mfma_f32_16x16x32_bf16 v[108:111], v[144:147], v[172:175], v[108:111]
	v_mfma_f32_16x16x32_bf16 v[108:111], v[148:151], v[176:179], v[108:111]
	v_mfma_f32_16x16x32_bf16 v[104:107], v[152:155], v[172:175], v[104:107]
	v_mfma_f32_16x16x32_bf16 v[104:107], v[140:143], v[176:179], v[104:107]
	v_mfma_f32_16x16x32_bf16 v[100:103], v[144:147], v[180:183], v[100:103]
	v_mfma_f32_16x16x32_bf16 v[100:103], v[148:151], v[184:187], v[100:103]
	v_mfma_f32_16x16x32_bf16 v[96:99], v[152:155], v[180:183], v[96:99]
	v_mfma_f32_16x16x32_bf16 v[96:99], v[140:143], v[184:187], v[96:99]
	s_barrier
; #define LDA(dst, b, h) _Pragma("unroll") for (int m = 0; m < 4; ++m) _Pragma("unroll") for (int k = 0; k < 2; ++k) \
;     dst[m][k] = *reinterpret_cast<const bf16x8*>(SA(b, h) + lds_byte(wr * 64 + m * 16 + fr, k * 32 + fq * 8))
; #define LDB(dst, b, h) _Pragma("unroll") for (int n = 0; n < 2; ++n) _Pragma("unroll") for (int k = 0; k < 2; ++k) \
;     dst[n][k] = *reinterpret_cast<const bf16x8*>(SB(b, h) + lds_byte(wc * 32 + n * 16 + fr, k * 32 + fq * 8))
; #define WAIT_V(n) asm volatile("s_waitcnt vmcnt(" #n ")" ::: "memory")
; #define WAIT_L(n) asm volatile("s_waitcnt lgkmcnt(" #n ")" ::: "memory")
; #define BAR __builtin_amdgcn_s_barrier()
;     ...
;       LDB(B1, 1, 1); WAIT_V(0); BAR; WAIT_L(0); MMA(0, 1, At, B1); BAR;
;       LDA(At, 1, 1); BAR; WAIT_L(0); MMA(1, 0, At, B0); MMA(1, 1, At, B1); BAR; }
;     if (wr == 0) BAR;
	ds_read_b128 v[188:191], v135
	ds_read_b128 v[192:195], v136
	ds_read_b128 v[196:199], v137
	ds_read_b128 v[136:139], v138
	s_waitcnt vmcnt(0)
	s_barrier
	s_waitcnt lgkmcnt(0)
	v_mfma_f32_16x16x32_bf16 v[92:95], v[188:191], v[156:159], v[92:95]
	v_mfma_f32_16x16x32_bf16 v[92:95], v[192:195], v[160:163], v[92:95]
	v_mfma_f32_16x16x32_bf16 v[88:91], v[196:199], v[156:159], v[88:91]
	v_mfma_f32_16x16x32_bf16 v[88:91], v[136:139], v[160:163], v[88:91]
	v_mfma_f32_16x16x32_bf16 v[84:87], v[188:191], v[164:167], v[84:87]
	v_mfma_f32_16x16x32_bf16 v[84:87], v[192:195], v[168:171], v[84:87]
	v_mfma_f32_16x16x32_bf16 v[80:83], v[196:199], v[164:167], v[80:83]
	v_mfma_f32_16x16x32_bf16 v[80:83], v[136:139], v[168:171], v[80:83]
	v_mfma_f32_16x16x32_bf16 v[76:79], v[188:191], v[172:175], v[76:79]
	v_mfma_f32_16x16x32_bf16 v[76:79], v[192:195], v[176:179], v[76:79]
	v_mfma_f32_16x16x32_bf16 v[72:75], v[196:199], v[172:175], v[72:75]
	v_mfma_f32_16x16x32_bf16 v[72:75], v[136:139], v[176:179], v[72:75]
	v_mfma_f32_16x16x32_bf16 v[68:71], v[188:191], v[180:183], v[68:71]
	v_mfma_f32_16x16x32_bf16 v[68:71], v[192:195], v[184:187], v[68:71]
	v_mfma_f32_16x16x32_bf16 v[64:67], v[196:199], v[180:183], v[64:67]
	v_mfma_f32_16x16x32_bf16 v[64:67], v[136:139], v[184:187], v[64:67]
	s_barrier
	ds_read_b128 v[156:159], v131 offset:49152
	ds_read_b128 v[160:163], v131 offset:50176
	ds_read_b128 v[164:167], v134 offset:49152
	ds_read_b128 v[168:171], v134 offset:50176
	ds_read_b128 v[172:175], v133 offset:49152
	ds_read_b128 v[176:179], v133 offset:50176
	ds_read_b128 v[180:183], v132 offset:49152
	ds_read_b128 v[132:135], v132 offset:50176
	s_barrier
	s_waitcnt lgkmcnt(0)
	v_mfma_f32_16x16x32_bf16 v[60:63], v[144:147], v[156:159], v[60:63]
	v_mfma_f32_16x16x32_bf16 v[60:63], v[148:151], v[160:163], v[60:63]
	v_mfma_f32_16x16x32_bf16 v[56:59], v[152:155], v[156:159], v[56:59]
	v_mfma_f32_16x16x32_bf16 v[56:59], v[140:143], v[160:163], v[56:59]
	v_mfma_f32_16x16x32_bf16 v[52:55], v[144:147], v[164:167], v[52:55]
	v_mfma_f32_16x16x32_bf16 v[52:55], v[148:151], v[168:171], v[52:55]
	v_mfma_f32_16x16x32_bf16 v[48:51], v[152:155], v[164:167], v[48:51]
	v_mfma_f32_16x16x32_bf16 v[48:51], v[140:143], v[168:171], v[48:51]
	v_mfma_f32_16x16x32_bf16 v[44:47], v[144:147], v[172:175], v[44:47]
	v_mfma_f32_16x16x32_bf16 v[44:47], v[148:151], v[176:179], v[44:47]
	v_mfma_f32_16x16x32_bf16 v[40:43], v[152:155], v[172:175], v[40:43]
	v_mfma_f32_16x16x32_bf16 v[40:43], v[140:143], v[176:179], v[40:43]
	v_mfma_f32_16x16x32_bf16 v[36:39], v[144:147], v[180:183], v[36:39]
	v_mfma_f32_16x16x32_bf16 v[36:39], v[148:151], v[132:135], v[36:39]
	v_mfma_f32_16x16x32_bf16 v[32:35], v[152:155], v[180:183], v[32:35]
	v_mfma_f32_16x16x32_bf16 v[32:35], v[140:143], v[132:135], v[32:35]
	v_mfma_f32_16x16x32_bf16 v[28:31], v[188:191], v[156:159], v[28:31]
	v_mfma_f32_16x16x32_bf16 v[28:31], v[192:195], v[160:163], v[28:31]
	v_mfma_f32_16x16x32_bf16 v[24:27], v[196:199], v[156:159], v[24:27]
	v_mfma_f32_16x16x32_bf16 v[24:27], v[136:139], v[160:163], v[24:27]
	v_mfma_f32_16x16x32_bf16 v[20:23], v[188:191], v[164:167], v[20:23]
	v_mfma_f32_16x16x32_bf16 v[20:23], v[192:195], v[168:171], v[20:23]
	v_mfma_f32_16x16x32_bf16 v[16:19], v[196:199], v[164:167], v[16:19]
	v_mfma_f32_16x16x32_bf16 v[16:19], v[136:139], v[168:171], v[16:19]
	v_mfma_f32_16x16x32_bf16 v[12:15], v[188:191], v[172:175], v[12:15]
	v_mfma_f32_16x16x32_bf16 v[12:15], v[192:195], v[176:179], v[12:15]
	v_mfma_f32_16x16x32_bf16 v[8:11], v[196:199], v[172:175], v[8:11]
	v_mfma_f32_16x16x32_bf16 v[8:11], v[136:139], v[176:179], v[8:11]
	v_mfma_f32_16x16x32_bf16 v[4:7], v[188:191], v[180:183], v[4:7]
	v_mfma_f32_16x16x32_bf16 v[4:7], v[192:195], v[132:135], v[4:7]
	v_mfma_f32_16x16x32_bf16 v[0:3], v[196:199], v[180:183], v[0:3]
	v_mfma_f32_16x16x32_bf16 v[0:3], v[136:139], v[132:135], v[0:3]
	v_cmp_gt_u32_e32 vcc, s35, v130
	s_barrier
	s_and_saveexec_b64 s[10:11], vcc
	s_cbranch_execz .LBB0_559
	s_barrier

; #define WAIT_V(n) asm volatile("s_waitcnt vmcnt(" #n ")" ::: "memory")
; #define BAR __builtin_amdgcn_s_barrier()
;     ...
;     const int tid = opaque_tid(wave);
;     const int wid = tid >> 6, lane = tid & 63, wr = wid >> 2, wc = wid & 3, fr = lane & 15, fq = lane >> 4;
;     int offA[2], offB[2];
;     _Pragma("unroll") for (int i = 0; i < 2; ++i) {
;       int r, c; stage_rc(tid * 16 + i * 8192, r, c);
;       offA[i] = (r * lda + c) * 2; offB[i] = (r * ldb + c) * 2;
;     }
;     const int brow = pm * BM;
;     f32x4 acc[2][2][4][2];
;     _Pragma("unroll") for (int a = 0; a < 2; ++a) _Pragma("unroll") for (int b = 0; b < 2; ++b) _Pragma("unroll") for (int m = 0; m < 4; ++m) _Pragma("unroll") for (int n = 0; n < 2; ++n)
;       acc[a][b][m][n] = f32x4{0.f, 0.f, 0.f, 0.f};
;     bf16x8 At[4][2], B0[2][2], B1[2][2];
;     if (wr == 1) BAR;
;     if (first_tile) { WAIT_V(0); }
;     else if constexpr (mode == MODE_RESID_LN) { WAIT_V(0); }
;     else if constexpr (mode == MODE_SWIGLU) { WAIT_V(6); }
;     else if constexpr (mode == MODE_V) { WAIT_V(24); }
;     else { WAIT_V(12); }
;     first_tile = false;
;     BAR;
;     BAR;
.LBB0_656:
	v_bfe_i32 v4, v128, 27, 1
	v_lshlrev_b32_e32 v2, 4, v128
	v_lshrrev_b32_e32 v4, 22, v4
	v_add_u32_e32 v4, v2, v4
	v_and_b32_e32 v4, 0xfffffc00, v4
	v_sub_u32_e32 v4, v2, v4
	v_lshrrev_b32_e32 v5, 4, v4
	v_bitop3_b32 v4, v5, v4, 32 bitop3:0x6c
	v_ashrrev_i32_e32 v3, 31, v128
	v_ashrrev_i32_e32 v6, 31, v4
	v_lshrrev_b32_e32 v3, 26, v3
	v_lshrrev_b32_e32 v6, 26, v6
	v_add_u32_e32 v3, v128, v3
	v_add_u32_e32 v6, v4, v6
	v_ashrrev_i32_e32 v3, 6, v3
	v_lshrrev_b32_e32 v7, 6, v6
	v_and_b32_e32 v6, 0xc0, v6
	v_lshlrev_b32_e32 v5, 3, v3
	v_lshlrev_b32_e32 v3, 5, v3
	v_sub_u32_e32 v4, v4, v6
	v_and_b32_e32 v5, 0xffff0, v5
	v_and_b32_e32 v3, 32, v3
	v_ashrrev_i16_sdwa v4, v216, sext(v4) dst_sel:DWORD dst_unused:UNUSED_PAD src0_sel:DWORD src1_sel:BYTE_0
	v_add_u32_sdwa v3, v3, sext(v4) dst_sel:DWORD dst_unused:UNUSED_PAD src0_sel:DWORD src1_sel:WORD_0
	v_add_lshl_u32 v4, v7, v5, 12
	v_add_u32_e32 v2, 0x2000, v2
	v_lshl_add_u32 v141, v3, 1, v4
	v_ashrrev_i32_e32 v3, 31, v2
	v_lshrrev_b32_e32 v3, 22, v3
	v_add_u32_e32 v3, v2, v3
	v_ashrrev_i32_e32 v3, 10, v3
	v_mul_i32_i24_e32 v4, 0x400, v3
	v_sub_u32_e32 v2, v2, v4
	v_lshrrev_b32_e32 v4, 4, v2
	v_bitop3_b32 v2, v4, v2, 32 bitop3:0x6c
	v_ashrrev_i32_e32 v5, 31, v2
	v_lshrrev_b32_e32 v5, 26, v5
	v_add_u32_e32 v5, v2, v5
	v_lshrrev_b32_e32 v6, 6, v5
	v_and_b32_e32 v5, 0xc0, v5
	v_lshlrev_b32_e32 v4, 3, v3
	v_lshlrev_b32_e32 v3, 5, v3
	v_sub_u32_e32 v2, v2, v5
	v_and_b32_e32 v4, 0xffff0, v4
	v_and_b32_e32 v3, 32, v3
	v_ashrrev_i16_sdwa v2, v216, sext(v2) dst_sel:DWORD dst_unused:UNUSED_PAD src0_sel:DWORD src1_sel:BYTE_0
	v_add_u32_sdwa v2, v3, sext(v2) dst_sel:DWORD dst_unused:UNUSED_PAD src0_sel:DWORD src1_sel:WORD_0
	v_add_lshl_u32 v3, v6, v4, 12
	v_lshl_add_u32 v142, v2, 1, v3
	v_and_b32_e32 v3, 15, v0
	v_lshlrev_b32_e32 v5, 2, v0
	v_and_b32_e32 v2, 48, v0
	v_lshlrev_b32_e32 v3, 6, v3
	v_and_b32_e32 v5, 32, v5
	v_or_b32_e32 v4, v3, v2
	v_bitop3_b32 v3, v3, v5, v2 bitop3:0x36
	v_lshlrev_b32_e32 v6, 6, v128
	s_movk_i32 s1, 0x3000
	v_and_or_b32 v3, v6, s1, v3
	v_lshlrev_b32_e32 v0, 6, v0
	s_movk_i32 s1, 0x3c0
	v_lshlrev_b32_e32 v1, 13, v1
	v_and_or_b32 v0, v0, s1, v2
	v_bitop3_b32 v0, v1, v0, v5 bitop3:0xf6
	v_or_b32_e32 v6, 0x400, v3
	v_or_b32_e32 v7, 0x800, v3
	v_or_b32_e32 v8, 0xc00, v3
	v_or_b32_e32 v132, 0x800, v0
	v_or_b32_e32 v131, 0x1000, v0
	v_or_b32_e32 v130, 0x1800, v0
	v_mov_b32_e32 v0, 0
	v_bitop3_b32 v129, v4, v1, v5 bitop3:0xde
	s_mov_b32 s1, -2
	s_mov_b32 s3, 0
	v_or_b32_e32 v147, 0x10000, v3
	v_or_b32_e32 v148, 0x10000, v6
	v_or_b32_e32 v149, 0x10000, v7
	v_or_b32_e32 v150, 0x10000, v8
	v_or_b32_e32 v143, 0x14000, v3
	v_or_b32_e32 v144, 0x14000, v6
	v_or_b32_e32 v145, 0x14000, v7
	v_or_b32_e32 v146, 0x14000, v8
	v_or_b32_e32 v137, 0x18000, v3
	v_or_b32_e32 v138, 0x18000, v6
	v_or_b32_e32 v139, 0x18000, v7
	v_or_b32_e32 v140, 0x18000, v8
	v_or_b32_e32 v133, 0x1c000, v3
	v_or_b32_e32 v134, 0x1c000, v6
	v_or_b32_e32 v135, 0x1c000, v7
	v_or_b32_e32 v136, 0x1c000, v8
	v_mov_b32_e32 v1, v0
	v_mov_b32_e32 v2, v0
	v_mov_b32_e32 v3, v0
	v_mov_b32_e32 v4, v0
	v_mov_b32_e32 v5, v0
	v_mov_b32_e32 v6, v0
	v_mov_b32_e32 v7, v0
	v_mov_b32_e32 v8, v0
	v_mov_b32_e32 v9, v0
	v_mov_b32_e32 v10, v0
	v_mov_b32_e32 v11, v0
	v_mov_b32_e32 v12, v0
	v_mov_b32_e32 v13, v0
	v_mov_b32_e32 v14, v0
	v_mov_b32_e32 v15, v0
	v_mov_b32_e32 v16, v0
	v_mov_b32_e32 v17, v0
	v_mov_b32_e32 v18, v0
	v_mov_b32_e32 v19, v0
	v_mov_b32_e32 v20, v0
	v_mov_b32_e32 v21, v0
	v_mov_b32_e32 v22, v0
	v_mov_b32_e32 v23, v0
	v_mov_b32_e32 v24, v0
	v_mov_b32_e32 v25, v0
	v_mov_b32_e32 v26, v0
	v_mov_b32_e32 v27, v0
	v_mov_b32_e32 v28, v0
	v_mov_b32_e32 v29, v0
	v_mov_b32_e32 v30, v0
	v_mov_b32_e32 v31, v0
	v_mov_b32_e32 v32, v0
	v_mov_b32_e32 v33, v0
	v_mov_b32_e32 v34, v0
	v_mov_b32_e32 v35, v0
	v_mov_b32_e32 v36, v0
	v_mov_b32_e32 v37, v0
	v_mov_b32_e32 v38, v0
	v_mov_b32_e32 v39, v0
	v_mov_b32_e32 v40, v0
	v_mov_b32_e32 v41, v0
	v_mov_b32_e32 v42, v0
	v_mov_b32_e32 v43, v0
	v_mov_b32_e32 v44, v0
	v_mov_b32_e32 v45, v0
	v_mov_b32_e32 v46, v0
	v_mov_b32_e32 v47, v0
	v_mov_b32_e32 v48, v0
	v_mov_b32_e32 v49, v0
	v_mov_b32_e32 v50, v0
	v_mov_b32_e32 v51, v0
	v_mov_b32_e32 v52, v0
	v_mov_b32_e32 v53, v0
	v_mov_b32_e32 v54, v0
	v_mov_b32_e32 v55, v0
	v_mov_b32_e32 v56, v0
	v_mov_b32_e32 v57, v0
	v_mov_b32_e32 v58, v0
	v_mov_b32_e32 v59, v0
	v_mov_b32_e32 v60, v0
	v_mov_b32_e32 v61, v0
	v_mov_b32_e32 v62, v0
	v_mov_b32_e32 v63, v0
	v_mov_b32_e32 v68, v0
	v_mov_b32_e32 v69, v0
	v_mov_b32_e32 v70, v0
	v_mov_b32_e32 v71, v0
	v_mov_b32_e32 v80, v0
	v_mov_b32_e32 v81, v0
	v_mov_b32_e32 v82, v0
	v_mov_b32_e32 v83, v0
	v_mov_b32_e32 v88, v0
	v_mov_b32_e32 v89, v0
	v_mov_b32_e32 v90, v0
	v_mov_b32_e32 v91, v0
	v_mov_b32_e32 v92, v0
	v_mov_b32_e32 v93, v0
	v_mov_b32_e32 v94, v0
	v_mov_b32_e32 v95, v0
	v_mov_b32_e32 v96, v0
	v_mov_b32_e32 v97, v0
	v_mov_b32_e32 v98, v0
	v_mov_b32_e32 v99, v0
	v_mov_b32_e32 v100, v0
	v_mov_b32_e32 v101, v0
	v_mov_b32_e32 v102, v0
	v_mov_b32_e32 v103, v0
	v_mov_b32_e32 v104, v0
	v_mov_b32_e32 v105, v0
	v_mov_b32_e32 v106, v0
	v_mov_b32_e32 v107, v0
	v_mov_b32_e32 v108, v0
	v_mov_b32_e32 v109, v0
	v_mov_b32_e32 v110, v0
	v_mov_b32_e32 v111, v0
	v_mov_b32_e32 v112, v0
	v_mov_b32_e32 v113, v0
	v_mov_b32_e32 v114, v0
	v_mov_b32_e32 v115, v0
	v_mov_b32_e32 v116, v0
	v_mov_b32_e32 v117, v0
	v_mov_b32_e32 v118, v0
	v_mov_b32_e32 v119, v0
	v_mov_b32_e32 v120, v0
	v_mov_b32_e32 v121, v0
	v_mov_b32_e32 v122, v0
	v_mov_b32_e32 v123, v0
	v_mov_b32_e32 v124, v0
	v_mov_b32_e32 v125, v0
	v_mov_b32_e32 v126, v0
	v_mov_b32_e32 v127, v0
	v_mov_b32_e32 v64, v0
	v_mov_b32_e32 v65, v0
	v_mov_b32_e32 v66, v0
	v_mov_b32_e32 v67, v0
	v_mov_b32_e32 v72, v0
	v_mov_b32_e32 v73, v0
	v_mov_b32_e32 v74, v0
	v_mov_b32_e32 v75, v0
	v_mov_b32_e32 v76, v0
	v_mov_b32_e32 v77, v0
	v_mov_b32_e32 v78, v0
	v_mov_b32_e32 v79, v0
	v_mov_b32_e32 v84, v0
	v_mov_b32_e32 v85, v0
	v_mov_b32_e32 v86, v0
	v_mov_b32_e32 v87, v0
	s_barrier
	s_barrier
	s_branch .Lmy_rot_657

; #define STAGE(P, RS, SOFF, OFF, kt) do { const int _so = (SOFF) + (kt) * (BK * 2); \
;     _Pragma("unroll") for (int _i = 0; _i < 2; ++_i) { \
;       __builtin_amdgcn_raw_ptr_buffer_load_lds(RS, (__attribute__((address_space(3))) void*)((P) + wave * 1024 + _i * 8192), 16, OFF[_i], _so, 0, 0); } } while (0)
; #define LDA(dst, b, h) _Pragma("unroll") for (int m = 0; m < 4; ++m) _Pragma("unroll") for (int k = 0; k < 2; ++k) \
;     dst[m][k] = *reinterpret_cast<const bf16x8*>(SA(b, h) + lds_byte(wr * 64 + m * 16 + fr, k * 32 + fq * 8))
; #define LDB(dst, b, h) _Pragma("unroll") for (int n = 0; n < 2; ++n) _Pragma("unroll") for (int k = 0; k < 2; ++k) \
;     dst[n][k] = *reinterpret_cast<const bf16x8*>(SB(b, h) + lds_byte(wc * 32 + n * 16 + fr, k * 32 + fq * 8))
; #define WAIT_V(n) asm volatile("s_waitcnt vmcnt(" #n ")" ::: "memory")
; #define WAIT_L(n) asm volatile("s_waitcnt lgkmcnt(" #n ")" ::: "memory")
; #define BAR __builtin_amdgcn_s_barrier()
; #define SCHED __builtin_amdgcn_sched_barrier(0)
;     ...
;       LDB(B0, 0, 0); SCHED; LDA(At, 0, 0); STAGE(SA(1, 1), rsA, sA1, offA, t + 1);
;       WAIT_L(8); BAR; WAIT_L(0); MMA(0, 0, At, B0); BAR; SCHED;
;       LDB(B1, 0, 1); STAGE(SB(0, 0), rsB, sB0, offB, t + 2);
;       BAR; WAIT_L(0); MMA(0, 1, At, B1); BAR;
;       LDA(At, 0, 1); STAGE(SA(0, 0), rsA, sA0, offA, t + 2);
;       BAR; WAIT_L(0); MMA(1, 0, At, B0); BAR; SCHED;
;       STAGE(SB(0, 1), rsB, sB1, offB, t + 2);
;       WAIT_V(6); BAR; MMA(1, 1, At, B1); BAR;
.Lmy_rot_657:
	ds_read_b128 v[152:155], v147
	ds_read_b128 v[156:159], v148
	ds_read_b128 v[160:163], v149
	ds_read_b128 v[164:167], v150
	s_add_i32 s5, s81, s3
	s_add_i32 s6, s5, 0x80
	s_mov_b32 m0, s39
	ds_read_b128 v[168:171], v129
	ds_read_b128 v[172:175], v129 offset:1024
	ds_read_b128 v[176:179], v132
	ds_read_b128 v[180:183], v132 offset:1024
	ds_read_b128 v[184:187], v131
	ds_read_b128 v[188:191], v131 offset:1024
	ds_read_b128 v[192:195], v130
	ds_read_b128 v[196:199], v130 offset:1024
	buffer_load_dwordx4 v141, s[8:11], s6 offen lds
	s_mov_b32 m0, s58
	s_nop 0
	buffer_load_dwordx4 v142, s[8:11], s6 offen lds
	s_waitcnt lgkmcnt(8)
	s_barrier
	s_waitcnt lgkmcnt(0)
	v_mfma_f32_16x16x32_bf16 v[124:127], v[152:155], v[168:171], v[124:127]
	v_mfma_f32_16x16x32_bf16 v[124:127], v[156:159], v[172:175], v[124:127]
	v_mfma_f32_16x16x32_bf16 v[120:123], v[160:163], v[168:171], v[120:123]
	v_mfma_f32_16x16x32_bf16 v[120:123], v[164:167], v[172:175], v[120:123]
	v_mfma_f32_16x16x32_bf16 v[116:119], v[152:155], v[176:179], v[116:119]
	v_mfma_f32_16x16x32_bf16 v[116:119], v[156:159], v[180:183], v[116:119]
	v_mfma_f32_16x16x32_bf16 v[112:115], v[160:163], v[176:179], v[112:115]
	v_mfma_f32_16x16x32_bf16 v[112:115], v[164:167], v[180:183], v[112:115]
	v_mfma_f32_16x16x32_bf16 v[108:111], v[152:155], v[184:187], v[108:111]
	v_mfma_f32_16x16x32_bf16 v[108:111], v[156:159], v[188:191], v[108:111]
	v_mfma_f32_16x16x32_bf16 v[104:107], v[160:163], v[184:187], v[104:107]
	v_mfma_f32_16x16x32_bf16 v[104:107], v[164:167], v[188:191], v[104:107]
	v_mfma_f32_16x16x32_bf16 v[100:103], v[152:155], v[192:195], v[100:103]
	v_mfma_f32_16x16x32_bf16 v[100:103], v[156:159], v[196:199], v[100:103]
	v_mfma_f32_16x16x32_bf16 v[96:99], v[160:163], v[192:195], v[96:99]
	v_mfma_f32_16x16x32_bf16 v[96:99], v[164:167], v[196:199], v[96:99]
	s_barrier
	s_add_i32 s6, s83, s3
	s_add_i32 s7, s6, 0x100
	s_mov_b32 s14, s10
	s_mov_b32 s15, s11
	s_mov_b32 m0, s85
	ds_read_b128 v[200:203], v143
	ds_read_b128 v[204:207], v144
	ds_read_b128 v[208:211], v145
	ds_read_b128 v[212:215], v146
	buffer_load_dwordx4 v141, s[12:15], s7 offen lds
	s_mov_b32 m0, s75
	s_nop 0
	buffer_load_dwordx4 v142, s[12:15], s7 offen lds
	s_barrier
	s_waitcnt lgkmcnt(0)
	v_mfma_f32_16x16x32_bf16 v[92:95], v[200:203], v[168:171], v[92:95]
	v_mfma_f32_16x16x32_bf16 v[92:95], v[204:207], v[172:175], v[92:95]
	v_mfma_f32_16x16x32_bf16 v[88:91], v[208:211], v[168:171], v[88:91]
	v_mfma_f32_16x16x32_bf16 v[88:91], v[212:215], v[172:175], v[88:91]
	v_mfma_f32_16x16x32_bf16 v[80:83], v[200:203], v[176:179], v[80:83]
	v_mfma_f32_16x16x32_bf16 v[80:83], v[204:207], v[180:183], v[80:83]
	v_mfma_f32_16x16x32_bf16 v[68:71], v[208:211], v[176:179], v[68:71]
	v_mfma_f32_16x16x32_bf16 v[68:71], v[212:215], v[180:183], v[68:71]
	v_mfma_f32_16x16x32_bf16 v[60:63], v[200:203], v[184:187], v[60:63]
	v_mfma_f32_16x16x32_bf16 v[60:63], v[204:207], v[188:191], v[60:63]
	v_mfma_f32_16x16x32_bf16 v[56:59], v[208:211], v[184:187], v[56:59]
	v_mfma_f32_16x16x32_bf16 v[56:59], v[212:215], v[188:191], v[56:59]
	v_mfma_f32_16x16x32_bf16 v[52:55], v[200:203], v[192:195], v[52:55]
	v_mfma_f32_16x16x32_bf16 v[52:55], v[204:207], v[196:199], v[52:55]
	v_mfma_f32_16x16x32_bf16 v[48:51], v[208:211], v[192:195], v[48:51]
	v_mfma_f32_16x16x32_bf16 v[48:51], v[212:215], v[196:199], v[48:51]
	s_barrier
	s_add_i32 s7, s82, s3
	s_add_i32 s22, s7, 0x100
	s_mov_b32 m0, s38
	ds_read_b128 v[168:171], v129 offset:16384
	ds_read_b128 v[172:175], v129 offset:17408
	ds_read_b128 v[176:179], v132 offset:16384
	ds_read_b128 v[180:183], v132 offset:17408
	ds_read_b128 v[184:187], v131 offset:16384
	ds_read_b128 v[188:191], v131 offset:17408
	ds_read_b128 v[192:195], v130 offset:16384
	ds_read_b128 v[196:199], v130 offset:17408
	buffer_load_dwordx4 v141, s[8:11], s22 offen lds
	s_mov_b32 m0, s95
	s_nop 0
	buffer_load_dwordx4 v142, s[8:11], s22 offen lds
	s_barrier
	s_waitcnt lgkmcnt(0)
	v_mfma_f32_16x16x32_bf16 v[44:47], v[152:155], v[168:171], v[44:47]
	v_mfma_f32_16x16x32_bf16 v[44:47], v[156:159], v[172:175], v[44:47]
	v_mfma_f32_16x16x32_bf16 v[40:43], v[160:163], v[168:171], v[40:43]
	v_mfma_f32_16x16x32_bf16 v[40:43], v[164:167], v[172:175], v[40:43]
	v_mfma_f32_16x16x32_bf16 v[36:39], v[152:155], v[176:179], v[36:39]
	v_mfma_f32_16x16x32_bf16 v[36:39], v[156:159], v[180:183], v[36:39]
	v_mfma_f32_16x16x32_bf16 v[32:35], v[160:163], v[176:179], v[32:35]
	v_mfma_f32_16x16x32_bf16 v[32:35], v[164:167], v[180:183], v[32:35]
	v_mfma_f32_16x16x32_bf16 v[28:31], v[152:155], v[184:187], v[28:31]
	v_mfma_f32_16x16x32_bf16 v[28:31], v[156:159], v[188:191], v[28:31]
	v_mfma_f32_16x16x32_bf16 v[24:27], v[160:163], v[184:187], v[24:27]
	v_mfma_f32_16x16x32_bf16 v[24:27], v[164:167], v[188:191], v[24:27]
	v_mfma_f32_16x16x32_bf16 v[20:23], v[152:155], v[192:195], v[20:23]
	v_mfma_f32_16x16x32_bf16 v[20:23], v[156:159], v[196:199], v[20:23]
	v_mfma_f32_16x16x32_bf16 v[16:19], v[160:163], v[192:195], v[16:19]
	v_mfma_f32_16x16x32_bf16 v[16:19], v[164:167], v[196:199], v[16:19]
	s_barrier
	s_add_i32 s22, s84, s3
	s_add_i32 s23, s22, 0x100
	s_mov_b32 m0, s86
	s_nop 0
	buffer_load_dwordx4 v141, s[12:15], s23 offen lds
	s_mov_b32 m0, s28
	s_nop 0
	buffer_load_dwordx4 v142, s[12:15], s23 offen lds
	s_waitcnt vmcnt(6)
	s_barrier
; #define STAGE(P, RS, SOFF, OFF, kt) do { const int _so = (SOFF) + (kt) * (BK * 2); \
;     _Pragma("unroll") for (int _i = 0; _i < 2; ++_i) { \
;       __builtin_amdgcn_raw_ptr_buffer_load_lds(RS, (__attribute__((address_space(3))) void*)((P) + wave * 1024 + _i * 8192), 16, OFF[_i], _so, 0, 0); } } while (0)
; #define LDA(dst, b, h) _Pragma("unroll") for (int m = 0; m < 4; ++m) _Pragma("unroll") for (int k = 0; k < 2; ++k) \
;     dst[m][k] = *reinterpret_cast<const bf16x8*>(SA(b, h) + lds_byte(wr * 64 + m * 16 + fr, k * 32 + fq * 8))
; #define LDB(dst, b, h) _Pragma("unroll") for (int n = 0; n < 2; ++n) _Pragma("unroll") for (int k = 0; k < 2; ++k) \
;     dst[n][k] = *reinterpret_cast<const bf16x8*>(SB(b, h) + lds_byte(wc * 32 + n * 16 + fr, k * 32 + fq * 8))
; #define WAIT_V(n) asm volatile("s_waitcnt vmcnt(" #n ")" ::: "memory")
; #define WAIT_L(n) asm volatile("s_waitcnt lgkmcnt(" #n ")" ::: "memory")
; #define BAR __builtin_amdgcn_s_barrier()
; #define SCHED __builtin_amdgcn_sched_barrier(0)
;     ...
;       WAIT_V(6); BAR; MMA(1, 1, At, B1); BAR;
;       LDB(B0, 1, 0); SCHED; LDA(At, 1, 0); STAGE(SA(0, 1), rsA, sA1, offA, t + 2);
;       WAIT_L(8); BAR; WAIT_L(0); MMA(0, 0, At, B0); BAR; SCHED;
;       LDB(B1, 1, 1); STAGE(SB(1, 0), rsB, sB0, offB, t + 3);
;       BAR; WAIT_L(0); MMA(0, 1, At, B1); BAR;
;       LDA(At, 1, 1); STAGE(SA(1, 0), rsA, sA0, offA, t + 3);
;       BAR; WAIT_L(0); MMA(1, 0, At, B0); BAR; SCHED;
	v_mfma_f32_16x16x32_bf16 v[12:15], v[200:203], v[168:171], v[12:15]
	v_mfma_f32_16x16x32_bf16 v[12:15], v[204:207], v[172:175], v[12:15]
	v_mfma_f32_16x16x32_bf16 v[8:11], v[208:211], v[168:171], v[8:11]
	v_mfma_f32_16x16x32_bf16 v[8:11], v[212:215], v[172:175], v[8:11]
	v_mfma_f32_16x16x32_bf16 v[4:7], v[200:203], v[176:179], v[4:7]
	v_mfma_f32_16x16x32_bf16 v[4:7], v[204:207], v[180:183], v[4:7]
	v_mfma_f32_16x16x32_bf16 v[0:3], v[208:211], v[176:179], v[0:3]
	v_mfma_f32_16x16x32_bf16 v[0:3], v[212:215], v[180:183], v[0:3]
	v_mfma_f32_16x16x32_bf16 v[64:67], v[200:203], v[184:187], v[64:67]
	v_mfma_f32_16x16x32_bf16 v[64:67], v[204:207], v[188:191], v[64:67]
	v_mfma_f32_16x16x32_bf16 v[72:75], v[208:211], v[184:187], v[72:75]
	v_mfma_f32_16x16x32_bf16 v[72:75], v[212:215], v[188:191], v[72:75]
	v_mfma_f32_16x16x32_bf16 v[76:79], v[200:203], v[192:195], v[76:79]
	v_mfma_f32_16x16x32_bf16 v[76:79], v[204:207], v[196:199], v[76:79]
	v_mfma_f32_16x16x32_bf16 v[84:87], v[208:211], v[192:195], v[84:87]
	v_mfma_f32_16x16x32_bf16 v[84:87], v[212:215], v[196:199], v[84:87]
	s_barrier
	ds_read_b128 v[152:155], v137
	ds_read_b128 v[156:159], v138
	ds_read_b128 v[160:163], v139
	ds_read_b128 v[164:167], v140
	s_addk_i32 s5, 0x100
	s_mov_b32 m0, s87
	ds_read_b128 v[168:171], v129 offset:32768
	ds_read_b128 v[172:175], v129 offset:33792
	ds_read_b128 v[176:179], v132 offset:32768
	ds_read_b128 v[180:183], v132 offset:33792
	ds_read_b128 v[184:187], v131 offset:32768
	ds_read_b128 v[188:191], v131 offset:33792
	ds_read_b128 v[192:195], v130 offset:32768
	ds_read_b128 v[196:199], v130 offset:33792
	buffer_load_dwordx4 v141, s[8:11], s5 offen lds
	s_mov_b32 m0, s97
	s_nop 0
	buffer_load_dwordx4 v142, s[8:11], s5 offen lds
	s_waitcnt lgkmcnt(8)
	s_barrier
	s_waitcnt lgkmcnt(0)
	v_mfma_f32_16x16x32_bf16 v[124:127], v[152:155], v[168:171], v[124:127]
	v_mfma_f32_16x16x32_bf16 v[124:127], v[156:159], v[172:175], v[124:127]
	v_mfma_f32_16x16x32_bf16 v[120:123], v[160:163], v[168:171], v[120:123]
	v_mfma_f32_16x16x32_bf16 v[120:123], v[164:167], v[172:175], v[120:123]
	v_mfma_f32_16x16x32_bf16 v[116:119], v[152:155], v[176:179], v[116:119]
	v_mfma_f32_16x16x32_bf16 v[116:119], v[156:159], v[180:183], v[116:119]
	v_mfma_f32_16x16x32_bf16 v[112:115], v[160:163], v[176:179], v[112:115]
	v_mfma_f32_16x16x32_bf16 v[112:115], v[164:167], v[180:183], v[112:115]
	v_mfma_f32_16x16x32_bf16 v[108:111], v[152:155], v[184:187], v[108:111]
	v_mfma_f32_16x16x32_bf16 v[108:111], v[156:159], v[188:191], v[108:111]
	v_mfma_f32_16x16x32_bf16 v[104:107], v[160:163], v[184:187], v[104:107]
	v_mfma_f32_16x16x32_bf16 v[104:107], v[164:167], v[188:191], v[104:107]
	v_mfma_f32_16x16x32_bf16 v[100:103], v[152:155], v[192:195], v[100:103]
	v_mfma_f32_16x16x32_bf16 v[100:103], v[156:159], v[196:199], v[100:103]
	v_mfma_f32_16x16x32_bf16 v[96:99], v[160:163], v[192:195], v[96:99]
	v_mfma_f32_16x16x32_bf16 v[96:99], v[164:167], v[196:199], v[96:99]
	s_barrier
	s_addk_i32 s6, 0x180
	s_mov_b32 m0, s92
	ds_read_b128 v[200:203], v133
	ds_read_b128 v[204:207], v134
	ds_read_b128 v[208:211], v135
	ds_read_b128 v[212:215], v136
	buffer_load_dwordx4 v141, s[12:15], s6 offen lds
	s_mov_b32 m0, s29
	s_nop 0
	buffer_load_dwordx4 v142, s[12:15], s6 offen lds
	s_barrier
	s_waitcnt lgkmcnt(0)
	v_mfma_f32_16x16x32_bf16 v[92:95], v[200:203], v[168:171], v[92:95]
	v_mfma_f32_16x16x32_bf16 v[92:95], v[204:207], v[172:175], v[92:95]
	v_mfma_f32_16x16x32_bf16 v[88:91], v[208:211], v[168:171], v[88:91]
	v_mfma_f32_16x16x32_bf16 v[88:91], v[212:215], v[172:175], v[88:91]
	v_mfma_f32_16x16x32_bf16 v[80:83], v[200:203], v[176:179], v[80:83]
	v_mfma_f32_16x16x32_bf16 v[80:83], v[204:207], v[180:183], v[80:83]
	v_mfma_f32_16x16x32_bf16 v[68:71], v[208:211], v[176:179], v[68:71]
	v_mfma_f32_16x16x32_bf16 v[68:71], v[212:215], v[180:183], v[68:71]
	v_mfma_f32_16x16x32_bf16 v[60:63], v[200:203], v[184:187], v[60:63]
	v_mfma_f32_16x16x32_bf16 v[60:63], v[204:207], v[188:191], v[60:63]
	v_mfma_f32_16x16x32_bf16 v[56:59], v[208:211], v[184:187], v[56:59]
	v_mfma_f32_16x16x32_bf16 v[56:59], v[212:215], v[188:191], v[56:59]
	v_mfma_f32_16x16x32_bf16 v[52:55], v[200:203], v[192:195], v[52:55]
	v_mfma_f32_16x16x32_bf16 v[52:55], v[204:207], v[196:199], v[52:55]
	v_mfma_f32_16x16x32_bf16 v[48:51], v[208:211], v[192:195], v[48:51]
	v_mfma_f32_16x16x32_bf16 v[48:51], v[212:215], v[196:199], v[48:51]
	s_barrier
	s_addk_i32 s7, 0x180
	s_mov_b32 m0, s93
	ds_read_b128 v[168:171], v129 offset:49152
	ds_read_b128 v[172:175], v129 offset:50176
	ds_read_b128 v[176:179], v132 offset:49152
	ds_read_b128 v[180:183], v132 offset:50176
	ds_read_b128 v[184:187], v131 offset:49152
	ds_read_b128 v[188:191], v131 offset:50176
	ds_read_b128 v[192:195], v130 offset:49152
	ds_read_b128 v[196:199], v130 offset:50176
	buffer_load_dwordx4 v141, s[8:11], s7 offen lds
	s_mov_b32 m0, s56
	s_nop 0
	buffer_load_dwordx4 v142, s[8:11], s7 offen lds
	s_barrier
	s_waitcnt lgkmcnt(0)
	v_mfma_f32_16x16x32_bf16 v[44:47], v[152:155], v[168:171], v[44:47]
	v_mfma_f32_16x16x32_bf16 v[44:47], v[156:159], v[172:175], v[44:47]
	v_mfma_f32_16x16x32_bf16 v[40:43], v[160:163], v[168:171], v[40:43]
	v_mfma_f32_16x16x32_bf16 v[40:43], v[164:167], v[172:175], v[40:43]
	v_mfma_f32_16x16x32_bf16 v[36:39], v[152:155], v[176:179], v[36:39]
	v_mfma_f32_16x16x32_bf16 v[36:39], v[156:159], v[180:183], v[36:39]
	v_mfma_f32_16x16x32_bf16 v[32:35], v[160:163], v[176:179], v[32:35]
	v_mfma_f32_16x16x32_bf16 v[32:35], v[164:167], v[180:183], v[32:35]
	v_mfma_f32_16x16x32_bf16 v[28:31], v[152:155], v[184:187], v[28:31]
	v_mfma_f32_16x16x32_bf16 v[28:31], v[156:159], v[188:191], v[28:31]
	v_mfma_f32_16x16x32_bf16 v[24:27], v[160:163], v[184:187], v[24:27]
	v_mfma_f32_16x16x32_bf16 v[24:27], v[164:167], v[188:191], v[24:27]
	v_mfma_f32_16x16x32_bf16 v[20:23], v[152:155], v[192:195], v[20:23]
	v_mfma_f32_16x16x32_bf16 v[20:23], v[156:159], v[196:199], v[20:23]
	v_mfma_f32_16x16x32_bf16 v[16:19], v[160:163], v[192:195], v[16:19]
	v_mfma_f32_16x16x32_bf16 v[16:19], v[164:167], v[196:199], v[16:19]
	s_barrier
; #define STAGE(P, RS, SOFF, OFF, kt) do { const int _so = (SOFF) + (kt) * (BK * 2); \
;     _Pragma("unroll") for (int _i = 0; _i < 2; ++_i) { \
;       __builtin_amdgcn_raw_ptr_buffer_load_lds(RS, (__attribute__((address_space(3))) void*)((P) + wave * 1024 + _i * 8192), 16, OFF[_i], _so, 0, 0); } } while (0)
; #define LDA(dst, b, h) _Pragma("unroll") for (int m = 0; m < 4; ++m) _Pragma("unroll") for (int k = 0; k < 2; ++k) \
;     dst[m][k] = *reinterpret_cast<const bf16x8*>(SA(b, h) + lds_byte(wr * 64 + m * 16 + fr, k * 32 + fq * 8))
; #define LDB(dst, b, h) _Pragma("unroll") for (int n = 0; n < 2; ++n) _Pragma("unroll") for (int k = 0; k < 2; ++k) \
;     dst[n][k] = *reinterpret_cast<const bf16x8*>(SB(b, h) + lds_byte(wc * 32 + n * 16 + fr, k * 32 + fq * 8))
; #define WAIT_V(n) asm volatile("s_waitcnt vmcnt(" #n ")" ::: "memory")
; #define WAIT_L(n) asm volatile("s_waitcnt lgkmcnt(" #n ")" ::: "memory")
; #define BAR __builtin_amdgcn_s_barrier()
;     ...
;       STAGE(SB(1, 1), rsB, sB1, offB, t + 3);
;       WAIT_V(6); BAR; MMA(1, 1, At, B1); BAR;
;     }
;     { LDB(B0, 0, 0); LDA(At, 0, 0); STAGE(SA(1, 1), rsA, sA1, offA, nt - 1);
;       BAR; WAIT_L(0); MMA(0, 0, At, B0); BAR;
;       LDB(B1, 0, 1); BAR; WAIT_L(0); MMA(0, 1, At, B1); BAR;
;       LDA(At, 0, 1); WAIT_V(4); BAR; WAIT_L(0); MMA(1, 0, At, B0); MMA(1, 1, At, B1); BAR; }
	s_addk_i32 s22, 0x180
	s_mov_b32 m0, s94
	s_nop 0
	buffer_load_dwordx4 v141, s[12:15], s22 offen lds
	s_mov_b32 m0, s57
	s_nop 0
	buffer_load_dwordx4 v142, s[12:15], s22 offen lds
	s_add_i32 s1, s1, 2
	s_addk_i32 s3, 0x100
	s_cmp_gt_u32 s1, 27
	s_cbranch_scc0 .LBB0_657
	s_waitcnt vmcnt(6)
	s_barrier
	v_mfma_f32_16x16x32_bf16 v[12:15], v[200:203], v[168:171], v[12:15]
	v_mfma_f32_16x16x32_bf16 v[12:15], v[204:207], v[172:175], v[12:15]
	v_mfma_f32_16x16x32_bf16 v[8:11], v[208:211], v[168:171], v[8:11]
	v_mfma_f32_16x16x32_bf16 v[8:11], v[212:215], v[172:175], v[8:11]
	v_mfma_f32_16x16x32_bf16 v[4:7], v[200:203], v[176:179], v[4:7]
	v_mfma_f32_16x16x32_bf16 v[4:7], v[204:207], v[180:183], v[4:7]
	v_mfma_f32_16x16x32_bf16 v[0:3], v[208:211], v[176:179], v[0:3]
	v_mfma_f32_16x16x32_bf16 v[0:3], v[212:215], v[180:183], v[0:3]
	v_mfma_f32_16x16x32_bf16 v[64:67], v[200:203], v[184:187], v[64:67]
	v_mfma_f32_16x16x32_bf16 v[64:67], v[204:207], v[188:191], v[64:67]
	v_mfma_f32_16x16x32_bf16 v[72:75], v[208:211], v[184:187], v[72:75]
	v_mfma_f32_16x16x32_bf16 v[72:75], v[212:215], v[188:191], v[72:75]
	v_mfma_f32_16x16x32_bf16 v[76:79], v[200:203], v[192:195], v[76:79]
	v_mfma_f32_16x16x32_bf16 v[76:79], v[204:207], v[196:199], v[76:79]
	v_mfma_f32_16x16x32_bf16 v[84:87], v[208:211], v[192:195], v[84:87]
	v_mfma_f32_16x16x32_bf16 v[84:87], v[212:215], v[196:199], v[84:87]
	s_barrier
	s_add_i32 s1, s81, 0xf80
	s_mov_b32 m0, s39
	ds_read_b128 v[152:155], v147
	ds_read_b128 v[156:159], v148
	ds_read_b128 v[160:163], v149
	ds_read_b128 v[148:151], v150
	ds_read_b128 v[164:167], v129
	ds_read_b128 v[168:171], v129 offset:1024
	ds_read_b128 v[172:175], v132
	ds_read_b128 v[176:179], v132 offset:1024
	ds_read_b128 v[180:183], v131
	ds_read_b128 v[184:187], v131 offset:1024
	ds_read_b128 v[188:191], v130
	ds_read_b128 v[192:195], v130 offset:1024
	buffer_load_dwordx4 v141, s[8:11], s1 offen lds
	s_mov_b32 m0, s58
	s_nop 0
	buffer_load_dwordx4 v142, s[8:11], s1 offen lds
	s_barrier
	s_waitcnt lgkmcnt(0)
	v_mfma_f32_16x16x32_bf16 v[124:127], v[152:155], v[164:167], v[124:127]
	v_mfma_f32_16x16x32_bf16 v[124:127], v[156:159], v[168:171], v[124:127]
	v_mfma_f32_16x16x32_bf16 v[120:123], v[160:163], v[164:167], v[120:123]
	v_mfma_f32_16x16x32_bf16 v[120:123], v[148:151], v[168:171], v[120:123]
	v_mfma_f32_16x16x32_bf16 v[116:119], v[152:155], v[172:175], v[116:119]
	v_mfma_f32_16x16x32_bf16 v[116:119], v[156:159], v[176:179], v[116:119]
	v_mfma_f32_16x16x32_bf16 v[112:115], v[160:163], v[172:175], v[112:115]
	v_mfma_f32_16x16x32_bf16 v[112:115], v[148:151], v[176:179], v[112:115]
	v_mfma_f32_16x16x32_bf16 v[108:111], v[152:155], v[180:183], v[108:111]
	v_mfma_f32_16x16x32_bf16 v[108:111], v[156:159], v[184:187], v[108:111]
	v_mfma_f32_16x16x32_bf16 v[104:107], v[160:163], v[180:183], v[104:107]
	v_mfma_f32_16x16x32_bf16 v[104:107], v[148:151], v[184:187], v[104:107]
	v_mfma_f32_16x16x32_bf16 v[100:103], v[152:155], v[188:191], v[100:103]
	v_mfma_f32_16x16x32_bf16 v[100:103], v[156:159], v[192:195], v[100:103]
	v_mfma_f32_16x16x32_bf16 v[96:99], v[160:163], v[188:191], v[96:99]
	v_mfma_f32_16x16x32_bf16 v[96:99], v[148:151], v[192:195], v[96:99]
	s_barrier
	ds_read_b128 v[196:199], v143
	ds_read_b128 v[200:203], v144
	ds_read_b128 v[142:145], v145
	ds_read_b128 v[204:207], v146
	s_barrier
	s_waitcnt lgkmcnt(0)
	v_mfma_f32_16x16x32_bf16 v[88:91], v[142:145], v[164:167], v[88:91]
	v_mfma_f32_16x16x32_bf16 v[80:83], v[196:199], v[172:175], v[80:83]
	v_mfma_f32_16x16x32_bf16 v[60:63], v[196:199], v[180:183], v[60:63]
	v_mfma_f32_16x16x32_bf16 v[56:59], v[142:145], v[180:183], v[56:59]
	v_mfma_f32_16x16x32_bf16 v[52:55], v[196:199], v[188:191], v[52:55]
	v_mfma_f32_16x16x32_bf16 v[48:51], v[142:145], v[188:191], v[48:51]
	v_mfma_f32_16x16x32_bf16 v[92:95], v[196:199], v[164:167], v[92:95]
	v_mfma_f32_16x16x32_bf16 v[68:71], v[142:145], v[172:175], v[68:71]
	v_mfma_f32_16x16x32_bf16 v[88:91], v[204:207], v[168:171], v[88:91]
	v_mfma_f32_16x16x32_bf16 v[80:83], v[200:203], v[176:179], v[80:83]
	v_mfma_f32_16x16x32_bf16 v[60:63], v[200:203], v[184:187], v[60:63]
	v_mfma_f32_16x16x32_bf16 v[56:59], v[204:207], v[184:187], v[56:59]
	v_mfma_f32_16x16x32_bf16 v[52:55], v[200:203], v[192:195], v[52:55]
	v_mfma_f32_16x16x32_bf16 v[48:51], v[204:207], v[192:195], v[48:51]
	v_mfma_f32_16x16x32_bf16 v[164:167], v[200:203], v[168:171], v[92:95]
	v_mfma_f32_16x16x32_bf16 v[168:171], v[204:207], v[176:179], v[68:71]
	s_barrier
	s_nop 0
	ds_read_b128 v[68:71], v129 offset:16384
	ds_read_b128 v[92:95], v129 offset:17408
	ds_read_b128 v[172:175], v132 offset:16384
	ds_read_b128 v[176:179], v132 offset:17408
	ds_read_b128 v[180:183], v131 offset:16384
	ds_read_b128 v[184:187], v131 offset:17408
	ds_read_b128 v[188:191], v130 offset:16384
	ds_read_b128 v[192:195], v130 offset:17408
	s_waitcnt vmcnt(4)
	s_barrier
; #define LDA(dst, b, h) _Pragma("unroll") for (int m = 0; m < 4; ++m) _Pragma("unroll") for (int k = 0; k < 2; ++k) \
;     dst[m][k] = *reinterpret_cast<const bf16x8*>(SA(b, h) + lds_byte(wr * 64 + m * 16 + fr, k * 32 + fq * 8))
; #define LDB(dst, b, h) _Pragma("unroll") for (int n = 0; n < 2; ++n) _Pragma("unroll") for (int k = 0; k < 2; ++k) \
;     dst[n][k] = *reinterpret_cast<const bf16x8*>(SB(b, h) + lds_byte(wc * 32 + n * 16 + fr, k * 32 + fq * 8))
; #define WAIT_V(n) asm volatile("s_waitcnt vmcnt(" #n ")" ::: "memory")
; #define WAIT_L(n) asm volatile("s_waitcnt lgkmcnt(" #n ")" ::: "memory")
; #define BAR __builtin_amdgcn_s_barrier()
;     ...
;       LDA(At, 0, 1); WAIT_V(4); BAR; WAIT_L(0); MMA(1, 0, At, B0); MMA(1, 1, At, B1); BAR; }
;     { LDB(B0, 1, 0); LDA(At, 1, 0); WAIT_V(2); BAR; WAIT_L(0); MMA(0, 0, At, B0); BAR;
	s_waitcnt lgkmcnt(0)
	v_mfma_f32_16x16x32_bf16 v[44:47], v[152:155], v[68:71], v[44:47]
	v_mfma_f32_16x16x32_bf16 v[40:43], v[160:163], v[68:71], v[40:43]
	v_mfma_f32_16x16x32_bf16 v[36:39], v[152:155], v[172:175], v[36:39]
	v_mfma_f32_16x16x32_bf16 v[32:35], v[160:163], v[172:175], v[32:35]
	v_mfma_f32_16x16x32_bf16 v[28:31], v[152:155], v[180:183], v[28:31]
	v_mfma_f32_16x16x32_bf16 v[24:27], v[160:163], v[180:183], v[24:27]
	v_mfma_f32_16x16x32_bf16 v[20:23], v[152:155], v[188:191], v[20:23]
	v_mfma_f32_16x16x32_bf16 v[16:19], v[160:163], v[188:191], v[16:19]
	v_mfma_f32_16x16x32_bf16 v[44:47], v[156:159], v[92:95], v[44:47]
	v_mfma_f32_16x16x32_bf16 v[40:43], v[148:151], v[92:95], v[40:43]
	v_mfma_f32_16x16x32_bf16 v[36:39], v[156:159], v[176:179], v[36:39]
	v_mfma_f32_16x16x32_bf16 v[32:35], v[148:151], v[176:179], v[32:35]
	v_mfma_f32_16x16x32_bf16 v[28:31], v[156:159], v[184:187], v[28:31]
	v_mfma_f32_16x16x32_bf16 v[24:27], v[148:151], v[184:187], v[24:27]
	v_mfma_f32_16x16x32_bf16 v[20:23], v[156:159], v[192:195], v[20:23]
	v_mfma_f32_16x16x32_bf16 v[16:19], v[148:151], v[192:195], v[16:19]
	v_mfma_f32_16x16x32_bf16 v[4:7], v[196:199], v[172:175], v[4:7]
	v_mfma_f32_16x16x32_bf16 v[0:3], v[142:145], v[172:175], v[0:3]
	v_mfma_f32_16x16x32_bf16 v[12:15], v[196:199], v[68:71], v[12:15]
	v_mfma_f32_16x16x32_bf16 v[8:11], v[142:145], v[68:71], v[8:11]
	v_mfma_f32_16x16x32_bf16 v[64:67], v[196:199], v[180:183], v[64:67]
	v_mfma_f32_16x16x32_bf16 v[68:71], v[142:145], v[180:183], v[72:75]
	v_mfma_f32_16x16x32_bf16 v[72:75], v[196:199], v[188:191], v[76:79]
	v_mfma_f32_16x16x32_bf16 v[76:79], v[142:145], v[188:191], v[84:87]
	v_mfma_f32_16x16x32_bf16 v[4:7], v[200:203], v[176:179], v[4:7]
	v_mfma_f32_16x16x32_bf16 v[0:3], v[204:207], v[176:179], v[0:3]
	v_mfma_f32_16x16x32_bf16 v[142:145], v[200:203], v[92:95], v[12:15]
	v_mfma_f32_16x16x32_bf16 v[146:149], v[204:207], v[92:95], v[8:11]
	v_mfma_f32_16x16x32_bf16 v[150:153], v[200:203], v[184:187], v[64:67]
	v_mfma_f32_16x16x32_bf16 v[154:157], v[204:207], v[184:187], v[68:71]
	v_mfma_f32_16x16x32_bf16 v[158:161], v[200:203], v[192:195], v[72:75]
	v_mfma_f32_16x16x32_bf16 v[172:175], v[204:207], v[192:195], v[76:79]
	s_barrier
	ds_read_b128 v[8:11], v137
	ds_read_b128 v[12:15], v138
	ds_read_b128 v[176:179], v139
	ds_read_b128 v[138:141], v140
	ds_read_b128 v[64:67], v129 offset:32768
	ds_read_b128 v[72:75], v129 offset:33792
	ds_read_b128 v[180:183], v132 offset:32768
	ds_read_b128 v[184:187], v132 offset:33792
	ds_read_b128 v[188:191], v131 offset:32768
	ds_read_b128 v[192:195], v131 offset:33792
	ds_read_b128 v[196:199], v130 offset:32768
	ds_read_b128 v[200:203], v130 offset:33792
	s_waitcnt vmcnt(2)
	s_barrier
	s_waitcnt lgkmcnt(0)
	v_mfma_f32_16x16x32_bf16 v[68:71], v[8:11], v[64:67], v[124:127]
	v_mfma_f32_16x16x32_bf16 v[76:79], v[176:179], v[64:67], v[120:123]
	v_mfma_f32_16x16x32_bf16 v[84:87], v[8:11], v[180:183], v[116:119]
	v_mfma_f32_16x16x32_bf16 v[92:95], v[176:179], v[180:183], v[112:115]
	v_mfma_f32_16x16x32_bf16 v[112:115], v[8:11], v[188:191], v[108:111]
	v_mfma_f32_16x16x32_bf16 v[104:107], v[176:179], v[188:191], v[104:107]
	v_mfma_f32_16x16x32_bf16 v[120:123], v[8:11], v[196:199], v[100:103]
	v_mfma_f32_16x16x32_bf16 v[96:99], v[176:179], v[196:199], v[96:99]
	v_mfma_f32_16x16x32_bf16 v[124:127], v[12:15], v[72:75], v[68:71]
	v_mfma_f32_16x16x32_bf16 v[116:119], v[138:141], v[72:75], v[76:79]
	v_mfma_f32_16x16x32_bf16 v[108:111], v[12:15], v[184:187], v[84:87]
	v_mfma_f32_16x16x32_bf16 v[100:103], v[138:141], v[184:187], v[92:95]
	v_mfma_f32_16x16x32_bf16 v[92:95], v[12:15], v[192:195], v[112:115]
	v_mfma_f32_16x16x32_bf16 v[84:87], v[138:141], v[192:195], v[104:107]
	v_mfma_f32_16x16x32_bf16 v[76:79], v[12:15], v[200:203], v[120:123]
	v_mfma_f32_16x16x32_bf16 v[68:71], v[138:141], v[200:203], v[96:99]
	s_barrier
; #define LDA(dst, b, h) _Pragma("unroll") for (int m = 0; m < 4; ++m) _Pragma("unroll") for (int k = 0; k < 2; ++k) \
;     dst[m][k] = *reinterpret_cast<const bf16x8*>(SA(b, h) + lds_byte(wr * 64 + m * 16 + fr, k * 32 + fq * 8))
; #define LDB(dst, b, h) _Pragma("unroll") for (int n = 0; n < 2; ++n) _Pragma("unroll") for (int k = 0; k < 2; ++k) \
;     dst[n][k] = *reinterpret_cast<const bf16x8*>(SB(b, h) + lds_byte(wc * 32 + n * 16 + fr, k * 32 + fq * 8))
; #define WAIT_V(n) asm volatile("s_waitcnt vmcnt(" #n ")" ::: "memory")
; #define WAIT_L(n) asm volatile("s_waitcnt lgkmcnt(" #n ")" ::: "memory")
; #define BAR __builtin_amdgcn_s_barrier()
;     ...
;       LDB(B1, 1, 1); WAIT_V(0); BAR; WAIT_L(0); MMA(0, 1, At, B1); BAR;
;       LDA(At, 1, 1); BAR; WAIT_L(0); MMA(1, 0, At, B0); MMA(1, 1, At, B1); BAR; }
;     if (wr == 0) BAR;
	ds_read_b128 v[204:207], v133
	ds_read_b128 v[208:211], v134
	ds_read_b128 v[212:215], v135
	ds_read_b128 v[134:137], v136
	s_waitcnt vmcnt(0)
	s_barrier
	s_waitcnt lgkmcnt(0)
	v_mfma_f32_16x16x32_bf16 v[96:99], v[204:207], v[64:67], v[164:167]
	v_mfma_f32_16x16x32_bf16 v[64:67], v[212:215], v[64:67], v[88:91]
	v_mfma_f32_16x16x32_bf16 v[80:83], v[204:207], v[180:183], v[80:83]
	v_mfma_f32_16x16x32_bf16 v[88:91], v[212:215], v[180:183], v[168:171]
	v_mfma_f32_16x16x32_bf16 v[60:63], v[204:207], v[188:191], v[60:63]
	v_mfma_f32_16x16x32_bf16 v[56:59], v[212:215], v[188:191], v[56:59]
	v_mfma_f32_16x16x32_bf16 v[52:55], v[204:207], v[196:199], v[52:55]
	v_mfma_f32_16x16x32_bf16 v[48:51], v[212:215], v[196:199], v[48:51]
	v_mfma_f32_16x16x32_bf16 v[120:123], v[208:211], v[72:75], v[96:99]
	v_mfma_f32_16x16x32_bf16 v[112:115], v[134:137], v[72:75], v[64:67]
	v_mfma_f32_16x16x32_bf16 v[104:107], v[208:211], v[184:187], v[80:83]
	v_mfma_f32_16x16x32_bf16 v[96:99], v[134:137], v[184:187], v[88:91]
	v_mfma_f32_16x16x32_bf16 v[88:91], v[208:211], v[192:195], v[60:63]
	v_mfma_f32_16x16x32_bf16 v[80:83], v[134:137], v[192:195], v[56:59]
	v_mfma_f32_16x16x32_bf16 v[72:75], v[208:211], v[200:203], v[52:55]
	v_mfma_f32_16x16x32_bf16 v[64:67], v[134:137], v[200:203], v[48:51]
	s_barrier
	s_nop 0
	ds_read_b128 v[48:51], v129 offset:49152
	ds_read_b128 v[162:165], v129 offset:50176
	ds_read_b128 v[52:55], v132 offset:49152
	ds_read_b128 v[166:169], v132 offset:50176
	ds_read_b128 v[180:183], v131 offset:49152
	ds_read_b128 v[184:187], v131 offset:50176
	ds_read_b128 v[188:191], v130 offset:49152
	ds_read_b128 v[130:133], v130 offset:50176
	s_barrier
	s_waitcnt lgkmcnt(0)
	v_mfma_f32_16x16x32_bf16 v[44:47], v[8:11], v[48:51], v[44:47]
	v_mfma_f32_16x16x32_bf16 v[40:43], v[176:179], v[48:51], v[40:43]
	v_mfma_f32_16x16x32_bf16 v[36:39], v[8:11], v[52:55], v[36:39]
	v_mfma_f32_16x16x32_bf16 v[32:35], v[176:179], v[52:55], v[32:35]
	v_mfma_f32_16x16x32_bf16 v[28:31], v[8:11], v[180:183], v[28:31]
	v_mfma_f32_16x16x32_bf16 v[24:27], v[176:179], v[180:183], v[24:27]
	v_mfma_f32_16x16x32_bf16 v[8:11], v[8:11], v[188:191], v[20:23]
	v_mfma_f32_16x16x32_bf16 v[16:19], v[176:179], v[188:191], v[16:19]
	v_mfma_f32_16x16x32_bf16 v[60:63], v[12:15], v[162:165], v[44:47]
	v_mfma_f32_16x16x32_bf16 v[56:59], v[138:141], v[162:165], v[40:43]
	v_mfma_f32_16x16x32_bf16 v[44:47], v[12:15], v[166:169], v[36:39]
	v_mfma_f32_16x16x32_bf16 v[40:43], v[138:141], v[166:169], v[32:35]
	v_mfma_f32_16x16x32_bf16 v[28:31], v[12:15], v[184:187], v[28:31]
	v_mfma_f32_16x16x32_bf16 v[24:27], v[138:141], v[184:187], v[24:27]
	v_mfma_f32_16x16x32_bf16 v[12:15], v[12:15], v[130:133], v[8:11]
	v_mfma_f32_16x16x32_bf16 v[8:11], v[138:141], v[130:133], v[16:19]
	v_mfma_f32_16x16x32_bf16 v[16:19], v[204:207], v[48:51], v[142:145]
	v_mfma_f32_16x16x32_bf16 v[20:23], v[212:215], v[48:51], v[146:149]
	v_mfma_f32_16x16x32_bf16 v[4:7], v[204:207], v[52:55], v[4:7]
	v_mfma_f32_16x16x32_bf16 v[0:3], v[212:215], v[52:55], v[0:3]
	v_mfma_f32_16x16x32_bf16 v[138:141], v[204:207], v[180:183], v[150:153]
	v_mfma_f32_16x16x32_bf16 v[142:145], v[212:215], v[180:183], v[154:157]
	v_mfma_f32_16x16x32_bf16 v[146:149], v[204:207], v[188:191], v[158:161]
	v_mfma_f32_16x16x32_bf16 v[150:153], v[212:215], v[188:191], v[172:175]
	v_mfma_f32_16x16x32_bf16 v[52:55], v[208:211], v[162:165], v[16:19]
	v_mfma_f32_16x16x32_bf16 v[48:51], v[134:137], v[162:165], v[20:23]
	v_mfma_f32_16x16x32_bf16 v[36:39], v[208:211], v[166:169], v[4:7]
	v_mfma_f32_16x16x32_bf16 v[32:35], v[134:137], v[166:169], v[0:3]
	v_mfma_f32_16x16x32_bf16 v[20:23], v[208:211], v[184:187], v[138:141]
	v_mfma_f32_16x16x32_bf16 v[16:19], v[134:137], v[184:187], v[142:145]
	v_mfma_f32_16x16x32_bf16 v[4:7], v[208:211], v[130:133], v[146:149]
	v_mfma_f32_16x16x32_bf16 v[0:3], v[134:137], v[130:133], v[150:153]
	v_cmp_gt_u32_e32 vcc, s73, v128
	s_barrier
	s_and_saveexec_b64 s[6:7], vcc
	s_cbranch_execz .LBB0_660
	s_barrier

; #define WAIT_V(n) asm volatile("s_waitcnt vmcnt(" #n ")" ::: "memory")
; #define BAR __builtin_amdgcn_s_barrier()
;     ...
;     const int tid = opaque_tid(wave);
;     const int wid = tid >> 6, lane = tid & 63, wr = wid >> 2, wc = wid & 3, fr = lane & 15, fq = lane >> 4;
;     int offA[2], offB[2];
;     _Pragma("unroll") for (int i = 0; i < 2; ++i) {
;       int r, c; stage_rc(tid * 16 + i * 8192, r, c);
;       offA[i] = (r * lda + c) * 2; offB[i] = (r * ldb + c) * 2;
;     }
;     const int brow = pm * BM;
;     f32x4 acc[2][2][4][2];
;     _Pragma("unroll") for (int a = 0; a < 2; ++a) _Pragma("unroll") for (int b = 0; b < 2; ++b) _Pragma("unroll") for (int m = 0; m < 4; ++m) _Pragma("unroll") for (int n = 0; n < 2; ++n)
;       acc[a][b][m][n] = f32x4{0.f, 0.f, 0.f, 0.f};
;     bf16x8 At[4][2], B0[2][2], B1[2][2];
;     if (wr == 1) BAR;
;     if (first_tile) { WAIT_V(0); }
;     else if constexpr (mode == MODE_RESID_LN) { WAIT_V(0); }
;     else if constexpr (mode == MODE_SWIGLU) { WAIT_V(6); }
;     else if constexpr (mode == MODE_V) { WAIT_V(24); }
;     else { WAIT_V(12); }
;     first_tile = false;
;     BAR;
;     BAR;
.LBB0_756:
	v_bfe_i32 v4, v128, 27, 1
	v_lshlrev_b32_e32 v2, 4, v128
	v_lshrrev_b32_e32 v4, 22, v4
	v_add_u32_e32 v4, v2, v4
	v_and_b32_e32 v4, 0xfffffc00, v4
	v_sub_u32_e32 v4, v2, v4
	v_lshrrev_b32_e32 v5, 4, v4
	v_bitop3_b32 v4, v5, v4, 32 bitop3:0x6c
	v_ashrrev_i32_e32 v3, 31, v128
	v_ashrrev_i32_e32 v6, 31, v4
	v_lshrrev_b32_e32 v3, 26, v3
	v_lshrrev_b32_e32 v6, 26, v6
	v_add_u32_e32 v3, v128, v3
	v_add_u32_e32 v6, v4, v6
	v_ashrrev_i32_e32 v3, 6, v3
	v_lshrrev_b32_e32 v7, 6, v6
	v_and_b32_e32 v6, 0xc0, v6
	v_lshlrev_b32_e32 v5, 3, v3
	v_lshlrev_b32_e32 v3, 5, v3
	v_sub_u32_e32 v4, v4, v6
	v_and_b32_e32 v5, 0x7fff0, v5
	v_and_b32_e32 v3, 32, v3
	v_ashrrev_i16_sdwa v4, v216, sext(v4) dst_sel:DWORD dst_unused:UNUSED_PAD src0_sel:DWORD src1_sel:BYTE_0
	v_add_u32_sdwa v3, v3, sext(v4) dst_sel:DWORD dst_unused:UNUSED_PAD src0_sel:DWORD src1_sel:WORD_0
	v_add_lshl_u32 v4, v7, v5, 13
	v_add_u32_e32 v2, 0x2000, v2
	v_lshl_add_u32 v141, v3, 1, v4
	v_ashrrev_i32_e32 v3, 31, v2
	v_lshrrev_b32_e32 v3, 22, v3
	v_add_u32_e32 v3, v2, v3
	v_ashrrev_i32_e32 v3, 10, v3
	v_mul_i32_i24_e32 v4, 0x400, v3
	v_sub_u32_e32 v2, v2, v4
	v_lshrrev_b32_e32 v4, 4, v2
	v_bitop3_b32 v2, v4, v2, 32 bitop3:0x6c
	v_ashrrev_i32_e32 v5, 31, v2
	v_lshrrev_b32_e32 v5, 26, v5
	v_add_u32_e32 v5, v2, v5
	v_lshrrev_b32_e32 v6, 6, v5
	v_and_b32_e32 v5, 0xc0, v5
	v_lshlrev_b32_e32 v4, 3, v3
	v_lshlrev_b32_e32 v3, 5, v3
	v_sub_u32_e32 v2, v2, v5
	v_and_b32_e32 v4, 0x7fff0, v4
	v_and_b32_e32 v3, 32, v3
	v_ashrrev_i16_sdwa v2, v216, sext(v2) dst_sel:DWORD dst_unused:UNUSED_PAD src0_sel:DWORD src1_sel:BYTE_0
	v_add_u32_sdwa v2, v3, sext(v2) dst_sel:DWORD dst_unused:UNUSED_PAD src0_sel:DWORD src1_sel:WORD_0
	v_add_lshl_u32 v3, v6, v4, 13
	v_lshl_add_u32 v142, v2, 1, v3
	v_and_b32_e32 v3, 15, v0
	v_lshlrev_b32_e32 v5, 2, v0
	v_and_b32_e32 v2, 48, v0
	v_lshlrev_b32_e32 v3, 6, v3
	v_and_b32_e32 v5, 32, v5
	v_lshlrev_b32_e32 v0, 6, v0
	v_or_b32_e32 v4, v3, v2
	v_bitop3_b32 v3, v3, v5, v2 bitop3:0x36
	v_lshlrev_b32_e32 v6, 6, v128
	v_lshlrev_b32_e32 v1, 13, v1
	v_and_or_b32 v0, v0, s72, v2
	v_and_or_b32 v3, v6, s71, v3
	v_bitop3_b32 v0, v1, v0, v5 bitop3:0xf6
	v_or_b32_e32 v6, 0x400, v3
	v_or_b32_e32 v7, 0x800, v3
	v_or_b32_e32 v8, 0xc00, v3
	v_or_b32_e32 v132, 0x800, v0
	v_or_b32_e32 v131, 0x1000, v0
	v_or_b32_e32 v130, 0x1800, v0
	v_mov_b32_e32 v0, 0
	v_bitop3_b32 v129, v4, v1, v5 bitop3:0xde
	s_mov_b32 s4, -2
	s_mov_b32 s5, 0
	v_or_b32_e32 v147, 0x10000, v3
	v_or_b32_e32 v148, 0x10000, v6
	v_or_b32_e32 v149, 0x10000, v7
	v_or_b32_e32 v150, 0x10000, v8
	v_or_b32_e32 v143, 0x14000, v3
	v_or_b32_e32 v144, 0x14000, v6
	v_or_b32_e32 v145, 0x14000, v7
	v_or_b32_e32 v146, 0x14000, v8
	v_or_b32_e32 v137, 0x18000, v3
	v_or_b32_e32 v138, 0x18000, v6
	v_or_b32_e32 v139, 0x18000, v7
	v_or_b32_e32 v140, 0x18000, v8
	v_or_b32_e32 v133, 0x1c000, v3
	v_or_b32_e32 v134, 0x1c000, v6
	v_or_b32_e32 v135, 0x1c000, v7
	v_or_b32_e32 v136, 0x1c000, v8
	v_mov_b32_e32 v1, v0
	v_mov_b32_e32 v2, v0
	v_mov_b32_e32 v3, v0
	v_mov_b32_e32 v4, v0
	v_mov_b32_e32 v5, v0
	v_mov_b32_e32 v6, v0
	v_mov_b32_e32 v7, v0
	v_mov_b32_e32 v8, v0
	v_mov_b32_e32 v9, v0
	v_mov_b32_e32 v10, v0
	v_mov_b32_e32 v11, v0
	v_mov_b32_e32 v12, v0
	v_mov_b32_e32 v13, v0
	v_mov_b32_e32 v14, v0
	v_mov_b32_e32 v15, v0
	v_mov_b32_e32 v16, v0
	v_mov_b32_e32 v17, v0
	v_mov_b32_e32 v18, v0
	v_mov_b32_e32 v19, v0
	v_mov_b32_e32 v20, v0
	v_mov_b32_e32 v21, v0
	v_mov_b32_e32 v22, v0
	v_mov_b32_e32 v23, v0
	v_mov_b32_e32 v24, v0
	v_mov_b32_e32 v25, v0
	v_mov_b32_e32 v26, v0
	v_mov_b32_e32 v27, v0
	v_mov_b32_e32 v28, v0
	v_mov_b32_e32 v29, v0
	v_mov_b32_e32 v30, v0
	v_mov_b32_e32 v31, v0
	v_mov_b32_e32 v32, v0
	v_mov_b32_e32 v33, v0
	v_mov_b32_e32 v34, v0
	v_mov_b32_e32 v35, v0
	v_mov_b32_e32 v36, v0
	v_mov_b32_e32 v37, v0
	v_mov_b32_e32 v38, v0
	v_mov_b32_e32 v39, v0
	v_mov_b32_e32 v40, v0
	v_mov_b32_e32 v41, v0
	v_mov_b32_e32 v42, v0
	v_mov_b32_e32 v43, v0
	v_mov_b32_e32 v44, v0
	v_mov_b32_e32 v45, v0
	v_mov_b32_e32 v46, v0
	v_mov_b32_e32 v47, v0
	v_mov_b32_e32 v48, v0
	v_mov_b32_e32 v49, v0
	v_mov_b32_e32 v50, v0
	v_mov_b32_e32 v51, v0
	v_mov_b32_e32 v52, v0
	v_mov_b32_e32 v53, v0
	v_mov_b32_e32 v54, v0
	v_mov_b32_e32 v55, v0
	v_mov_b32_e32 v56, v0
	v_mov_b32_e32 v57, v0
	v_mov_b32_e32 v58, v0
	v_mov_b32_e32 v59, v0
	v_mov_b32_e32 v60, v0
	v_mov_b32_e32 v61, v0
	v_mov_b32_e32 v62, v0
	v_mov_b32_e32 v63, v0
	v_mov_b32_e32 v68, v0
	v_mov_b32_e32 v69, v0
	v_mov_b32_e32 v70, v0
	v_mov_b32_e32 v71, v0
	v_mov_b32_e32 v80, v0
	v_mov_b32_e32 v81, v0
	v_mov_b32_e32 v82, v0
	v_mov_b32_e32 v83, v0
	v_mov_b32_e32 v88, v0
	v_mov_b32_e32 v89, v0
	v_mov_b32_e32 v90, v0
	v_mov_b32_e32 v91, v0
	v_mov_b32_e32 v92, v0
	v_mov_b32_e32 v93, v0
	v_mov_b32_e32 v94, v0
	v_mov_b32_e32 v95, v0
	v_mov_b32_e32 v96, v0
	v_mov_b32_e32 v97, v0
	v_mov_b32_e32 v98, v0
	v_mov_b32_e32 v99, v0
	v_mov_b32_e32 v100, v0
	v_mov_b32_e32 v101, v0
	v_mov_b32_e32 v102, v0
	v_mov_b32_e32 v103, v0
	v_mov_b32_e32 v104, v0
	v_mov_b32_e32 v105, v0
	v_mov_b32_e32 v106, v0
	v_mov_b32_e32 v107, v0
	v_mov_b32_e32 v108, v0
	v_mov_b32_e32 v109, v0
	v_mov_b32_e32 v110, v0
	v_mov_b32_e32 v111, v0
	v_mov_b32_e32 v112, v0
	v_mov_b32_e32 v113, v0
	v_mov_b32_e32 v114, v0
	v_mov_b32_e32 v115, v0
	v_mov_b32_e32 v116, v0
	v_mov_b32_e32 v117, v0
	v_mov_b32_e32 v118, v0
	v_mov_b32_e32 v119, v0
	v_mov_b32_e32 v120, v0
	v_mov_b32_e32 v121, v0
	v_mov_b32_e32 v122, v0
	v_mov_b32_e32 v123, v0
	v_mov_b32_e32 v124, v0
	v_mov_b32_e32 v125, v0
	v_mov_b32_e32 v126, v0
	v_mov_b32_e32 v127, v0
	v_mov_b32_e32 v64, v0
	v_mov_b32_e32 v65, v0
	v_mov_b32_e32 v66, v0
	v_mov_b32_e32 v67, v0
	v_mov_b32_e32 v72, v0
	v_mov_b32_e32 v73, v0
	v_mov_b32_e32 v74, v0
	v_mov_b32_e32 v75, v0
	v_mov_b32_e32 v76, v0
	v_mov_b32_e32 v77, v0
	v_mov_b32_e32 v78, v0
	v_mov_b32_e32 v79, v0
	v_mov_b32_e32 v84, v0
	v_mov_b32_e32 v85, v0
	v_mov_b32_e32 v86, v0
	v_mov_b32_e32 v87, v0
	s_barrier
	s_barrier
	s_branch .Lmy_rot_757

; #define STAGE(P, RS, SOFF, OFF, kt) do { const int _so = (SOFF) + (kt) * (BK * 2); \
;     _Pragma("unroll") for (int _i = 0; _i < 2; ++_i) { \
;       __builtin_amdgcn_raw_ptr_buffer_load_lds(RS, (__attribute__((address_space(3))) void*)((P) + wave * 1024 + _i * 8192), 16, OFF[_i], _so, 0, 0); } } while (0)
; #define LDA(dst, b, h) _Pragma("unroll") for (int m = 0; m < 4; ++m) _Pragma("unroll") for (int k = 0; k < 2; ++k) \
;     dst[m][k] = *reinterpret_cast<const bf16x8*>(SA(b, h) + lds_byte(wr * 64 + m * 16 + fr, k * 32 + fq * 8))
; #define LDB(dst, b, h) _Pragma("unroll") for (int n = 0; n < 2; ++n) _Pragma("unroll") for (int k = 0; k < 2; ++k) \
;     dst[n][k] = *reinterpret_cast<const bf16x8*>(SB(b, h) + lds_byte(wc * 32 + n * 16 + fr, k * 32 + fq * 8))
; #define WAIT_V(n) asm volatile("s_waitcnt vmcnt(" #n ")" ::: "memory")
; #define WAIT_L(n) asm volatile("s_waitcnt lgkmcnt(" #n ")" ::: "memory")
; #define BAR __builtin_amdgcn_s_barrier()
; #define SCHED __builtin_amdgcn_sched_barrier(0)
;     ...
;       LDB(B0, 0, 0); SCHED; LDA(At, 0, 0); STAGE(SA(1, 1), rsA, sA1, offA, t + 1);
;       WAIT_L(8); BAR; WAIT_L(0); MMA(0, 0, At, B0); BAR; SCHED;
;       LDB(B1, 0, 1); STAGE(SB(0, 0), rsB, sB0, offB, t + 2);
;       BAR; WAIT_L(0); MMA(0, 1, At, B1); BAR;
;       LDA(At, 0, 1); STAGE(SA(0, 0), rsA, sA0, offA, t + 2);
;       BAR; WAIT_L(0); MMA(1, 0, At, B0); BAR; SCHED;
;       STAGE(SB(0, 1), rsB, sB1, offB, t + 2);
;       WAIT_V(6); BAR; MMA(1, 1, At, B1); BAR;
.Lmy_rot_757:
	ds_read_b128 v[152:155], v147
	ds_read_b128 v[156:159], v148
	ds_read_b128 v[160:163], v149
	ds_read_b128 v[164:167], v150
	s_add_i32 s6, s85, s5
	s_add_i32 s7, s6, 0x80
	s_mov_b32 m0, s39
	ds_read_b128 v[168:171], v129
	ds_read_b128 v[172:175], v129 offset:1024
	ds_read_b128 v[176:179], v132
	ds_read_b128 v[180:183], v132 offset:1024
	ds_read_b128 v[184:187], v131
	ds_read_b128 v[188:191], v131 offset:1024
	ds_read_b128 v[192:195], v130
	ds_read_b128 v[196:199], v130 offset:1024
	buffer_load_dwordx4 v141, s[8:11], s7 offen lds
	s_mov_b32 m0, s56
	s_nop 0
	buffer_load_dwordx4 v142, s[8:11], s7 offen lds
	s_waitcnt lgkmcnt(8)
	s_barrier
	s_waitcnt lgkmcnt(0)
	v_mfma_f32_16x16x32_bf16 v[124:127], v[152:155], v[168:171], v[124:127]
	v_mfma_f32_16x16x32_bf16 v[124:127], v[156:159], v[172:175], v[124:127]
	v_mfma_f32_16x16x32_bf16 v[120:123], v[160:163], v[168:171], v[120:123]
	v_mfma_f32_16x16x32_bf16 v[120:123], v[164:167], v[172:175], v[120:123]
	v_mfma_f32_16x16x32_bf16 v[116:119], v[152:155], v[176:179], v[116:119]
	v_mfma_f32_16x16x32_bf16 v[116:119], v[156:159], v[180:183], v[116:119]
	v_mfma_f32_16x16x32_bf16 v[112:115], v[160:163], v[176:179], v[112:115]
	v_mfma_f32_16x16x32_bf16 v[112:115], v[164:167], v[180:183], v[112:115]
	v_mfma_f32_16x16x32_bf16 v[108:111], v[152:155], v[184:187], v[108:111]
	v_mfma_f32_16x16x32_bf16 v[108:111], v[156:159], v[188:191], v[108:111]
	v_mfma_f32_16x16x32_bf16 v[104:107], v[160:163], v[184:187], v[104:107]
	v_mfma_f32_16x16x32_bf16 v[104:107], v[164:167], v[188:191], v[104:107]
	v_mfma_f32_16x16x32_bf16 v[100:103], v[152:155], v[192:195], v[100:103]
	v_mfma_f32_16x16x32_bf16 v[100:103], v[156:159], v[196:199], v[100:103]
	v_mfma_f32_16x16x32_bf16 v[96:99], v[160:163], v[192:195], v[96:99]
	v_mfma_f32_16x16x32_bf16 v[96:99], v[164:167], v[196:199], v[96:99]
	s_barrier
	s_add_i32 s7, s87, s5
	s_add_i32 s23, s7, 0x100
	s_mov_b32 s14, s10
	s_mov_b32 s15, s11
	s_mov_b32 m0, s42
	ds_read_b128 v[200:203], v143
	ds_read_b128 v[204:207], v144
	ds_read_b128 v[208:211], v145
	ds_read_b128 v[212:215], v146
	buffer_load_dwordx4 v141, s[12:15], s23 offen lds
	s_mov_b32 m0, s49
	s_nop 0
	buffer_load_dwordx4 v142, s[12:15], s23 offen lds
	s_barrier
	s_waitcnt lgkmcnt(0)
	v_mfma_f32_16x16x32_bf16 v[92:95], v[200:203], v[168:171], v[92:95]
	v_mfma_f32_16x16x32_bf16 v[92:95], v[204:207], v[172:175], v[92:95]
	v_mfma_f32_16x16x32_bf16 v[88:91], v[208:211], v[168:171], v[88:91]
	v_mfma_f32_16x16x32_bf16 v[88:91], v[212:215], v[172:175], v[88:91]
	v_mfma_f32_16x16x32_bf16 v[80:83], v[200:203], v[176:179], v[80:83]
	v_mfma_f32_16x16x32_bf16 v[80:83], v[204:207], v[180:183], v[80:83]
	v_mfma_f32_16x16x32_bf16 v[68:71], v[208:211], v[176:179], v[68:71]
	v_mfma_f32_16x16x32_bf16 v[68:71], v[212:215], v[180:183], v[68:71]
	v_mfma_f32_16x16x32_bf16 v[60:63], v[200:203], v[184:187], v[60:63]
	v_mfma_f32_16x16x32_bf16 v[60:63], v[204:207], v[188:191], v[60:63]
	v_mfma_f32_16x16x32_bf16 v[56:59], v[208:211], v[184:187], v[56:59]
	v_mfma_f32_16x16x32_bf16 v[56:59], v[212:215], v[188:191], v[56:59]
	v_mfma_f32_16x16x32_bf16 v[52:55], v[200:203], v[192:195], v[52:55]
	v_mfma_f32_16x16x32_bf16 v[52:55], v[204:207], v[196:199], v[52:55]
	v_mfma_f32_16x16x32_bf16 v[48:51], v[208:211], v[192:195], v[48:51]
	v_mfma_f32_16x16x32_bf16 v[48:51], v[212:215], v[196:199], v[48:51]
	s_barrier
	s_add_i32 s23, s86, s5
	s_add_i32 s26, s23, 0x100
	s_mov_b32 m0, s33
	ds_read_b128 v[168:171], v129 offset:16384
	ds_read_b128 v[172:175], v129 offset:17408
	ds_read_b128 v[176:179], v132 offset:16384
	ds_read_b128 v[180:183], v132 offset:17408
	ds_read_b128 v[184:187], v131 offset:16384
	ds_read_b128 v[188:191], v131 offset:17408
	ds_read_b128 v[192:195], v130 offset:16384
	ds_read_b128 v[196:199], v130 offset:17408
	buffer_load_dwordx4 v141, s[8:11], s26 offen lds
	s_mov_b32 m0, s50
	s_nop 0
	buffer_load_dwordx4 v142, s[8:11], s26 offen lds
	s_barrier
	s_waitcnt lgkmcnt(0)
	v_mfma_f32_16x16x32_bf16 v[44:47], v[152:155], v[168:171], v[44:47]
	v_mfma_f32_16x16x32_bf16 v[44:47], v[156:159], v[172:175], v[44:47]
	v_mfma_f32_16x16x32_bf16 v[40:43], v[160:163], v[168:171], v[40:43]
	v_mfma_f32_16x16x32_bf16 v[40:43], v[164:167], v[172:175], v[40:43]
	v_mfma_f32_16x16x32_bf16 v[36:39], v[152:155], v[176:179], v[36:39]
	v_mfma_f32_16x16x32_bf16 v[36:39], v[156:159], v[180:183], v[36:39]
	v_mfma_f32_16x16x32_bf16 v[32:35], v[160:163], v[176:179], v[32:35]
	v_mfma_f32_16x16x32_bf16 v[32:35], v[164:167], v[180:183], v[32:35]
	v_mfma_f32_16x16x32_bf16 v[28:31], v[152:155], v[184:187], v[28:31]
	v_mfma_f32_16x16x32_bf16 v[28:31], v[156:159], v[188:191], v[28:31]
	v_mfma_f32_16x16x32_bf16 v[24:27], v[160:163], v[184:187], v[24:27]
	v_mfma_f32_16x16x32_bf16 v[24:27], v[164:167], v[188:191], v[24:27]
	v_mfma_f32_16x16x32_bf16 v[20:23], v[152:155], v[192:195], v[20:23]
	v_mfma_f32_16x16x32_bf16 v[20:23], v[156:159], v[196:199], v[20:23]
	v_mfma_f32_16x16x32_bf16 v[16:19], v[160:163], v[192:195], v[16:19]
	v_mfma_f32_16x16x32_bf16 v[16:19], v[164:167], v[196:199], v[16:19]
	s_barrier
	s_add_i32 s26, s90, s5
	s_add_i32 s27, s26, 0x100
	s_mov_b32 m0, s43
	s_nop 0
	buffer_load_dwordx4 v141, s[12:15], s27 offen lds
	s_mov_b32 m0, s51
	s_nop 0
	buffer_load_dwordx4 v142, s[12:15], s27 offen lds
	s_waitcnt vmcnt(6)
	s_barrier
; #define STAGE(P, RS, SOFF, OFF, kt) do { const int _so = (SOFF) + (kt) * (BK * 2); \
;     _Pragma("unroll") for (int _i = 0; _i < 2; ++_i) { \
;       __builtin_amdgcn_raw_ptr_buffer_load_lds(RS, (__attribute__((address_space(3))) void*)((P) + wave * 1024 + _i * 8192), 16, OFF[_i], _so, 0, 0); } } while (0)
; #define LDA(dst, b, h) _Pragma("unroll") for (int m = 0; m < 4; ++m) _Pragma("unroll") for (int k = 0; k < 2; ++k) \
;     dst[m][k] = *reinterpret_cast<const bf16x8*>(SA(b, h) + lds_byte(wr * 64 + m * 16 + fr, k * 32 + fq * 8))
; #define LDB(dst, b, h) _Pragma("unroll") for (int n = 0; n < 2; ++n) _Pragma("unroll") for (int k = 0; k < 2; ++k) \
;     dst[n][k] = *reinterpret_cast<const bf16x8*>(SB(b, h) + lds_byte(wc * 32 + n * 16 + fr, k * 32 + fq * 8))
; #define WAIT_V(n) asm volatile("s_waitcnt vmcnt(" #n ")" ::: "memory")
; #define WAIT_L(n) asm volatile("s_waitcnt lgkmcnt(" #n ")" ::: "memory")
; #define BAR __builtin_amdgcn_s_barrier()
; #define SCHED __builtin_amdgcn_sched_barrier(0)
;     ...
;       WAIT_V(6); BAR; MMA(1, 1, At, B1); BAR;
;       LDB(B0, 1, 0); SCHED; LDA(At, 1, 0); STAGE(SA(0, 1), rsA, sA1, offA, t + 2);
;       WAIT_L(8); BAR; WAIT_L(0); MMA(0, 0, At, B0); BAR; SCHED;
;       LDB(B1, 1, 1); STAGE(SB(1, 0), rsB, sB0, offB, t + 3);
;       BAR; WAIT_L(0); MMA(0, 1, At, B1); BAR;
;       LDA(At, 1, 1); STAGE(SA(1, 0), rsA, sA0, offA, t + 3);
;       BAR; WAIT_L(0); MMA(1, 0, At, B0); BAR; SCHED;
	v_mfma_f32_16x16x32_bf16 v[12:15], v[200:203], v[168:171], v[12:15]
	v_mfma_f32_16x16x32_bf16 v[12:15], v[204:207], v[172:175], v[12:15]
	v_mfma_f32_16x16x32_bf16 v[8:11], v[208:211], v[168:171], v[8:11]
	v_mfma_f32_16x16x32_bf16 v[8:11], v[212:215], v[172:175], v[8:11]
	v_mfma_f32_16x16x32_bf16 v[4:7], v[200:203], v[176:179], v[4:7]
	v_mfma_f32_16x16x32_bf16 v[4:7], v[204:207], v[180:183], v[4:7]
	v_mfma_f32_16x16x32_bf16 v[0:3], v[208:211], v[176:179], v[0:3]
	v_mfma_f32_16x16x32_bf16 v[0:3], v[212:215], v[180:183], v[0:3]
	v_mfma_f32_16x16x32_bf16 v[64:67], v[200:203], v[184:187], v[64:67]
	v_mfma_f32_16x16x32_bf16 v[64:67], v[204:207], v[188:191], v[64:67]
	v_mfma_f32_16x16x32_bf16 v[72:75], v[208:211], v[184:187], v[72:75]
	v_mfma_f32_16x16x32_bf16 v[72:75], v[212:215], v[188:191], v[72:75]
	v_mfma_f32_16x16x32_bf16 v[76:79], v[200:203], v[192:195], v[76:79]
	v_mfma_f32_16x16x32_bf16 v[76:79], v[204:207], v[196:199], v[76:79]
	v_mfma_f32_16x16x32_bf16 v[84:87], v[208:211], v[192:195], v[84:87]
	v_mfma_f32_16x16x32_bf16 v[84:87], v[212:215], v[196:199], v[84:87]
	s_barrier
	ds_read_b128 v[152:155], v137
	ds_read_b128 v[156:159], v138
	ds_read_b128 v[160:163], v139
	ds_read_b128 v[164:167], v140
	s_addk_i32 s6, 0x100
	s_mov_b32 m0, s44
	ds_read_b128 v[168:171], v129 offset:32768
	ds_read_b128 v[172:175], v129 offset:33792
	ds_read_b128 v[176:179], v132 offset:32768
	ds_read_b128 v[180:183], v132 offset:33792
	ds_read_b128 v[184:187], v131 offset:32768
	ds_read_b128 v[188:191], v131 offset:33792
	ds_read_b128 v[192:195], v130 offset:32768
	ds_read_b128 v[196:199], v130 offset:33792
	buffer_load_dwordx4 v141, s[8:11], s6 offen lds
	s_mov_b32 m0, s52
	s_nop 0
	buffer_load_dwordx4 v142, s[8:11], s6 offen lds
	s_waitcnt lgkmcnt(8)
	s_barrier
	s_waitcnt lgkmcnt(0)
	v_mfma_f32_16x16x32_bf16 v[124:127], v[152:155], v[168:171], v[124:127]
	v_mfma_f32_16x16x32_bf16 v[124:127], v[156:159], v[172:175], v[124:127]
	v_mfma_f32_16x16x32_bf16 v[120:123], v[160:163], v[168:171], v[120:123]
	v_mfma_f32_16x16x32_bf16 v[120:123], v[164:167], v[172:175], v[120:123]
	v_mfma_f32_16x16x32_bf16 v[116:119], v[152:155], v[176:179], v[116:119]
	v_mfma_f32_16x16x32_bf16 v[116:119], v[156:159], v[180:183], v[116:119]
	v_mfma_f32_16x16x32_bf16 v[112:115], v[160:163], v[176:179], v[112:115]
	v_mfma_f32_16x16x32_bf16 v[112:115], v[164:167], v[180:183], v[112:115]
	v_mfma_f32_16x16x32_bf16 v[108:111], v[152:155], v[184:187], v[108:111]
	v_mfma_f32_16x16x32_bf16 v[108:111], v[156:159], v[188:191], v[108:111]
	v_mfma_f32_16x16x32_bf16 v[104:107], v[160:163], v[184:187], v[104:107]
	v_mfma_f32_16x16x32_bf16 v[104:107], v[164:167], v[188:191], v[104:107]
	v_mfma_f32_16x16x32_bf16 v[100:103], v[152:155], v[192:195], v[100:103]
	v_mfma_f32_16x16x32_bf16 v[100:103], v[156:159], v[196:199], v[100:103]
	v_mfma_f32_16x16x32_bf16 v[96:99], v[160:163], v[192:195], v[96:99]
	v_mfma_f32_16x16x32_bf16 v[96:99], v[164:167], v[196:199], v[96:99]
	s_barrier
	s_addk_i32 s7, 0x180
	s_mov_b32 m0, s45
	ds_read_b128 v[200:203], v133
	ds_read_b128 v[204:207], v134
	ds_read_b128 v[208:211], v135
	ds_read_b128 v[212:215], v136
	buffer_load_dwordx4 v141, s[12:15], s7 offen lds
	s_mov_b32 m0, s53
	s_nop 0
	buffer_load_dwordx4 v142, s[12:15], s7 offen lds
	s_barrier
	s_waitcnt lgkmcnt(0)
	v_mfma_f32_16x16x32_bf16 v[92:95], v[200:203], v[168:171], v[92:95]
	v_mfma_f32_16x16x32_bf16 v[92:95], v[204:207], v[172:175], v[92:95]
	v_mfma_f32_16x16x32_bf16 v[88:91], v[208:211], v[168:171], v[88:91]
	v_mfma_f32_16x16x32_bf16 v[88:91], v[212:215], v[172:175], v[88:91]
	v_mfma_f32_16x16x32_bf16 v[80:83], v[200:203], v[176:179], v[80:83]
	v_mfma_f32_16x16x32_bf16 v[80:83], v[204:207], v[180:183], v[80:83]
	v_mfma_f32_16x16x32_bf16 v[68:71], v[208:211], v[176:179], v[68:71]
	v_mfma_f32_16x16x32_bf16 v[68:71], v[212:215], v[180:183], v[68:71]
	v_mfma_f32_16x16x32_bf16 v[60:63], v[200:203], v[184:187], v[60:63]
	v_mfma_f32_16x16x32_bf16 v[60:63], v[204:207], v[188:191], v[60:63]
	v_mfma_f32_16x16x32_bf16 v[56:59], v[208:211], v[184:187], v[56:59]
	v_mfma_f32_16x16x32_bf16 v[56:59], v[212:215], v[188:191], v[56:59]
	v_mfma_f32_16x16x32_bf16 v[52:55], v[200:203], v[192:195], v[52:55]
	v_mfma_f32_16x16x32_bf16 v[52:55], v[204:207], v[196:199], v[52:55]
	v_mfma_f32_16x16x32_bf16 v[48:51], v[208:211], v[192:195], v[48:51]
	v_mfma_f32_16x16x32_bf16 v[48:51], v[212:215], v[196:199], v[48:51]
	s_barrier
	s_addk_i32 s23, 0x180
	s_mov_b32 m0, s46
	ds_read_b128 v[168:171], v129 offset:49152
	ds_read_b128 v[172:175], v129 offset:50176
	ds_read_b128 v[176:179], v132 offset:49152
	ds_read_b128 v[180:183], v132 offset:50176
	ds_read_b128 v[184:187], v131 offset:49152
	ds_read_b128 v[188:191], v131 offset:50176
	ds_read_b128 v[192:195], v130 offset:49152
	ds_read_b128 v[196:199], v130 offset:50176
	buffer_load_dwordx4 v141, s[8:11], s23 offen lds
	s_mov_b32 m0, s54
	s_nop 0
	buffer_load_dwordx4 v142, s[8:11], s23 offen lds
	s_barrier
	s_waitcnt lgkmcnt(0)
	v_mfma_f32_16x16x32_bf16 v[44:47], v[152:155], v[168:171], v[44:47]
	v_mfma_f32_16x16x32_bf16 v[44:47], v[156:159], v[172:175], v[44:47]
	v_mfma_f32_16x16x32_bf16 v[40:43], v[160:163], v[168:171], v[40:43]
	v_mfma_f32_16x16x32_bf16 v[40:43], v[164:167], v[172:175], v[40:43]
	v_mfma_f32_16x16x32_bf16 v[36:39], v[152:155], v[176:179], v[36:39]
	v_mfma_f32_16x16x32_bf16 v[36:39], v[156:159], v[180:183], v[36:39]
	v_mfma_f32_16x16x32_bf16 v[32:35], v[160:163], v[176:179], v[32:35]
	v_mfma_f32_16x16x32_bf16 v[32:35], v[164:167], v[180:183], v[32:35]
	v_mfma_f32_16x16x32_bf16 v[28:31], v[152:155], v[184:187], v[28:31]
	v_mfma_f32_16x16x32_bf16 v[28:31], v[156:159], v[188:191], v[28:31]
	v_mfma_f32_16x16x32_bf16 v[24:27], v[160:163], v[184:187], v[24:27]
	v_mfma_f32_16x16x32_bf16 v[24:27], v[164:167], v[188:191], v[24:27]
	v_mfma_f32_16x16x32_bf16 v[20:23], v[152:155], v[192:195], v[20:23]
	v_mfma_f32_16x16x32_bf16 v[20:23], v[156:159], v[196:199], v[20:23]
	v_mfma_f32_16x16x32_bf16 v[16:19], v[160:163], v[192:195], v[16:19]
	v_mfma_f32_16x16x32_bf16 v[16:19], v[164:167], v[196:199], v[16:19]
	s_barrier
; #define STAGE(P, RS, SOFF, OFF, kt) do { const int _so = (SOFF) + (kt) * (BK * 2); \
;     _Pragma("unroll") for (int _i = 0; _i < 2; ++_i) { \
;       __builtin_amdgcn_raw_ptr_buffer_load_lds(RS, (__attribute__((address_space(3))) void*)((P) + wave * 1024 + _i * 8192), 16, OFF[_i], _so, 0, 0); } } while (0)
; #define LDA(dst, b, h) _Pragma("unroll") for (int m = 0; m < 4; ++m) _Pragma("unroll") for (int k = 0; k < 2; ++k) \
;     dst[m][k] = *reinterpret_cast<const bf16x8*>(SA(b, h) + lds_byte(wr * 64 + m * 16 + fr, k * 32 + fq * 8))
; #define LDB(dst, b, h) _Pragma("unroll") for (int n = 0; n < 2; ++n) _Pragma("unroll") for (int k = 0; k < 2; ++k) \
;     dst[n][k] = *reinterpret_cast<const bf16x8*>(SB(b, h) + lds_byte(wc * 32 + n * 16 + fr, k * 32 + fq * 8))
; #define WAIT_V(n) asm volatile("s_waitcnt vmcnt(" #n ")" ::: "memory")
; #define WAIT_L(n) asm volatile("s_waitcnt lgkmcnt(" #n ")" ::: "memory")
; #define BAR __builtin_amdgcn_s_barrier()
;     ...
;       STAGE(SB(1, 1), rsB, sB1, offB, t + 3);
;       WAIT_V(6); BAR; MMA(1, 1, At, B1); BAR;
;     }
;     { LDB(B0, 0, 0); LDA(At, 0, 0); STAGE(SA(1, 1), rsA, sA1, offA, nt - 1);
;       BAR; WAIT_L(0); MMA(0, 0, At, B0); BAR;
;       LDB(B1, 0, 1); BAR; WAIT_L(0); MMA(0, 1, At, B1); BAR;
;       LDA(At, 0, 1); WAIT_V(4); BAR; WAIT_L(0); MMA(1, 0, At, B0); MMA(1, 1, At, B1); BAR; }
	s_addk_i32 s26, 0x180
	s_mov_b32 m0, s47
	s_nop 0
	buffer_load_dwordx4 v141, s[12:15], s26 offen lds
	s_mov_b32 m0, s55
	s_nop 0
	buffer_load_dwordx4 v142, s[12:15], s26 offen lds
	s_add_i32 s4, s4, 2
	s_addk_i32 s5, 0x100
	s_cmp_gt_u32 s4, 59
	s_cbranch_scc0 .LBB0_757
	s_waitcnt vmcnt(6)
	s_barrier
	v_mfma_f32_16x16x32_bf16 v[12:15], v[200:203], v[168:171], v[12:15]
	v_mfma_f32_16x16x32_bf16 v[12:15], v[204:207], v[172:175], v[12:15]
	v_mfma_f32_16x16x32_bf16 v[8:11], v[208:211], v[168:171], v[8:11]
	v_mfma_f32_16x16x32_bf16 v[8:11], v[212:215], v[172:175], v[8:11]
	v_mfma_f32_16x16x32_bf16 v[4:7], v[200:203], v[176:179], v[4:7]
	v_mfma_f32_16x16x32_bf16 v[4:7], v[204:207], v[180:183], v[4:7]
	v_mfma_f32_16x16x32_bf16 v[0:3], v[208:211], v[176:179], v[0:3]
	v_mfma_f32_16x16x32_bf16 v[0:3], v[212:215], v[180:183], v[0:3]
	v_mfma_f32_16x16x32_bf16 v[64:67], v[200:203], v[184:187], v[64:67]
	v_mfma_f32_16x16x32_bf16 v[64:67], v[204:207], v[188:191], v[64:67]
	v_mfma_f32_16x16x32_bf16 v[72:75], v[208:211], v[184:187], v[72:75]
	v_mfma_f32_16x16x32_bf16 v[72:75], v[212:215], v[188:191], v[72:75]
	v_mfma_f32_16x16x32_bf16 v[76:79], v[200:203], v[192:195], v[76:79]
	v_mfma_f32_16x16x32_bf16 v[76:79], v[204:207], v[196:199], v[76:79]
	v_mfma_f32_16x16x32_bf16 v[84:87], v[208:211], v[192:195], v[84:87]
	v_mfma_f32_16x16x32_bf16 v[84:87], v[212:215], v[196:199], v[84:87]
	s_barrier
	s_add_i32 s4, s85, 0x1f80
	s_mov_b32 m0, s39
	ds_read_b128 v[152:155], v147
	ds_read_b128 v[156:159], v148
	ds_read_b128 v[160:163], v149
	ds_read_b128 v[148:151], v150
	ds_read_b128 v[164:167], v129
	ds_read_b128 v[168:171], v129 offset:1024
	ds_read_b128 v[172:175], v132
	ds_read_b128 v[176:179], v132 offset:1024
	ds_read_b128 v[180:183], v131
	ds_read_b128 v[184:187], v131 offset:1024
	ds_read_b128 v[188:191], v130
	ds_read_b128 v[192:195], v130 offset:1024
	buffer_load_dwordx4 v141, s[8:11], s4 offen lds
	s_mov_b32 m0, s56
	s_nop 0
	buffer_load_dwordx4 v142, s[8:11], s4 offen lds
	s_barrier
	s_waitcnt lgkmcnt(0)
	v_mfma_f32_16x16x32_bf16 v[124:127], v[152:155], v[164:167], v[124:127]
	v_mfma_f32_16x16x32_bf16 v[124:127], v[156:159], v[168:171], v[124:127]
	v_mfma_f32_16x16x32_bf16 v[120:123], v[160:163], v[164:167], v[120:123]
	v_mfma_f32_16x16x32_bf16 v[120:123], v[148:151], v[168:171], v[120:123]
	v_mfma_f32_16x16x32_bf16 v[116:119], v[152:155], v[172:175], v[116:119]
	v_mfma_f32_16x16x32_bf16 v[116:119], v[156:159], v[176:179], v[116:119]
	v_mfma_f32_16x16x32_bf16 v[112:115], v[160:163], v[172:175], v[112:115]
	v_mfma_f32_16x16x32_bf16 v[112:115], v[148:151], v[176:179], v[112:115]
	v_mfma_f32_16x16x32_bf16 v[108:111], v[152:155], v[180:183], v[108:111]
	v_mfma_f32_16x16x32_bf16 v[108:111], v[156:159], v[184:187], v[108:111]
	v_mfma_f32_16x16x32_bf16 v[104:107], v[160:163], v[180:183], v[104:107]
	v_mfma_f32_16x16x32_bf16 v[104:107], v[148:151], v[184:187], v[104:107]
	v_mfma_f32_16x16x32_bf16 v[100:103], v[152:155], v[188:191], v[100:103]
	v_mfma_f32_16x16x32_bf16 v[100:103], v[156:159], v[192:195], v[100:103]
	v_mfma_f32_16x16x32_bf16 v[96:99], v[160:163], v[188:191], v[96:99]
	v_mfma_f32_16x16x32_bf16 v[96:99], v[148:151], v[192:195], v[96:99]
	s_barrier
	ds_read_b128 v[196:199], v143
	ds_read_b128 v[200:203], v144
	ds_read_b128 v[142:145], v145
	ds_read_b128 v[204:207], v146
	s_barrier
	s_waitcnt lgkmcnt(0)
	v_mfma_f32_16x16x32_bf16 v[88:91], v[142:145], v[164:167], v[88:91]
	v_mfma_f32_16x16x32_bf16 v[80:83], v[196:199], v[172:175], v[80:83]
	v_mfma_f32_16x16x32_bf16 v[60:63], v[196:199], v[180:183], v[60:63]
	v_mfma_f32_16x16x32_bf16 v[56:59], v[142:145], v[180:183], v[56:59]
	v_mfma_f32_16x16x32_bf16 v[52:55], v[196:199], v[188:191], v[52:55]
	v_mfma_f32_16x16x32_bf16 v[48:51], v[142:145], v[188:191], v[48:51]
	v_mfma_f32_16x16x32_bf16 v[92:95], v[196:199], v[164:167], v[92:95]
	v_mfma_f32_16x16x32_bf16 v[68:71], v[142:145], v[172:175], v[68:71]
	v_mfma_f32_16x16x32_bf16 v[88:91], v[204:207], v[168:171], v[88:91]
	v_mfma_f32_16x16x32_bf16 v[80:83], v[200:203], v[176:179], v[80:83]
	v_mfma_f32_16x16x32_bf16 v[60:63], v[200:203], v[184:187], v[60:63]
	v_mfma_f32_16x16x32_bf16 v[56:59], v[204:207], v[184:187], v[56:59]
	v_mfma_f32_16x16x32_bf16 v[52:55], v[200:203], v[192:195], v[52:55]
	v_mfma_f32_16x16x32_bf16 v[48:51], v[204:207], v[192:195], v[48:51]
	v_mfma_f32_16x16x32_bf16 v[164:167], v[200:203], v[168:171], v[92:95]
	v_mfma_f32_16x16x32_bf16 v[168:171], v[204:207], v[176:179], v[68:71]
	s_barrier
	s_nop 0
	ds_read_b128 v[68:71], v129 offset:16384
	ds_read_b128 v[92:95], v129 offset:17408
	ds_read_b128 v[172:175], v132 offset:16384
	ds_read_b128 v[176:179], v132 offset:17408
	ds_read_b128 v[180:183], v131 offset:16384
	ds_read_b128 v[184:187], v131 offset:17408
	ds_read_b128 v[188:191], v130 offset:16384
	ds_read_b128 v[192:195], v130 offset:17408
	s_waitcnt vmcnt(4)
	s_barrier
; #define LDA(dst, b, h) _Pragma("unroll") for (int m = 0; m < 4; ++m) _Pragma("unroll") for (int k = 0; k < 2; ++k) \
;     dst[m][k] = *reinterpret_cast<const bf16x8*>(SA(b, h) + lds_byte(wr * 64 + m * 16 + fr, k * 32 + fq * 8))
; #define LDB(dst, b, h) _Pragma("unroll") for (int n = 0; n < 2; ++n) _Pragma("unroll") for (int k = 0; k < 2; ++k) \
;     dst[n][k] = *reinterpret_cast<const bf16x8*>(SB(b, h) + lds_byte(wc * 32 + n * 16 + fr, k * 32 + fq * 8))
; #define WAIT_V(n) asm volatile("s_waitcnt vmcnt(" #n ")" ::: "memory")
; #define WAIT_L(n) asm volatile("s_waitcnt lgkmcnt(" #n ")" ::: "memory")
; #define BAR __builtin_amdgcn_s_barrier()
;     ...
;       LDA(At, 0, 1); WAIT_V(4); BAR; WAIT_L(0); MMA(1, 0, At, B0); MMA(1, 1, At, B1); BAR; }
;     { LDB(B0, 1, 0); LDA(At, 1, 0); WAIT_V(2); BAR; WAIT_L(0); MMA(0, 0, At, B0); BAR;
;       LDB(B1, 1, 1); WAIT_V(0); BAR; WAIT_L(0); MMA(0, 1, At, B1); BAR;
	s_waitcnt lgkmcnt(0)
	v_mfma_f32_16x16x32_bf16 v[44:47], v[152:155], v[68:71], v[44:47]
	v_mfma_f32_16x16x32_bf16 v[40:43], v[160:163], v[68:71], v[40:43]
	v_mfma_f32_16x16x32_bf16 v[36:39], v[152:155], v[172:175], v[36:39]
	v_mfma_f32_16x16x32_bf16 v[32:35], v[160:163], v[172:175], v[32:35]
	v_mfma_f32_16x16x32_bf16 v[28:31], v[152:155], v[180:183], v[28:31]
	v_mfma_f32_16x16x32_bf16 v[24:27], v[160:163], v[180:183], v[24:27]
	v_mfma_f32_16x16x32_bf16 v[20:23], v[152:155], v[188:191], v[20:23]
	v_mfma_f32_16x16x32_bf16 v[16:19], v[160:163], v[188:191], v[16:19]
	v_mfma_f32_16x16x32_bf16 v[44:47], v[156:159], v[92:95], v[44:47]
	v_mfma_f32_16x16x32_bf16 v[40:43], v[148:151], v[92:95], v[40:43]
	v_mfma_f32_16x16x32_bf16 v[36:39], v[156:159], v[176:179], v[36:39]
	v_mfma_f32_16x16x32_bf16 v[32:35], v[148:151], v[176:179], v[32:35]
	v_mfma_f32_16x16x32_bf16 v[28:31], v[156:159], v[184:187], v[28:31]
	v_mfma_f32_16x16x32_bf16 v[24:27], v[148:151], v[184:187], v[24:27]
	v_mfma_f32_16x16x32_bf16 v[20:23], v[156:159], v[192:195], v[20:23]
	v_mfma_f32_16x16x32_bf16 v[16:19], v[148:151], v[192:195], v[16:19]
	v_mfma_f32_16x16x32_bf16 v[4:7], v[196:199], v[172:175], v[4:7]
	v_mfma_f32_16x16x32_bf16 v[0:3], v[142:145], v[172:175], v[0:3]
	v_mfma_f32_16x16x32_bf16 v[12:15], v[196:199], v[68:71], v[12:15]
	v_mfma_f32_16x16x32_bf16 v[8:11], v[142:145], v[68:71], v[8:11]
	v_mfma_f32_16x16x32_bf16 v[64:67], v[196:199], v[180:183], v[64:67]
	v_mfma_f32_16x16x32_bf16 v[68:71], v[142:145], v[180:183], v[72:75]
	v_mfma_f32_16x16x32_bf16 v[72:75], v[196:199], v[188:191], v[76:79]
	v_mfma_f32_16x16x32_bf16 v[76:79], v[142:145], v[188:191], v[84:87]
	v_mfma_f32_16x16x32_bf16 v[4:7], v[200:203], v[176:179], v[4:7]
	v_mfma_f32_16x16x32_bf16 v[0:3], v[204:207], v[176:179], v[0:3]
	v_mfma_f32_16x16x32_bf16 v[142:145], v[200:203], v[92:95], v[12:15]
	v_mfma_f32_16x16x32_bf16 v[146:149], v[204:207], v[92:95], v[8:11]
	v_mfma_f32_16x16x32_bf16 v[150:153], v[200:203], v[184:187], v[64:67]
	v_mfma_f32_16x16x32_bf16 v[154:157], v[204:207], v[184:187], v[68:71]
	v_mfma_f32_16x16x32_bf16 v[158:161], v[200:203], v[192:195], v[72:75]
	v_mfma_f32_16x16x32_bf16 v[172:175], v[204:207], v[192:195], v[76:79]
	s_barrier
	ds_read_b128 v[8:11], v137
	ds_read_b128 v[12:15], v138
	ds_read_b128 v[176:179], v139
	ds_read_b128 v[138:141], v140
	ds_read_b128 v[64:67], v129 offset:32768
	ds_read_b128 v[72:75], v129 offset:33792
	ds_read_b128 v[180:183], v132 offset:32768
	ds_read_b128 v[184:187], v132 offset:33792
	ds_read_b128 v[188:191], v131 offset:32768
	ds_read_b128 v[192:195], v131 offset:33792
	ds_read_b128 v[196:199], v130 offset:32768
	ds_read_b128 v[200:203], v130 offset:33792
	s_waitcnt vmcnt(2)
	s_barrier
	s_waitcnt lgkmcnt(0)
	v_mfma_f32_16x16x32_bf16 v[68:71], v[8:11], v[64:67], v[124:127]
	v_mfma_f32_16x16x32_bf16 v[76:79], v[176:179], v[64:67], v[120:123]
	v_mfma_f32_16x16x32_bf16 v[84:87], v[8:11], v[180:183], v[116:119]
	v_mfma_f32_16x16x32_bf16 v[92:95], v[176:179], v[180:183], v[112:115]
	v_mfma_f32_16x16x32_bf16 v[112:115], v[8:11], v[188:191], v[108:111]
	v_mfma_f32_16x16x32_bf16 v[104:107], v[176:179], v[188:191], v[104:107]
	v_mfma_f32_16x16x32_bf16 v[120:123], v[8:11], v[196:199], v[100:103]
	v_mfma_f32_16x16x32_bf16 v[96:99], v[176:179], v[196:199], v[96:99]
	v_mfma_f32_16x16x32_bf16 v[124:127], v[12:15], v[72:75], v[68:71]
	v_mfma_f32_16x16x32_bf16 v[116:119], v[138:141], v[72:75], v[76:79]
	v_mfma_f32_16x16x32_bf16 v[108:111], v[12:15], v[184:187], v[84:87]
	v_mfma_f32_16x16x32_bf16 v[100:103], v[138:141], v[184:187], v[92:95]
	v_mfma_f32_16x16x32_bf16 v[92:95], v[12:15], v[192:195], v[112:115]
	v_mfma_f32_16x16x32_bf16 v[84:87], v[138:141], v[192:195], v[104:107]
	v_mfma_f32_16x16x32_bf16 v[76:79], v[12:15], v[200:203], v[120:123]
	v_mfma_f32_16x16x32_bf16 v[68:71], v[138:141], v[200:203], v[96:99]
	s_barrier
; #define LDA(dst, b, h) _Pragma("unroll") for (int m = 0; m < 4; ++m) _Pragma("unroll") for (int k = 0; k < 2; ++k) \
;     dst[m][k] = *reinterpret_cast<const bf16x8*>(SA(b, h) + lds_byte(wr * 64 + m * 16 + fr, k * 32 + fq * 8))
; #define LDB(dst, b, h) _Pragma("unroll") for (int n = 0; n < 2; ++n) _Pragma("unroll") for (int k = 0; k < 2; ++k) \
;     dst[n][k] = *reinterpret_cast<const bf16x8*>(SB(b, h) + lds_byte(wc * 32 + n * 16 + fr, k * 32 + fq * 8))
; #define WAIT_V(n) asm volatile("s_waitcnt vmcnt(" #n ")" ::: "memory")
; #define WAIT_L(n) asm volatile("s_waitcnt lgkmcnt(" #n ")" ::: "memory")
; #define BAR __builtin_amdgcn_s_barrier()
;     ...
;     { LDB(B0, 1, 0); LDA(At, 1, 0); WAIT_V(2); BAR; WAIT_L(0); MMA(0, 0, At, B0); BAR;
;       LDB(B1, 1, 1); WAIT_V(0); BAR; WAIT_L(0); MMA(0, 1, At, B1); BAR;
;       LDA(At, 1, 1); BAR; WAIT_L(0); MMA(1, 0, At, B0); MMA(1, 1, At, B1); BAR; }
;     if (wr == 0) BAR;
	ds_read_b128 v[204:207], v133
	ds_read_b128 v[208:211], v134
	ds_read_b128 v[212:215], v135
	ds_read_b128 v[134:137], v136
	s_waitcnt vmcnt(0)
	s_barrier
	s_waitcnt lgkmcnt(0)
	v_mfma_f32_16x16x32_bf16 v[96:99], v[204:207], v[64:67], v[164:167]
	v_mfma_f32_16x16x32_bf16 v[64:67], v[212:215], v[64:67], v[88:91]
	v_mfma_f32_16x16x32_bf16 v[80:83], v[204:207], v[180:183], v[80:83]
	v_mfma_f32_16x16x32_bf16 v[88:91], v[212:215], v[180:183], v[168:171]
	v_mfma_f32_16x16x32_bf16 v[60:63], v[204:207], v[188:191], v[60:63]
	v_mfma_f32_16x16x32_bf16 v[56:59], v[212:215], v[188:191], v[56:59]
	v_mfma_f32_16x16x32_bf16 v[52:55], v[204:207], v[196:199], v[52:55]
	v_mfma_f32_16x16x32_bf16 v[48:51], v[212:215], v[196:199], v[48:51]
	v_mfma_f32_16x16x32_bf16 v[120:123], v[208:211], v[72:75], v[96:99]
	v_mfma_f32_16x16x32_bf16 v[112:115], v[134:137], v[72:75], v[64:67]
	v_mfma_f32_16x16x32_bf16 v[104:107], v[208:211], v[184:187], v[80:83]
	v_mfma_f32_16x16x32_bf16 v[96:99], v[134:137], v[184:187], v[88:91]
	v_mfma_f32_16x16x32_bf16 v[88:91], v[208:211], v[192:195], v[60:63]
	v_mfma_f32_16x16x32_bf16 v[80:83], v[134:137], v[192:195], v[56:59]
	v_mfma_f32_16x16x32_bf16 v[72:75], v[208:211], v[200:203], v[52:55]
	v_mfma_f32_16x16x32_bf16 v[64:67], v[134:137], v[200:203], v[48:51]
	s_barrier
	s_nop 0
	ds_read_b128 v[48:51], v129 offset:49152
	ds_read_b128 v[162:165], v129 offset:50176
	ds_read_b128 v[52:55], v132 offset:49152
	ds_read_b128 v[166:169], v132 offset:50176
	ds_read_b128 v[180:183], v131 offset:49152
	ds_read_b128 v[184:187], v131 offset:50176
	ds_read_b128 v[188:191], v130 offset:49152
	ds_read_b128 v[130:133], v130 offset:50176
	s_barrier
	s_waitcnt lgkmcnt(0)
	v_mfma_f32_16x16x32_bf16 v[44:47], v[8:11], v[48:51], v[44:47]
	v_mfma_f32_16x16x32_bf16 v[40:43], v[176:179], v[48:51], v[40:43]
	v_mfma_f32_16x16x32_bf16 v[36:39], v[8:11], v[52:55], v[36:39]
	v_mfma_f32_16x16x32_bf16 v[32:35], v[176:179], v[52:55], v[32:35]
	v_mfma_f32_16x16x32_bf16 v[28:31], v[8:11], v[180:183], v[28:31]
	v_mfma_f32_16x16x32_bf16 v[24:27], v[176:179], v[180:183], v[24:27]
	v_mfma_f32_16x16x32_bf16 v[8:11], v[8:11], v[188:191], v[20:23]
	v_mfma_f32_16x16x32_bf16 v[16:19], v[176:179], v[188:191], v[16:19]
	v_mfma_f32_16x16x32_bf16 v[60:63], v[12:15], v[162:165], v[44:47]
	v_mfma_f32_16x16x32_bf16 v[56:59], v[138:141], v[162:165], v[40:43]
	v_mfma_f32_16x16x32_bf16 v[44:47], v[12:15], v[166:169], v[36:39]
	v_mfma_f32_16x16x32_bf16 v[40:43], v[138:141], v[166:169], v[32:35]
	v_mfma_f32_16x16x32_bf16 v[28:31], v[12:15], v[184:187], v[28:31]
	v_mfma_f32_16x16x32_bf16 v[24:27], v[138:141], v[184:187], v[24:27]
	v_mfma_f32_16x16x32_bf16 v[12:15], v[12:15], v[130:133], v[8:11]
	v_mfma_f32_16x16x32_bf16 v[8:11], v[138:141], v[130:133], v[16:19]
	v_mfma_f32_16x16x32_bf16 v[16:19], v[204:207], v[48:51], v[142:145]
	v_mfma_f32_16x16x32_bf16 v[20:23], v[212:215], v[48:51], v[146:149]
	v_mfma_f32_16x16x32_bf16 v[4:7], v[204:207], v[52:55], v[4:7]
	v_mfma_f32_16x16x32_bf16 v[0:3], v[212:215], v[52:55], v[0:3]
	v_mfma_f32_16x16x32_bf16 v[138:141], v[204:207], v[180:183], v[150:153]
	v_mfma_f32_16x16x32_bf16 v[142:145], v[212:215], v[180:183], v[154:157]
	v_mfma_f32_16x16x32_bf16 v[146:149], v[204:207], v[188:191], v[158:161]
	v_mfma_f32_16x16x32_bf16 v[150:153], v[212:215], v[188:191], v[172:175]
	v_mfma_f32_16x16x32_bf16 v[52:55], v[208:211], v[162:165], v[16:19]
	v_mfma_f32_16x16x32_bf16 v[48:51], v[134:137], v[162:165], v[20:23]
	v_mfma_f32_16x16x32_bf16 v[36:39], v[208:211], v[166:169], v[4:7]
	v_mfma_f32_16x16x32_bf16 v[32:35], v[134:137], v[166:169], v[0:3]
	v_mfma_f32_16x16x32_bf16 v[20:23], v[208:211], v[184:187], v[138:141]
	v_mfma_f32_16x16x32_bf16 v[16:19], v[134:137], v[184:187], v[142:145]
	v_mfma_f32_16x16x32_bf16 v[4:7], v[208:211], v[130:133], v[146:149]
	v_mfma_f32_16x16x32_bf16 v[0:3], v[134:137], v[130:133], v[150:153]
	v_cmp_gt_u32_e32 vcc, s74, v128
	s_barrier
	s_and_saveexec_b64 s[4:5], vcc
	s_cbranch_execz .LBB0_760
	s_barrier
